# v7 plus: redundant setprio pairs removed in GEMM K-loops; mixprep wave sums last 4 steps via DPP
# speedup vs baseline: 1.0184x; 1.0005x over previous
; #define PG8_STAGE(bufoff, gbase, voff) do { _Pragma("unroll") for (int _i = 0; _i < 2; ++_i) \
;         __builtin_amdgcn_global_load_lds((const unsigned*)((const char*)(gbase) + (voff)[_i]), (PG8_LAS unsigned*)(lds + (bufoff) + ldsw + _i * 8192), 16, 0, 0); } while (0)
; #define PG8_LDA(dst, b, h) do { _Pragma("unroll") for (int m = 0; m < 4; ++m) _Pragma("unroll") for (int k = 0; k < 2; ++k) dst[m][k] = *(const PG8_LAS bf16x8*)(lds + PG8_SA(b, h) + aoff + m * 2048 + k * 1024); } while (0)
; #define PG8_LDB(dst, b, h) do { _Pragma("unroll") for (int n = 0; n < 2; ++n) _Pragma("unroll") for (int k = 0; k < 2; ++k) dst[n][k] = *(const PG8_LAS bf16x8*)(lds + PG8_SB(b, h) + boff + n * 2048 + k * 1024); } while (0)
; #define PG8_MMA(ai, bj, At, Bt) do { __builtin_amdgcn_s_setprio(1); _Pragma("unroll") for (int m = 0; m < 4; ++m) _Pragma("unroll") for (int n = 0; n < 2; ++n) _Pragma("unroll") for (int k = 0; k < 2; ++k) \
;         acc[ai][bj][m][n] = __builtin_amdgcn_mfma_f32_16x16x32_bf16(Bt[n][k], At[m][k], acc[ai][bj][m][n], 0, 0, 0); __builtin_amdgcn_s_setprio(0); } while (0)
; #define PG8_BAR __builtin_amdgcn_s_barrier()
; template <class Epi, class Sched, bool ALIGN_EPI = false, bool SP2 = false>
; __device__ __forceinline__ void gemm_phase(PG8_LAS unsigned char* lds, int tid_in, const Gemm g, const Sched& S, const Epi& E) {
;     ...
;             PG8_LDB(B0, 0, 0); PG8_LDB(B1, 0, 1); PG8_SCHED; PG8_LDA(At, 0, 0); PG8_STAGE(PG8_SA(1, 1), a1 + hstep, voffA);
;             PG8_WAIT_V(8); PG8_WAIT_L(0); PG8_BAR; PG8_MMA(0, 0, At, B0); PG8_MMA(0, 1, At, B1); PG8_BAR; PG8_SCHED;
;             PG8_LDA(At, 0, 1); PG8_STAGE(PG8_SB(0, 0), b2, voffB); PG8_STAGE(PG8_SB(0, 1), b2 + hstep, voffB); PG8_STAGE(PG8_SA(0, 0), a2, voffA);
;             PG8_WAIT_V(8); PG8_WAIT_L(0); PG8_BAR; PG8_MMA(1, 0, At, B0); PG8_MMA(1, 1, At, B1); PG8_BAR; PG8_SCHED;
;             PG8_LDB(B0, 1, 0); PG8_LDB(B1, 1, 1); PG8_SCHED; PG8_LDA(At, 1, 0); PG8_STAGE(PG8_SA(0, 1), a2 + hstep, voffA);
;             PG8_WAIT_V(8); PG8_WAIT_L(0); PG8_BAR; PG8_MMA(0, 0, At, B0); PG8_MMA(0, 1, At, B1); PG8_BAR; PG8_SCHED;
;             PG8_LDA(At, 1, 1); PG8_STAGE(PG8_SB(1, 0), b3, voffB); PG8_STAGE(PG8_SB(1, 1), b3 + hstep, voffB); PG8_STAGE(PG8_SA(1, 0), a3, voffA);
;             PG8_WAIT_V(8); PG8_WAIT_L(0); PG8_BAR; PG8_MMA(1, 0, At, B0); PG8_MMA(1, 1, At, B1); PG8_BAR; PG8_SCHED;
.LBB0_137:
	s_add_u32 s18, s34, 0xfffc0080
	s_addc_u32 s33, s35, -1
	s_add_i32 s36, 0, 0x10000
	s_cmp_eq_u32 s29, 12
	s_cselect_b32 s49, s1, s33
	s_cselect_b32 s48, s15, s18
	s_cselect_b32 s43, s13, s28
	s_cselect_b32 s42, s20, s21
	s_add_i32 s18, 0, 0x14000
	v_add_u32_e32 v142, s36, v162
	v_add_u32_e32 v160, s18, v162
	ds_read_b128 v[130:133], v142
	ds_read_b128 v[134:137], v142 offset:1024
	ds_read_b128 v[138:141], v142 offset:2048
	ds_read_b128 v[142:145], v142 offset:3072
	ds_read_b128 v[156:159], v160
	ds_read_b128 v[164:167], v160 offset:1024
	ds_read_b128 v[168:171], v160 offset:2048
	ds_read_b128 v[172:175], v160 offset:3072
	v_lshl_add_u64 v[160:161], s[34:35], 0, v[152:153]
	s_add_i32 m0, s51, 0xc000
	ds_read_b128 v[176:179], v163
	ds_read_b128 v[180:183], v163 offset:1024
	ds_read_b128 v[184:187], v163 offset:2048
	ds_read_b128 v[188:191], v163 offset:3072
	ds_read_b128 v[192:195], v163 offset:4096
	ds_read_b128 v[196:199], v163 offset:5120
	ds_read_b128 v[200:203], v163 offset:6144
	ds_read_b128 v[218:221], v163 offset:7168
	global_load_lds_dwordx4 v[160:161], off
	v_lshl_add_u64 v[160:161], s[34:35], 0, v[154:155]
	s_add_i32 m0, s51, 0xe000
	s_nop 0
	global_load_lds_dwordx4 v[160:161], off
	s_waitcnt vmcnt(8)
	s_waitcnt lgkmcnt(0)
	s_barrier
	s_setprio 1
	s_waitcnt lgkmcnt(0)
	v_mfma_f32_16x16x32_bf16 v[126:129], v[130:133], v[176:179], v[126:129]
	v_mfma_f32_16x16x32_bf16 v[122:125], v[138:141], v[176:179], v[122:125]
	v_mfma_f32_16x16x32_bf16 v[118:121], v[130:133], v[184:187], v[118:121]
	v_mfma_f32_16x16x32_bf16 v[110:113], v[138:141], v[184:187], v[110:113]
	v_mfma_f32_16x16x32_bf16 v[102:105], v[130:133], v[192:195], v[102:105]
	v_mfma_f32_16x16x32_bf16 v[94:97], v[138:141], v[192:195], v[94:97]
	v_mfma_f32_16x16x32_bf16 v[86:89], v[130:133], v[200:203], v[86:89]
	v_mfma_f32_16x16x32_bf16 v[78:81], v[138:141], v[200:203], v[78:81]
	v_mfma_f32_16x16x32_bf16 v[126:129], v[134:137], v[180:183], v[126:129]
	v_mfma_f32_16x16x32_bf16 v[122:125], v[142:145], v[180:183], v[122:125]
	v_mfma_f32_16x16x32_bf16 v[118:121], v[134:137], v[188:191], v[118:121]
	v_mfma_f32_16x16x32_bf16 v[110:113], v[142:145], v[188:191], v[110:113]
	v_mfma_f32_16x16x32_bf16 v[102:105], v[134:137], v[196:199], v[102:105]
	v_mfma_f32_16x16x32_bf16 v[94:97], v[142:145], v[196:199], v[94:97]
	v_mfma_f32_16x16x32_bf16 v[86:89], v[134:137], v[218:221], v[86:89]
	v_mfma_f32_16x16x32_bf16 v[78:81], v[142:145], v[218:221], v[78:81]
	v_mfma_f32_16x16x32_bf16 v[114:117], v[156:159], v[176:179], v[114:117]
	v_mfma_f32_16x16x32_bf16 v[106:109], v[168:171], v[176:179], v[106:109]
	v_mfma_f32_16x16x32_bf16 v[98:101], v[156:159], v[184:187], v[98:101]
	v_mfma_f32_16x16x32_bf16 v[90:93], v[168:171], v[184:187], v[90:93]
	v_mfma_f32_16x16x32_bf16 v[82:85], v[156:159], v[192:195], v[82:85]
	v_mfma_f32_16x16x32_bf16 v[74:77], v[168:171], v[192:195], v[74:77]
	v_mfma_f32_16x16x32_bf16 v[70:73], v[156:159], v[200:203], v[70:73]
	v_mfma_f32_16x16x32_bf16 v[66:69], v[168:171], v[200:203], v[66:69]
	v_mfma_f32_16x16x32_bf16 v[114:117], v[164:167], v[180:183], v[114:117]
	v_mfma_f32_16x16x32_bf16 v[106:109], v[172:175], v[180:183], v[106:109]
	v_mfma_f32_16x16x32_bf16 v[98:101], v[164:167], v[188:191], v[98:101]
	v_mfma_f32_16x16x32_bf16 v[90:93], v[172:175], v[188:191], v[90:93]
	v_mfma_f32_16x16x32_bf16 v[82:85], v[164:167], v[196:199], v[82:85]
	v_mfma_f32_16x16x32_bf16 v[74:77], v[172:175], v[196:199], v[74:77]
	v_mfma_f32_16x16x32_bf16 v[70:73], v[164:167], v[218:221], v[70:73]
	v_mfma_f32_16x16x32_bf16 v[66:69], v[172:175], v[218:221], v[66:69]
	s_setprio 0
	s_barrier
	s_add_i32 s33, s36, s50
	v_lshl_add_u64 v[160:161], s[42:43], 0, v[8:9]
	s_mov_b32 m0, s33
	ds_read_b128 v[176:179], v163 offset:16384
	ds_read_b128 v[180:183], v163 offset:17408
	ds_read_b128 v[184:187], v163 offset:18432
	ds_read_b128 v[188:191], v163 offset:19456
	ds_read_b128 v[192:195], v163 offset:20480
	ds_read_b128 v[196:199], v163 offset:21504
	ds_read_b128 v[200:203], v163 offset:22528
	ds_read_b128 v[218:221], v163 offset:23552
	global_load_lds_dwordx4 v[160:161], off
	s_add_i32 m0, s33, 0x2000
	s_add_u32 s36, s42, 0x40000
	v_lshl_add_u64 v[204:205], s[42:43], 0, v[146:147]
	s_addc_u32 s37, s43, 0
	s_add_i32 s18, s18, s50
	global_load_lds_dwordx4 v[204:205], off
	v_lshl_add_u64 v[210:211], s[36:37], 0, v[8:9]
	s_mov_b32 m0, s18
	v_lshl_add_u64 v[212:213], s[48:49], 0, v[148:149]
	global_load_lds_dwordx4 v[210:211], off
	v_lshl_add_u64 v[210:211], s[36:37], 0, v[146:147]
	s_add_i32 m0, s18, 0x2000
	s_nop 0
	global_load_lds_dwordx4 v[210:211], off
	v_lshl_add_u64 v[210:211], s[48:49], 0, v[150:151]
	s_mov_b32 m0, s51
	s_nop 0
	global_load_lds_dwordx4 v[210:211], off
	s_mov_b32 m0, s58
	s_nop 0
	global_load_lds_dwordx4 v[212:213], off
	s_waitcnt vmcnt(8)
	s_waitcnt lgkmcnt(0)
	s_barrier
; #define PG8_STAGE(bufoff, gbase, voff) do { _Pragma("unroll") for (int _i = 0; _i < 2; ++_i) \
;         __builtin_amdgcn_global_load_lds((const unsigned*)((const char*)(gbase) + (voff)[_i]), (PG8_LAS unsigned*)(lds + (bufoff) + ldsw + _i * 8192), 16, 0, 0); } while (0)
; #define PG8_LDA(dst, b, h) do { _Pragma("unroll") for (int m = 0; m < 4; ++m) _Pragma("unroll") for (int k = 0; k < 2; ++k) dst[m][k] = *(const PG8_LAS bf16x8*)(lds + PG8_SA(b, h) + aoff + m * 2048 + k * 1024); } while (0)
; #define PG8_LDB(dst, b, h) do { _Pragma("unroll") for (int n = 0; n < 2; ++n) _Pragma("unroll") for (int k = 0; k < 2; ++k) dst[n][k] = *(const PG8_LAS bf16x8*)(lds + PG8_SB(b, h) + boff + n * 2048 + k * 1024); } while (0)
; #define PG8_MMA(ai, bj, At, Bt) do { __builtin_amdgcn_s_setprio(1); _Pragma("unroll") for (int m = 0; m < 4; ++m) _Pragma("unroll") for (int n = 0; n < 2; ++n) _Pragma("unroll") for (int k = 0; k < 2; ++k) \
;         acc[ai][bj][m][n] = __builtin_amdgcn_mfma_f32_16x16x32_bf16(Bt[n][k], At[m][k], acc[ai][bj][m][n], 0, 0, 0); __builtin_amdgcn_s_setprio(0); } while (0)
; #define PG8_WAIT_V(n) asm volatile("s_waitcnt vmcnt(" #n ")" ::: "memory")
; #define PG8_WAIT_L(n) asm volatile("s_waitcnt lgkmcnt(" #n ")" ::: "memory")
; #define PG8_BAR __builtin_amdgcn_s_barrier()
; #define PG8_SCHED __builtin_amdgcn_sched_barrier(0)
; template <class Epi, class Sched, bool ALIGN_EPI = false, bool SP2 = false>
; __device__ __forceinline__ void gemm_phase(PG8_LAS unsigned char* lds, int tid_in, const Gemm g, const Sched& S, const Epi& E) {
;     ...
;             PG8_WAIT_V(8); PG8_WAIT_L(0); PG8_BAR; PG8_MMA(1, 0, At, B0); PG8_MMA(1, 1, At, B1); PG8_BAR; PG8_SCHED;
;             PG8_LDB(B0, 1, 0); PG8_LDB(B1, 1, 1); PG8_SCHED; PG8_LDA(At, 1, 0); PG8_STAGE(PG8_SA(0, 1), a2 + hstep, voffA);
;             PG8_WAIT_V(8); PG8_WAIT_L(0); PG8_BAR; PG8_MMA(0, 0, At, B0); PG8_MMA(0, 1, At, B1); PG8_BAR; PG8_SCHED;
	s_setprio 1
	s_waitcnt lgkmcnt(0)
	v_mfma_f32_16x16x32_bf16 v[62:65], v[130:133], v[176:179], v[62:65]
	v_mfma_f32_16x16x32_bf16 v[58:61], v[138:141], v[176:179], v[58:61]
	v_mfma_f32_16x16x32_bf16 v[54:57], v[130:133], v[184:187], v[54:57]
	v_mfma_f32_16x16x32_bf16 v[46:49], v[138:141], v[184:187], v[46:49]
	v_mfma_f32_16x16x32_bf16 v[38:41], v[130:133], v[192:195], v[38:41]
	v_mfma_f32_16x16x32_bf16 v[30:33], v[138:141], v[192:195], v[30:33]
	v_mfma_f32_16x16x32_bf16 v[22:25], v[130:133], v[200:203], v[22:25]
	v_mfma_f32_16x16x32_bf16 v[14:17], v[138:141], v[200:203], v[14:17]
	v_mfma_f32_16x16x32_bf16 v[62:65], v[134:137], v[180:183], v[62:65]
	v_mfma_f32_16x16x32_bf16 v[58:61], v[142:145], v[180:183], v[58:61]
	v_mfma_f32_16x16x32_bf16 v[54:57], v[134:137], v[188:191], v[54:57]
	v_mfma_f32_16x16x32_bf16 v[46:49], v[142:145], v[188:191], v[46:49]
	v_mfma_f32_16x16x32_bf16 v[38:41], v[134:137], v[196:199], v[38:41]
	v_mfma_f32_16x16x32_bf16 v[30:33], v[142:145], v[196:199], v[30:33]
	v_mfma_f32_16x16x32_bf16 v[22:25], v[134:137], v[218:221], v[22:25]
	v_mfma_f32_16x16x32_bf16 v[14:17], v[142:145], v[218:221], v[14:17]
	v_mfma_f32_16x16x32_bf16 v[50:53], v[156:159], v[176:179], v[50:53]
	v_mfma_f32_16x16x32_bf16 v[42:45], v[168:171], v[176:179], v[42:45]
	v_mfma_f32_16x16x32_bf16 v[34:37], v[156:159], v[184:187], v[34:37]
	v_mfma_f32_16x16x32_bf16 v[26:29], v[168:171], v[184:187], v[26:29]
	v_mfma_f32_16x16x32_bf16 v[18:21], v[156:159], v[192:195], v[18:21]
	v_mfma_f32_16x16x32_bf16 v[10:13], v[168:171], v[192:195], v[10:13]
	v_mfma_f32_16x16x32_bf16 v[4:7], v[156:159], v[200:203], v[4:7]
	v_mfma_f32_16x16x32_bf16 v[0:3], v[168:171], v[200:203], v[0:3]
	v_mfma_f32_16x16x32_bf16 v[50:53], v[164:167], v[180:183], v[50:53]
	v_mfma_f32_16x16x32_bf16 v[42:45], v[172:175], v[180:183], v[42:45]
	v_mfma_f32_16x16x32_bf16 v[34:37], v[164:167], v[188:191], v[34:37]
	v_mfma_f32_16x16x32_bf16 v[26:29], v[172:175], v[188:191], v[26:29]
	v_mfma_f32_16x16x32_bf16 v[18:21], v[164:167], v[196:199], v[18:21]
	v_mfma_f32_16x16x32_bf16 v[10:13], v[172:175], v[196:199], v[10:13]
	v_mfma_f32_16x16x32_bf16 v[4:7], v[164:167], v[218:221], v[4:7]
	v_mfma_f32_16x16x32_bf16 v[0:3], v[172:175], v[218:221], v[0:3]
	s_setprio 0
	s_barrier
	s_add_i32 s18, 0, 0x18000
	s_add_i32 s33, 0, 0x1c000
	v_add_u32_e32 v142, s18, v162
	v_add_u32_e32 v172, s33, v162
	ds_read_b128 v[130:133], v142
	ds_read_b128 v[134:137], v142 offset:1024
	ds_read_b128 v[138:141], v142 offset:2048
	ds_read_b128 v[142:145], v142 offset:3072
	ds_read_b128 v[156:159], v172
	ds_read_b128 v[164:167], v172 offset:1024
	ds_read_b128 v[168:171], v172 offset:2048
	ds_read_b128 v[172:175], v172 offset:3072
	s_add_u32 s36, s48, 0x40000
	s_addc_u32 s37, s49, 0
	s_mov_b32 m0, s59
	v_lshl_add_u64 v[214:215], s[36:37], 0, v[150:151]
	ds_read_b128 v[176:179], v163 offset:32768
	ds_read_b128 v[180:183], v163 offset:33792
	ds_read_b128 v[184:187], v163 offset:34816
	ds_read_b128 v[188:191], v163 offset:35840
	ds_read_b128 v[192:195], v163 offset:36864
	ds_read_b128 v[196:199], v163 offset:37888
	ds_read_b128 v[200:203], v163 offset:38912
	ds_read_b128 v[218:221], v163 offset:39936
	global_load_lds_dwordx4 v[214:215], off
	v_lshl_add_u64 v[214:215], s[36:37], 0, v[148:149]
	s_mov_b32 m0, s60
	s_nop 0
	global_load_lds_dwordx4 v[214:215], off
	s_waitcnt vmcnt(8)
	s_waitcnt lgkmcnt(0)
	s_barrier
	s_setprio 1
	s_waitcnt lgkmcnt(0)
	v_mfma_f32_16x16x32_bf16 v[126:129], v[130:133], v[176:179], v[126:129]
	v_mfma_f32_16x16x32_bf16 v[122:125], v[138:141], v[176:179], v[122:125]
	v_mfma_f32_16x16x32_bf16 v[118:121], v[130:133], v[184:187], v[118:121]
	v_mfma_f32_16x16x32_bf16 v[110:113], v[138:141], v[184:187], v[110:113]
	v_mfma_f32_16x16x32_bf16 v[102:105], v[130:133], v[192:195], v[102:105]
	v_mfma_f32_16x16x32_bf16 v[94:97], v[138:141], v[192:195], v[94:97]
	v_mfma_f32_16x16x32_bf16 v[86:89], v[130:133], v[200:203], v[86:89]
	v_mfma_f32_16x16x32_bf16 v[78:81], v[138:141], v[200:203], v[78:81]
	v_mfma_f32_16x16x32_bf16 v[126:129], v[134:137], v[180:183], v[126:129]
	v_mfma_f32_16x16x32_bf16 v[122:125], v[142:145], v[180:183], v[122:125]
	v_mfma_f32_16x16x32_bf16 v[118:121], v[134:137], v[188:191], v[118:121]
	v_mfma_f32_16x16x32_bf16 v[110:113], v[142:145], v[188:191], v[110:113]
	v_mfma_f32_16x16x32_bf16 v[102:105], v[134:137], v[196:199], v[102:105]
	v_mfma_f32_16x16x32_bf16 v[94:97], v[142:145], v[196:199], v[94:97]
	v_mfma_f32_16x16x32_bf16 v[86:89], v[134:137], v[218:221], v[86:89]
	v_mfma_f32_16x16x32_bf16 v[78:81], v[142:145], v[218:221], v[78:81]
	v_mfma_f32_16x16x32_bf16 v[114:117], v[156:159], v[176:179], v[114:117]
	v_mfma_f32_16x16x32_bf16 v[106:109], v[168:171], v[176:179], v[106:109]
	v_mfma_f32_16x16x32_bf16 v[98:101], v[156:159], v[184:187], v[98:101]
	v_mfma_f32_16x16x32_bf16 v[90:93], v[168:171], v[184:187], v[90:93]
	v_mfma_f32_16x16x32_bf16 v[82:85], v[156:159], v[192:195], v[82:85]
	v_mfma_f32_16x16x32_bf16 v[74:77], v[168:171], v[192:195], v[74:77]
	v_mfma_f32_16x16x32_bf16 v[70:73], v[156:159], v[200:203], v[70:73]
	v_mfma_f32_16x16x32_bf16 v[66:69], v[168:171], v[200:203], v[66:69]
	v_mfma_f32_16x16x32_bf16 v[114:117], v[164:167], v[180:183], v[114:117]
	v_mfma_f32_16x16x32_bf16 v[106:109], v[172:175], v[180:183], v[106:109]
	v_mfma_f32_16x16x32_bf16 v[98:101], v[164:167], v[188:191], v[98:101]
	v_mfma_f32_16x16x32_bf16 v[90:93], v[172:175], v[188:191], v[90:93]
	v_mfma_f32_16x16x32_bf16 v[82:85], v[164:167], v[196:199], v[82:85]
	v_mfma_f32_16x16x32_bf16 v[74:77], v[172:175], v[196:199], v[74:77]
	v_mfma_f32_16x16x32_bf16 v[70:73], v[164:167], v[218:221], v[70:73]
	v_mfma_f32_16x16x32_bf16 v[66:69], v[172:175], v[218:221], v[66:69]
	s_setprio 0
	s_barrier
; #define PG8_STAGE(bufoff, gbase, voff) do { _Pragma("unroll") for (int _i = 0; _i < 2; ++_i) \
;         __builtin_amdgcn_global_load_lds((const unsigned*)((const char*)(gbase) + (voff)[_i]), (PG8_LAS unsigned*)(lds + (bufoff) + ldsw + _i * 8192), 16, 0, 0); } while (0)
; #define PG8_LDA(dst, b, h) do { _Pragma("unroll") for (int m = 0; m < 4; ++m) _Pragma("unroll") for (int k = 0; k < 2; ++k) dst[m][k] = *(const PG8_LAS bf16x8*)(lds + PG8_SA(b, h) + aoff + m * 2048 + k * 1024); } while (0)
; #define PG8_MMA(ai, bj, At, Bt) do { __builtin_amdgcn_s_setprio(1); _Pragma("unroll") for (int m = 0; m < 4; ++m) _Pragma("unroll") for (int n = 0; n < 2; ++n) _Pragma("unroll") for (int k = 0; k < 2; ++k) \
;         acc[ai][bj][m][n] = __builtin_amdgcn_mfma_f32_16x16x32_bf16(Bt[n][k], At[m][k], acc[ai][bj][m][n], 0, 0, 0); __builtin_amdgcn_s_setprio(0); } while (0)
; #define PG8_WAIT_V(n) asm volatile("s_waitcnt vmcnt(" #n ")" ::: "memory")
; #define PG8_WAIT_L(n) asm volatile("s_waitcnt lgkmcnt(" #n ")" ::: "memory")
; #define PG8_BAR __builtin_amdgcn_s_barrier()
; #define PG8_SCHED __builtin_amdgcn_sched_barrier(0)
; template <class Epi, class Sched, bool ALIGN_EPI = false, bool SP2 = false>
; __device__ __forceinline__ void gemm_phase(PG8_LAS unsigned char* lds, int tid_in, const Gemm g, const Sched& S, const Epi& E) {
;     ...
;             PG8_LDA(At, 1, 1); PG8_STAGE(PG8_SB(1, 0), b3, voffB); PG8_STAGE(PG8_SB(1, 1), b3 + hstep, voffB); PG8_STAGE(PG8_SA(1, 0), a3, voffA);
;             PG8_WAIT_V(8); PG8_WAIT_L(0); PG8_BAR; PG8_MMA(1, 0, At, B0); PG8_MMA(1, 1, At, B1); PG8_BAR; PG8_SCHED;
;     ...
;         if constexpr (ALIGN_EPI) { if (wr == 0) PG8_BAR; }
	s_add_i32 s18, s18, s50
	v_lshl_add_u64 v[160:161], v[160:161], 0, s[24:25]
	s_mov_b32 m0, s18
	ds_read_b128 v[176:179], v163 offset:49152
	ds_read_b128 v[180:183], v163 offset:50176
	ds_read_b128 v[184:187], v163 offset:51200
	ds_read_b128 v[188:191], v163 offset:52224
	ds_read_b128 v[192:195], v163 offset:53248
	ds_read_b128 v[196:199], v163 offset:54272
	ds_read_b128 v[200:203], v163 offset:55296
	ds_read_b128 v[218:221], v163 offset:56320
	global_load_lds_dwordx4 v[160:161], off
	s_add_i32 m0, s18, 0x2000
	s_add_u32 s36, s42, 0x40080
	v_lshl_add_u64 v[160:161], v[204:205], 0, s[24:25]
	s_addc_u32 s37, s43, 0
	s_add_i32 s18, s33, s50
	global_load_lds_dwordx4 v[160:161], off
	v_lshl_add_u64 v[160:161], s[36:37], 0, v[8:9]
	s_mov_b32 m0, s18
	s_nop 0
	global_load_lds_dwordx4 v[160:161], off
	v_lshl_add_u64 v[160:161], s[36:37], 0, v[146:147]
	s_add_i32 m0, s18, 0x2000
	s_nop 0
	global_load_lds_dwordx4 v[160:161], off
	v_lshl_add_u64 v[160:161], v[210:211], 0, s[24:25]
	s_mov_b32 m0, s7
	s_nop 0
	global_load_lds_dwordx4 v[160:161], off
	v_lshl_add_u64 v[160:161], v[212:213], 0, s[24:25]
	s_mov_b32 m0, s8
	s_nop 0
	global_load_lds_dwordx4 v[160:161], off
	s_waitcnt vmcnt(8)
	s_waitcnt lgkmcnt(0)
	s_barrier
	s_setprio 1
	s_waitcnt lgkmcnt(0)
	v_mfma_f32_16x16x32_bf16 v[62:65], v[130:133], v[176:179], v[62:65]
	v_mfma_f32_16x16x32_bf16 v[58:61], v[138:141], v[176:179], v[58:61]
	v_mfma_f32_16x16x32_bf16 v[54:57], v[130:133], v[184:187], v[54:57]
	v_mfma_f32_16x16x32_bf16 v[46:49], v[138:141], v[184:187], v[46:49]
	v_mfma_f32_16x16x32_bf16 v[38:41], v[130:133], v[192:195], v[38:41]
	v_mfma_f32_16x16x32_bf16 v[30:33], v[138:141], v[192:195], v[30:33]
	v_mfma_f32_16x16x32_bf16 v[22:25], v[130:133], v[200:203], v[22:25]
	v_mfma_f32_16x16x32_bf16 v[14:17], v[138:141], v[200:203], v[14:17]
	v_mfma_f32_16x16x32_bf16 v[62:65], v[134:137], v[180:183], v[62:65]
	v_mfma_f32_16x16x32_bf16 v[58:61], v[142:145], v[180:183], v[58:61]
	v_mfma_f32_16x16x32_bf16 v[54:57], v[134:137], v[188:191], v[54:57]
	v_mfma_f32_16x16x32_bf16 v[46:49], v[142:145], v[188:191], v[46:49]
	v_mfma_f32_16x16x32_bf16 v[38:41], v[134:137], v[196:199], v[38:41]
	v_mfma_f32_16x16x32_bf16 v[30:33], v[142:145], v[196:199], v[30:33]
	v_mfma_f32_16x16x32_bf16 v[22:25], v[134:137], v[218:221], v[22:25]
	v_mfma_f32_16x16x32_bf16 v[14:17], v[142:145], v[218:221], v[14:17]
	v_mfma_f32_16x16x32_bf16 v[50:53], v[156:159], v[176:179], v[50:53]
	v_mfma_f32_16x16x32_bf16 v[42:45], v[168:171], v[176:179], v[42:45]
	v_mfma_f32_16x16x32_bf16 v[34:37], v[156:159], v[184:187], v[34:37]
	v_mfma_f32_16x16x32_bf16 v[26:29], v[168:171], v[184:187], v[26:29]
	v_mfma_f32_16x16x32_bf16 v[18:21], v[156:159], v[192:195], v[18:21]
	v_mfma_f32_16x16x32_bf16 v[10:13], v[168:171], v[192:195], v[10:13]
	v_mfma_f32_16x16x32_bf16 v[4:7], v[156:159], v[200:203], v[4:7]
	v_mfma_f32_16x16x32_bf16 v[0:3], v[168:171], v[200:203], v[0:3]
	v_mfma_f32_16x16x32_bf16 v[50:53], v[164:167], v[180:183], v[50:53]
	v_mfma_f32_16x16x32_bf16 v[42:45], v[172:175], v[180:183], v[42:45]
	v_mfma_f32_16x16x32_bf16 v[34:37], v[164:167], v[188:191], v[34:37]
	v_mfma_f32_16x16x32_bf16 v[26:29], v[172:175], v[188:191], v[26:29]
	v_mfma_f32_16x16x32_bf16 v[18:21], v[164:167], v[196:199], v[18:21]
	v_mfma_f32_16x16x32_bf16 v[10:13], v[172:175], v[196:199], v[10:13]
	v_mfma_f32_16x16x32_bf16 v[4:7], v[164:167], v[218:221], v[4:7]
	v_mfma_f32_16x16x32_bf16 v[0:3], v[172:175], v[218:221], v[0:3]
	s_setprio 0
	s_barrier
	s_add_i32 s29, s29, 2
	s_add_u32 s34, s34, 0x100
	s_addc_u32 s35, s35, 0
	s_add_u32 s21, s21, 0x100
	s_addc_u32 s28, s28, 0
	s_cmp_gt_u32 s29, 13
	s_cbranch_scc0 .LBB0_137
	s_and_b64 vcc, exec, s[10:11]
	s_cbranch_vccz .LBB0_140
	s_barrier

; __device__ __forceinline__ unsigned cvt_pk_bf16(float lo, float hi) { const f32x2c v = {lo, hi}; const bf16x2c b = __builtin_convertvector(v, bf16x2c); return __builtin_bit_cast(unsigned, b); }
; __device__ __forceinline__ float bf2f(bf16_t b) { return __uint_as_float(((unsigned)b) << 16); }
; __device__ __forceinline__ float bflo(unsigned u) { return __uint_as_float(u << 16); }
; __device__ __forceinline__ float bfhi(unsigned u) { return __uint_as_float(u & 0xffff0000u); }
; template <int NTOK, bool SMP>
; __device__ __forceinline__ void mix_tile(KP p, int l, float* lds, int tid, int s, int t0) {
;     ...
;         unsigned xq[TPW][3]; u32x2 xkv[TPW]; float k1[TPW], k2[TPW];
; #pragma unroll
;         for (int k = 0; k < TPW; ++k) {
;             const bf16_t* pr = P + (size_t)(mrow0 + wid + 8 * k) * PW;
; #pragma unroll
;             for (int j = 0; j < 3; ++j) xq[k][j] = *(const unsigned*)(pr + PC_Q + 2 * lane + 128 * j);
;             xkv[k] = *(const u32x2*)(pr + PC_KV + 4 * lane);
;             k1[k] = bf2f(pr[PC_KR + (lane & 15)]); k2[k] = bf2f(pr[PC_KR + 16 + (lane & 15)]);
;         }
;         const float* gq = p->in[I_QNG] + l * Q_LORA;
;         float gqv[6];
; #pragma unroll
;         for (int j = 0; j < 3; ++j) { gqv[2 * j] = gq[2 * lane + 128 * j]; gqv[2 * j + 1] = gq[2 * lane + 128 * j + 1]; }
;         const f32x4 gkv = *(const f32x4*)(p->in[I_KVNG] + l * KV_LORA + 4 * lane);
; #pragma unroll
;         for (int k = 0; k < TPW; ++k) {
;             const int i = wid + 8 * k;
;             {
;                 float x[6]; float ss = 0.f;
; #pragma unroll
;                 for (int j = 0; j < 3; ++j) { x[2 * j] = bflo(xq[k][j]); x[2 * j + 1] = bfhi(xq[k][j]); ss += x[2 * j] * x[2 * j] + x[2 * j + 1] * x[2 * j + 1]; }
;                 ss = wave_sum(ss, lane); const float r = rsqrtf(ss * (1.f / 384.f) + RMS_EPS);
; #pragma unroll
;                 for (int j = 0; j < 3; ++j) *(unsigned*)(QN + (size_t)(mrow0 + i) * 384 + 2 * lane + 128 * j) = cvt_pk_bf16(x[2 * j] * r * gqv[2 * j], x[2 * j + 1] * r * gqv[2 * j + 1]);
;             }
;             {
;                 f32x4 x = {bflo(xkv[k][0]), bfhi(xkv[k][0]), bflo(xkv[k][1]), bfhi(xkv[k][1])};
;                 float ss = x[0] * x[0] + x[1] * x[1] + x[2] * x[2] + x[3] * x[3];
;                 ss = wave_sum(ss, lane); const float r = rsqrtf(ss * (1.f / 256.f) + RMS_EPS);
.LBB0_204:
	s_cmpk_lt_i32 s34, 0x810
	s_mov_b64 s[30:31], -1
	s_cbranch_scc0 .LBB0_304
	s_cmpk_lt_i32 s34, 0x800
	v_lshlrev_b32_e32 v190, 1, v102
	v_lshlrev_b32_e32 v188, 1, v104
	v_lshlrev_b32_e32 v186, 1, v106
	v_lshlrev_b32_e32 v173, 2, v102
	v_lshlrev_b32_e32 v182, 2, v104
	v_lshlrev_b32_e32 v184, 2, v100
	s_cbranch_scc0 .LBB0_257
	s_ashr_i32 s18, s34, 6
	s_lshl_b32 s0, s34, 5
	s_and_b32 s35, s0, 0x7e0
	s_lshl_b32 s60, s18, 11
	s_or_b32 s40, s60, s35
	v_add_u32_e32 v22, s40, v98
	v_ashrrev_i32_e32 v23, 31, v22
	v_readlane_b32 s36, v252, 0
	v_lshlrev_b64 v[0:1], 12, v[22:23]
	v_readlane_b32 s37, v252, 1
	v_mov_b32_e32 v191, v9
	v_mov_b32_e32 v189, v9
	v_lshl_add_u64 v[0:1], s[36:37], 0, v[0:1]
	v_lshl_add_u64 v[2:3], v[0:1], 0, v[190:191]
	s_barrier
	global_load_dword v8, v[2:3], off
	global_load_dword v41, v[2:3], off offset:256
	global_load_dword v51, v[2:3], off offset:512
	v_lshl_add_u64 v[2:3], v[0:1], 0, v[188:189]
	global_load_dwordx2 v[24:25], v[2:3], off offset:768
	s_add_i32 s48, s18, s44
	s_ashr_i32 s49, s48, 31
	s_lshl_b64 s[50:51], s[48:49], 11
	s_or_b32 s28, s50, s35
	s_mov_b32 s29, s51
	s_lshl_b64 s[30:31], s[28:29], 10
	s_mul_hi_u32 s29, s28, 0xfffffc80
	s_add_u32 s30, s36, s30
	s_load_dwordx2 s[0:1], s[62:63], 0x40
	s_load_dwordx2 s[20:21], s[62:63], 0x50
	s_mul_i32 s18, s51, 0xfffffc80
	s_addc_u32 s31, s37, s31
	s_sub_i32 s36, s29, s28
	s_mul_i32 s33, s28, 0xfffffc80
	s_mov_b64 s[28:29], 0x8000
	s_add_i32 s36, s36, s18
	v_mov_b32_e32 v187, v9
	v_lshl_add_u64 v[4:5], v[0:1], 0, s[28:29]
	s_mov_b64 s[28:29], 0x18000
	s_add_u32 s58, s30, s33
	v_lshl_add_u64 v[2:3], v[0:1], 0, v[186:187]
	v_lshl_add_u64 v[6:7], v[0:1], 0, s[22:23]
	v_lshl_add_u64 v[0:1], v[0:1], 0, s[28:29]
	s_addc_u32 s59, s31, s36
	s_lshl_b64 s[28:29], s[16:17], 2
	v_lshl_add_u64 v[10:11], v[4:5], 0, v[190:191]
	v_lshl_add_u64 v[12:13], v[4:5], 0, v[188:189]
	v_lshl_add_u64 v[4:5], v[4:5], 0, v[186:187]
	v_lshl_add_u64 v[14:15], v[6:7], 0, v[190:191]
	v_lshl_add_u64 v[16:17], v[6:7], 0, v[188:189]
	v_lshl_add_u64 v[6:7], v[6:7], 0, v[186:187]
	v_lshl_add_u64 v[42:43], v[0:1], 0, v[190:191]
	global_load_ushort v39, v[2:3], off offset:1280
	global_load_ushort v40, v[2:3], off offset:1312
	global_load_dword v38, v[10:11], off
	global_load_dword v37, v[10:11], off offset:256
	global_load_dword v36, v[10:11], off offset:512
	global_load_dwordx2 v[20:21], v[12:13], off offset:768
	global_load_ushort v34, v[4:5], off offset:1280
	global_load_ushort v35, v[4:5], off offset:1312
	global_load_dword v33, v[14:15], off
	global_load_dword v32, v[14:15], off offset:256
	global_load_dword v31, v[14:15], off offset:512
	global_load_dwordx2 v[18:19], v[16:17], off offset:768
	global_load_ushort v29, v[6:7], off offset:1280
	global_load_ushort v30, v[6:7], off offset:1312
	global_load_dword v28, v[42:43], off
	global_load_dword v27, v[42:43], off offset:256
	global_load_dword v26, v[42:43], off offset:512
	s_waitcnt lgkmcnt(0)
	s_add_u32 s0, s0, s28
	s_addc_u32 s1, s1, s29
	global_load_dwordx2 v[10:11], v173, s[0:1]
	global_load_dwordx2 v[6:7], v173, s[0:1] offset:512
	global_load_dwordx2 v[4:5], v173, s[0:1] offset:1024
	s_lshl_b64 s[42:43], s[6:7], 2
	s_add_u32 s0, s20, s42
	s_addc_u32 s1, s21, s43
	v_lshl_add_u64 v[44:45], v[0:1], 0, v[188:189]
	v_lshl_add_u64 v[46:47], v[0:1], 0, v[186:187]
	global_load_dwordx4 v[0:3], v182, s[0:1]
	v_mov_b32_e32 v183, v9
	s_mov_b64 s[0:1], 0x10100000
	v_mov_b32_e32 v185, v9
	v_lshlrev_b64 v[198:199], 9, v[22:23]
	v_readlane_b32 s38, v252, 2
	v_readlane_b32 s39, v252, 3
	s_waitcnt vmcnt(24)
	v_and_b32_e32 v43, 0xffff0000, v8
	v_lshlrev_b32_e32 v42, 16, v8
	s_waitcnt vmcnt(22)
	v_lshlrev_b32_e32 v50, 16, v51
	v_and_b32_e32 v51, 0xffff0000, v51
	v_mov_b32_e32 v16, v43
	v_mov_b32_e32 v17, v51
	s_waitcnt vmcnt(21)
	v_and_b32_e32 v54, 0xffff0000, v25
	v_lshlrev_b32_e32 v48, 16, v41
	v_and_b32_e32 v49, 0xffff0000, v41
	v_lshlrev_b32_e32 v52, 16, v24
	v_mov_b32_e32 v14, v42
	v_mov_b32_e32 v15, v50
	v_pk_mul_f32 v[16:17], v[16:17], v[16:17]
	v_and_b32_e32 v53, 0xffff0000, v24
	v_lshlrev_b32_e32 v57, 16, v25
	v_mov_b32_e32 v56, v54
	v_pk_mul_f32 v[12:13], v[48:49], v[48:49]
	v_pk_fma_f32 v[14:15], v[14:15], v[14:15], v[16:17]
	v_pk_mul_f32 v[16:17], v[52:53], v[52:53]
	v_pk_mul_f32 v[58:59], v[56:57], v[56:57]
	v_mov_b32_e32 v60, v16
	v_mov_b32_e32 v61, v12
	v_mov_b32_e32 v12, v17
	v_pk_mov_b32 v[16:17], v[58:59], v[14:15] op_sel:[1,0]
	v_mov_b32_e32 v59, v15
	global_load_dwordx2 v[14:15], v[44:45], off offset:768
	global_load_ushort v8, v[46:47], off offset:1280
	global_load_ushort v24, v[46:47], off offset:1312
	v_pk_add_f32 v[12:13], v[60:61], v[12:13]
	v_lshl_add_u64 v[44:45], s[30:31], 0, v[182:183]
	v_pk_add_f32 v[12:13], v[16:17], v[12:13]
	s_nop 0
	v_pk_add_f32 v[12:13], v[58:59], v[12:13]
	ds_bpermute_b32 v17, v101, v13
	ds_bpermute_b32 v16, v101, v12
	s_waitcnt lgkmcnt(0)
	v_pk_add_f32 v[12:13], v[12:13], v[16:17]
	ds_bpermute_b32 v17, v107, v13
	ds_bpermute_b32 v16, v107, v12
	s_waitcnt lgkmcnt(0)
	v_pk_add_f32 v[12:13], v[12:13], v[16:17]
	s_nop 1
	v_mov_b32_dpp v17, v13 row_mirror row_mask:0xf bank_mask:0xf
	s_nop 1
	v_mov_b32_dpp v16, v12 row_mirror row_mask:0xf bank_mask:0xf
	s_waitcnt lgkmcnt(0)
	v_pk_add_f32 v[12:13], v[12:13], v[16:17]
	s_nop 1
	v_mov_b32_dpp v17, v13 row_half_mirror row_mask:0xf bank_mask:0xf
	s_nop 1
	v_mov_b32_dpp v16, v12 row_half_mirror row_mask:0xf bank_mask:0xf
	s_waitcnt lgkmcnt(0)
	v_pk_add_f32 v[12:13], v[12:13], v[16:17]
	s_nop 1
	v_mov_b32_dpp v17, v13 quad_perm:[2,3,0,1] row_mask:0xf bank_mask:0xf
	s_nop 1
	v_mov_b32_dpp v16, v12 quad_perm:[2,3,0,1] row_mask:0xf bank_mask:0xf
	s_waitcnt lgkmcnt(0)
; __device__ __forceinline__ unsigned cvt_pk_bf16(float lo, float hi) { const f32x2c v = {lo, hi}; const bf16x2c b = __builtin_convertvector(v, bf16x2c); return __builtin_bit_cast(unsigned, b); }
; __device__ __forceinline__ float bflo(unsigned u) { return __uint_as_float(u << 16); }
; __device__ __forceinline__ float bfhi(unsigned u) { return __uint_as_float(u & 0xffff0000u); }
; __device__ __forceinline__ bf16_t f2bf(float f) { return (bf16_t)(cvt_pk_bf16(f, 0.f) & 0xffffu); }
; template <int NTOK, bool SMP>
; __device__ __forceinline__ void mix_tile(KP p, int l, float* lds, int tid, int s, int t0) {
;     ...
;         for (int k = 0; k < TPW; ++k) {
;             const int i = wid + 8 * k;
;             {
;                 float x[6]; float ss = 0.f;
; #pragma unroll
;                 for (int j = 0; j < 3; ++j) { x[2 * j] = bflo(xq[k][j]); x[2 * j + 1] = bfhi(xq[k][j]); ss += x[2 * j] * x[2 * j] + x[2 * j + 1] * x[2 * j + 1]; }
;                 ss = wave_sum(ss, lane); const float r = rsqrtf(ss * (1.f / 384.f) + RMS_EPS);
; #pragma unroll
;                 for (int j = 0; j < 3; ++j) *(unsigned*)(QN + (size_t)(mrow0 + i) * 384 + 2 * lane + 128 * j) = cvt_pk_bf16(x[2 * j] * r * gqv[2 * j], x[2 * j + 1] * r * gqv[2 * j + 1]);
;             }
;             {
;                 f32x4 x = {bflo(xkv[k][0]), bfhi(xkv[k][0]), bflo(xkv[k][1]), bfhi(xkv[k][1])};
;                 float ss = x[0] * x[0] + x[1] * x[1] + x[2] * x[2] + x[3] * x[3];
;                 ss = wave_sum(ss, lane); const float r = rsqrtf(ss * (1.f / 256.f) + RMS_EPS);
;                 x = x * r * gkv;
;                 __builtin_nontemporal_store(x, (f32x4*)(ckv_out + (size_t)i * 256 + 4 * lane));
;                 u32x2 o; o[0] = cvt_pk_bf16(x[0], x[1]); o[1] = cvt_pk_bf16(x[2], x[3]);
;                 *(u32x2*)(CKV + (size_t)(arow0 + i) * 256 + 4 * lane) = o;
;             }
;             if (lane < 16) {
;                 const float cs = rope[(pos0 + i) * 32 + lane], sn = rope[(pos0 + i) * 32 + 16 + lane];
;                 const float o1 = k1[k] * cs - k2[k] * sn, o2 = k1[k] * sn + k2[k] * cs;
;                 kr_out[(size_t)i * 32 + lane] = o1; kr_out[(size_t)i * 32 + 16 + lane] = o2;
;                 KR[(size_t)(arow0 + i) * 32 + lane] = f2bf(o1); KR[(size_t)(arow0 + i) * 32 + 16 + lane] = f2bf(o2);
;             }
	v_pk_add_f32 v[46:47], v[12:13], v[16:17]
	s_nop 1
	v_mov_b32_dpp v59, v47 quad_perm:[1,0,3,2] row_mask:0xf bank_mask:0xf
	s_nop 1
	v_mov_b32_dpp v58, v46 quad_perm:[1,0,3,2] row_mask:0xf bank_mask:0xf
	v_lshl_add_u64 v[16:17], v[44:45], 0, s[0:1]
	v_lshl_add_u64 v[12:13], s[58:59], 0, v[184:185]
	s_mov_b64 s[0:1], 0x20100000
	v_lshl_add_u64 v[12:13], v[12:13], 0, s[0:1]
	s_mov_b32 s0, 0x3b800000
	s_waitcnt lgkmcnt(0)
	v_pk_add_f32 v[44:45], v[46:47], v[58:59]
	s_mov_b32 s1, 0x3b2aaaab
	v_mov_b32_e32 v46, 0x358637bd
	v_pk_fma_f32 v[44:45], v[44:45], s[0:1], v[46:47] op_sel_hi:[1,1,0]
	s_movk_i32 s0, 0x300
	v_mul_f32_e32 v41, 0x4b800000, v45
	v_cmp_gt_f32_e32 vcc, s96, v45
	v_mad_i64_i32 v[46:47], s[0:1], v22, s0, v[108:109]
	s_nop 0
	v_cndmask_b32_e32 v41, v45, v41, vcc
	v_rsq_f32_e32 v41, v41
	v_and_b32_e32 v55, s0, v25
	v_mul_f32_e32 v25, 0x45800000, v41
	v_cndmask_b32_e32 v58, v41, v25, vcc
	v_pk_mul_f32 v[42:43], v[58:59], v[42:43] op_sel_hi:[0,1]
	s_waitcnt vmcnt(6)
	v_pk_mul_f32 v[42:43], v[10:11], v[42:43]
	v_cmp_gt_f32_e32 vcc, s96, v44
	v_cvt_pk_bf16_f32 v25, v42, v43
	v_pk_mul_f32 v[42:43], v[58:59], v[48:49] op_sel_hi:[0,1]
	s_waitcnt vmcnt(5)
	v_pk_mul_f32 v[42:43], v[6:7], v[42:43]
	global_store_dword v[46:47], v25, off
	v_cvt_pk_bf16_f32 v25, v42, v43
	global_store_dword v[46:47], v25, off offset:256
	v_mul_f32_e32 v25, 0x4b800000, v44
	v_cndmask_b32_e32 v25, v44, v25, vcc
	v_rsq_f32_e32 v25, v25
	v_pk_mul_f32 v[42:43], v[58:59], v[50:51] op_sel_hi:[0,1]
	s_waitcnt vmcnt(6)
	v_pk_mul_f32 v[42:43], v[4:5], v[42:43]
	v_pk_mov_b32 v[44:45], v[56:57], v[54:55] op_sel:[1,0]
	v_cvt_pk_bf16_f32 v41, v42, v43
	global_store_dword v[46:47], v41, off offset:512
	v_mul_f32_e32 v41, 0x45800000, v25
	v_cndmask_b32_e32 v42, v25, v41, vcc
	v_pk_mul_f32 v[46:47], v[42:43], v[52:53] op_sel_hi:[0,1]
	v_pk_mul_f32 v[42:43], v[42:43], v[44:45] op_sel_hi:[0,1]
	s_waitcnt vmcnt(6)
	v_pk_mul_f32 v[44:45], v[2:3], v[42:43]
	v_pk_mul_f32 v[42:43], v[0:1], v[46:47]
	v_lshl_add_u64 v[46:47], v[16:17], 0, v[114:115]
	global_store_dwordx4 v[46:47], v[42:45], off nt
	s_nop 1
	v_cvt_pk_bf16_f32 v42, v42, v43
	v_cvt_pk_bf16_f32 v43, v44, v45
	v_lshl_add_u64 v[44:45], v[110:111], 0, v[198:199]
	global_store_dwordx2 v[44:45], v[42:43], off
	s_and_saveexec_b64 s[30:31], s[4:5]
	s_cbranch_execz .LBB0_208
	v_lshlrev_b32_e32 v25, 16, v40
	v_add_u32_e32 v40, s35, v98
	v_lshl_or_b32 v40, v40, 5, v100
	v_readlane_b32 s0, v252, 4
	v_ashrrev_i32_e32 v41, 31, v40
	v_readlane_b32 s1, v252, 5
	v_lshlrev_b32_e32 v39, 16, v39
	v_lshlrev_b64 v[22:23], 6, v[22:23]
	v_lshl_add_u64 v[40:41], v[40:41], 2, s[0:1]
	global_load_dword v42, v[40:41], off
	s_nop 0
	global_load_dword v40, v[40:41], off offset:64
	v_lshl_add_u64 v[22:23], v[112:113], 0, v[22:23]
	s_waitcnt vmcnt(0)
	v_mul_f32_e32 v41, v40, v25
	v_fma_f32 v43, v42, v39, -v41
	v_mul_f32_e32 v39, v40, v39
	v_fmac_f32_e32 v39, v42, v25
	v_lshl_add_u64 v[40:41], v[12:13], 0, v[116:117]
	v_cvt_pk_bf16_f32 v25, v43, s0
	global_store_dword v[40:41], v43, off
	global_store_dword v[40:41], v39, off offset:64
	global_store_short v[22:23], v25, off
	v_cvt_pk_bf16_f32 v25, v39, s0
	global_store_short v[22:23], v25, off offset:32
.LBB0_208:
	s_or_b64 exec, exec, s[30:31]
	v_and_b32_e32 v41, 0xffff0000, v38
	v_and_b32_e32 v43, 0xffff0000, v36
	v_lshlrev_b32_e32 v40, 16, v38
	v_lshlrev_b32_e32 v42, 16, v36
	v_mov_b32_e32 v44, v41
	v_mov_b32_e32 v45, v43
	v_lshlrev_b32_e32 v38, 16, v37
	v_and_b32_e32 v39, 0xffff0000, v37
	v_mov_b32_e32 v36, v40
	v_mov_b32_e32 v37, v42
	v_pk_mul_f32 v[44:45], v[44:45], v[44:45]
	v_pk_mul_f32 v[22:23], v[38:39], v[38:39]
	v_pk_fma_f32 v[36:37], v[36:37], v[36:37], v[44:45]
	v_lshlrev_b32_e32 v44, 16, v20
	v_and_b32_e32 v45, 0xffff0000, v20
	v_and_b32_e32 v20, 0xffff0000, v21
	v_pk_mul_f32 v[46:47], v[44:45], v[44:45]
	v_lshlrev_b32_e32 v49, 16, v21
	v_mov_b32_e32 v48, v20
	v_pk_mul_f32 v[50:51], v[48:49], v[48:49]
	v_mov_b32_e32 v52, v46
	v_mov_b32_e32 v53, v22
	v_mov_b32_e32 v22, v47
	v_pk_add_f32 v[22:23], v[52:53], v[22:23]
	v_pk_mov_b32 v[46:47], v[50:51], v[36:37] op_sel:[1,0]
	v_mov_b32_e32 v51, v37
	v_pk_add_f32 v[22:23], v[46:47], v[22:23]
	s_mov_b32 s0, 0x3b800000
	v_pk_add_f32 v[22:23], v[50:51], v[22:23]
	ds_bpermute_b32 v37, v101, v23
	ds_bpermute_b32 v36, v101, v22
	s_mov_b32 s1, 0x3b2aaaab
	s_waitcnt lgkmcnt(0)
	v_pk_add_f32 v[22:23], v[22:23], v[36:37]
	ds_bpermute_b32 v37, v107, v23
	ds_bpermute_b32 v36, v107, v22
	s_waitcnt lgkmcnt(0)
	v_pk_add_f32 v[22:23], v[22:23], v[36:37]
	s_nop 1
	v_mov_b32_dpp v37, v23 row_mirror row_mask:0xf bank_mask:0xf
	s_nop 1
	v_mov_b32_dpp v36, v22 row_mirror row_mask:0xf bank_mask:0xf
	s_waitcnt lgkmcnt(0)
	v_pk_add_f32 v[22:23], v[22:23], v[36:37]
	s_nop 1
	v_mov_b32_dpp v37, v23 row_half_mirror row_mask:0xf bank_mask:0xf
	s_nop 1
	v_mov_b32_dpp v36, v22 row_half_mirror row_mask:0xf bank_mask:0xf
	s_waitcnt lgkmcnt(0)
	v_pk_add_f32 v[22:23], v[22:23], v[36:37]
	s_nop 1
	v_mov_b32_dpp v37, v23 quad_perm:[2,3,0,1] row_mask:0xf bank_mask:0xf
	s_nop 1
	v_mov_b32_dpp v36, v22 quad_perm:[2,3,0,1] row_mask:0xf bank_mask:0xf
	s_waitcnt lgkmcnt(0)
	v_pk_add_f32 v[36:37], v[22:23], v[36:37]
	s_nop 1
	v_mov_b32_dpp v47, v37 quad_perm:[1,0,3,2] row_mask:0xf bank_mask:0xf
	s_nop 1
	v_mov_b32_dpp v46, v36 quad_perm:[1,0,3,2] row_mask:0xf bank_mask:0xf
	v_add_u32_e32 v22, s40, v118
	v_ashrrev_i32_e32 v23, 31, v22
	v_lshlrev_b64 v[194:195], 9, v[22:23]
	s_waitcnt lgkmcnt(0)
; __device__ __forceinline__ unsigned cvt_pk_bf16(float lo, float hi) { const f32x2c v = {lo, hi}; const bf16x2c b = __builtin_convertvector(v, bf16x2c); return __builtin_bit_cast(unsigned, b); }
; __device__ __forceinline__ float bflo(unsigned u) { return __uint_as_float(u << 16); }
; __device__ __forceinline__ float bfhi(unsigned u) { return __uint_as_float(u & 0xffff0000u); }
; __device__ __forceinline__ bf16_t f2bf(float f) { return (bf16_t)(cvt_pk_bf16(f, 0.f) & 0xffffu); }
; template <int NTOK, bool SMP>
; __device__ __forceinline__ void mix_tile(KP p, int l, float* lds, int tid, int s, int t0) {
;     ...
;         for (int k = 0; k < TPW; ++k) {
;             const int i = wid + 8 * k;
;             {
;                 float x[6]; float ss = 0.f;
; #pragma unroll
;                 for (int j = 0; j < 3; ++j) { x[2 * j] = bflo(xq[k][j]); x[2 * j + 1] = bfhi(xq[k][j]); ss += x[2 * j] * x[2 * j] + x[2 * j + 1] * x[2 * j + 1]; }
;                 ss = wave_sum(ss, lane); const float r = rsqrtf(ss * (1.f / 384.f) + RMS_EPS);
; #pragma unroll
;                 for (int j = 0; j < 3; ++j) *(unsigned*)(QN + (size_t)(mrow0 + i) * 384 + 2 * lane + 128 * j) = cvt_pk_bf16(x[2 * j] * r * gqv[2 * j], x[2 * j + 1] * r * gqv[2 * j + 1]);
;             }
;             {
;                 f32x4 x = {bflo(xkv[k][0]), bfhi(xkv[k][0]), bflo(xkv[k][1]), bfhi(xkv[k][1])};
;                 float ss = x[0] * x[0] + x[1] * x[1] + x[2] * x[2] + x[3] * x[3];
;                 ss = wave_sum(ss, lane); const float r = rsqrtf(ss * (1.f / 256.f) + RMS_EPS);
;                 x = x * r * gkv;
;                 __builtin_nontemporal_store(x, (f32x4*)(ckv_out + (size_t)i * 256 + 4 * lane));
;                 u32x2 o; o[0] = cvt_pk_bf16(x[0], x[1]); o[1] = cvt_pk_bf16(x[2], x[3]);
;                 *(u32x2*)(CKV + (size_t)(arow0 + i) * 256 + 4 * lane) = o;
;             }
;             if (lane < 16) {
;                 const float cs = rope[(pos0 + i) * 32 + lane], sn = rope[(pos0 + i) * 32 + 16 + lane];
;                 const float o1 = k1[k] * cs - k2[k] * sn, o2 = k1[k] * sn + k2[k] * cs;
;                 kr_out[(size_t)i * 32 + lane] = o1; kr_out[(size_t)i * 32 + 16 + lane] = o2;
;                 KR[(size_t)(arow0 + i) * 32 + lane] = f2bf(o1); KR[(size_t)(arow0 + i) * 32 + 16 + lane] = f2bf(o2);
;             }
	v_pk_add_f32 v[36:37], v[36:37], v[46:47]
	v_mov_b32_e32 v46, 0x358637bd
	v_pk_fma_f32 v[36:37], v[36:37], s[0:1], v[46:47] op_sel_hi:[1,1,0]
	s_movk_i32 s0, 0x300
	v_mul_f32_e32 v25, 0x4b800000, v37
	v_cmp_gt_f32_e32 vcc, s96, v37
	v_mad_i64_i32 v[46:47], s[0:1], v22, s0, v[108:109]
	s_nop 0
	v_cndmask_b32_e32 v25, v37, v25, vcc
	v_rsq_f32_e32 v25, v25
	v_and_b32_e32 v21, s0, v21
	v_pk_mov_b32 v[20:21], v[48:49], v[20:21] op_sel:[1,0]
	v_mul_f32_e32 v37, 0x45800000, v25
	v_cndmask_b32_e32 v50, v25, v37, vcc
	v_pk_mul_f32 v[40:41], v[50:51], v[40:41] op_sel_hi:[0,1]
	v_pk_mul_f32 v[40:41], v[10:11], v[40:41]
	v_pk_mul_f32 v[38:39], v[50:51], v[38:39] op_sel_hi:[0,1]
	v_cvt_pk_bf16_f32 v25, v40, v41
	v_pk_mul_f32 v[38:39], v[6:7], v[38:39]
	global_store_dword v[46:47], v25, off
	v_cvt_pk_bf16_f32 v25, v38, v39
	global_store_dword v[46:47], v25, off offset:256
	v_mul_f32_e32 v25, 0x4b800000, v36
	v_cmp_gt_f32_e32 vcc, s96, v36
	v_pk_mul_f32 v[38:39], v[50:51], v[42:43] op_sel_hi:[0,1]
	s_nop 0
	v_cndmask_b32_e32 v25, v36, v25, vcc
	v_rsq_f32_e32 v25, v25
	v_pk_mul_f32 v[36:37], v[4:5], v[38:39]
	s_nop 0
	v_cvt_pk_bf16_f32 v36, v36, v37
	global_store_dword v[46:47], v36, off offset:512
	v_mul_f32_e32 v36, 0x45800000, v25
	v_cndmask_b32_e32 v36, v25, v36, vcc
	v_pk_mul_f32 v[40:41], v[36:37], v[44:45] op_sel_hi:[0,1]
	v_pk_mul_f32 v[20:21], v[36:37], v[20:21] op_sel_hi:[0,1]
	v_pk_mul_f32 v[38:39], v[2:3], v[20:21]
	v_pk_mul_f32 v[36:37], v[0:1], v[40:41]
	v_lshl_add_u64 v[20:21], v[16:17], 0, v[120:121]
	global_store_dwordx4 v[20:21], v[36:39], off nt
	v_cvt_pk_bf16_f32 v20, v36, v37
	v_cvt_pk_bf16_f32 v21, v38, v39
	v_lshl_add_u64 v[36:37], v[110:111], 0, v[194:195]
	global_store_dwordx2 v[36:37], v[20:21], off
	s_and_saveexec_b64 s[30:31], s[4:5]
	s_cbranch_execz .LBB0_210
	v_add_u32_e32 v20, s35, v118
	v_lshl_or_b32 v20, v20, 5, v100
	v_readlane_b32 s0, v252, 4
	v_ashrrev_i32_e32 v21, 31, v20
	v_readlane_b32 s1, v252, 5
	v_lshlrev_b32_e32 v25, 16, v34
	v_lshlrev_b32_e32 v34, 16, v35
	v_lshl_add_u64 v[20:21], v[20:21], 2, s[0:1]
	global_load_dword v35, v[20:21], off
	s_nop 0
	global_load_dword v20, v[20:21], off offset:64
	s_waitcnt vmcnt(0)
	v_mul_f32_e32 v21, v20, v34
	v_fma_f32 v36, v35, v25, -v21
	v_mul_f32_e32 v25, v20, v25
	v_lshl_add_u64 v[20:21], v[12:13], 0, v[122:123]
	v_fmac_f32_e32 v25, v35, v34
	global_store_dword v[20:21], v36, off
	global_store_dword v[20:21], v25, off offset:64
	v_lshlrev_b64 v[20:21], 6, v[22:23]
	v_cvt_pk_bf16_f32 v34, v36, s0
	v_lshl_add_u64 v[20:21], v[112:113], 0, v[20:21]
	v_cvt_pk_bf16_f32 v22, v25, s0
	global_store_short v[20:21], v34, off
	global_store_short v[20:21], v22, off offset:32
.LBB0_210:
	s_or_b64 exec, exec, s[30:31]
	v_lshlrev_b32_e32 v22, 16, v33
	v_and_b32_e32 v23, 0xffff0000, v33
	v_and_b32_e32 v33, 0xffff0000, v31
	v_lshlrev_b32_e32 v34, 16, v32
	v_and_b32_e32 v35, 0xffff0000, v32
	v_lshlrev_b32_e32 v32, 16, v31
	v_mov_b32_e32 v38, v23
	v_mov_b32_e32 v39, v33
	v_mov_b32_e32 v36, v22
	v_mov_b32_e32 v37, v32
	v_pk_mul_f32 v[38:39], v[38:39], v[38:39]
	v_pk_mul_f32 v[20:21], v[34:35], v[34:35]
	v_pk_fma_f32 v[36:37], v[36:37], v[36:37], v[38:39]
	v_lshlrev_b32_e32 v38, 16, v18
	v_and_b32_e32 v39, 0xffff0000, v18
	v_and_b32_e32 v18, 0xffff0000, v19
	v_pk_mul_f32 v[40:41], v[38:39], v[38:39]
	v_lshlrev_b32_e32 v43, 16, v19
	v_mov_b32_e32 v42, v18
	v_pk_mul_f32 v[44:45], v[42:43], v[42:43]
	v_mov_b32_e32 v46, v40
	v_mov_b32_e32 v47, v20
	v_mov_b32_e32 v20, v41
	v_pk_add_f32 v[20:21], v[46:47], v[20:21]
	v_pk_mov_b32 v[40:41], v[44:45], v[36:37] op_sel:[1,0]
	v_mov_b32_e32 v45, v37
	v_pk_add_f32 v[20:21], v[40:41], v[20:21]
	s_mov_b32 s0, 0x3b800000
	v_pk_add_f32 v[20:21], v[44:45], v[20:21]
	ds_bpermute_b32 v37, v101, v21
	ds_bpermute_b32 v36, v101, v20
	s_mov_b32 s1, 0x3b2aaaab
	s_waitcnt lgkmcnt(0)
	v_pk_add_f32 v[20:21], v[20:21], v[36:37]
	ds_bpermute_b32 v37, v107, v21
	ds_bpermute_b32 v36, v107, v20
	s_waitcnt lgkmcnt(0)
	v_pk_add_f32 v[20:21], v[20:21], v[36:37]
	s_nop 1
	v_mov_b32_dpp v37, v21 row_mirror row_mask:0xf bank_mask:0xf
	s_nop 1
	v_mov_b32_dpp v36, v20 row_mirror row_mask:0xf bank_mask:0xf
	s_waitcnt lgkmcnt(0)
	v_pk_add_f32 v[20:21], v[20:21], v[36:37]
	s_nop 1
	v_mov_b32_dpp v37, v21 row_half_mirror row_mask:0xf bank_mask:0xf
	s_nop 1
	v_mov_b32_dpp v36, v20 row_half_mirror row_mask:0xf bank_mask:0xf
	s_waitcnt lgkmcnt(0)
	v_pk_add_f32 v[20:21], v[20:21], v[36:37]
	s_nop 1
	v_mov_b32_dpp v37, v21 quad_perm:[2,3,0,1] row_mask:0xf bank_mask:0xf
	s_nop 1
	v_mov_b32_dpp v36, v20 quad_perm:[2,3,0,1] row_mask:0xf bank_mask:0xf
	s_waitcnt lgkmcnt(0)
	v_pk_add_f32 v[36:37], v[20:21], v[36:37]
	s_nop 1
	v_mov_b32_dpp v41, v37 quad_perm:[1,0,3,2] row_mask:0xf bank_mask:0xf
	s_nop 1
	v_mov_b32_dpp v40, v36 quad_perm:[1,0,3,2] row_mask:0xf bank_mask:0xf
	v_add_u32_e32 v20, s40, v124
	v_ashrrev_i32_e32 v21, 31, v20
	v_lshlrev_b64 v[196:197], 9, v[20:21]
	s_waitcnt lgkmcnt(0)
	v_pk_add_f32 v[36:37], v[36:37], v[40:41]
	v_mov_b32_e32 v40, 0x358637bd
	v_pk_fma_f32 v[36:37], v[36:37], s[0:1], v[40:41] op_sel_hi:[1,1,0]
	s_movk_i32 s0, 0x300
	v_mul_f32_e32 v25, 0x4b800000, v37
	v_cmp_gt_f32_e32 vcc, s96, v37
	v_mad_i64_i32 v[40:41], s[0:1], v20, s0, v[108:109]
	s_nop 0
	v_cndmask_b32_e32 v25, v37, v25, vcc
	v_rsq_f32_e32 v25, v25
	v_and_b32_e32 v19, s0, v19
	v_pk_mov_b32 v[18:19], v[42:43], v[18:19] op_sel:[1,0]
	v_mul_f32_e32 v31, 0x45800000, v25
	v_cndmask_b32_e32 v44, v25, v31, vcc
	v_pk_mul_f32 v[22:23], v[44:45], v[22:23] op_sel_hi:[0,1]
	v_pk_mul_f32 v[22:23], v[10:11], v[22:23]
	v_mul_f32_e32 v25, 0x4b800000, v36
	v_cvt_pk_bf16_f32 v22, v22, v23
	global_store_dword v[40:41], v22, off
	v_pk_mul_f32 v[22:23], v[44:45], v[34:35] op_sel_hi:[0,1]
	v_cmp_gt_f32_e32 vcc, s96, v36
	v_pk_mul_f32 v[22:23], v[6:7], v[22:23]
	s_nop 0
	v_cndmask_b32_e32 v25, v36, v25, vcc
	v_cvt_pk_bf16_f32 v22, v22, v23
	v_rsq_f32_e32 v25, v25
	global_store_dword v[40:41], v22, off offset:256
	v_pk_mul_f32 v[22:23], v[44:45], v[32:33] op_sel_hi:[0,1]
	v_pk_mul_f32 v[22:23], v[4:5], v[22:23]
	s_nop 0
	v_cvt_pk_bf16_f32 v22, v22, v23
	global_store_dword v[40:41], v22, off offset:512
	v_mul_f32_e32 v22, 0x45800000, v25
	v_cndmask_b32_e32 v22, v25, v22, vcc
	v_pk_mul_f32 v[32:33], v[22:23], v[38:39] op_sel_hi:[0,1]
	v_pk_mul_f32 v[18:19], v[22:23], v[18:19] op_sel_hi:[0,1]
	v_pk_mul_f32 v[34:35], v[2:3], v[18:19]
	v_pk_mul_f32 v[32:33], v[0:1], v[32:33]
	v_lshl_add_u64 v[18:19], v[16:17], 0, v[126:127]
	global_store_dwordx4 v[18:19], v[32:35], off nt
	v_cvt_pk_bf16_f32 v18, v32, v33
	v_cvt_pk_bf16_f32 v19, v34, v35
	v_lshl_add_u64 v[22:23], v[110:111], 0, v[196:197]
	global_store_dwordx2 v[22:23], v[18:19], off
	s_and_saveexec_b64 s[30:31], s[4:5]
	s_mov_b64 s[38:39], 0x800
	s_cbranch_execz .LBB0_212
; __device__ __forceinline__ unsigned cvt_pk_bf16(float lo, float hi) { const f32x2c v = {lo, hi}; const bf16x2c b = __builtin_convertvector(v, bf16x2c); return __builtin_bit_cast(unsigned, b); }
; __device__ __forceinline__ float bflo(unsigned u) { return __uint_as_float(u << 16); }
; __device__ __forceinline__ float bfhi(unsigned u) { return __uint_as_float(u & 0xffff0000u); }
; __device__ __forceinline__ bf16_t f2bf(float f) { return (bf16_t)(cvt_pk_bf16(f, 0.f) & 0xffffu); }
; template <int NTOK, bool SMP>
; __device__ __forceinline__ void mix_tile(KP p, int l, float* lds, int tid, int s, int t0) {
;     ...
;         for (int k = 0; k < TPW; ++k) {
;             const int i = wid + 8 * k;
;             {
;                 float x[6]; float ss = 0.f;
; #pragma unroll
;                 for (int j = 0; j < 3; ++j) { x[2 * j] = bflo(xq[k][j]); x[2 * j + 1] = bfhi(xq[k][j]); ss += x[2 * j] * x[2 * j] + x[2 * j + 1] * x[2 * j + 1]; }
;                 ss = wave_sum(ss, lane); const float r = rsqrtf(ss * (1.f / 384.f) + RMS_EPS);
; #pragma unroll
;                 for (int j = 0; j < 3; ++j) *(unsigned*)(QN + (size_t)(mrow0 + i) * 384 + 2 * lane + 128 * j) = cvt_pk_bf16(x[2 * j] * r * gqv[2 * j], x[2 * j + 1] * r * gqv[2 * j + 1]);
;             }
;             {
;                 f32x4 x = {bflo(xkv[k][0]), bfhi(xkv[k][0]), bflo(xkv[k][1]), bfhi(xkv[k][1])};
;                 float ss = x[0] * x[0] + x[1] * x[1] + x[2] * x[2] + x[3] * x[3];
;                 ss = wave_sum(ss, lane); const float r = rsqrtf(ss * (1.f / 256.f) + RMS_EPS);
;                 x = x * r * gkv;
;                 __builtin_nontemporal_store(x, (f32x4*)(ckv_out + (size_t)i * 256 + 4 * lane));
;                 u32x2 o; o[0] = cvt_pk_bf16(x[0], x[1]); o[1] = cvt_pk_bf16(x[2], x[3]);
;                 *(u32x2*)(CKV + (size_t)(arow0 + i) * 256 + 4 * lane) = o;
;             }
;             if (lane < 16) {
;                 const float cs = rope[(pos0 + i) * 32 + lane], sn = rope[(pos0 + i) * 32 + 16 + lane];
;                 const float o1 = k1[k] * cs - k2[k] * sn, o2 = k1[k] * sn + k2[k] * cs;
;                 kr_out[(size_t)i * 32 + lane] = o1; kr_out[(size_t)i * 32 + 16 + lane] = o2;
;                 KR[(size_t)(arow0 + i) * 32 + lane] = f2bf(o1); KR[(size_t)(arow0 + i) * 32 + 16 + lane] = f2bf(o2);
;             }
	v_add_u32_e32 v18, s35, v124
	v_lshl_or_b32 v18, v18, 5, v100
	v_readlane_b32 s0, v252, 4
	v_ashrrev_i32_e32 v19, 31, v18
	v_readlane_b32 s1, v252, 5
	v_lshlrev_b32_e32 v23, 16, v30
	v_lshlrev_b32_e32 v22, 16, v29
	v_lshl_add_u64 v[18:19], v[18:19], 2, s[0:1]
	global_load_dword v25, v[18:19], off
	s_nop 0
	global_load_dword v18, v[18:19], off offset:64
	s_waitcnt vmcnt(0)
	v_mul_f32_e32 v19, v18, v23
	v_fma_f32 v29, v25, v22, -v19
	v_mul_f32_e32 v22, v18, v22
	v_lshl_add_u64 v[18:19], v[12:13], 0, v[128:129]
	v_fmac_f32_e32 v22, v25, v23
	global_store_dword v[18:19], v29, off
	global_store_dword v[18:19], v22, off offset:64
	v_lshlrev_b64 v[18:19], 6, v[20:21]
	v_cvt_pk_bf16_f32 v23, v29, s0
	v_lshl_add_u64 v[18:19], v[112:113], 0, v[18:19]
	v_cvt_pk_bf16_f32 v20, v22, s0
	global_store_short v[18:19], v23, off
	global_store_short v[18:19], v20, off offset:32
.LBB0_212:
	s_or_b64 exec, exec, s[30:31]
	v_and_b32_e32 v21, 0xffff0000, v28
	v_and_b32_e32 v29, 0xffff0000, v26
	v_lshlrev_b32_e32 v20, 16, v28
	v_lshlrev_b32_e32 v28, 16, v26
	v_mov_b32_e32 v30, v21
	v_mov_b32_e32 v31, v29
	v_lshlrev_b32_e32 v22, 16, v27
	v_and_b32_e32 v23, 0xffff0000, v27
	v_mov_b32_e32 v26, v20
	v_mov_b32_e32 v27, v28
	v_pk_mul_f32 v[30:31], v[30:31], v[30:31]
	v_pk_mul_f32 v[18:19], v[22:23], v[22:23]
	v_pk_fma_f32 v[26:27], v[26:27], v[26:27], v[30:31]
	s_waitcnt vmcnt(17)
	v_lshlrev_b32_e32 v30, 16, v14
	v_and_b32_e32 v31, 0xffff0000, v14
	v_and_b32_e32 v14, 0xffff0000, v15
	v_pk_mul_f32 v[32:33], v[30:31], v[30:31]
	v_lshlrev_b32_e32 v35, 16, v15
	v_mov_b32_e32 v34, v14
	v_pk_mul_f32 v[36:37], v[34:35], v[34:35]
	v_mov_b32_e32 v38, v32
	v_mov_b32_e32 v39, v18
	v_mov_b32_e32 v18, v33
	v_pk_add_f32 v[18:19], v[38:39], v[18:19]
	v_pk_mov_b32 v[32:33], v[36:37], v[26:27] op_sel:[1,0]
	v_mov_b32_e32 v37, v27
	v_pk_add_f32 v[18:19], v[32:33], v[18:19]
	s_mov_b32 s0, 0x3b800000
	v_pk_add_f32 v[18:19], v[36:37], v[18:19]
	ds_bpermute_b32 v27, v101, v19
	ds_bpermute_b32 v26, v101, v18
	s_mov_b32 s1, 0x3b2aaaab
	s_waitcnt lgkmcnt(0)
	v_pk_add_f32 v[18:19], v[18:19], v[26:27]
	ds_bpermute_b32 v27, v107, v19
	ds_bpermute_b32 v26, v107, v18
	s_waitcnt lgkmcnt(0)
	v_pk_add_f32 v[18:19], v[18:19], v[26:27]
	s_nop 1
	v_mov_b32_dpp v27, v19 row_mirror row_mask:0xf bank_mask:0xf
	s_nop 1
	v_mov_b32_dpp v26, v18 row_mirror row_mask:0xf bank_mask:0xf
	s_waitcnt lgkmcnt(0)
	v_pk_add_f32 v[18:19], v[18:19], v[26:27]
	s_nop 1
	v_mov_b32_dpp v27, v19 row_half_mirror row_mask:0xf bank_mask:0xf
	s_nop 1
	v_mov_b32_dpp v26, v18 row_half_mirror row_mask:0xf bank_mask:0xf
	s_waitcnt lgkmcnt(0)
	v_pk_add_f32 v[18:19], v[18:19], v[26:27]
	s_nop 1
	v_mov_b32_dpp v27, v19 quad_perm:[2,3,0,1] row_mask:0xf bank_mask:0xf
	s_nop 1
	v_mov_b32_dpp v26, v18 quad_perm:[2,3,0,1] row_mask:0xf bank_mask:0xf
	s_waitcnt lgkmcnt(0)
	v_pk_add_f32 v[26:27], v[18:19], v[26:27]
	s_nop 1
	v_mov_b32_dpp v33, v27 quad_perm:[1,0,3,2] row_mask:0xf bank_mask:0xf
	s_nop 1
	v_mov_b32_dpp v32, v26 quad_perm:[1,0,3,2] row_mask:0xf bank_mask:0xf
	v_add_u32_e32 v18, s40, v130
	v_ashrrev_i32_e32 v19, 31, v18
	v_lshlrev_b64 v[192:193], 9, v[18:19]
	s_waitcnt lgkmcnt(0)
	v_pk_add_f32 v[26:27], v[26:27], v[32:33]
	v_mov_b32_e32 v32, 0x358637bd
	v_pk_fma_f32 v[26:27], v[26:27], s[0:1], v[32:33] op_sel_hi:[1,1,0]
	s_movk_i32 s0, 0x300
	v_mul_f32_e32 v25, 0x4b800000, v27
	v_cmp_gt_f32_e32 vcc, s96, v27
	v_mad_i64_i32 v[32:33], s[0:1], v18, s0, v[108:109]
	s_nop 0
	v_cndmask_b32_e32 v25, v27, v25, vcc
	v_rsq_f32_e32 v25, v25
	v_and_b32_e32 v15, s0, v15
	v_mul_f32_e32 v27, 0x45800000, v25
	v_cndmask_b32_e32 v36, v25, v27, vcc
	v_pk_mul_f32 v[20:21], v[36:37], v[20:21] op_sel_hi:[0,1]
	v_pk_mul_f32 v[10:11], v[10:11], v[20:21]
	v_cmp_gt_f32_e32 vcc, s96, v26
	v_cvt_pk_bf16_f32 v10, v10, v11
	global_store_dword v[32:33], v10, off
	v_pk_mul_f32 v[10:11], v[36:37], v[22:23] op_sel_hi:[0,1]
	v_pk_mul_f32 v[6:7], v[6:7], v[10:11]
	v_mul_f32_e32 v10, 0x4b800000, v26
	v_cndmask_b32_e32 v10, v26, v10, vcc
	v_cvt_pk_bf16_f32 v6, v6, v7
	v_rsq_f32_e32 v10, v10
	global_store_dword v[32:33], v6, off offset:256
	v_pk_mul_f32 v[6:7], v[36:37], v[28:29] op_sel_hi:[0,1]
	v_pk_mul_f32 v[4:5], v[4:5], v[6:7]
	s_nop 0
	v_cvt_pk_bf16_f32 v4, v4, v5
	global_store_dword v[32:33], v4, off offset:512
	v_mul_f32_e32 v4, 0x45800000, v10
	v_cndmask_b32_e32 v4, v10, v4, vcc
	v_pk_mov_b32 v[10:11], v[34:35], v[14:15] op_sel:[1,0]
	v_pk_mul_f32 v[6:7], v[4:5], v[30:31] op_sel_hi:[0,1]
	v_pk_mul_f32 v[4:5], v[4:5], v[10:11] op_sel_hi:[0,1]
	v_pk_mul_f32 v[2:3], v[2:3], v[4:5]
	v_pk_mul_f32 v[0:1], v[0:1], v[6:7]
	v_lshl_add_u64 v[4:5], v[16:17], 0, v[132:133]
	global_store_dwordx4 v[4:5], v[0:3], off nt
	s_nop 1
	v_cvt_pk_bf16_f32 v0, v0, v1
	v_cvt_pk_bf16_f32 v1, v2, v3
	v_lshl_add_u64 v[2:3], v[110:111], 0, v[192:193]
	global_store_dwordx2 v[2:3], v[0:1], off
	s_and_saveexec_b64 s[30:31], s[4:5]
	s_cbranch_execz .LBB0_214
	v_add_u32_e32 v0, s35, v130
	v_lshl_or_b32 v0, v0, 5, v100
	v_readlane_b32 s0, v252, 4
	v_ashrrev_i32_e32 v1, 31, v0
	v_readlane_b32 s1, v252, 5
	s_waitcnt vmcnt(20)
	v_lshlrev_b32_e32 v7, 16, v24
	v_lshlrev_b32_e32 v6, 16, v8
	v_lshl_add_u64 v[0:1], v[0:1], 2, s[0:1]
	global_load_dword v4, v[0:1], off offset:64
	global_load_dword v5, v[0:1], off
	v_lshl_add_u64 v[0:1], v[12:13], 0, v[134:135]
	v_lshlrev_b64 v[2:3], 6, v[18:19]
	v_lshl_add_u64 v[2:3], v[112:113], 0, v[2:3]
	s_waitcnt vmcnt(1)
	v_mul_f32_e32 v8, v4, v7
	v_mul_f32_e32 v4, v4, v6
	s_waitcnt vmcnt(0)
	v_fma_f32 v6, v5, v6, -v8
	v_fmac_f32_e32 v4, v5, v7
	global_store_dword v[0:1], v6, off
	global_store_dword v[0:1], v4, off offset:64
	v_cvt_pk_bf16_f32 v0, v6, s0
	v_cvt_pk_bf16_f32 v1, v4, s0
	global_store_short v[2:3], v0, off
	global_store_short v[2:3], v1, off offset:32

; __device__ __forceinline__ unsigned cvt_pk_bf16(float lo, float hi) { const f32x2c v = {lo, hi}; const bf16x2c b = __builtin_convertvector(v, bf16x2c); return __builtin_bit_cast(unsigned, b); }
; __device__ __forceinline__ float sigmoidf_(float x) { return __builtin_amdgcn_rcpf(1.f + __builtin_amdgcn_exp2f(-1.4426950408889634f * x)); }
; template <int NTOK, bool SMP>
; __device__ __forceinline__ void mix_tile(KP p, int l, float* lds, int tid, int s, int t0) {
;     ...
;     {
;         const f32x4 g = *(const f32x4*)(p->in[I_CLG] + l * 256 + 4 * lane), bb = *(const f32x4*)(p->in[I_CLB] + l * 256 + 4 * lane);
; #pragma unroll
;         for (int k = 0; k < TPW; ++k) {
;             const int i = wid + 8 * k;
;             const f32x4 x = *(const f32x4*)(cvs + i * 256 + 4 * lane);
;             const float mu = wave_sum(x[0] + x[1] + x[2] + x[3], lane) * (1.f / 256.f);
;             const f32x4 d = x - mu;
;             const float var = wave_sum(d[0] * d[0] + d[1] * d[1] + d[2] * d[2] + d[3] * d[3], lane) * (1.f / 256.f);
;             const float r = rsqrtf(var + LN_EPS);
;             f32x4 y = d * r * g + bb;
; #pragma unroll
;             for (int j = 0; j < 4; ++j) y[j] = y[j] * sigmoidf_(y[j]);
;             u32x2 o; o[0] = cvt_pk_bf16(y[0], y[1]); o[1] = cvt_pk_bf16(y[2], y[3]);
;             *(u32x2*)(CVN + (size_t)(mrow0 + i) * 256 + 4 * lane) = o;
;         }
.LBB0_256:
	v_add_u32_e32 v8, v218, v219
	s_waitcnt lgkmcnt(0)
	s_barrier
	ds_read_b128 v[10:13], v8 offset:63488
	s_load_dwordx4 s[28:31], s[62:63], 0x80
	s_waitcnt lgkmcnt(0)
	v_add_f32_e32 v8, v10, v11
	v_add_f32_e32 v8, v12, v8
	v_add_f32_e32 v8, v13, v8
	ds_bpermute_b32 v14, v101, v8
	s_add_u32 s0, s28, s42
	s_addc_u32 s1, s29, s43
	global_load_dwordx4 v[0:3], v182, s[0:1]
	s_add_u32 s0, s30, s42
	s_waitcnt lgkmcnt(0)
	v_add_f32_e32 v8, v8, v14
	ds_bpermute_b32 v14, v107, v8
	s_addc_u32 s1, s31, s43
	global_load_dwordx4 v[4:7], v182, s[0:1]
	s_mov_b32 s0, 0x3727c5ac
	s_mov_b64 s[30:31], 0
	s_waitcnt lgkmcnt(0)
	v_add_f32_e32 v8, v8, v14
	s_nop 1
	v_mov_b32_dpp v14, v8 row_mirror row_mask:0xf bank_mask:0xf
	s_waitcnt lgkmcnt(0)
	v_add_f32_e32 v8, v8, v14
	s_nop 1
	v_mov_b32_dpp v14, v8 row_half_mirror row_mask:0xf bank_mask:0xf
	s_waitcnt lgkmcnt(0)
	v_add_f32_e32 v8, v8, v14
	s_nop 1
	v_mov_b32_dpp v14, v8 quad_perm:[2,3,0,1] row_mask:0xf bank_mask:0xf
	s_waitcnt lgkmcnt(0)
	v_add_f32_e32 v8, v8, v14
	s_nop 1
	v_mov_b32_dpp v14, v8 quad_perm:[1,0,3,2] row_mask:0xf bank_mask:0xf
	s_waitcnt lgkmcnt(0)
	v_add_f32_e32 v8, v8, v14
	v_fmamk_f32 v15, v8, 0xbb800000, v11
	v_fmamk_f32 v14, v8, 0xbb800000, v10
	v_fmamk_f32 v13, v8, 0xbb800000, v13
	v_fmac_f32_e32 v12, 0xbb800000, v8
	v_add_u32_e32 v8, v218, v220
	ds_read_b128 v[18:21], v8 offset:63488
	v_pk_mul_f32 v[22:23], v[14:15], v[14:15]
	v_pk_mul_f32 v[16:17], v[12:13], v[12:13]
	v_mov_b32_e32 v29, v22
	v_lshl_add_u64 v[10:11], v[152:153], 0, v[198:199]
	s_waitcnt lgkmcnt(0)
	v_add_f32_e32 v8, v18, v19
	v_add_f32_e32 v8, v20, v8
	v_add_f32_e32 v8, v21, v8
	ds_bpermute_b32 v24, v101, v8
	s_waitcnt lgkmcnt(0)
	v_add_f32_e32 v8, v8, v24
	ds_bpermute_b32 v24, v107, v8
	s_waitcnt lgkmcnt(0)
	v_add_f32_e32 v8, v8, v24
	s_nop 1
	v_mov_b32_dpp v24, v8 row_mirror row_mask:0xf bank_mask:0xf
	s_waitcnt lgkmcnt(0)
	v_add_f32_e32 v8, v8, v24
	s_nop 1
	v_mov_b32_dpp v24, v8 row_half_mirror row_mask:0xf bank_mask:0xf
	s_waitcnt lgkmcnt(0)
	v_add_f32_e32 v8, v8, v24
	s_nop 1
	v_mov_b32_dpp v24, v8 quad_perm:[2,3,0,1] row_mask:0xf bank_mask:0xf
	s_waitcnt lgkmcnt(0)
	v_add_f32_e32 v8, v8, v24
	s_nop 1
	v_mov_b32_dpp v24, v8 quad_perm:[1,0,3,2] row_mask:0xf bank_mask:0xf
	s_waitcnt lgkmcnt(0)
	v_add_f32_e32 v8, v8, v24
	v_fmamk_f32 v25, v8, 0xbb800000, v19
	v_fmamk_f32 v24, v8, 0xbb800000, v18
	v_fmamk_f32 v21, v8, 0xbb800000, v21
	v_fmac_f32_e32 v20, 0xbb800000, v8
	v_pk_mul_f32 v[26:27], v[24:25], v[24:25]
	v_pk_mul_f32 v[18:19], v[20:21], v[20:21]
	v_mov_b32_e32 v28, v26
	v_mov_b32_e32 v22, v27
	v_pk_add_f32 v[22:23], v[28:29], v[22:23]
	v_mov_b32_e32 v26, v18
	v_mov_b32_e32 v27, v16
	v_pk_add_f32 v[22:23], v[26:27], v[22:23]
	v_mov_b32_e32 v16, v19
	v_pk_add_f32 v[16:17], v[16:17], v[22:23]
	ds_bpermute_b32 v19, v101, v17
	ds_bpermute_b32 v18, v101, v16
	s_waitcnt lgkmcnt(0)
	v_pk_add_f32 v[16:17], v[16:17], v[18:19]
	ds_bpermute_b32 v19, v107, v17
	ds_bpermute_b32 v18, v107, v16
	s_waitcnt lgkmcnt(0)
	v_pk_add_f32 v[16:17], v[16:17], v[18:19]
	s_nop 1
	v_mov_b32_dpp v19, v17 row_mirror row_mask:0xf bank_mask:0xf
	s_nop 1
	v_mov_b32_dpp v18, v16 row_mirror row_mask:0xf bank_mask:0xf
	s_waitcnt lgkmcnt(0)
	v_pk_add_f32 v[16:17], v[16:17], v[18:19]
	s_nop 1
	v_mov_b32_dpp v19, v17 row_half_mirror row_mask:0xf bank_mask:0xf
	s_nop 1
	v_mov_b32_dpp v18, v16 row_half_mirror row_mask:0xf bank_mask:0xf
	s_waitcnt lgkmcnt(0)
	v_pk_add_f32 v[16:17], v[16:17], v[18:19]
	s_nop 1
	v_mov_b32_dpp v19, v17 quad_perm:[2,3,0,1] row_mask:0xf bank_mask:0xf
	s_nop 1
	v_mov_b32_dpp v18, v16 quad_perm:[2,3,0,1] row_mask:0xf bank_mask:0xf
	s_waitcnt lgkmcnt(0)
	v_pk_add_f32 v[16:17], v[16:17], v[18:19]
	s_nop 1
	v_mov_b32_dpp v19, v17 quad_perm:[1,0,3,2] row_mask:0xf bank_mask:0xf
	s_nop 1
	v_mov_b32_dpp v18, v16 quad_perm:[1,0,3,2] row_mask:0xf bank_mask:0xf
	s_waitcnt lgkmcnt(0)
	v_pk_add_f32 v[16:17], v[16:17], v[18:19]
	v_mov_b64_e32 v[18:19], s[0:1]
	s_mov_b32 s0, 0x3b800000
	s_mov_b32 s1, 0x3b2aaaab
	v_pk_fma_f32 v[16:17], v[16:17], s[0:1], v[18:19] op_sel_hi:[1,0,0]
	s_nop 0
	v_mul_f32_e32 v8, 0x4b800000, v17
	v_cmp_gt_f32_e64 s[42:43], s96, v17
	v_cmp_gt_f32_e32 vcc, s96, v16
	s_nop 0
	v_cndmask_b32_e64 v8, v17, v8, s[42:43]
	v_rsq_f32_e32 v8, v8
	s_nop 0
	v_mul_f32_e32 v17, 0x45800000, v8
	v_cndmask_b32_e64 v8, v8, v17, s[42:43]
	v_pk_mul_f32 v[14:15], v[14:15], v[8:9] op_sel_hi:[1,0]
	v_pk_mul_f32 v[12:13], v[12:13], v[8:9] op_sel_hi:[1,0]
	s_waitcnt vmcnt(0)
	v_pk_fma_f32 v[14:15], v[0:1], v[14:15], v[4:5]
	v_pk_fma_f32 v[12:13], v[2:3], v[12:13], v[6:7]
	v_mul_f32_e32 v8, 0xbfb8aa3b, v14
	v_exp_f32_e32 v8, v8
	s_nop 0
	v_add_f32_e32 v8, 1.0, v8
	v_rcp_f32_e32 v22, v8
	v_mul_f32_e32 v8, 0xbfb8aa3b, v15
	v_exp_f32_e32 v8, v8
	s_nop 0
	v_add_f32_e32 v8, 1.0, v8
	v_rcp_f32_e32 v23, v8
	v_mul_f32_e32 v8, 0xbfb8aa3b, v12
	v_exp_f32_e32 v8, v8
	v_pk_mul_f32 v[14:15], v[14:15], v[22:23]
	s_nop 0
	v_cvt_pk_bf16_f32 v14, v14, v15
	v_add_f32_e32 v8, 1.0, v8
	v_rcp_f32_e32 v22, v8
	v_mul_f32_e32 v8, 0xbfb8aa3b, v13
	v_exp_f32_e32 v8, v8
	s_nop 0
	v_add_f32_e32 v8, 1.0, v8
	v_rcp_f32_e32 v23, v8
	v_mul_f32_e32 v8, 0x4b800000, v16
	v_cndmask_b32_e32 v8, v16, v8, vcc
	v_rsq_f32_e32 v8, v8
	v_pk_mul_f32 v[12:13], v[12:13], v[22:23]
	s_nop 0
	v_cvt_pk_bf16_f32 v15, v12, v13
	global_store_dwordx2 v[10:11], v[14:15], off
	v_mul_f32_e32 v10, 0x45800000, v8
	v_cndmask_b32_e32 v8, v8, v10, vcc
	v_pk_mul_f32 v[10:11], v[24:25], v[8:9] op_sel_hi:[1,0]
	v_pk_mul_f32 v[12:13], v[20:21], v[8:9] op_sel_hi:[1,0]
	v_pk_fma_f32 v[10:11], v[0:1], v[10:11], v[4:5]
	v_pk_fma_f32 v[12:13], v[2:3], v[12:13], v[6:7]
	v_mul_f32_e32 v8, 0xbfb8aa3b, v10
	v_exp_f32_e32 v8, v8
	s_nop 0
	v_add_f32_e32 v8, 1.0, v8
	v_rcp_f32_e32 v14, v8
	v_mul_f32_e32 v8, 0xbfb8aa3b, v11
	v_exp_f32_e32 v8, v8
	s_nop 0
	v_add_f32_e32 v8, 1.0, v8
	v_rcp_f32_e32 v15, v8
	v_mul_f32_e32 v8, 0xbfb8aa3b, v12
	v_exp_f32_e32 v8, v8
	v_pk_mul_f32 v[10:11], v[10:11], v[14:15]
	s_nop 0
	v_cvt_pk_bf16_f32 v10, v10, v11
	v_add_f32_e32 v8, 1.0, v8
	v_rcp_f32_e32 v14, v8
	v_mul_f32_e32 v8, 0xbfb8aa3b, v13
	v_exp_f32_e32 v8, v8
	s_nop 0
	v_add_f32_e32 v8, 1.0, v8
	v_rcp_f32_e32 v15, v8
	s_nop 0
	v_pk_mul_f32 v[12:13], v[12:13], v[14:15]
	s_nop 0
	v_cvt_pk_bf16_f32 v11, v12, v13
	v_lshl_add_u64 v[12:13], v[152:153], 0, v[194:195]
	global_store_dwordx2 v[12:13], v[10:11], off
	ds_read_b128 v[10:13], v243 offset:63488
	s_waitcnt lgkmcnt(0)
; __device__ __forceinline__ unsigned cvt_pk_bf16(float lo, float hi) { const f32x2c v = {lo, hi}; const bf16x2c b = __builtin_convertvector(v, bf16x2c); return __builtin_bit_cast(unsigned, b); }
; __device__ __forceinline__ float sigmoidf_(float x) { return __builtin_amdgcn_rcpf(1.f + __builtin_amdgcn_exp2f(-1.4426950408889634f * x)); }
; template <int NTOK, bool SMP>
; __device__ __forceinline__ void mix_tile(KP p, int l, float* lds, int tid, int s, int t0) {
;     ...
;     {
;         const f32x4 g = *(const f32x4*)(p->in[I_CLG] + l * 256 + 4 * lane), bb = *(const f32x4*)(p->in[I_CLB] + l * 256 + 4 * lane);
; #pragma unroll
;         for (int k = 0; k < TPW; ++k) {
;             const int i = wid + 8 * k;
;             const f32x4 x = *(const f32x4*)(cvs + i * 256 + 4 * lane);
;             const float mu = wave_sum(x[0] + x[1] + x[2] + x[3], lane) * (1.f / 256.f);
;             const f32x4 d = x - mu;
;             const float var = wave_sum(d[0] * d[0] + d[1] * d[1] + d[2] * d[2] + d[3] * d[3], lane) * (1.f / 256.f);
;             const float r = rsqrtf(var + LN_EPS);
;             f32x4 y = d * r * g + bb;
; #pragma unroll
;             for (int j = 0; j < 4; ++j) y[j] = y[j] * sigmoidf_(y[j]);
;             u32x2 o; o[0] = cvt_pk_bf16(y[0], y[1]); o[1] = cvt_pk_bf16(y[2], y[3]);
;             *(u32x2*)(CVN + (size_t)(mrow0 + i) * 256 + 4 * lane) = o;
;         }
	v_add_f32_e32 v8, v10, v11
	v_add_f32_e32 v8, v12, v8
	v_add_f32_e32 v8, v13, v8
	ds_bpermute_b32 v14, v101, v8
	s_waitcnt lgkmcnt(0)
	v_add_f32_e32 v8, v8, v14
	ds_bpermute_b32 v14, v107, v8
	s_waitcnt lgkmcnt(0)
	v_add_f32_e32 v8, v8, v14
	s_nop 1
	v_mov_b32_dpp v14, v8 row_mirror row_mask:0xf bank_mask:0xf
	s_waitcnt lgkmcnt(0)
	v_add_f32_e32 v8, v8, v14
	s_nop 1
	v_mov_b32_dpp v14, v8 row_half_mirror row_mask:0xf bank_mask:0xf
	s_waitcnt lgkmcnt(0)
	v_add_f32_e32 v8, v8, v14
	s_nop 1
	v_mov_b32_dpp v14, v8 quad_perm:[2,3,0,1] row_mask:0xf bank_mask:0xf
	s_waitcnt lgkmcnt(0)
	v_add_f32_e32 v8, v8, v14
	s_nop 1
	v_mov_b32_dpp v14, v8 quad_perm:[1,0,3,2] row_mask:0xf bank_mask:0xf
	s_waitcnt lgkmcnt(0)
	v_add_f32_e32 v8, v8, v14
	ds_read_b128 v[14:17], v247 offset:63488
	v_fmamk_f32 v21, v8, 0xbb800000, v11
	v_fmamk_f32 v20, v8, 0xbb800000, v10
	v_fmamk_f32 v13, v8, 0xbb800000, v13
	v_fmac_f32_e32 v12, 0xbb800000, v8
	s_waitcnt lgkmcnt(0)
	v_add_f32_e32 v8, v14, v15
	v_add_f32_e32 v8, v16, v8
	v_add_f32_e32 v8, v17, v8
	ds_bpermute_b32 v26, v101, v8
	v_pk_mul_f32 v[24:25], v[20:21], v[20:21]
	v_pk_mul_f32 v[22:23], v[12:13], v[12:13]
	v_mov_b32_e32 v31, v24
	v_lshl_add_u64 v[10:11], v[152:153], 0, v[196:197]
	s_waitcnt lgkmcnt(0)
	v_add_f32_e32 v8, v8, v26
	ds_bpermute_b32 v26, v107, v8
	s_waitcnt lgkmcnt(0)
	v_add_f32_e32 v8, v8, v26
	s_nop 1
	v_mov_b32_dpp v26, v8 row_mirror row_mask:0xf bank_mask:0xf
	s_waitcnt lgkmcnt(0)
	v_add_f32_e32 v8, v8, v26
	s_nop 1
	v_mov_b32_dpp v26, v8 row_half_mirror row_mask:0xf bank_mask:0xf
	s_waitcnt lgkmcnt(0)
	v_add_f32_e32 v8, v8, v26
	s_nop 1
	v_mov_b32_dpp v26, v8 quad_perm:[2,3,0,1] row_mask:0xf bank_mask:0xf
	s_waitcnt lgkmcnt(0)
	v_add_f32_e32 v8, v8, v26
	s_nop 1
	v_mov_b32_dpp v26, v8 quad_perm:[1,0,3,2] row_mask:0xf bank_mask:0xf
	s_waitcnt lgkmcnt(0)
	v_add_f32_e32 v8, v8, v26
	v_fmamk_f32 v15, v8, 0xbb800000, v15
	v_fmamk_f32 v14, v8, 0xbb800000, v14
	v_fmamk_f32 v17, v8, 0xbb800000, v17
	v_fmac_f32_e32 v16, 0xbb800000, v8
	v_pk_mul_f32 v[28:29], v[14:15], v[14:15]
	v_pk_mul_f32 v[26:27], v[16:17], v[16:17]
	v_mov_b32_e32 v30, v28
	v_mov_b32_e32 v24, v29
	v_pk_add_f32 v[24:25], v[30:31], v[24:25]
	v_mov_b32_e32 v28, v26
	v_mov_b32_e32 v29, v22
	v_pk_add_f32 v[24:25], v[28:29], v[24:25]
	v_mov_b32_e32 v22, v27
	v_pk_add_f32 v[22:23], v[22:23], v[24:25]
	ds_bpermute_b32 v25, v101, v23
	ds_bpermute_b32 v24, v101, v22
	s_waitcnt lgkmcnt(0)
	v_pk_add_f32 v[22:23], v[22:23], v[24:25]
	ds_bpermute_b32 v25, v107, v23
	ds_bpermute_b32 v24, v107, v22
	s_waitcnt lgkmcnt(0)
	v_pk_add_f32 v[22:23], v[22:23], v[24:25]
	s_nop 1
	v_mov_b32_dpp v25, v23 row_mirror row_mask:0xf bank_mask:0xf
	s_nop 1
	v_mov_b32_dpp v24, v22 row_mirror row_mask:0xf bank_mask:0xf
	s_waitcnt lgkmcnt(0)
	v_pk_add_f32 v[22:23], v[22:23], v[24:25]
	s_nop 1
	v_mov_b32_dpp v25, v23 row_half_mirror row_mask:0xf bank_mask:0xf
	s_nop 1
	v_mov_b32_dpp v24, v22 row_half_mirror row_mask:0xf bank_mask:0xf
	s_waitcnt lgkmcnt(0)
	v_pk_add_f32 v[22:23], v[22:23], v[24:25]
	s_nop 1
	v_mov_b32_dpp v25, v23 quad_perm:[2,3,0,1] row_mask:0xf bank_mask:0xf
	s_nop 1
	v_mov_b32_dpp v24, v22 quad_perm:[2,3,0,1] row_mask:0xf bank_mask:0xf
	s_waitcnt lgkmcnt(0)
	v_pk_add_f32 v[22:23], v[22:23], v[24:25]
	s_nop 1
	v_mov_b32_dpp v25, v23 quad_perm:[1,0,3,2] row_mask:0xf bank_mask:0xf
	s_nop 1
	v_mov_b32_dpp v24, v22 quad_perm:[1,0,3,2] row_mask:0xf bank_mask:0xf
	s_waitcnt lgkmcnt(0)
	v_pk_add_f32 v[22:23], v[22:23], v[24:25]
	s_nop 0
	v_pk_fma_f32 v[18:19], v[22:23], s[0:1], v[18:19] op_sel_hi:[1,0,0]
	s_nop 0
	v_mul_f32_e32 v8, 0x4b800000, v19
	v_cmp_gt_f32_e64 s[42:43], s96, v19
	v_cmp_gt_f32_e32 vcc, s96, v18
	s_nop 0
	v_cndmask_b32_e64 v8, v19, v8, s[42:43]
	v_rsq_f32_e32 v8, v8
	s_nop 0
	v_mul_f32_e32 v19, 0x45800000, v8
	v_cndmask_b32_e64 v8, v8, v19, s[42:43]
	v_pk_mul_f32 v[20:21], v[20:21], v[8:9] op_sel_hi:[1,0]
	v_pk_mul_f32 v[12:13], v[12:13], v[8:9] op_sel_hi:[1,0]
	v_pk_fma_f32 v[20:21], v[0:1], v[20:21], v[4:5]
	v_pk_fma_f32 v[12:13], v[2:3], v[12:13], v[6:7]
	v_mul_f32_e32 v8, 0xbfb8aa3b, v20
	v_exp_f32_e32 v8, v8
	s_nop 0
	v_add_f32_e32 v8, 1.0, v8
	v_rcp_f32_e32 v22, v8
	v_mul_f32_e32 v8, 0xbfb8aa3b, v21
	v_exp_f32_e32 v8, v8
	s_nop 0
	v_add_f32_e32 v8, 1.0, v8
	v_rcp_f32_e32 v23, v8
	v_mul_f32_e32 v8, 0xbfb8aa3b, v12
	v_exp_f32_e32 v8, v8
	v_pk_mul_f32 v[20:21], v[20:21], v[22:23]
	s_nop 0
	v_cvt_pk_bf16_f32 v20, v20, v21
	v_add_f32_e32 v8, 1.0, v8
	v_rcp_f32_e32 v22, v8
	v_mul_f32_e32 v8, 0xbfb8aa3b, v13
	v_exp_f32_e32 v8, v8
	s_nop 0
	v_add_f32_e32 v8, 1.0, v8
	v_rcp_f32_e32 v23, v8
	v_mul_f32_e32 v8, 0x4b800000, v18
	v_cndmask_b32_e32 v8, v18, v8, vcc
	v_rsq_f32_e32 v8, v8
	v_pk_mul_f32 v[12:13], v[12:13], v[22:23]
	s_nop 0
	v_cvt_pk_bf16_f32 v21, v12, v13
	global_store_dwordx2 v[10:11], v[20:21], off
	v_mul_f32_e32 v10, 0x45800000, v8
	v_cndmask_b32_e32 v8, v8, v10, vcc
	v_pk_mul_f32 v[10:11], v[14:15], v[8:9] op_sel_hi:[1,0]
	v_pk_mul_f32 v[12:13], v[16:17], v[8:9] op_sel_hi:[1,0]
	v_pk_fma_f32 v[0:1], v[0:1], v[10:11], v[4:5]
	v_pk_fma_f32 v[2:3], v[2:3], v[12:13], v[6:7]
	v_mul_f32_e32 v4, 0xbfb8aa3b, v0
	v_mul_f32_e32 v5, 0xbfb8aa3b, v1
	v_exp_f32_e32 v4, v4
	v_exp_f32_e32 v5, v5
	v_add_f32_e32 v4, 1.0, v4
	v_add_f32_e32 v5, 1.0, v5
	v_rcp_f32_e32 v4, v4
	v_rcp_f32_e32 v5, v5
	s_nop 0
	v_pk_mul_f32 v[0:1], v[0:1], v[4:5]
	v_mul_f32_e32 v4, 0xbfb8aa3b, v2
	v_mul_f32_e32 v5, 0xbfb8aa3b, v3
	v_exp_f32_e32 v4, v4
	v_exp_f32_e32 v5, v5
	v_cvt_pk_bf16_f32 v0, v0, v1
	v_add_f32_e32 v4, 1.0, v4
	v_add_f32_e32 v5, 1.0, v5
	v_rcp_f32_e32 v4, v4
	v_rcp_f32_e32 v5, v5
	s_nop 0
	v_pk_mul_f32 v[2:3], v[2:3], v[4:5]
	s_nop 0
	v_cvt_pk_bf16_f32 v1, v2, v3
; __device__ __forceinline__ unsigned cvt_pk_bf16(float lo, float hi) { const f32x2c v = {lo, hi}; const bf16x2c b = __builtin_convertvector(v, bf16x2c); return __builtin_bit_cast(unsigned, b); }
; template <int NTOK, bool SMP>
; __device__ __forceinline__ void mix_tile(KP p, int l, float* lds, int tid, int s, int t0) {
;     ...
;         unsigned xq[TPW][3]; u32x2 xkv[TPW]; float k1[TPW], k2[TPW];
; #pragma unroll
;         for (int k = 0; k < TPW; ++k) {
;             const bf16_t* pr = P + (size_t)(mrow0 + wid + 8 * k) * PW;
; #pragma unroll
;             for (int j = 0; j < 3; ++j) xq[k][j] = *(const unsigned*)(pr + PC_Q + 2 * lane + 128 * j);
;             xkv[k] = *(const u32x2*)(pr + PC_KV + 4 * lane);
;             k1[k] = bf2f(pr[PC_KR + (lane & 15)]); k2[k] = bf2f(pr[PC_KR + 16 + (lane & 15)]);
;         }
;         const float* gq = p->in[I_QNG] + l * Q_LORA;
;         float gqv[6];
; #pragma unroll
;         for (int j = 0; j < 3; ++j) { gqv[2 * j] = gq[2 * lane + 128 * j]; gqv[2 * j + 1] = gq[2 * lane + 128 * j + 1]; }
;         const f32x4 gkv = *(const f32x4*)(p->in[I_KVNG] + l * KV_LORA + 4 * lane);
; #pragma unroll
;         for (int k = 0; k < TPW; ++k) {
;             const int i = wid + 8 * k;
;             {
;                 float x[6]; float ss = 0.f;
; #pragma unroll
;                 for (int j = 0; j < 3; ++j) { x[2 * j] = bflo(xq[k][j]); x[2 * j + 1] = bfhi(xq[k][j]); ss += x[2 * j] * x[2 * j] + x[2 * j + 1] * x[2 * j + 1]; }
;                 ss = wave_sum(ss, lane); const float r = rsqrtf(ss * (1.f / 384.f) + RMS_EPS);
; #pragma unroll
;                 for (int j = 0; j < 3; ++j) *(unsigned*)(QN + (size_t)(mrow0 + i) * 384 + 2 * lane + 128 * j) = cvt_pk_bf16(x[2 * j] * r * gqv[2 * j], x[2 * j + 1] * r * gqv[2 * j + 1]);
;             }
;             {
;                 f32x4 x = {bflo(xkv[k][0]), bfhi(xkv[k][0]), bflo(xkv[k][1]), bfhi(xkv[k][1])};
;                 float ss = x[0] * x[0] + x[1] * x[1] + x[2] * x[2] + x[3] * x[3];
;                 ss = wave_sum(ss, lane); const float r = rsqrtf(ss * (1.f / 256.f) + RMS_EPS);
;                 x = x * r * gkv;
;                 __builtin_nontemporal_store(x, (f32x4*)(ckv_out + (size_t)i * 256 + 4 * lane));
;                 u32x2 o; o[0] = cvt_pk_bf16(x[0], x[1]); o[1] = cvt_pk_bf16(x[2], x[3]);
;                 *(u32x2*)(CKV + (size_t)(arow0 + i) * 256 + 4 * lane) = o;
;             }
.LBB0_257:
	s_and_b64 vcc, exec, s[30:31]
	s_cbranch_vccz .LBB0_303
	s_add_i32 s18, s34, 0xfffff800
	s_lshl_b32 s1, s18, 4
	s_or_b32 s0, s1, 0x10000
	v_add_u32_e32 v50, s0, v98
	v_readlane_b32 s28, v252, 0
	v_ashrrev_i32_e32 v51, 31, v50
	v_readlane_b32 s29, v252, 1
	v_lshlrev_b64 v[0:1], 12, v[50:51]
	v_mov_b32_e32 v191, v9
	v_lshl_add_u64 v[0:1], s[28:29], 0, v[0:1]
	v_lshl_add_u64 v[2:3], v[0:1], 0, v[190:191]
	s_barrier
	global_load_dword v27, v[2:3], off
	global_load_dword v29, v[2:3], off offset:256
	global_load_dword v31, v[2:3], off offset:512
	v_mov_b32_e32 v189, v9
	v_lshl_add_u64 v[2:3], v[0:1], 0, v[188:189]
	global_load_dwordx2 v[18:19], v[2:3], off offset:768
	s_add_i32 s48, s18, s8
	s_ashr_i32 s49, s48, 31
	s_lshl_b64 s[20:21], s[48:49], 14
	s_add_u32 s42, s28, s20
	v_readlane_b32 s30, v252, 2
	s_addc_u32 s43, s29, s21
	s_mul_i32 s20, s48, 0xffffc800
	s_add_u32 s30, s42, s20
	v_mov_b32_e32 v187, v9
	s_mov_b64 s[20:21], 0x8000
	v_lshl_add_u64 v[2:3], v[0:1], 0, v[186:187]
	v_lshl_add_u64 v[0:1], v[0:1], 0, s[20:21]
	global_load_ushort v24, v[2:3], off offset:1280
	global_load_ushort v25, v[2:3], off offset:1312
	v_lshl_add_u64 v[2:3], v[0:1], 0, v[190:191]
	global_load_dword v23, v[2:3], off
	global_load_dword v22, v[2:3], off offset:256
	global_load_dword v21, v[2:3], off offset:512
	v_lshl_add_u64 v[2:3], v[0:1], 0, v[188:189]
	v_lshl_add_u64 v[0:1], v[0:1], 0, v[186:187]
	global_load_dwordx2 v[4:5], v[2:3], off offset:768
	global_load_ushort v8, v[0:1], off offset:1280
	global_load_ushort v20, v[0:1], off offset:1312
	s_load_dwordx2 s[28:29], s[62:63], 0x40
	s_load_dwordx2 s[58:59], s[62:63], 0x50
	v_readlane_b32 s31, v252, 3
	s_mul_hi_i32 s18, s48, 0xffffc800
	s_addc_u32 s31, s43, s18
	s_lshl_b64 s[20:21], s[16:17], 2
	s_waitcnt lgkmcnt(0)
	s_add_u32 s20, s28, s20
	s_addc_u32 s21, s29, s21
	global_load_dwordx2 v[12:13], v173, s[20:21]
	global_load_dwordx2 v[10:11], v173, s[20:21] offset:512
	global_load_dwordx2 v[6:7], v173, s[20:21] offset:1024
	s_mul_i32 s18, s34, 0x840
	s_add_i32 s18, s18, 0xffbf0800
	s_lshl_b64 s[50:51], s[6:7], 2
	s_add_u32 s20, s58, s50
	s_addc_u32 s21, s59, s51
	global_load_dwordx4 v[0:3], v182, s[20:21]
	v_mov_b32_e32 v183, v9
	v_lshl_add_u64 v[14:15], s[42:43], 0, v[182:183]
	s_mov_b64 s[20:21], 0x22500000
	v_mov_b32_e32 v185, v9
	v_lshl_add_u64 v[16:17], v[14:15], 0, s[20:21]
	v_lshl_add_u64 v[14:15], s[30:31], 0, v[184:185]
	s_mov_b64 s[20:21], 0x22600000
	v_lshl_add_u64 v[14:15], v[14:15], 0, s[20:21]
	s_movk_i32 s20, 0x300
	v_mad_i64_i32 v[32:33], s[20:21], v50, s20, v[108:109]
	s_mov_b32 s20, 0x3b800000
	s_mov_b32 s21, 0x3b2aaaab
	s_waitcnt vmcnt(15)
	v_lshlrev_b32_e32 v26, 16, v27
	v_and_b32_e32 v27, 0xffff0000, v27
	s_waitcnt vmcnt(13)
	v_lshlrev_b32_e32 v30, 16, v31
	v_and_b32_e32 v31, 0xffff0000, v31
	v_mov_b32_e32 v38, v27
	v_mov_b32_e32 v39, v31
	v_mov_b32_e32 v36, v26
	v_mov_b32_e32 v37, v30
	v_pk_mul_f32 v[38:39], v[38:39], v[38:39]
	v_lshlrev_b32_e32 v28, 16, v29
	v_and_b32_e32 v29, 0xffff0000, v29
	v_pk_fma_f32 v[36:37], v[36:37], v[36:37], v[38:39]
	s_waitcnt vmcnt(12)
	v_lshlrev_b32_e32 v38, 16, v18
	v_and_b32_e32 v39, 0xffff0000, v18
	v_and_b32_e32 v42, 0xffff0000, v19
	v_pk_mul_f32 v[34:35], v[28:29], v[28:29]
	v_pk_mul_f32 v[40:41], v[38:39], v[38:39]
	v_and_b32_e32 v43, s0, v19
	v_lshlrev_b32_e32 v19, 16, v19
	v_mov_b32_e32 v18, v42
	v_pk_mul_f32 v[44:45], v[18:19], v[18:19]
	v_mov_b32_e32 v46, v40
	v_mov_b32_e32 v47, v34
	v_mov_b32_e32 v34, v41
	v_pk_add_f32 v[34:35], v[46:47], v[34:35]
	v_pk_mov_b32 v[40:41], v[44:45], v[36:37] op_sel:[1,0]
	v_mov_b32_e32 v45, v37
	v_pk_add_f32 v[34:35], v[40:41], v[34:35]
	v_pk_mov_b32 v[18:19], v[18:19], v[42:43] op_sel:[1,0]
	v_pk_add_f32 v[34:35], v[44:45], v[34:35]
	ds_bpermute_b32 v37, v101, v35
	ds_bpermute_b32 v36, v101, v34
	s_waitcnt lgkmcnt(0)
	v_pk_add_f32 v[34:35], v[34:35], v[36:37]
	ds_bpermute_b32 v37, v107, v35
	ds_bpermute_b32 v36, v107, v34
	s_waitcnt lgkmcnt(0)
	v_pk_add_f32 v[34:35], v[34:35], v[36:37]
	s_nop 1
	v_mov_b32_dpp v37, v35 row_mirror row_mask:0xf bank_mask:0xf
	s_nop 1
	v_mov_b32_dpp v36, v34 row_mirror row_mask:0xf bank_mask:0xf
	s_waitcnt lgkmcnt(0)
	v_pk_add_f32 v[34:35], v[34:35], v[36:37]
	s_nop 1
	v_mov_b32_dpp v37, v35 row_half_mirror row_mask:0xf bank_mask:0xf
	s_nop 1
	v_mov_b32_dpp v36, v34 row_half_mirror row_mask:0xf bank_mask:0xf
	s_waitcnt lgkmcnt(0)
	v_pk_add_f32 v[34:35], v[34:35], v[36:37]
	s_nop 1
	v_mov_b32_dpp v37, v35 quad_perm:[2,3,0,1] row_mask:0xf bank_mask:0xf
	s_nop 1
	v_mov_b32_dpp v36, v34 quad_perm:[2,3,0,1] row_mask:0xf bank_mask:0xf
	s_waitcnt lgkmcnt(0)
	v_pk_add_f32 v[34:35], v[34:35], v[36:37]
	s_nop 1
	v_mov_b32_dpp v37, v35 quad_perm:[1,0,3,2] row_mask:0xf bank_mask:0xf
	s_nop 1
	v_mov_b32_dpp v36, v34 quad_perm:[1,0,3,2] row_mask:0xf bank_mask:0xf
	s_waitcnt lgkmcnt(0)
	v_pk_add_f32 v[34:35], v[34:35], v[36:37]
	v_mov_b32_e32 v36, 0x358637bd
	v_pk_fma_f32 v[34:35], v[34:35], s[20:21], v[36:37] op_sel_hi:[1,1,0]
	s_nop 0
	v_mul_f32_e32 v36, 0x4b800000, v35
	v_cmp_gt_f32_e64 s[42:43], s96, v35
	v_cmp_gt_f32_e32 vcc, s96, v34
	s_nop 0
	v_cndmask_b32_e64 v35, v35, v36, s[42:43]
	v_rsq_f32_e32 v35, v35
	s_nop 0
	v_mul_f32_e32 v36, 0x45800000, v35
	v_cndmask_b32_e64 v36, v35, v36, s[42:43]
	v_pk_mul_f32 v[26:27], v[36:37], v[26:27] op_sel_hi:[0,1]
	s_waitcnt vmcnt(3)
	v_pk_mul_f32 v[26:27], v[12:13], v[26:27]
	s_nop 0
	v_cvt_pk_bf16_f32 v26, v26, v27
	global_store_dword v[32:33], v26, off
	v_pk_mul_f32 v[26:27], v[36:37], v[28:29] op_sel_hi:[0,1]
	s_waitcnt vmcnt(3)
	v_pk_mul_f32 v[26:27], v[10:11], v[26:27]
	s_nop 0
	v_cvt_pk_bf16_f32 v26, v26, v27
	global_store_dword v[32:33], v26, off offset:256
	v_pk_mul_f32 v[26:27], v[36:37], v[30:31] op_sel_hi:[0,1]
	s_waitcnt vmcnt(3)
	v_pk_mul_f32 v[26:27], v[6:7], v[26:27]
	s_nop 0
	v_cvt_pk_bf16_f32 v26, v26, v27
	global_store_dword v[32:33], v26, off offset:512
	v_mul_f32_e32 v26, 0x4b800000, v34
	v_cndmask_b32_e32 v26, v34, v26, vcc
	v_rsq_f32_e32 v26, v26
	s_nop 0
	v_mul_f32_e32 v27, 0x45800000, v26
	v_cndmask_b32_e32 v26, v26, v27, vcc
	v_pk_mul_f32 v[30:31], v[26:27], v[38:39] op_sel_hi:[0,1]
	v_pk_mul_f32 v[18:19], v[26:27], v[18:19] op_sel_hi:[0,1]
	s_waitcnt vmcnt(3)
	v_pk_mul_f32 v[28:29], v[2:3], v[18:19]
	v_pk_mul_f32 v[26:27], v[0:1], v[30:31]
	v_lshl_add_u64 v[18:19], v[16:17], 0, v[114:115]
	global_store_dwordx4 v[18:19], v[26:29], off nt
	v_add_u32_e32 v18, s18, v98
	v_ashrrev_i32_e32 v19, 31, v18
	v_cvt_pk_bf16_f32 v26, v26, v27
	v_cvt_pk_bf16_f32 v27, v28, v29
	v_lshlrev_b64 v[28:29], 9, v[18:19]
	v_lshl_add_u64 v[28:29], v[110:111], 0, v[28:29]
	global_store_dwordx2 v[28:29], v[26:27], off
	s_and_saveexec_b64 s[42:43], s[4:5]
	s_cbranch_execz .LBB0_260
; __device__ __forceinline__ unsigned cvt_pk_bf16(float lo, float hi) { const f32x2c v = {lo, hi}; const bf16x2c b = __builtin_convertvector(v, bf16x2c); return __builtin_bit_cast(unsigned, b); }
; __device__ __forceinline__ float bflo(unsigned u) { return __uint_as_float(u << 16); }
; __device__ __forceinline__ float bfhi(unsigned u) { return __uint_as_float(u & 0xffff0000u); }
; __device__ __forceinline__ bf16_t f2bf(float f) { return (bf16_t)(cvt_pk_bf16(f, 0.f) & 0xffffu); }
; template <int NTOK, bool SMP>
; __device__ __forceinline__ void mix_tile(KP p, int l, float* lds, int tid, int s, int t0) {
;     ...
;         for (int k = 0; k < TPW; ++k) {
;             const int i = wid + 8 * k;
;             {
;                 float x[6]; float ss = 0.f;
; #pragma unroll
;                 for (int j = 0; j < 3; ++j) { x[2 * j] = bflo(xq[k][j]); x[2 * j + 1] = bfhi(xq[k][j]); ss += x[2 * j] * x[2 * j] + x[2 * j + 1] * x[2 * j + 1]; }
;                 ss = wave_sum(ss, lane); const float r = rsqrtf(ss * (1.f / 384.f) + RMS_EPS);
; #pragma unroll
;                 for (int j = 0; j < 3; ++j) *(unsigned*)(QN + (size_t)(mrow0 + i) * 384 + 2 * lane + 128 * j) = cvt_pk_bf16(x[2 * j] * r * gqv[2 * j], x[2 * j + 1] * r * gqv[2 * j + 1]);
;             }
;             {
;                 f32x4 x = {bflo(xkv[k][0]), bfhi(xkv[k][0]), bflo(xkv[k][1]), bfhi(xkv[k][1])};
;                 float ss = x[0] * x[0] + x[1] * x[1] + x[2] * x[2] + x[3] * x[3];
;                 ss = wave_sum(ss, lane); const float r = rsqrtf(ss * (1.f / 256.f) + RMS_EPS);
;                 x = x * r * gkv;
;                 __builtin_nontemporal_store(x, (f32x4*)(ckv_out + (size_t)i * 256 + 4 * lane));
;                 u32x2 o; o[0] = cvt_pk_bf16(x[0], x[1]); o[1] = cvt_pk_bf16(x[2], x[3]);
;                 *(u32x2*)(CKV + (size_t)(arow0 + i) * 256 + 4 * lane) = o;
;             }
;             if (lane < 16) {
;                 const float cs = rope[(pos0 + i) * 32 + lane], sn = rope[(pos0 + i) * 32 + 16 + lane];
;                 const float o1 = k1[k] * cs - k2[k] * sn, o2 = k1[k] * sn + k2[k] * cs;
;                 kr_out[(size_t)i * 32 + lane] = o1; kr_out[(size_t)i * 32 + 16 + lane] = o2;
;                 KR[(size_t)(arow0 + i) * 32 + lane] = f2bf(o1); KR[(size_t)(arow0 + i) * 32 + 16 + lane] = f2bf(o2);
;             }
	global_load_dword v26, v[154:155], off
	global_load_dword v27, v[156:157], off
	v_lshlrev_b32_e32 v25, 16, v25
	v_lshlrev_b32_e32 v24, 16, v24
	v_lshlrev_b64 v[18:19], 6, v[18:19]
	v_lshl_add_u64 v[18:19], v[112:113], 0, v[18:19]
	s_waitcnt vmcnt(0)
	v_mul_f32_e32 v28, v27, v25
	v_mul_f32_e32 v27, v27, v24
	v_fma_f32 v28, v26, v24, -v28
	v_fmac_f32_e32 v27, v26, v25
	v_lshl_add_u64 v[24:25], v[14:15], 0, v[116:117]
	global_store_dword v[24:25], v28, off
	global_store_dword v[24:25], v27, off offset:64
	v_cvt_pk_bf16_f32 v24, v28, s0
	global_store_short v[18:19], v24, off
	v_cvt_pk_bf16_f32 v24, v27, s0
	global_store_short v[18:19], v24, off offset:32
.LBB0_260:
	s_or_b64 exec, exec, s[42:43]
	v_lshlrev_b32_e32 v18, 16, v23
	v_and_b32_e32 v19, 0xffff0000, v23
	v_and_b32_e32 v23, 0xffff0000, v21
	v_lshlrev_b32_e32 v24, 16, v22
	v_and_b32_e32 v25, 0xffff0000, v22
	v_lshlrev_b32_e32 v22, 16, v21
	v_mov_b32_e32 v30, v19
	v_mov_b32_e32 v31, v23
	v_mov_b32_e32 v28, v18
	v_mov_b32_e32 v29, v22
	v_pk_mul_f32 v[30:31], v[30:31], v[30:31]
	v_pk_mul_f32 v[26:27], v[24:25], v[24:25]
	v_pk_fma_f32 v[28:29], v[28:29], v[28:29], v[30:31]
	v_lshlrev_b32_e32 v30, 16, v4
	v_and_b32_e32 v31, 0xffff0000, v4
	v_and_b32_e32 v4, 0xffff0000, v5
	v_pk_mul_f32 v[32:33], v[30:31], v[30:31]
	v_lshlrev_b32_e32 v35, 16, v5
	v_mov_b32_e32 v34, v4
	v_pk_mul_f32 v[36:37], v[34:35], v[34:35]
	v_mov_b32_e32 v38, v32
	v_mov_b32_e32 v39, v26
	v_mov_b32_e32 v26, v33
	v_pk_add_f32 v[26:27], v[38:39], v[26:27]
	v_pk_mov_b32 v[32:33], v[36:37], v[28:29] op_sel:[1,0]
	v_mov_b32_e32 v37, v29
	v_pk_add_f32 v[26:27], v[32:33], v[26:27]
	v_add_u32_e32 v52, s0, v118
	v_pk_add_f32 v[26:27], v[36:37], v[26:27]
	ds_bpermute_b32 v29, v101, v27
	ds_bpermute_b32 v28, v101, v26
	v_and_b32_e32 v5, s0, v5
	v_pk_mov_b32 v[4:5], v[34:35], v[4:5] op_sel:[1,0]
	s_waitcnt lgkmcnt(0)
	v_pk_add_f32 v[26:27], v[26:27], v[28:29]
	ds_bpermute_b32 v29, v107, v27
	ds_bpermute_b32 v28, v107, v26
	s_waitcnt lgkmcnt(0)
	v_pk_add_f32 v[26:27], v[26:27], v[28:29]
	s_nop 1
	v_mov_b32_dpp v29, v27 row_mirror row_mask:0xf bank_mask:0xf
	s_nop 1
	v_mov_b32_dpp v28, v26 row_mirror row_mask:0xf bank_mask:0xf
	s_waitcnt lgkmcnt(0)
	v_pk_add_f32 v[26:27], v[26:27], v[28:29]
	s_nop 1
	v_mov_b32_dpp v29, v27 row_half_mirror row_mask:0xf bank_mask:0xf
	s_nop 1
	v_mov_b32_dpp v28, v26 row_half_mirror row_mask:0xf bank_mask:0xf
	s_waitcnt lgkmcnt(0)
	v_pk_add_f32 v[26:27], v[26:27], v[28:29]
	s_nop 1
	v_mov_b32_dpp v29, v27 quad_perm:[2,3,0,1] row_mask:0xf bank_mask:0xf
	s_nop 1
	v_mov_b32_dpp v28, v26 quad_perm:[2,3,0,1] row_mask:0xf bank_mask:0xf
	s_waitcnt lgkmcnt(0)
	v_pk_add_f32 v[26:27], v[26:27], v[28:29]
	s_nop 1
	v_mov_b32_dpp v29, v27 quad_perm:[1,0,3,2] row_mask:0xf bank_mask:0xf
	s_nop 1
	v_mov_b32_dpp v28, v26 quad_perm:[1,0,3,2] row_mask:0xf bank_mask:0xf
	s_waitcnt lgkmcnt(0)
	v_pk_add_f32 v[26:27], v[26:27], v[28:29]
	v_mov_b32_e32 v28, 0x358637bd
	v_pk_fma_f32 v[26:27], v[26:27], s[20:21], v[28:29] op_sel_hi:[1,1,0]
	s_movk_i32 s20, 0x300
	v_mul_f32_e32 v21, 0x4b800000, v27
	v_cmp_gt_f32_e32 vcc, s96, v27
	v_mad_i64_i32 v[28:29], s[20:21], v52, s20, v[108:109]
	s_nop 0
	v_cndmask_b32_e32 v21, v27, v21, vcc
	v_rsq_f32_e32 v21, v21
	s_nop 0
	v_mul_f32_e32 v27, 0x45800000, v21
	v_cndmask_b32_e32 v32, v21, v27, vcc
	v_pk_mul_f32 v[18:19], v[32:33], v[18:19] op_sel_hi:[0,1]
	v_pk_mul_f32 v[12:13], v[12:13], v[18:19]
	v_cmp_gt_f32_e32 vcc, s96, v26
	v_cvt_pk_bf16_f32 v12, v12, v13
	global_store_dword v[28:29], v12, off
	v_pk_mul_f32 v[12:13], v[32:33], v[24:25] op_sel_hi:[0,1]
	v_pk_mul_f32 v[10:11], v[10:11], v[12:13]
	v_mul_f32_e32 v12, 0x4b800000, v26
	v_cndmask_b32_e32 v12, v26, v12, vcc
	v_cvt_pk_bf16_f32 v10, v10, v11
	v_rsq_f32_e32 v12, v12
	global_store_dword v[28:29], v10, off offset:256
	v_pk_mul_f32 v[10:11], v[32:33], v[22:23] op_sel_hi:[0,1]
	v_pk_mul_f32 v[6:7], v[6:7], v[10:11]
	s_nop 0
	v_cvt_pk_bf16_f32 v6, v6, v7
	global_store_dword v[28:29], v6, off offset:512
	v_mul_f32_e32 v6, 0x45800000, v12
	v_cndmask_b32_e32 v6, v12, v6, vcc
	v_pk_mul_f32 v[10:11], v[6:7], v[30:31] op_sel_hi:[0,1]
	v_pk_mul_f32 v[4:5], v[6:7], v[4:5] op_sel_hi:[0,1]
	v_pk_mul_f32 v[2:3], v[2:3], v[4:5]
	v_pk_mul_f32 v[0:1], v[0:1], v[10:11]
	v_lshl_add_u64 v[4:5], v[16:17], 0, v[120:121]
	global_store_dwordx4 v[4:5], v[0:3], off nt
	v_cvt_pk_bf16_f32 v4, v0, v1
	v_cvt_pk_bf16_f32 v5, v2, v3
	v_add_u32_e32 v0, s18, v118
	v_ashrrev_i32_e32 v1, 31, v0
	v_lshlrev_b64 v[2:3], 9, v[0:1]
	v_lshl_add_u64 v[2:3], v[110:111], 0, v[2:3]
	global_store_dwordx2 v[2:3], v[4:5], off
	s_and_saveexec_b64 s[42:43], s[4:5]
	s_cbranch_execz .LBB0_262
	global_load_dword v4, v[160:161], off
	global_load_dword v5, v[158:159], off
	v_lshlrev_b32_e32 v7, 16, v20
	v_lshlrev_b32_e32 v6, 16, v8
	v_lshl_add_u64 v[2:3], v[14:15], 0, v[122:123]
	v_lshlrev_b64 v[0:1], 6, v[0:1]
	v_lshl_add_u64 v[0:1], v[112:113], 0, v[0:1]
	s_waitcnt vmcnt(1)
	v_mul_f32_e32 v8, v4, v7
	v_mul_f32_e32 v4, v4, v6
	s_waitcnt vmcnt(0)
	v_fma_f32 v6, v5, v6, -v8
	v_fmac_f32_e32 v4, v5, v7
	global_store_dword v[2:3], v6, off
	global_store_dword v[2:3], v4, off offset:64
	v_cvt_pk_bf16_f32 v2, v6, s0
	v_cvt_pk_bf16_f32 v3, v4, s0
	global_store_short v[0:1], v2, off
	global_store_short v[0:1], v3, off offset:32

; __device__ __forceinline__ unsigned cvt_pk_bf16(float lo, float hi) { const f32x2c v = {lo, hi}; const bf16x2c b = __builtin_convertvector(v, bf16x2c); return __builtin_bit_cast(unsigned, b); }
; __device__ __forceinline__ float sigmoidf_(float x) { return __builtin_amdgcn_rcpf(1.f + __builtin_amdgcn_exp2f(-1.4426950408889634f * x)); }
; template <int NTOK, bool SMP>
; __device__ __forceinline__ void mix_tile(KP p, int l, float* lds, int tid, int s, int t0) {
;     ...
;     {
;         const f32x4 g = *(const f32x4*)(p->in[I_CLG] + l * 256 + 4 * lane), bb = *(const f32x4*)(p->in[I_CLB] + l * 256 + 4 * lane);
; #pragma unroll
;         for (int k = 0; k < TPW; ++k) {
;             const int i = wid + 8 * k;
;             const f32x4 x = *(const f32x4*)(cvs + i * 256 + 4 * lane);
;             const float mu = wave_sum(x[0] + x[1] + x[2] + x[3], lane) * (1.f / 256.f);
;             const f32x4 d = x - mu;
;             const float var = wave_sum(d[0] * d[0] + d[1] * d[1] + d[2] * d[2] + d[3] * d[3], lane) * (1.f / 256.f);
;             const float r = rsqrtf(var + LN_EPS);
;             f32x4 y = d * r * g + bb;
; #pragma unroll
;             for (int j = 0; j < 4; ++j) y[j] = y[j] * sigmoidf_(y[j]);
;             u32x2 o; o[0] = cvt_pk_bf16(y[0], y[1]); o[1] = cvt_pk_bf16(y[2], y[3]);
;             *(u32x2*)(CVN + (size_t)(mrow0 + i) * 256 + 4 * lane) = o;
;         }
.LBB0_302:
	s_or_b64 exec, exec, s[30:31]
	v_add_u32_e32 v8, v218, v219
	s_waitcnt lgkmcnt(0)
	s_barrier
	ds_read_b128 v[12:15], v8 offset:63488
	s_load_dwordx4 s[28:31], s[62:63], 0x80
	v_lshlrev_b64 v[192:193], 9, v[52:53]
	s_waitcnt lgkmcnt(0)
	v_add_f32_e32 v8, v12, v13
	v_add_f32_e32 v8, v14, v8
	v_add_f32_e32 v8, v15, v8
	ds_bpermute_b32 v10, v101, v8
	s_add_u32 s0, s28, s50
	s_addc_u32 s1, s29, s51
	global_load_dwordx4 v[0:3], v182, s[0:1]
	s_add_u32 s0, s30, s50
	s_waitcnt lgkmcnt(0)
	v_add_f32_e32 v8, v8, v10
	ds_bpermute_b32 v10, v107, v8
	s_addc_u32 s1, s31, s51
	global_load_dwordx4 v[4:7], v182, s[0:1]
	s_mov_b32 s0, 0x3b800000
	s_mov_b32 s1, 0x3b2aaaab
	s_waitcnt lgkmcnt(0)
	v_add_f32_e32 v8, v8, v10
	s_nop 1
	v_mov_b32_dpp v10, v8 row_mirror row_mask:0xf bank_mask:0xf
	s_waitcnt lgkmcnt(0)
	v_add_f32_e32 v8, v8, v10
	s_nop 1
	v_mov_b32_dpp v10, v8 row_half_mirror row_mask:0xf bank_mask:0xf
	s_waitcnt lgkmcnt(0)
	v_add_f32_e32 v8, v8, v10
	s_nop 1
	v_mov_b32_dpp v10, v8 quad_perm:[2,3,0,1] row_mask:0xf bank_mask:0xf
	s_waitcnt lgkmcnt(0)
	v_add_f32_e32 v8, v8, v10
	s_nop 1
	v_mov_b32_dpp v10, v8 quad_perm:[1,0,3,2] row_mask:0xf bank_mask:0xf
	s_waitcnt lgkmcnt(0)
	v_add_f32_e32 v8, v8, v10
	v_fmamk_f32 v19, v8, 0xbb800000, v13
	v_fmamk_f32 v18, v8, 0xbb800000, v12
	v_fmamk_f32 v15, v8, 0xbb800000, v15
	v_fmac_f32_e32 v14, 0xbb800000, v8
	v_lshlrev_b64 v[10:11], 9, v[50:51]
	v_add_u32_e32 v8, v218, v220
	v_lshl_add_u64 v[16:17], v[152:153], 0, v[10:11]
	ds_read_b128 v[10:13], v8 offset:63488
	v_pk_mul_f32 v[22:23], v[18:19], v[18:19]
	v_pk_mul_f32 v[20:21], v[14:15], v[14:15]
	v_mov_b32_e32 v29, v22
	s_waitcnt lgkmcnt(0)
	v_add_f32_e32 v8, v10, v11
	v_add_f32_e32 v8, v12, v8
	v_add_f32_e32 v8, v13, v8
	ds_bpermute_b32 v24, v101, v8
	s_waitcnt lgkmcnt(0)
	v_add_f32_e32 v8, v8, v24
	ds_bpermute_b32 v24, v107, v8
	s_waitcnt lgkmcnt(0)
	v_add_f32_e32 v8, v8, v24
	s_nop 1
	v_mov_b32_dpp v24, v8 row_mirror row_mask:0xf bank_mask:0xf
	s_waitcnt lgkmcnt(0)
	v_add_f32_e32 v8, v8, v24
	s_nop 1
	v_mov_b32_dpp v24, v8 row_half_mirror row_mask:0xf bank_mask:0xf
	s_waitcnt lgkmcnt(0)
	v_add_f32_e32 v8, v8, v24
	s_nop 1
	v_mov_b32_dpp v24, v8 quad_perm:[2,3,0,1] row_mask:0xf bank_mask:0xf
	s_waitcnt lgkmcnt(0)
	v_add_f32_e32 v8, v8, v24
	s_nop 1
	v_mov_b32_dpp v24, v8 quad_perm:[1,0,3,2] row_mask:0xf bank_mask:0xf
	s_waitcnt lgkmcnt(0)
	v_add_f32_e32 v8, v8, v24
	v_fmamk_f32 v11, v8, 0xbb800000, v11
	v_fmamk_f32 v10, v8, 0xbb800000, v10
	v_fmamk_f32 v13, v8, 0xbb800000, v13
	v_fmac_f32_e32 v12, 0xbb800000, v8
	v_pk_mul_f32 v[26:27], v[10:11], v[10:11]
	v_pk_mul_f32 v[24:25], v[12:13], v[12:13]
	v_mov_b32_e32 v28, v26
	v_mov_b32_e32 v22, v27
	v_pk_add_f32 v[22:23], v[28:29], v[22:23]
	v_mov_b32_e32 v26, v24
	v_mov_b32_e32 v27, v20
	v_pk_add_f32 v[22:23], v[26:27], v[22:23]
	v_mov_b32_e32 v20, v25
	v_pk_add_f32 v[20:21], v[20:21], v[22:23]
	ds_bpermute_b32 v23, v101, v21
	ds_bpermute_b32 v22, v101, v20
	s_waitcnt lgkmcnt(0)
	v_pk_add_f32 v[20:21], v[20:21], v[22:23]
	ds_bpermute_b32 v23, v107, v21
	ds_bpermute_b32 v22, v107, v20
	s_waitcnt lgkmcnt(0)
	v_pk_add_f32 v[20:21], v[20:21], v[22:23]
	s_nop 1
	v_mov_b32_dpp v23, v21 row_mirror row_mask:0xf bank_mask:0xf
	s_nop 1
	v_mov_b32_dpp v22, v20 row_mirror row_mask:0xf bank_mask:0xf
	s_waitcnt lgkmcnt(0)
	v_pk_add_f32 v[20:21], v[20:21], v[22:23]
	s_nop 1
	v_mov_b32_dpp v23, v21 row_half_mirror row_mask:0xf bank_mask:0xf
	s_nop 1
	v_mov_b32_dpp v22, v20 row_half_mirror row_mask:0xf bank_mask:0xf
	s_waitcnt lgkmcnt(0)
	v_pk_add_f32 v[20:21], v[20:21], v[22:23]
	s_nop 1
	v_mov_b32_dpp v23, v21 quad_perm:[2,3,0,1] row_mask:0xf bank_mask:0xf
	s_nop 1
	v_mov_b32_dpp v22, v20 quad_perm:[2,3,0,1] row_mask:0xf bank_mask:0xf
	s_waitcnt lgkmcnt(0)
	v_pk_add_f32 v[20:21], v[20:21], v[22:23]
	s_nop 1
	v_mov_b32_dpp v23, v21 quad_perm:[1,0,3,2] row_mask:0xf bank_mask:0xf
	s_nop 1
	v_mov_b32_dpp v22, v20 quad_perm:[1,0,3,2] row_mask:0xf bank_mask:0xf
	s_waitcnt lgkmcnt(0)
	v_pk_add_f32 v[20:21], v[20:21], v[22:23]
	s_nop 0
	v_pk_fma_f32 v[20:21], v[20:21], s[0:1], v[206:207] op_sel_hi:[1,0,0]
	s_nop 0
	v_mul_f32_e32 v8, 0x4b800000, v21
	v_cmp_gt_f32_e64 s[42:43], s96, v21
	v_cmp_gt_f32_e32 vcc, s96, v20
	s_nop 0
	v_cndmask_b32_e64 v8, v21, v8, s[42:43]
	v_rsq_f32_e32 v8, v8
	s_nop 0
	v_mul_f32_e32 v21, 0x45800000, v8
	v_cndmask_b32_e64 v8, v8, v21, s[42:43]
	v_pk_mul_f32 v[18:19], v[18:19], v[8:9] op_sel_hi:[1,0]
	v_pk_mul_f32 v[14:15], v[14:15], v[8:9] op_sel_hi:[1,0]
	s_waitcnt vmcnt(0)
	v_pk_fma_f32 v[18:19], v[0:1], v[18:19], v[4:5]
	v_pk_fma_f32 v[14:15], v[2:3], v[14:15], v[6:7]
	v_mul_f32_e32 v8, 0xbfb8aa3b, v18
	v_exp_f32_e32 v8, v8
	s_nop 0
	v_add_f32_e32 v8, 1.0, v8
	v_rcp_f32_e32 v22, v8
	v_mul_f32_e32 v8, 0xbfb8aa3b, v19
	v_exp_f32_e32 v8, v8
	s_nop 0
	v_add_f32_e32 v8, 1.0, v8
	v_rcp_f32_e32 v23, v8
	v_mul_f32_e32 v8, 0xbfb8aa3b, v14
	v_exp_f32_e32 v8, v8
	v_pk_mul_f32 v[18:19], v[18:19], v[22:23]
	s_nop 0
	v_cvt_pk_bf16_f32 v18, v18, v19
	v_add_f32_e32 v8, 1.0, v8
	v_rcp_f32_e32 v22, v8
	v_mul_f32_e32 v8, 0xbfb8aa3b, v15
	v_exp_f32_e32 v8, v8
	s_nop 0
	v_add_f32_e32 v8, 1.0, v8
	v_rcp_f32_e32 v23, v8
	v_mul_f32_e32 v8, 0x4b800000, v20
	v_cndmask_b32_e32 v8, v20, v8, vcc
	v_rsq_f32_e32 v8, v8
	v_pk_mul_f32 v[14:15], v[14:15], v[22:23]
	s_nop 0
	v_cvt_pk_bf16_f32 v19, v14, v15
	v_mul_f32_e32 v14, 0x45800000, v8
	v_cndmask_b32_e32 v8, v8, v14, vcc
	v_pk_mul_f32 v[10:11], v[10:11], v[8:9] op_sel_hi:[1,0]
	v_pk_mul_f32 v[12:13], v[12:13], v[8:9] op_sel_hi:[1,0]
	v_pk_fma_f32 v[0:1], v[0:1], v[10:11], v[4:5]
	v_pk_fma_f32 v[2:3], v[2:3], v[12:13], v[6:7]
	v_mul_f32_e32 v4, 0xbfb8aa3b, v0
	v_mul_f32_e32 v5, 0xbfb8aa3b, v1
	v_exp_f32_e32 v4, v4
	v_exp_f32_e32 v5, v5
	global_store_dwordx2 v[16:17], v[18:19], off
	v_add_f32_e32 v4, 1.0, v4
	v_add_f32_e32 v5, 1.0, v5
	v_rcp_f32_e32 v4, v4
	v_rcp_f32_e32 v5, v5
	s_nop 0
	v_pk_mul_f32 v[0:1], v[0:1], v[4:5]
	v_mul_f32_e32 v4, 0xbfb8aa3b, v2
	v_mul_f32_e32 v5, 0xbfb8aa3b, v3
	v_exp_f32_e32 v4, v4
	v_exp_f32_e32 v5, v5
	v_cvt_pk_bf16_f32 v0, v0, v1
	v_add_f32_e32 v4, 1.0, v4
	v_add_f32_e32 v5, 1.0, v5
	v_rcp_f32_e32 v4, v4
	v_rcp_f32_e32 v5, v5
	s_nop 0
	v_pk_mul_f32 v[2:3], v[2:3], v[4:5]
	s_nop 0
	v_cvt_pk_bf16_f32 v1, v2, v3

; #define PG8_STAGE(bufoff, gbase, voff) do { _Pragma("unroll") for (int _i = 0; _i < 2; ++_i) \
;         __builtin_amdgcn_global_load_lds((const unsigned*)((const char*)(gbase) + (voff)[_i]), (PG8_LAS unsigned*)(lds + (bufoff) + ldsw + _i * 8192), 16, 0, 0); } while (0)
; #define PG8_LDA(dst, b, h) do { _Pragma("unroll") for (int m = 0; m < 4; ++m) _Pragma("unroll") for (int k = 0; k < 2; ++k) dst[m][k] = *(const PG8_LAS bf16x8*)(lds + PG8_SA(b, h) + aoff + m * 2048 + k * 1024); } while (0)
; #define PG8_LDB(dst, b, h) do { _Pragma("unroll") for (int n = 0; n < 2; ++n) _Pragma("unroll") for (int k = 0; k < 2; ++k) dst[n][k] = *(const PG8_LAS bf16x8*)(lds + PG8_SB(b, h) + boff + n * 2048 + k * 1024); } while (0)
; #define PG8_MMA(ai, bj, At, Bt) do { __builtin_amdgcn_s_setprio(1); _Pragma("unroll") for (int m = 0; m < 4; ++m) _Pragma("unroll") for (int n = 0; n < 2; ++n) _Pragma("unroll") for (int k = 0; k < 2; ++k) \
;         acc[ai][bj][m][n] = __builtin_amdgcn_mfma_f32_16x16x32_bf16(Bt[n][k], At[m][k], acc[ai][bj][m][n], 0, 0, 0); __builtin_amdgcn_s_setprio(0); } while (0)
; #define PG8_WAIT_V(n) asm volatile("s_waitcnt vmcnt(" #n ")" ::: "memory")
; #define PG8_WAIT_L(n) asm volatile("s_waitcnt lgkmcnt(" #n ")" ::: "memory")
; #define PG8_BAR __builtin_amdgcn_s_barrier()
; #define PG8_SCHED __builtin_amdgcn_sched_barrier(0)
; template <class Epi, class Sched, bool ALIGN_EPI = false, bool SP2 = false>
; __device__ __forceinline__ void gemm_phase(PG8_LAS unsigned char* lds, int tid_in, const Gemm g, const Sched& S, const Epi& E) {
;     ...
;             PG8_LDB(B0, 0, 0); PG8_LDB(B1, 0, 1); PG8_SCHED; PG8_LDA(At, 0, 0); PG8_STAGE(PG8_SA(1, 1), a1 + hstep, voffA);
;             PG8_WAIT_V(8); PG8_WAIT_L(0); PG8_BAR; PG8_MMA(0, 0, At, B0); PG8_MMA(0, 1, At, B1); PG8_BAR; PG8_SCHED;
;             PG8_LDA(At, 0, 1); PG8_STAGE(PG8_SB(0, 0), b2, voffB); PG8_STAGE(PG8_SB(0, 1), b2 + hstep, voffB); PG8_STAGE(PG8_SA(0, 0), a2, voffA);
;             PG8_WAIT_V(8); PG8_WAIT_L(0); PG8_BAR; PG8_MMA(1, 0, At, B0); PG8_MMA(1, 1, At, B1); PG8_BAR; PG8_SCHED;
.LBB0_395:
	s_add_i32 s37, 0, 0x10000
	s_add_i32 s18, 0, 0x14000
	v_add_u32_e32 v8, s37, v174
	v_add_u32_e32 v10, s18, v174
	ds_read_b128 v[12:15], v8
	ds_read_b128 v[16:19], v8 offset:1024
	ds_read_b128 v[20:23], v8 offset:2048
	ds_read_b128 v[24:27], v8 offset:3072
	ds_read_b128 v[28:31], v10
	ds_read_b128 v[32:35], v10 offset:1024
	ds_read_b128 v[36:39], v10 offset:2048
	ds_read_b128 v[40:43], v10 offset:3072
	s_add_u32 s6, s34, 0x18080
	s_addc_u32 s7, s35, 0
	s_add_i32 s50, s43, 0xc000
	v_lshl_add_u64 v[68:69], s[6:7], 0, v[164:165]
	s_mov_b32 m0, s50
	ds_read_b128 v[0:3], v175
	ds_read_b128 v[4:7], v175 offset:1024
	ds_read_b128 v[44:47], v175 offset:2048
	ds_read_b128 v[48:51], v175 offset:3072
	ds_read_b128 v[52:55], v175 offset:4096
	ds_read_b128 v[56:59], v175 offset:5120
	ds_read_b128 v[60:63], v175 offset:6144
	ds_read_b128 v[64:67], v175 offset:7168
	global_load_lds_dwordx4 v[68:69], off
	v_lshl_add_u64 v[68:69], s[6:7], 0, v[162:163]
	s_add_i32 s6, s43, 0xe000
	s_mov_b32 m0, s6
	s_nop 0
	global_load_lds_dwordx4 v[68:69], off
	s_waitcnt vmcnt(8)
	s_waitcnt lgkmcnt(0)
	s_barrier
	s_setprio 1
	s_waitcnt lgkmcnt(0)
	v_mfma_f32_16x16x32_bf16 v[68:71], v[12:15], v[0:3], 0
	v_mfma_f32_16x16x32_bf16 v[72:75], v[20:23], v[0:3], 0
	v_mfma_f32_16x16x32_bf16 v[76:79], v[12:15], v[44:47], 0
	v_mfma_f32_16x16x32_bf16 v[80:83], v[20:23], v[44:47], 0
	v_mfma_f32_16x16x32_bf16 v[84:87], v[12:15], v[52:55], 0
	v_mfma_f32_16x16x32_bf16 v[88:91], v[20:23], v[52:55], 0
	v_mfma_f32_16x16x32_bf16 v[92:95], v[12:15], v[60:63], 0
	v_mfma_f32_16x16x32_bf16 v[96:99], v[20:23], v[60:63], 0
	v_mfma_f32_16x16x32_bf16 v[68:71], v[16:19], v[4:7], v[68:71]
	v_mfma_f32_16x16x32_bf16 v[72:75], v[24:27], v[4:7], v[72:75]
	v_mfma_f32_16x16x32_bf16 v[76:79], v[16:19], v[48:51], v[76:79]
	v_mfma_f32_16x16x32_bf16 v[80:83], v[24:27], v[48:51], v[80:83]
	v_mfma_f32_16x16x32_bf16 v[84:87], v[16:19], v[56:59], v[84:87]
	v_mfma_f32_16x16x32_bf16 v[88:91], v[24:27], v[56:59], v[88:91]
	v_mfma_f32_16x16x32_bf16 v[92:95], v[16:19], v[64:67], v[92:95]
	v_mfma_f32_16x16x32_bf16 v[96:99], v[24:27], v[64:67], v[96:99]
	v_mfma_f32_16x16x32_bf16 v[100:103], v[28:31], v[0:3], 0
	v_mfma_f32_16x16x32_bf16 v[0:3], v[36:39], v[0:3], 0
	v_mfma_f32_16x16x32_bf16 v[104:107], v[40:43], v[4:7], v[0:3]
	v_mfma_f32_16x16x32_bf16 v[0:3], v[28:31], v[44:47], 0
	v_mfma_f32_16x16x32_bf16 v[108:111], v[32:35], v[48:51], v[0:3]
	v_mfma_f32_16x16x32_bf16 v[0:3], v[36:39], v[44:47], 0
	v_mfma_f32_16x16x32_bf16 v[44:47], v[40:43], v[48:51], v[0:3]
	v_mfma_f32_16x16x32_bf16 v[0:3], v[28:31], v[52:55], 0
	v_mfma_f32_16x16x32_bf16 v[48:51], v[32:35], v[56:59], v[0:3]
	v_mfma_f32_16x16x32_bf16 v[0:3], v[36:39], v[52:55], 0
	v_mfma_f32_16x16x32_bf16 v[52:55], v[40:43], v[56:59], v[0:3]
	v_mfma_f32_16x16x32_bf16 v[0:3], v[28:31], v[60:63], 0
	v_mfma_f32_16x16x32_bf16 v[56:59], v[32:35], v[64:67], v[0:3]
	v_mfma_f32_16x16x32_bf16 v[0:3], v[36:39], v[60:63], 0
	v_mfma_f32_16x16x32_bf16 v[100:103], v[32:35], v[4:7], v[100:103]
	v_mfma_f32_16x16x32_bf16 v[60:63], v[40:43], v[64:67], v[0:3]
	s_setprio 0
	s_barrier
	s_nop 3
	v_lshl_add_u64 v[0:1], s[8:9], 0, v[164:165]
	s_mov_b64 s[56:57], 0x100
	s_add_i32 s37, s37, s42
	v_lshl_add_u64 v[2:3], v[0:1], 0, s[56:57]
	s_mov_b32 m0, s37
	s_add_i32 s7, s37, 0x2000
	ds_read_b128 v[64:67], v175 offset:16384
	ds_read_b128 v[112:115], v175 offset:17408
	ds_read_b128 v[116:119], v175 offset:18432
	ds_read_b128 v[120:123], v175 offset:19456
	ds_read_b128 v[124:127], v175 offset:20480
	ds_read_b128 v[128:131], v175 offset:21504
	ds_read_b128 v[132:135], v175 offset:22528
	ds_read_b128 v[136:139], v175 offset:23552
	global_load_lds_dwordx4 v[2:3], off
	v_lshl_add_u64 v[2:3], s[8:9], 0, v[162:163]
	s_add_u32 s38, s8, 0x18100
	v_lshl_add_u64 v[4:5], v[2:3], 0, s[56:57]
	s_mov_b32 m0, s7
	s_addc_u32 s39, s9, 0
	s_add_i32 s18, s18, s42
	global_load_lds_dwordx4 v[4:5], off
	v_lshl_add_u64 v[4:5], s[38:39], 0, v[164:165]
	s_mov_b32 m0, s18
	s_add_i32 s36, s18, 0x2000
	global_load_lds_dwordx4 v[4:5], off
	v_lshl_add_u64 v[4:5], s[38:39], 0, v[162:163]
	s_mov_b32 m0, s36
	s_nop 0
	global_load_lds_dwordx4 v[4:5], off
	v_lshl_add_u64 v[4:5], s[34:35], 0, v[164:165]
	v_lshl_add_u64 v[6:7], v[4:5], 0, s[56:57]
	s_mov_b32 m0, s43
	s_nop 0
	global_load_lds_dwordx4 v[6:7], off
	v_lshl_add_u64 v[6:7], s[34:35], 0, v[162:163]
	v_lshl_add_u64 v[140:141], v[6:7], 0, s[56:57]
	s_mov_b32 m0, s44
	s_nop 0
	global_load_lds_dwordx4 v[140:141], off
	s_waitcnt vmcnt(8)
	s_waitcnt lgkmcnt(0)
	s_barrier
	s_setprio 1
	s_waitcnt lgkmcnt(0)
	v_mfma_f32_16x16x32_bf16 v[140:143], v[12:15], v[64:67], 0
	v_mfma_f32_16x16x32_bf16 v[148:151], v[12:15], v[116:119], 0
	v_mfma_f32_16x16x32_bf16 v[156:159], v[12:15], v[124:127], 0
	v_mfma_f32_16x16x32_bf16 v[12:15], v[12:15], v[132:135], 0
	v_mfma_f32_16x16x32_bf16 v[140:143], v[16:19], v[112:115], v[140:143]
	v_mfma_f32_16x16x32_bf16 v[144:147], v[20:23], v[64:67], 0
	v_mfma_f32_16x16x32_bf16 v[148:151], v[16:19], v[120:123], v[148:151]
	v_mfma_f32_16x16x32_bf16 v[152:155], v[20:23], v[116:119], 0
	v_mfma_f32_16x16x32_bf16 v[156:159], v[16:19], v[128:131], v[156:159]
	v_mfma_f32_16x16x32_bf16 v[166:169], v[20:23], v[124:127], 0
	v_mfma_f32_16x16x32_bf16 v[14:17], v[16:19], v[136:139], v[12:15]
	v_mfma_f32_16x16x32_bf16 v[18:21], v[20:23], v[132:135], 0
	v_mfma_f32_16x16x32_bf16 v[152:155], v[24:27], v[120:123], v[152:155]
	v_mfma_f32_16x16x32_bf16 v[18:21], v[24:27], v[136:139], v[18:21]
	v_mfma_f32_16x16x32_bf16 v[144:147], v[24:27], v[112:115], v[144:147]
	v_mfma_f32_16x16x32_bf16 v[166:169], v[24:27], v[128:131], v[166:169]
	v_mfma_f32_16x16x32_bf16 v[22:25], v[28:31], v[64:67], 0
	v_mfma_f32_16x16x32_bf16 v[64:67], v[36:39], v[64:67], 0
	v_mfma_f32_16x16x32_bf16 v[22:25], v[32:35], v[112:115], v[22:25]
	v_mfma_f32_16x16x32_bf16 v[64:67], v[40:43], v[112:115], v[64:67]
	v_mfma_f32_16x16x32_bf16 v[112:115], v[28:31], v[116:119], 0
	v_mfma_f32_16x16x32_bf16 v[116:119], v[36:39], v[116:119], 0
	v_mfma_f32_16x16x32_bf16 v[112:115], v[32:35], v[120:123], v[112:115]
	v_mfma_f32_16x16x32_bf16 v[116:119], v[40:43], v[120:123], v[116:119]
	v_mfma_f32_16x16x32_bf16 v[120:123], v[28:31], v[124:127], 0
	v_mfma_f32_16x16x32_bf16 v[26:29], v[28:31], v[132:135], 0
	v_mfma_f32_16x16x32_bf16 v[120:123], v[32:35], v[128:131], v[120:123]
	v_mfma_f32_16x16x32_bf16 v[124:127], v[36:39], v[124:127], 0
	v_mfma_f32_16x16x32_bf16 v[26:29], v[32:35], v[136:139], v[26:29]
	v_mfma_f32_16x16x32_bf16 v[30:33], v[36:39], v[132:135], 0
	v_mfma_f32_16x16x32_bf16 v[124:127], v[40:43], v[128:131], v[124:127]
	v_mfma_f32_16x16x32_bf16 v[30:33], v[40:43], v[136:139], v[30:33]
	s_setprio 0
	s_barrier
; #define PG8_STAGE(bufoff, gbase, voff) do { _Pragma("unroll") for (int _i = 0; _i < 2; ++_i) \
;         __builtin_amdgcn_global_load_lds((const unsigned*)((const char*)(gbase) + (voff)[_i]), (PG8_LAS unsigned*)(lds + (bufoff) + ldsw + _i * 8192), 16, 0, 0); } while (0)
; #define PG8_LDA(dst, b, h) do { _Pragma("unroll") for (int m = 0; m < 4; ++m) _Pragma("unroll") for (int k = 0; k < 2; ++k) dst[m][k] = *(const PG8_LAS bf16x8*)(lds + PG8_SA(b, h) + aoff + m * 2048 + k * 1024); } while (0)
; #define PG8_LDB(dst, b, h) do { _Pragma("unroll") for (int n = 0; n < 2; ++n) _Pragma("unroll") for (int k = 0; k < 2; ++k) dst[n][k] = *(const PG8_LAS bf16x8*)(lds + PG8_SB(b, h) + boff + n * 2048 + k * 1024); } while (0)
; #define PG8_MMA(ai, bj, At, Bt) do { __builtin_amdgcn_s_setprio(1); _Pragma("unroll") for (int m = 0; m < 4; ++m) _Pragma("unroll") for (int n = 0; n < 2; ++n) _Pragma("unroll") for (int k = 0; k < 2; ++k) \
;         acc[ai][bj][m][n] = __builtin_amdgcn_mfma_f32_16x16x32_bf16(Bt[n][k], At[m][k], acc[ai][bj][m][n], 0, 0, 0); __builtin_amdgcn_s_setprio(0); } while (0)
; #define PG8_WAIT_V(n) asm volatile("s_waitcnt vmcnt(" #n ")" ::: "memory")
; #define PG8_WAIT_L(n) asm volatile("s_waitcnt lgkmcnt(" #n ")" ::: "memory")
; #define PG8_BAR __builtin_amdgcn_s_barrier()
; #define PG8_SCHED __builtin_amdgcn_sched_barrier(0)
; template <class Epi, class Sched, bool ALIGN_EPI = false, bool SP2 = false>
; __device__ __forceinline__ void gemm_phase(PG8_LAS unsigned char* lds, int tid_in, const Gemm g, const Sched& S, const Epi& E) {
;     ...
;             PG8_LDB(B0, 1, 0); PG8_LDB(B1, 1, 1); PG8_SCHED; PG8_LDA(At, 1, 0); PG8_STAGE(PG8_SA(0, 1), a2 + hstep, voffA);
;             PG8_WAIT_V(8); PG8_WAIT_L(0); PG8_BAR; PG8_MMA(0, 0, At, B0); PG8_MMA(0, 1, At, B1); PG8_BAR; PG8_SCHED;
	s_add_i32 s53, 0, 0x18000
	s_add_i32 s51, 0, 0x1c000
	v_add_u32_e32 v11, s53, v174
	v_add_u32_e32 v12, s51, v174
	ds_read_b128 v[34:37], v11
	ds_read_b128 v[38:41], v11 offset:1024
	ds_read_b128 v[128:131], v11 offset:2048
	ds_read_b128 v[132:135], v11 offset:3072
	ds_read_b128 v[136:139], v12
	ds_read_b128 v[170:173], v12 offset:1024
	ds_read_b128 v[176:179], v12 offset:2048
	ds_read_b128 v[180:183], v12 offset:3072
	s_add_u32 s38, s34, 0x18100
	s_addc_u32 s39, s35, 0
	s_mov_b32 m0, s45
	v_lshl_add_u64 v[42:43], s[38:39], 0, v[164:165]
	ds_read_b128 v[184:187], v175 offset:32768
	ds_read_b128 v[188:191], v175 offset:33792
	ds_read_b128 v[192:195], v175 offset:34816
	ds_read_b128 v[196:199], v175 offset:35840
	ds_read_b128 v[200:203], v175 offset:36864
	ds_read_b128 v[218:221], v175 offset:37888
	ds_read_b128 v[222:225], v175 offset:38912
	ds_read_b128 v[226:229], v175 offset:39936
	global_load_lds_dwordx4 v[42:43], off
	v_lshl_add_u64 v[42:43], s[38:39], 0, v[162:163]
	s_mov_b32 m0, s46
	s_nop 0
	global_load_lds_dwordx4 v[42:43], off
	s_waitcnt vmcnt(8)
	s_waitcnt lgkmcnt(0)
	s_barrier
	s_setprio 1
	s_waitcnt lgkmcnt(0)
	v_mfma_f32_16x16x32_bf16 v[68:71], v[34:37], v[184:187], v[68:71]
	v_mfma_f32_16x16x32_bf16 v[72:75], v[128:131], v[184:187], v[72:75]
	v_mfma_f32_16x16x32_bf16 v[76:79], v[34:37], v[192:195], v[76:79]
	v_mfma_f32_16x16x32_bf16 v[80:83], v[128:131], v[192:195], v[80:83]
	v_mfma_f32_16x16x32_bf16 v[84:87], v[34:37], v[200:203], v[84:87]
	v_mfma_f32_16x16x32_bf16 v[88:91], v[128:131], v[200:203], v[88:91]
	v_mfma_f32_16x16x32_bf16 v[92:95], v[34:37], v[222:225], v[92:95]
	v_mfma_f32_16x16x32_bf16 v[96:99], v[128:131], v[222:225], v[96:99]
	v_mfma_f32_16x16x32_bf16 v[68:71], v[38:41], v[188:191], v[68:71]
	v_mfma_f32_16x16x32_bf16 v[72:75], v[132:135], v[188:191], v[72:75]
	v_mfma_f32_16x16x32_bf16 v[76:79], v[38:41], v[196:199], v[76:79]
	v_mfma_f32_16x16x32_bf16 v[80:83], v[132:135], v[196:199], v[80:83]
	v_mfma_f32_16x16x32_bf16 v[84:87], v[38:41], v[218:221], v[84:87]
	v_mfma_f32_16x16x32_bf16 v[88:91], v[132:135], v[218:221], v[88:91]
	v_mfma_f32_16x16x32_bf16 v[92:95], v[38:41], v[226:229], v[92:95]
	v_mfma_f32_16x16x32_bf16 v[96:99], v[132:135], v[226:229], v[96:99]
	v_mfma_f32_16x16x32_bf16 v[100:103], v[136:139], v[184:187], v[100:103]
	v_mfma_f32_16x16x32_bf16 v[104:107], v[176:179], v[184:187], v[104:107]
	v_mfma_f32_16x16x32_bf16 v[108:111], v[136:139], v[192:195], v[108:111]
	v_mfma_f32_16x16x32_bf16 v[42:45], v[176:179], v[192:195], v[44:47]
	v_mfma_f32_16x16x32_bf16 v[46:49], v[136:139], v[200:203], v[48:51]
	v_mfma_f32_16x16x32_bf16 v[50:53], v[176:179], v[200:203], v[52:55]
	v_mfma_f32_16x16x32_bf16 v[54:57], v[136:139], v[222:225], v[56:59]
	v_mfma_f32_16x16x32_bf16 v[58:61], v[176:179], v[222:225], v[60:63]
	v_mfma_f32_16x16x32_bf16 v[100:103], v[170:173], v[188:191], v[100:103]
	v_mfma_f32_16x16x32_bf16 v[104:107], v[180:183], v[188:191], v[104:107]
	v_mfma_f32_16x16x32_bf16 v[108:111], v[170:173], v[196:199], v[108:111]
	v_mfma_f32_16x16x32_bf16 v[42:45], v[180:183], v[196:199], v[42:45]
	v_mfma_f32_16x16x32_bf16 v[46:49], v[170:173], v[218:221], v[46:49]
	v_mfma_f32_16x16x32_bf16 v[50:53], v[180:183], v[218:221], v[50:53]
	v_mfma_f32_16x16x32_bf16 v[54:57], v[170:173], v[226:229], v[54:57]
	v_mfma_f32_16x16x32_bf16 v[58:61], v[180:183], v[226:229], v[58:61]
	s_setprio 0
	s_barrier
	s_add_i32 s53, s53, s42
	s_mov_b64 s[58:59], 0x180
	s_add_i32 s38, s53, 0x2000
	v_lshl_add_u64 v[62:63], v[0:1], 0, s[58:59]
	s_mov_b32 m0, s53
	s_add_u32 s56, s8, 0x18180
	ds_read_b128 v[184:187], v175 offset:49152
	ds_read_b128 v[188:191], v175 offset:50176
	ds_read_b128 v[192:195], v175 offset:51200
	ds_read_b128 v[196:199], v175 offset:52224
	ds_read_b128 v[200:203], v175 offset:53248
	ds_read_b128 v[218:221], v175 offset:54272
	ds_read_b128 v[222:225], v175 offset:55296
	ds_read_b128 v[226:229], v175 offset:56320
	global_load_lds_dwordx4 v[62:63], off
	v_lshl_add_u64 v[62:63], v[2:3], 0, s[58:59]
	s_mov_b32 m0, s38
	s_addc_u32 s57, s9, 0
	s_add_i32 s39, s51, s42
	global_load_lds_dwordx4 v[62:63], off
	v_lshl_add_u64 v[62:63], s[56:57], 0, v[164:165]
	s_mov_b32 m0, s39
	s_add_i32 s51, s39, 0x2000
	global_load_lds_dwordx4 v[62:63], off
	v_lshl_add_u64 v[62:63], s[56:57], 0, v[162:163]
	s_mov_b32 m0, s51
	s_nop 0
	global_load_lds_dwordx4 v[62:63], off
	v_lshl_add_u64 v[62:63], v[4:5], 0, s[58:59]
	s_mov_b32 m0, s20
	s_nop 0
	global_load_lds_dwordx4 v[62:63], off
	v_lshl_add_u64 v[62:63], v[6:7], 0, s[58:59]
	s_mov_b32 m0, s21
	s_nop 0
	global_load_lds_dwordx4 v[62:63], off
	s_waitcnt vmcnt(8)
	s_waitcnt lgkmcnt(0)
	s_barrier
; #define PG8_STAGE(bufoff, gbase, voff) do { _Pragma("unroll") for (int _i = 0; _i < 2; ++_i) \
;         __builtin_amdgcn_global_load_lds((const unsigned*)((const char*)(gbase) + (voff)[_i]), (PG8_LAS unsigned*)(lds + (bufoff) + ldsw + _i * 8192), 16, 0, 0); } while (0)
; #define PG8_LDA(dst, b, h) do { _Pragma("unroll") for (int m = 0; m < 4; ++m) _Pragma("unroll") for (int k = 0; k < 2; ++k) dst[m][k] = *(const PG8_LAS bf16x8*)(lds + PG8_SA(b, h) + aoff + m * 2048 + k * 1024); } while (0)
; #define PG8_MMA(ai, bj, At, Bt) do { __builtin_amdgcn_s_setprio(1); _Pragma("unroll") for (int m = 0; m < 4; ++m) _Pragma("unroll") for (int n = 0; n < 2; ++n) _Pragma("unroll") for (int k = 0; k < 2; ++k) \
;         acc[ai][bj][m][n] = __builtin_amdgcn_mfma_f32_16x16x32_bf16(Bt[n][k], At[m][k], acc[ai][bj][m][n], 0, 0, 0); __builtin_amdgcn_s_setprio(0); } while (0)
; #define PG8_WAIT_V(n) asm volatile("s_waitcnt vmcnt(" #n ")" ::: "memory")
; #define PG8_WAIT_L(n) asm volatile("s_waitcnt lgkmcnt(" #n ")" ::: "memory")
; #define PG8_BAR __builtin_amdgcn_s_barrier()
; #define PG8_SCHED __builtin_amdgcn_sched_barrier(0)
; template <class Epi, class Sched, bool ALIGN_EPI = false, bool SP2 = false>
; __device__ __forceinline__ void gemm_phase(PG8_LAS unsigned char* lds, int tid_in, const Gemm g, const Sched& S, const Epi& E) {
;     ...
;             PG8_WAIT_V(8); PG8_WAIT_L(0); PG8_BAR; PG8_MMA(0, 0, At, B0); PG8_MMA(0, 1, At, B1); PG8_BAR; PG8_SCHED;
;             PG8_LDA(At, 1, 1); PG8_STAGE(PG8_SB(1, 0), b3, voffB); PG8_STAGE(PG8_SB(1, 1), b3 + hstep, voffB); PG8_STAGE(PG8_SA(1, 0), a3, voffA);
;             PG8_WAIT_V(8); PG8_WAIT_L(0); PG8_BAR; PG8_MMA(1, 0, At, B0); PG8_MMA(1, 1, At, B1); PG8_BAR; PG8_SCHED;
	s_setprio 1
	s_waitcnt lgkmcnt(0)
	v_mfma_f32_16x16x32_bf16 v[152:155], v[128:131], v[192:195], v[152:155]
	v_mfma_f32_16x16x32_bf16 v[156:159], v[34:37], v[200:203], v[156:159]
	v_mfma_f32_16x16x32_bf16 v[14:17], v[34:37], v[222:225], v[14:17]
	v_mfma_f32_16x16x32_bf16 v[18:21], v[128:131], v[222:225], v[18:21]
	v_mfma_f32_16x16x32_bf16 v[140:143], v[34:37], v[184:187], v[140:143]
	v_mfma_f32_16x16x32_bf16 v[144:147], v[128:131], v[184:187], v[144:147]
	v_mfma_f32_16x16x32_bf16 v[148:151], v[34:37], v[192:195], v[148:151]
	v_mfma_f32_16x16x32_bf16 v[152:155], v[132:135], v[196:199], v[152:155]
	v_mfma_f32_16x16x32_bf16 v[156:159], v[38:41], v[218:221], v[156:159]
	v_mfma_f32_16x16x32_bf16 v[166:169], v[128:131], v[200:203], v[166:169]
	v_mfma_f32_16x16x32_bf16 v[14:17], v[38:41], v[226:229], v[14:17]
	v_mfma_f32_16x16x32_bf16 v[18:21], v[132:135], v[226:229], v[18:21]
	v_mfma_f32_16x16x32_bf16 v[140:143], v[38:41], v[188:191], v[140:143]
	v_mfma_f32_16x16x32_bf16 v[144:147], v[132:135], v[188:191], v[144:147]
	v_mfma_f32_16x16x32_bf16 v[148:151], v[38:41], v[196:199], v[148:151]
	v_mfma_f32_16x16x32_bf16 v[166:169], v[132:135], v[218:221], v[166:169]
	v_mfma_f32_16x16x32_bf16 v[22:25], v[136:139], v[184:187], v[22:25]
	v_mfma_f32_16x16x32_bf16 v[34:37], v[176:179], v[184:187], v[64:67]
	v_mfma_f32_16x16x32_bf16 v[38:41], v[136:139], v[192:195], v[112:115]
	v_mfma_f32_16x16x32_bf16 v[62:65], v[176:179], v[192:195], v[116:119]
	v_mfma_f32_16x16x32_bf16 v[112:115], v[136:139], v[200:203], v[120:123]
	v_mfma_f32_16x16x32_bf16 v[26:29], v[136:139], v[222:225], v[26:29]
	v_mfma_f32_16x16x32_bf16 v[30:33], v[176:179], v[222:225], v[30:33]
	v_mfma_f32_16x16x32_bf16 v[22:25], v[170:173], v[188:191], v[22:25]
	v_mfma_f32_16x16x32_bf16 v[34:37], v[180:183], v[188:191], v[34:37]
	v_mfma_f32_16x16x32_bf16 v[38:41], v[170:173], v[196:199], v[38:41]
	v_mfma_f32_16x16x32_bf16 v[62:65], v[180:183], v[196:199], v[62:65]
	v_mfma_f32_16x16x32_bf16 v[112:115], v[170:173], v[218:221], v[112:115]
	v_mfma_f32_16x16x32_bf16 v[116:119], v[176:179], v[200:203], v[124:127]
	v_mfma_f32_16x16x32_bf16 v[26:29], v[170:173], v[226:229], v[26:29]
	v_mfma_f32_16x16x32_bf16 v[30:33], v[180:183], v[226:229], v[30:33]
	v_mfma_f32_16x16x32_bf16 v[116:119], v[180:183], v[218:221], v[116:119]
	s_setprio 0
	s_barrier
	ds_read_b128 v[120:123], v8
	ds_read_b128 v[124:127], v8 offset:1024
	ds_read_b128 v[128:131], v8 offset:2048
	ds_read_b128 v[132:135], v8 offset:3072
	ds_read_b128 v[136:139], v10
	ds_read_b128 v[170:173], v10 offset:1024
	ds_read_b128 v[176:179], v10 offset:2048
	ds_read_b128 v[180:183], v10 offset:3072
	s_add_u32 s56, s34, 0x18180
	s_addc_u32 s57, s35, 0
	s_mov_b32 m0, s50
	v_lshl_add_u64 v[66:67], s[56:57], 0, v[164:165]
	ds_read_b128 v[184:187], v175
	ds_read_b128 v[188:191], v175 offset:1024
	ds_read_b128 v[192:195], v175 offset:2048
	ds_read_b128 v[196:199], v175 offset:3072
	ds_read_b128 v[200:203], v175 offset:4096
	ds_read_b128 v[218:221], v175 offset:5120
	ds_read_b128 v[222:225], v175 offset:6144
	ds_read_b128 v[226:229], v175 offset:7168
	global_load_lds_dwordx4 v[66:67], off
	v_lshl_add_u64 v[66:67], s[56:57], 0, v[162:163]
	s_mov_b32 m0, s6
	s_nop 0
	global_load_lds_dwordx4 v[66:67], off
	s_waitcnt vmcnt(8)
	s_waitcnt lgkmcnt(0)
	s_barrier
	s_setprio 1
	s_waitcnt lgkmcnt(0)
	v_mfma_f32_16x16x32_bf16 v[66:69], v[120:123], v[184:187], v[68:71]
	v_mfma_f32_16x16x32_bf16 v[70:73], v[128:131], v[184:187], v[72:75]
	v_mfma_f32_16x16x32_bf16 v[74:77], v[120:123], v[192:195], v[76:79]
	v_mfma_f32_16x16x32_bf16 v[78:81], v[128:131], v[192:195], v[80:83]
	v_mfma_f32_16x16x32_bf16 v[82:85], v[120:123], v[200:203], v[84:87]
	v_mfma_f32_16x16x32_bf16 v[86:89], v[128:131], v[200:203], v[88:91]
	v_mfma_f32_16x16x32_bf16 v[90:93], v[120:123], v[222:225], v[92:95]
	v_mfma_f32_16x16x32_bf16 v[94:97], v[128:131], v[222:225], v[96:99]
	v_mfma_f32_16x16x32_bf16 v[66:69], v[124:127], v[188:191], v[66:69]
	v_mfma_f32_16x16x32_bf16 v[70:73], v[132:135], v[188:191], v[70:73]
	v_mfma_f32_16x16x32_bf16 v[74:77], v[124:127], v[196:199], v[74:77]
	v_mfma_f32_16x16x32_bf16 v[78:81], v[132:135], v[196:199], v[78:81]
	v_mfma_f32_16x16x32_bf16 v[82:85], v[124:127], v[218:221], v[82:85]
	v_mfma_f32_16x16x32_bf16 v[86:89], v[132:135], v[218:221], v[86:89]
	v_mfma_f32_16x16x32_bf16 v[90:93], v[124:127], v[226:229], v[90:93]
	v_mfma_f32_16x16x32_bf16 v[94:97], v[132:135], v[226:229], v[94:97]
	v_mfma_f32_16x16x32_bf16 v[98:101], v[136:139], v[184:187], v[100:103]
	v_mfma_f32_16x16x32_bf16 v[102:105], v[176:179], v[184:187], v[104:107]
	v_mfma_f32_16x16x32_bf16 v[106:109], v[136:139], v[192:195], v[108:111]
	v_mfma_f32_16x16x32_bf16 v[42:45], v[176:179], v[192:195], v[42:45]
	v_mfma_f32_16x16x32_bf16 v[46:49], v[136:139], v[200:203], v[46:49]
	v_mfma_f32_16x16x32_bf16 v[50:53], v[176:179], v[200:203], v[50:53]
	v_mfma_f32_16x16x32_bf16 v[54:57], v[136:139], v[222:225], v[54:57]
	v_mfma_f32_16x16x32_bf16 v[58:61], v[176:179], v[222:225], v[58:61]
	v_mfma_f32_16x16x32_bf16 v[98:101], v[170:173], v[188:191], v[98:101]
	v_mfma_f32_16x16x32_bf16 v[102:105], v[180:183], v[188:191], v[102:105]
	v_mfma_f32_16x16x32_bf16 v[106:109], v[170:173], v[196:199], v[106:109]
	v_mfma_f32_16x16x32_bf16 v[42:45], v[180:183], v[196:199], v[42:45]
	v_mfma_f32_16x16x32_bf16 v[46:49], v[170:173], v[218:221], v[46:49]
	v_mfma_f32_16x16x32_bf16 v[50:53], v[180:183], v[218:221], v[50:53]
	v_mfma_f32_16x16x32_bf16 v[54:57], v[170:173], v[226:229], v[54:57]
	v_mfma_f32_16x16x32_bf16 v[58:61], v[180:183], v[226:229], v[58:61]
	s_setprio 0
	s_barrier
; #define PG8_STAGE(bufoff, gbase, voff) do { _Pragma("unroll") for (int _i = 0; _i < 2; ++_i) \
;         __builtin_amdgcn_global_load_lds((const unsigned*)((const char*)(gbase) + (voff)[_i]), (PG8_LAS unsigned*)(lds + (bufoff) + ldsw + _i * 8192), 16, 0, 0); } while (0)
; #define PG8_LDA(dst, b, h) do { _Pragma("unroll") for (int m = 0; m < 4; ++m) _Pragma("unroll") for (int k = 0; k < 2; ++k) dst[m][k] = *(const PG8_LAS bf16x8*)(lds + PG8_SA(b, h) + aoff + m * 2048 + k * 1024); } while (0)
; #define PG8_LDB(dst, b, h) do { _Pragma("unroll") for (int n = 0; n < 2; ++n) _Pragma("unroll") for (int k = 0; k < 2; ++k) dst[n][k] = *(const PG8_LAS bf16x8*)(lds + PG8_SB(b, h) + boff + n * 2048 + k * 1024); } while (0)
; #define PG8_MMA(ai, bj, At, Bt) do { __builtin_amdgcn_s_setprio(1); _Pragma("unroll") for (int m = 0; m < 4; ++m) _Pragma("unroll") for (int n = 0; n < 2; ++n) _Pragma("unroll") for (int k = 0; k < 2; ++k) \
;         acc[ai][bj][m][n] = __builtin_amdgcn_mfma_f32_16x16x32_bf16(Bt[n][k], At[m][k], acc[ai][bj][m][n], 0, 0, 0); __builtin_amdgcn_s_setprio(0); } while (0)
; #define PG8_WAIT_V(n) asm volatile("s_waitcnt vmcnt(" #n ")" ::: "memory")
; #define PG8_WAIT_L(n) asm volatile("s_waitcnt lgkmcnt(" #n ")" ::: "memory")
; #define PG8_BAR __builtin_amdgcn_s_barrier()
; #define PG8_SCHED __builtin_amdgcn_sched_barrier(0)
; template <class Epi, class Sched, bool ALIGN_EPI = false, bool SP2 = false>
; __device__ __forceinline__ void gemm_phase(PG8_LAS unsigned char* lds, int tid_in, const Gemm g, const Sched& S, const Epi& E) {
;     ...
;             PG8_LDA(At, 0, 1); PG8_STAGE(PG8_SB(0, 0), b2, voffB); PG8_STAGE(PG8_SB(0, 1), b2 + hstep, voffB); PG8_STAGE(PG8_SA(0, 0), a2, voffA);
;             PG8_WAIT_V(8); PG8_WAIT_L(0); PG8_BAR; PG8_MMA(1, 0, At, B0); PG8_MMA(1, 1, At, B1); PG8_BAR; PG8_SCHED;
;             PG8_LDB(B0, 1, 0); PG8_LDB(B1, 1, 1); PG8_SCHED; PG8_LDA(At, 1, 0); PG8_STAGE(PG8_SA(0, 1), a2 + hstep, voffA);
;             PG8_WAIT_V(8); PG8_WAIT_L(0); PG8_BAR; PG8_MMA(0, 0, At, B0); PG8_MMA(0, 1, At, B1); PG8_BAR; PG8_SCHED;
	s_mov_b64 s[58:59], 0x200
	s_mov_b32 m0, s37
	v_lshl_add_u64 v[110:111], v[0:1], 0, s[58:59]
	s_add_u32 s56, s8, 0x18200
	ds_read_b128 v[184:187], v175 offset:16384
	ds_read_b128 v[188:191], v175 offset:17408
	ds_read_b128 v[192:195], v175 offset:18432
	ds_read_b128 v[196:199], v175 offset:19456
	ds_read_b128 v[200:203], v175 offset:20480
	ds_read_b128 v[218:221], v175 offset:21504
	ds_read_b128 v[222:225], v175 offset:22528
	ds_read_b128 v[226:229], v175 offset:23552
	global_load_lds_dwordx4 v[110:111], off
	v_lshl_add_u64 v[110:111], v[2:3], 0, s[58:59]
	s_mov_b32 m0, s7
	s_addc_u32 s57, s9, 0
	global_load_lds_dwordx4 v[110:111], off
	v_lshl_add_u64 v[110:111], s[56:57], 0, v[164:165]
	s_mov_b32 m0, s18
	s_nop 0
	global_load_lds_dwordx4 v[110:111], off
	v_lshl_add_u64 v[110:111], s[56:57], 0, v[162:163]
	s_mov_b32 m0, s36
	s_nop 0
	global_load_lds_dwordx4 v[110:111], off
	v_lshl_add_u64 v[110:111], v[4:5], 0, s[58:59]
	s_mov_b32 m0, s43
	s_nop 0
	global_load_lds_dwordx4 v[110:111], off
	v_lshl_add_u64 v[110:111], v[6:7], 0, s[58:59]
	s_mov_b32 m0, s44
	s_nop 0
	global_load_lds_dwordx4 v[110:111], off
	s_waitcnt vmcnt(8)
	s_waitcnt lgkmcnt(0)
	s_barrier
	s_setprio 1
	s_waitcnt lgkmcnt(0)
	v_mfma_f32_16x16x32_bf16 v[152:155], v[128:131], v[192:195], v[152:155]
	v_mfma_f32_16x16x32_bf16 v[156:159], v[120:123], v[200:203], v[156:159]
	v_mfma_f32_16x16x32_bf16 v[14:17], v[120:123], v[222:225], v[14:17]
	v_mfma_f32_16x16x32_bf16 v[18:21], v[128:131], v[222:225], v[18:21]
	v_mfma_f32_16x16x32_bf16 v[140:143], v[120:123], v[184:187], v[140:143]
	v_mfma_f32_16x16x32_bf16 v[144:147], v[128:131], v[184:187], v[144:147]
	v_mfma_f32_16x16x32_bf16 v[148:151], v[120:123], v[192:195], v[148:151]
	v_mfma_f32_16x16x32_bf16 v[152:155], v[132:135], v[196:199], v[152:155]
	v_mfma_f32_16x16x32_bf16 v[156:159], v[124:127], v[218:221], v[156:159]
	v_mfma_f32_16x16x32_bf16 v[166:169], v[128:131], v[200:203], v[166:169]
	v_mfma_f32_16x16x32_bf16 v[14:17], v[124:127], v[226:229], v[14:17]
	v_mfma_f32_16x16x32_bf16 v[18:21], v[132:135], v[226:229], v[18:21]
	v_mfma_f32_16x16x32_bf16 v[140:143], v[124:127], v[188:191], v[140:143]
	v_mfma_f32_16x16x32_bf16 v[144:147], v[132:135], v[188:191], v[144:147]
	v_mfma_f32_16x16x32_bf16 v[148:151], v[124:127], v[196:199], v[148:151]
	v_mfma_f32_16x16x32_bf16 v[166:169], v[132:135], v[218:221], v[166:169]
	v_mfma_f32_16x16x32_bf16 v[22:25], v[136:139], v[184:187], v[22:25]
	v_mfma_f32_16x16x32_bf16 v[34:37], v[176:179], v[184:187], v[34:37]
	v_mfma_f32_16x16x32_bf16 v[38:41], v[136:139], v[192:195], v[38:41]
	v_mfma_f32_16x16x32_bf16 v[62:65], v[176:179], v[192:195], v[62:65]
	v_mfma_f32_16x16x32_bf16 v[110:113], v[136:139], v[200:203], v[112:115]
	v_mfma_f32_16x16x32_bf16 v[26:29], v[136:139], v[222:225], v[26:29]
	v_mfma_f32_16x16x32_bf16 v[30:33], v[176:179], v[222:225], v[30:33]
	v_mfma_f32_16x16x32_bf16 v[22:25], v[170:173], v[188:191], v[22:25]
	v_mfma_f32_16x16x32_bf16 v[34:37], v[180:183], v[188:191], v[34:37]
	v_mfma_f32_16x16x32_bf16 v[38:41], v[170:173], v[196:199], v[38:41]
	v_mfma_f32_16x16x32_bf16 v[62:65], v[180:183], v[196:199], v[62:65]
	v_mfma_f32_16x16x32_bf16 v[110:113], v[170:173], v[218:221], v[110:113]
	v_mfma_f32_16x16x32_bf16 v[114:117], v[176:179], v[200:203], v[116:119]
	v_mfma_f32_16x16x32_bf16 v[26:29], v[170:173], v[226:229], v[26:29]
	v_mfma_f32_16x16x32_bf16 v[30:33], v[180:183], v[226:229], v[30:33]
	v_mfma_f32_16x16x32_bf16 v[114:117], v[180:183], v[218:221], v[114:117]
	s_setprio 0
	s_barrier
	ds_read_b128 v[118:121], v11
	ds_read_b128 v[122:125], v11 offset:1024
	ds_read_b128 v[126:129], v11 offset:2048
	ds_read_b128 v[130:133], v11 offset:3072
	ds_read_b128 v[134:137], v12
	ds_read_b128 v[170:173], v12 offset:1024
	ds_read_b128 v[176:179], v12 offset:2048
	ds_read_b128 v[180:183], v12 offset:3072
	s_add_u32 s56, s34, 0x18200
	s_addc_u32 s57, s35, 0
	s_mov_b32 m0, s45
	v_lshl_add_u64 v[138:139], s[56:57], 0, v[164:165]
	ds_read_b128 v[184:187], v175 offset:32768
	ds_read_b128 v[188:191], v175 offset:33792
	ds_read_b128 v[192:195], v175 offset:34816
	ds_read_b128 v[196:199], v175 offset:35840
	ds_read_b128 v[200:203], v175 offset:36864
	ds_read_b128 v[218:221], v175 offset:37888
	ds_read_b128 v[222:225], v175 offset:38912
	ds_read_b128 v[226:229], v175 offset:39936
	global_load_lds_dwordx4 v[138:139], off
	v_lshl_add_u64 v[138:139], s[56:57], 0, v[162:163]
	s_mov_b32 m0, s46
	s_nop 0
	global_load_lds_dwordx4 v[138:139], off
	s_waitcnt vmcnt(8)
	s_waitcnt lgkmcnt(0)
	s_barrier
; #define PG8_STAGE(bufoff, gbase, voff) do { _Pragma("unroll") for (int _i = 0; _i < 2; ++_i) \
;         __builtin_amdgcn_global_load_lds((const unsigned*)((const char*)(gbase) + (voff)[_i]), (PG8_LAS unsigned*)(lds + (bufoff) + ldsw + _i * 8192), 16, 0, 0); } while (0)
; #define PG8_LDA(dst, b, h) do { _Pragma("unroll") for (int m = 0; m < 4; ++m) _Pragma("unroll") for (int k = 0; k < 2; ++k) dst[m][k] = *(const PG8_LAS bf16x8*)(lds + PG8_SA(b, h) + aoff + m * 2048 + k * 1024); } while (0)
; #define PG8_MMA(ai, bj, At, Bt) do { __builtin_amdgcn_s_setprio(1); _Pragma("unroll") for (int m = 0; m < 4; ++m) _Pragma("unroll") for (int n = 0; n < 2; ++n) _Pragma("unroll") for (int k = 0; k < 2; ++k) \
;         acc[ai][bj][m][n] = __builtin_amdgcn_mfma_f32_16x16x32_bf16(Bt[n][k], At[m][k], acc[ai][bj][m][n], 0, 0, 0); __builtin_amdgcn_s_setprio(0); } while (0)
; #define PG8_WAIT_V(n) asm volatile("s_waitcnt vmcnt(" #n ")" ::: "memory")
; #define PG8_WAIT_L(n) asm volatile("s_waitcnt lgkmcnt(" #n ")" ::: "memory")
; #define PG8_BAR __builtin_amdgcn_s_barrier()
; #define PG8_SCHED __builtin_amdgcn_sched_barrier(0)
; template <class Epi, class Sched, bool ALIGN_EPI = false, bool SP2 = false>
; __device__ __forceinline__ void gemm_phase(PG8_LAS unsigned char* lds, int tid_in, const Gemm g, const Sched& S, const Epi& E) {
;     ...
;             PG8_WAIT_V(8); PG8_WAIT_L(0); PG8_BAR; PG8_MMA(0, 0, At, B0); PG8_MMA(0, 1, At, B1); PG8_BAR; PG8_SCHED;
;             PG8_LDA(At, 1, 1); PG8_STAGE(PG8_SB(1, 0), b3, voffB); PG8_STAGE(PG8_SB(1, 1), b3 + hstep, voffB); PG8_STAGE(PG8_SA(1, 0), a3, voffA);
;             PG8_WAIT_V(8); PG8_WAIT_L(0); PG8_BAR; PG8_MMA(1, 0, At, B0); PG8_MMA(1, 1, At, B1); PG8_BAR; PG8_SCHED;
	s_setprio 1
	s_waitcnt lgkmcnt(0)
	v_mfma_f32_16x16x32_bf16 v[66:69], v[118:121], v[184:187], v[66:69]
	v_mfma_f32_16x16x32_bf16 v[70:73], v[126:129], v[184:187], v[70:73]
	v_mfma_f32_16x16x32_bf16 v[74:77], v[118:121], v[192:195], v[74:77]
	v_mfma_f32_16x16x32_bf16 v[78:81], v[126:129], v[192:195], v[78:81]
	v_mfma_f32_16x16x32_bf16 v[82:85], v[118:121], v[200:203], v[82:85]
	v_mfma_f32_16x16x32_bf16 v[86:89], v[126:129], v[200:203], v[86:89]
	v_mfma_f32_16x16x32_bf16 v[90:93], v[118:121], v[222:225], v[90:93]
	v_mfma_f32_16x16x32_bf16 v[94:97], v[126:129], v[222:225], v[94:97]
	v_mfma_f32_16x16x32_bf16 v[66:69], v[122:125], v[188:191], v[66:69]
	v_mfma_f32_16x16x32_bf16 v[70:73], v[130:133], v[188:191], v[70:73]
	v_mfma_f32_16x16x32_bf16 v[74:77], v[122:125], v[196:199], v[74:77]
	v_mfma_f32_16x16x32_bf16 v[78:81], v[130:133], v[196:199], v[78:81]
	v_mfma_f32_16x16x32_bf16 v[82:85], v[122:125], v[218:221], v[82:85]
	v_mfma_f32_16x16x32_bf16 v[86:89], v[130:133], v[218:221], v[86:89]
	v_mfma_f32_16x16x32_bf16 v[90:93], v[122:125], v[226:229], v[90:93]
	v_mfma_f32_16x16x32_bf16 v[94:97], v[130:133], v[226:229], v[94:97]
	v_mfma_f32_16x16x32_bf16 v[98:101], v[134:137], v[184:187], v[98:101]
	v_mfma_f32_16x16x32_bf16 v[102:105], v[176:179], v[184:187], v[102:105]
	v_mfma_f32_16x16x32_bf16 v[106:109], v[134:137], v[192:195], v[106:109]
	v_mfma_f32_16x16x32_bf16 v[42:45], v[176:179], v[192:195], v[42:45]
	v_mfma_f32_16x16x32_bf16 v[46:49], v[134:137], v[200:203], v[46:49]
	v_mfma_f32_16x16x32_bf16 v[50:53], v[176:179], v[200:203], v[50:53]
	v_mfma_f32_16x16x32_bf16 v[54:57], v[134:137], v[222:225], v[54:57]
	v_mfma_f32_16x16x32_bf16 v[58:61], v[176:179], v[222:225], v[58:61]
	v_mfma_f32_16x16x32_bf16 v[98:101], v[170:173], v[188:191], v[98:101]
	v_mfma_f32_16x16x32_bf16 v[102:105], v[180:183], v[188:191], v[102:105]
	v_mfma_f32_16x16x32_bf16 v[106:109], v[170:173], v[196:199], v[106:109]
	v_mfma_f32_16x16x32_bf16 v[42:45], v[180:183], v[196:199], v[42:45]
	v_mfma_f32_16x16x32_bf16 v[46:49], v[170:173], v[218:221], v[46:49]
	v_mfma_f32_16x16x32_bf16 v[50:53], v[180:183], v[218:221], v[50:53]
	v_mfma_f32_16x16x32_bf16 v[54:57], v[170:173], v[226:229], v[54:57]
	v_mfma_f32_16x16x32_bf16 v[58:61], v[180:183], v[226:229], v[58:61]
	s_setprio 0
	s_barrier
	s_mov_b64 s[56:57], 0x280
	s_mov_b32 m0, s53
	v_lshl_add_u64 v[0:1], v[0:1], 0, s[56:57]
	s_add_u32 s8, s8, 0x18280
	ds_read_b128 v[184:187], v175 offset:49152
	ds_read_b128 v[188:191], v175 offset:50176
	ds_read_b128 v[192:195], v175 offset:51200
	ds_read_b128 v[196:199], v175 offset:52224
	ds_read_b128 v[200:203], v175 offset:53248
	ds_read_b128 v[218:221], v175 offset:54272
	ds_read_b128 v[222:225], v175 offset:55296
	ds_read_b128 v[226:229], v175 offset:56320
	global_load_lds_dwordx4 v[0:1], off
	v_lshl_add_u64 v[0:1], v[2:3], 0, s[56:57]
	s_mov_b32 m0, s38
	s_addc_u32 s9, s9, 0
	global_load_lds_dwordx4 v[0:1], off
	v_lshl_add_u64 v[0:1], s[8:9], 0, v[164:165]
	s_mov_b32 m0, s39
	s_nop 0
	global_load_lds_dwordx4 v[0:1], off
	v_lshl_add_u64 v[0:1], s[8:9], 0, v[162:163]
	s_mov_b32 m0, s51
	s_nop 0
	global_load_lds_dwordx4 v[0:1], off
	v_lshl_add_u64 v[0:1], v[4:5], 0, s[56:57]
	s_mov_b32 m0, s20
	s_nop 0
	global_load_lds_dwordx4 v[0:1], off
	v_lshl_add_u64 v[0:1], v[6:7], 0, s[56:57]
	s_mov_b32 m0, s21
	s_nop 0
	global_load_lds_dwordx4 v[0:1], off
	s_waitcnt vmcnt(8)
	s_waitcnt lgkmcnt(0)
	s_barrier
	s_setprio 1
	s_waitcnt lgkmcnt(0)
	v_mfma_f32_16x16x32_bf16 v[0:3], v[118:121], v[184:187], v[140:143]
	v_mfma_f32_16x16x32_bf16 v[4:7], v[126:129], v[184:187], v[144:147]
	v_mfma_f32_16x16x32_bf16 v[14:17], v[118:121], v[222:225], v[14:17]
	v_mfma_f32_16x16x32_bf16 v[18:21], v[126:129], v[222:225], v[18:21]
	v_mfma_f32_16x16x32_bf16 v[0:3], v[122:125], v[188:191], v[0:3]
	v_mfma_f32_16x16x32_bf16 v[4:7], v[130:133], v[188:191], v[4:7]
	v_mfma_f32_16x16x32_bf16 v[138:141], v[118:121], v[192:195], v[148:151]
	v_mfma_f32_16x16x32_bf16 v[142:145], v[126:129], v[192:195], v[152:155]
	v_mfma_f32_16x16x32_bf16 v[146:149], v[118:121], v[200:203], v[156:159]
	v_mfma_f32_16x16x32_bf16 v[150:153], v[126:129], v[200:203], v[166:169]
	v_mfma_f32_16x16x32_bf16 v[14:17], v[122:125], v[226:229], v[14:17]
	v_mfma_f32_16x16x32_bf16 v[18:21], v[130:133], v[226:229], v[18:21]
	v_mfma_f32_16x16x32_bf16 v[138:141], v[122:125], v[196:199], v[138:141]
	v_mfma_f32_16x16x32_bf16 v[142:145], v[130:133], v[196:199], v[142:145]
	v_mfma_f32_16x16x32_bf16 v[146:149], v[122:125], v[218:221], v[146:149]
	v_mfma_f32_16x16x32_bf16 v[150:153], v[130:133], v[218:221], v[150:153]
	v_mfma_f32_16x16x32_bf16 v[22:25], v[134:137], v[184:187], v[22:25]
	v_mfma_f32_16x16x32_bf16 v[34:37], v[176:179], v[184:187], v[34:37]
	v_mfma_f32_16x16x32_bf16 v[38:41], v[134:137], v[192:195], v[38:41]
	v_mfma_f32_16x16x32_bf16 v[62:65], v[176:179], v[192:195], v[62:65]
	v_mfma_f32_16x16x32_bf16 v[110:113], v[134:137], v[200:203], v[110:113]
	v_mfma_f32_16x16x32_bf16 v[26:29], v[134:137], v[222:225], v[26:29]
	v_mfma_f32_16x16x32_bf16 v[30:33], v[176:179], v[222:225], v[30:33]
	v_mfma_f32_16x16x32_bf16 v[22:25], v[170:173], v[188:191], v[22:25]
	v_mfma_f32_16x16x32_bf16 v[34:37], v[180:183], v[188:191], v[34:37]
	v_mfma_f32_16x16x32_bf16 v[38:41], v[170:173], v[196:199], v[38:41]
	v_mfma_f32_16x16x32_bf16 v[62:65], v[180:183], v[196:199], v[62:65]
	v_mfma_f32_16x16x32_bf16 v[110:113], v[170:173], v[218:221], v[110:113]
	v_mfma_f32_16x16x32_bf16 v[114:117], v[176:179], v[200:203], v[114:117]
	v_mfma_f32_16x16x32_bf16 v[26:29], v[170:173], v[226:229], v[26:29]
	v_mfma_f32_16x16x32_bf16 v[30:33], v[180:183], v[226:229], v[30:33]
	v_mfma_f32_16x16x32_bf16 v[114:117], v[180:183], v[218:221], v[114:117]
	s_setprio 0
	s_barrier
; #define PG8_STAGE(bufoff, gbase, voff) do { _Pragma("unroll") for (int _i = 0; _i < 2; ++_i) \
;         __builtin_amdgcn_global_load_lds((const unsigned*)((const char*)(gbase) + (voff)[_i]), (PG8_LAS unsigned*)(lds + (bufoff) + ldsw + _i * 8192), 16, 0, 0); } while (0)
; #define PG8_LDA(dst, b, h) do { _Pragma("unroll") for (int m = 0; m < 4; ++m) _Pragma("unroll") for (int k = 0; k < 2; ++k) dst[m][k] = *(const PG8_LAS bf16x8*)(lds + PG8_SA(b, h) + aoff + m * 2048 + k * 1024); } while (0)
; #define PG8_LDB(dst, b, h) do { _Pragma("unroll") for (int n = 0; n < 2; ++n) _Pragma("unroll") for (int k = 0; k < 2; ++k) dst[n][k] = *(const PG8_LAS bf16x8*)(lds + PG8_SB(b, h) + boff + n * 2048 + k * 1024); } while (0)
; #define PG8_MMA(ai, bj, At, Bt) do { __builtin_amdgcn_s_setprio(1); _Pragma("unroll") for (int m = 0; m < 4; ++m) _Pragma("unroll") for (int n = 0; n < 2; ++n) _Pragma("unroll") for (int k = 0; k < 2; ++k) \
;         acc[ai][bj][m][n] = __builtin_amdgcn_mfma_f32_16x16x32_bf16(Bt[n][k], At[m][k], acc[ai][bj][m][n], 0, 0, 0); __builtin_amdgcn_s_setprio(0); } while (0)
; #define PG8_WAIT_V(n) asm volatile("s_waitcnt vmcnt(" #n ")" ::: "memory")
; #define PG8_WAIT_L(n) asm volatile("s_waitcnt lgkmcnt(" #n ")" ::: "memory")
; #define PG8_BAR __builtin_amdgcn_s_barrier()
; #define PG8_SCHED __builtin_amdgcn_sched_barrier(0)
; template <class Epi, class Sched, bool ALIGN_EPI = false, bool SP2 = false>
; __device__ __forceinline__ void gemm_phase(PG8_LAS unsigned char* lds, int tid_in, const Gemm g, const Sched& S, const Epi& E) {
;     ...
;             PG8_LDB(B0, 0, 0); PG8_LDB(B1, 0, 1); PG8_SCHED; PG8_LDA(At, 0, 0); PG8_STAGE(PG8_SA(1, 1), a1 + hstep, voffA);
;             PG8_WAIT_V(8); PG8_WAIT_L(0); PG8_BAR; PG8_MMA(0, 0, At, B0); PG8_MMA(0, 1, At, B1); PG8_BAR; PG8_SCHED;
;             PG8_LDA(At, 0, 1); PG8_STAGE(PG8_SB(0, 0), b2, voffB); PG8_STAGE(PG8_SB(0, 1), b2 + hstep, voffB); PG8_STAGE(PG8_SA(0, 0), a2, voffA);
;             PG8_WAIT_V(8); PG8_WAIT_L(0); PG8_BAR; PG8_MMA(1, 0, At, B0); PG8_MMA(1, 1, At, B1); PG8_BAR; PG8_SCHED;
	ds_read_b128 v[118:121], v8
	ds_read_b128 v[122:125], v8 offset:1024
	ds_read_b128 v[126:129], v8 offset:2048
	ds_read_b128 v[130:133], v8 offset:3072
	ds_read_b128 v[134:137], v10
	ds_read_b128 v[154:157], v10 offset:1024
	ds_read_b128 v[158:161], v10 offset:2048
	ds_read_b128 v[166:169], v10 offset:3072
	s_add_u32 s8, s34, 0x18280
	s_addc_u32 s9, s35, 0
	s_mov_b32 m0, s50
	v_lshl_add_u64 v[204:205], s[8:9], 0, v[164:165]
	ds_read_b128 v[170:173], v175
	ds_read_b128 v[176:179], v175 offset:1024
	ds_read_b128 v[180:183], v175 offset:2048
	ds_read_b128 v[184:187], v175 offset:3072
	ds_read_b128 v[188:191], v175 offset:4096
	ds_read_b128 v[192:195], v175 offset:5120
	ds_read_b128 v[196:199], v175 offset:6144
	ds_read_b128 v[200:203], v175 offset:7168
	global_load_lds_dwordx4 v[204:205], off
	v_lshl_add_u64 v[204:205], s[8:9], 0, v[162:163]
	s_mov_b32 m0, s6
	s_nop 0
	global_load_lds_dwordx4 v[204:205], off
	s_waitcnt vmcnt(8)
	s_waitcnt lgkmcnt(0)
	s_barrier
	s_setprio 1
	s_waitcnt lgkmcnt(0)
	v_mfma_f32_16x16x32_bf16 v[66:69], v[118:121], v[170:173], v[66:69]
	v_mfma_f32_16x16x32_bf16 v[70:73], v[126:129], v[170:173], v[70:73]
	v_mfma_f32_16x16x32_bf16 v[74:77], v[118:121], v[180:183], v[74:77]
	v_mfma_f32_16x16x32_bf16 v[78:81], v[126:129], v[180:183], v[78:81]
	v_mfma_f32_16x16x32_bf16 v[82:85], v[118:121], v[188:191], v[82:85]
	v_mfma_f32_16x16x32_bf16 v[86:89], v[126:129], v[188:191], v[86:89]
	v_mfma_f32_16x16x32_bf16 v[90:93], v[118:121], v[196:199], v[90:93]
	v_mfma_f32_16x16x32_bf16 v[66:69], v[122:125], v[176:179], v[66:69]
	v_mfma_f32_16x16x32_bf16 v[70:73], v[130:133], v[176:179], v[70:73]
	v_mfma_f32_16x16x32_bf16 v[74:77], v[122:125], v[184:187], v[74:77]
	v_mfma_f32_16x16x32_bf16 v[78:81], v[130:133], v[184:187], v[78:81]
	v_mfma_f32_16x16x32_bf16 v[82:85], v[122:125], v[192:195], v[82:85]
	v_mfma_f32_16x16x32_bf16 v[86:89], v[130:133], v[192:195], v[86:89]
	v_mfma_f32_16x16x32_bf16 v[218:221], v[122:125], v[200:203], v[90:93]
	v_mfma_f32_16x16x32_bf16 v[90:93], v[126:129], v[196:199], v[94:97]
	v_mfma_f32_16x16x32_bf16 v[222:225], v[130:133], v[200:203], v[90:93]
	v_mfma_f32_16x16x32_bf16 v[90:93], v[134:137], v[170:173], v[98:101]
	v_mfma_f32_16x16x32_bf16 v[98:101], v[154:157], v[176:179], v[90:93]
	v_mfma_f32_16x16x32_bf16 v[90:93], v[158:161], v[170:173], v[102:105]
	v_mfma_f32_16x16x32_bf16 v[42:45], v[158:161], v[180:183], v[42:45]
	v_mfma_f32_16x16x32_bf16 v[46:49], v[134:137], v[188:191], v[46:49]
	v_mfma_f32_16x16x32_bf16 v[50:53], v[158:161], v[188:191], v[50:53]
	v_mfma_f32_16x16x32_bf16 v[54:57], v[134:137], v[196:199], v[54:57]
	v_mfma_f32_16x16x32_bf16 v[58:61], v[158:161], v[196:199], v[58:61]
	v_mfma_f32_16x16x32_bf16 v[102:105], v[166:169], v[176:179], v[90:93]
	v_mfma_f32_16x16x32_bf16 v[90:93], v[134:137], v[180:183], v[106:109]
	v_mfma_f32_16x16x32_bf16 v[42:45], v[166:169], v[184:187], v[42:45]
	v_mfma_f32_16x16x32_bf16 v[46:49], v[154:157], v[192:195], v[46:49]
	v_mfma_f32_16x16x32_bf16 v[50:53], v[166:169], v[192:195], v[50:53]
	v_mfma_f32_16x16x32_bf16 v[54:57], v[154:157], v[200:203], v[54:57]
	v_mfma_f32_16x16x32_bf16 v[58:61], v[166:169], v[200:203], v[58:61]
	v_mfma_f32_16x16x32_bf16 v[170:173], v[154:157], v[184:187], v[90:93]
	s_setprio 0
	s_barrier
	s_mov_b32 m0, s37
	v_lshl_add_u64 v[204:205], s[30:31], 0, v[164:165]
	s_add_u32 s6, s30, 0x18000
	ds_read_b128 v[90:93], v175 offset:16384
	ds_read_b128 v[94:97], v175 offset:17408
	ds_read_b128 v[106:109], v175 offset:18432
	ds_read_b128 v[176:179], v175 offset:19456
	ds_read_b128 v[180:183], v175 offset:20480
	ds_read_b128 v[184:187], v175 offset:21504
	ds_read_b128 v[188:191], v175 offset:22528
	ds_read_b128 v[192:195], v175 offset:23552
	global_load_lds_dwordx4 v[204:205], off
	v_lshl_add_u64 v[210:211], s[30:31], 0, v[162:163]
	s_mov_b32 m0, s7
	s_addc_u32 s7, s31, 0
	global_load_lds_dwordx4 v[210:211], off
	v_lshl_add_u64 v[196:197], s[6:7], 0, v[164:165]
	s_mov_b32 m0, s18
	v_lshl_add_u64 v[212:213], s[16:17], 0, v[164:165]
	global_load_lds_dwordx4 v[196:197], off
	v_lshl_add_u64 v[196:197], s[6:7], 0, v[162:163]
	s_mov_b32 m0, s36
	v_lshl_add_u64 v[214:215], s[16:17], 0, v[162:163]
	global_load_lds_dwordx4 v[196:197], off
	s_mov_b32 m0, s43
	s_nop 0
	global_load_lds_dwordx4 v[212:213], off
	s_mov_b32 m0, s44
	s_nop 0
	global_load_lds_dwordx4 v[214:215], off
	s_waitcnt vmcnt(8)
	s_waitcnt lgkmcnt(0)
	s_barrier
	s_setprio 1
	s_waitcnt lgkmcnt(0)
	v_mfma_f32_16x16x32_bf16 v[0:3], v[118:121], v[90:93], v[0:3]
	v_mfma_f32_16x16x32_bf16 v[4:7], v[126:129], v[90:93], v[4:7]
	v_mfma_f32_16x16x32_bf16 v[14:17], v[118:121], v[188:191], v[14:17]
	v_mfma_f32_16x16x32_bf16 v[18:21], v[126:129], v[188:191], v[18:21]
	v_mfma_f32_16x16x32_bf16 v[0:3], v[122:125], v[94:97], v[0:3]
	v_mfma_f32_16x16x32_bf16 v[4:7], v[130:133], v[94:97], v[4:7]
	v_mfma_f32_16x16x32_bf16 v[138:141], v[118:121], v[106:109], v[138:141]
	v_mfma_f32_16x16x32_bf16 v[142:145], v[126:129], v[106:109], v[142:145]
	v_mfma_f32_16x16x32_bf16 v[146:149], v[118:121], v[180:183], v[146:149]
	v_mfma_f32_16x16x32_bf16 v[150:153], v[126:129], v[180:183], v[150:153]
	v_mfma_f32_16x16x32_bf16 v[14:17], v[122:125], v[192:195], v[14:17]
	v_mfma_f32_16x16x32_bf16 v[18:21], v[130:133], v[192:195], v[18:21]
	v_mfma_f32_16x16x32_bf16 v[138:141], v[122:125], v[176:179], v[138:141]
	v_mfma_f32_16x16x32_bf16 v[142:145], v[130:133], v[176:179], v[142:145]
	v_mfma_f32_16x16x32_bf16 v[146:149], v[122:125], v[184:187], v[146:149]
	v_mfma_f32_16x16x32_bf16 v[150:153], v[130:133], v[184:187], v[150:153]
	v_mfma_f32_16x16x32_bf16 v[62:65], v[158:161], v[106:109], v[62:65]
	v_mfma_f32_16x16x32_bf16 v[22:25], v[134:137], v[90:93], v[22:25]
	v_mfma_f32_16x16x32_bf16 v[34:37], v[158:161], v[90:93], v[34:37]
	v_mfma_f32_16x16x32_bf16 v[38:41], v[134:137], v[106:109], v[38:41]
	v_mfma_f32_16x16x32_bf16 v[118:121], v[166:169], v[176:179], v[62:65]
	v_mfma_f32_16x16x32_bf16 v[62:65], v[134:137], v[180:183], v[110:113]
	v_mfma_f32_16x16x32_bf16 v[26:29], v[134:137], v[188:191], v[26:29]
	v_mfma_f32_16x16x32_bf16 v[22:25], v[154:157], v[94:97], v[22:25]
	v_mfma_f32_16x16x32_bf16 v[34:37], v[166:169], v[94:97], v[34:37]
	v_mfma_f32_16x16x32_bf16 v[38:41], v[154:157], v[176:179], v[38:41]
	v_mfma_f32_16x16x32_bf16 v[130:133], v[154:157], v[184:187], v[62:65]
	v_mfma_f32_16x16x32_bf16 v[62:65], v[158:161], v[180:183], v[114:117]
	v_mfma_f32_16x16x32_bf16 v[134:137], v[154:157], v[192:195], v[26:29]
	v_mfma_f32_16x16x32_bf16 v[26:29], v[158:161], v[188:191], v[30:33]
	v_mfma_f32_16x16x32_bf16 v[114:117], v[166:169], v[184:187], v[62:65]
	v_mfma_f32_16x16x32_bf16 v[166:169], v[166:169], v[192:195], v[26:29]
	s_setprio 0
	s_barrier
; #define PG8_STAGE(bufoff, gbase, voff) do { _Pragma("unroll") for (int _i = 0; _i < 2; ++_i) \
;         __builtin_amdgcn_global_load_lds((const unsigned*)((const char*)(gbase) + (voff)[_i]), (PG8_LAS unsigned*)(lds + (bufoff) + ldsw + _i * 8192), 16, 0, 0); } while (0)
; #define PG8_LDA(dst, b, h) do { _Pragma("unroll") for (int m = 0; m < 4; ++m) _Pragma("unroll") for (int k = 0; k < 2; ++k) dst[m][k] = *(const PG8_LAS bf16x8*)(lds + PG8_SA(b, h) + aoff + m * 2048 + k * 1024); } while (0)
; #define PG8_LDB(dst, b, h) do { _Pragma("unroll") for (int n = 0; n < 2; ++n) _Pragma("unroll") for (int k = 0; k < 2; ++k) dst[n][k] = *(const PG8_LAS bf16x8*)(lds + PG8_SB(b, h) + boff + n * 2048 + k * 1024); } while (0)
; #define PG8_MMA(ai, bj, At, Bt) do { __builtin_amdgcn_s_setprio(1); _Pragma("unroll") for (int m = 0; m < 4; ++m) _Pragma("unroll") for (int n = 0; n < 2; ++n) _Pragma("unroll") for (int k = 0; k < 2; ++k) \
;         acc[ai][bj][m][n] = __builtin_amdgcn_mfma_f32_16x16x32_bf16(Bt[n][k], At[m][k], acc[ai][bj][m][n], 0, 0, 0); __builtin_amdgcn_s_setprio(0); } while (0)
; #define PG8_WAIT_V(n) asm volatile("s_waitcnt vmcnt(" #n ")" ::: "memory")
; #define PG8_WAIT_L(n) asm volatile("s_waitcnt lgkmcnt(" #n ")" ::: "memory")
; #define PG8_BAR __builtin_amdgcn_s_barrier()
; #define PG8_SCHED __builtin_amdgcn_sched_barrier(0)
; template <class Epi, class Sched, bool ALIGN_EPI = false, bool SP2 = false>
; __device__ __forceinline__ void gemm_phase(PG8_LAS unsigned char* lds, int tid_in, const Gemm g, const Sched& S, const Epi& E) {
;     ...
;             PG8_LDB(B0, 1, 0); PG8_LDB(B1, 1, 1); PG8_SCHED; PG8_LDA(At, 1, 0); PG8_STAGE(PG8_SA(0, 1), a2 + hstep, voffA);
;             PG8_WAIT_V(8); PG8_WAIT_L(0); PG8_BAR; PG8_MMA(0, 0, At, B0); PG8_MMA(0, 1, At, B1); PG8_BAR; PG8_SCHED;
;             PG8_LDA(At, 1, 1); PG8_STAGE(PG8_SB(1, 0), b3, voffB); PG8_STAGE(PG8_SB(1, 1), b3 + hstep, voffB); PG8_STAGE(PG8_SA(1, 0), a3, voffA);
;             PG8_WAIT_V(8); PG8_WAIT_L(0); PG8_BAR; PG8_MMA(1, 0, At, B0); PG8_MMA(1, 1, At, B1); PG8_BAR; PG8_SCHED;
;     ...
;         if constexpr (ALIGN_EPI) { if (wr == 0) PG8_BAR; }
	ds_read_b128 v[176:179], v11
	ds_read_b128 v[180:183], v11 offset:1024
	ds_read_b128 v[184:187], v11 offset:2048
	ds_read_b128 v[188:191], v11 offset:3072
	ds_read_b128 v[192:195], v12
	ds_read_b128 v[196:199], v12 offset:1024
	ds_read_b128 v[200:203], v12 offset:2048
	ds_read_b128 v[226:229], v12 offset:3072
	s_add_u32 s6, s16, 0x18000
	s_addc_u32 s7, s17, 0
	s_mov_b32 m0, s45
	v_lshl_add_u64 v[90:91], s[6:7], 0, v[164:165]
	ds_read_b128 v[10:13], v175 offset:32768
	ds_read_b128 v[26:29], v175 offset:33792
	ds_read_b128 v[30:33], v175 offset:34816
	ds_read_b128 v[62:65], v175 offset:35840
	ds_read_b128 v[230:233], v175 offset:36864
	ds_read_b128 v[234:237], v175 offset:37888
	ds_read_b128 v[238:241], v175 offset:38912
	ds_read_b128 v[248:251], v175 offset:39936
	global_load_lds_dwordx4 v[90:91], off
	v_lshl_add_u64 v[90:91], s[6:7], 0, v[162:163]
	s_mov_b32 m0, s46
	s_nop 0
	global_load_lds_dwordx4 v[90:91], off
	s_waitcnt vmcnt(8)
	s_waitcnt lgkmcnt(0)
	s_barrier
	s_setprio 1
	s_waitcnt lgkmcnt(0)
	v_mfma_f32_16x16x32_bf16 v[66:69], v[176:179], v[10:13], v[66:69]
	v_mfma_f32_16x16x32_bf16 v[158:161], v[180:183], v[26:29], v[66:69]
	v_mfma_f32_16x16x32_bf16 v[66:69], v[184:187], v[10:13], v[70:73]
	v_mfma_f32_16x16x32_bf16 v[154:157], v[188:191], v[26:29], v[66:69]
	v_mfma_f32_16x16x32_bf16 v[66:69], v[176:179], v[30:33], v[74:77]
	v_mfma_f32_16x16x32_bf16 v[110:113], v[180:183], v[62:65], v[66:69]
	v_mfma_f32_16x16x32_bf16 v[66:69], v[184:187], v[30:33], v[78:81]
	v_mfma_f32_16x16x32_bf16 v[106:109], v[188:191], v[62:65], v[66:69]
	v_mfma_f32_16x16x32_bf16 v[66:69], v[176:179], v[230:233], v[82:85]
	v_mfma_f32_16x16x32_bf16 v[94:97], v[180:183], v[234:237], v[66:69]
	v_mfma_f32_16x16x32_bf16 v[66:69], v[184:187], v[230:233], v[86:89]
	v_mfma_f32_16x16x32_bf16 v[90:93], v[188:191], v[234:237], v[66:69]
	v_mfma_f32_16x16x32_bf16 v[66:69], v[176:179], v[238:241], v[218:221]
	v_mfma_f32_16x16x32_bf16 v[78:81], v[180:183], v[248:251], v[66:69]
	v_mfma_f32_16x16x32_bf16 v[66:69], v[184:187], v[238:241], v[222:225]
	v_mfma_f32_16x16x32_bf16 v[74:77], v[188:191], v[248:251], v[66:69]
	v_mfma_f32_16x16x32_bf16 v[66:69], v[192:195], v[10:13], v[98:101]
	v_mfma_f32_16x16x32_bf16 v[10:13], v[200:203], v[10:13], v[102:105]
	v_mfma_f32_16x16x32_bf16 v[122:125], v[226:229], v[26:29], v[10:13]
	v_mfma_f32_16x16x32_bf16 v[10:13], v[192:195], v[30:33], v[170:173]
	v_mfma_f32_16x16x32_bf16 v[102:105], v[196:199], v[62:65], v[10:13]
	v_mfma_f32_16x16x32_bf16 v[10:13], v[200:203], v[30:33], v[42:45]
	v_mfma_f32_16x16x32_bf16 v[98:101], v[226:229], v[62:65], v[10:13]
	v_mfma_f32_16x16x32_bf16 v[10:13], v[192:195], v[230:233], v[46:49]
	v_mfma_f32_16x16x32_bf16 v[86:89], v[196:199], v[234:237], v[10:13]
	v_mfma_f32_16x16x32_bf16 v[10:13], v[200:203], v[230:233], v[50:53]
	v_mfma_f32_16x16x32_bf16 v[82:85], v[226:229], v[234:237], v[10:13]
	v_mfma_f32_16x16x32_bf16 v[10:13], v[192:195], v[238:241], v[54:57]
	v_mfma_f32_16x16x32_bf16 v[70:73], v[196:199], v[248:251], v[10:13]
	v_mfma_f32_16x16x32_bf16 v[10:13], v[200:203], v[238:241], v[58:61]
	v_mfma_f32_16x16x32_bf16 v[126:129], v[196:199], v[26:29], v[66:69]
	v_mfma_f32_16x16x32_bf16 v[66:69], v[226:229], v[248:251], v[10:13]
	s_setprio 0
	s_barrier
	s_mov_b32 m0, s53
	s_nop 2
	v_lshl_add_u64 v[10:11], v[204:205], 0, s[24:25]
	s_add_u32 s6, s30, 0x18080
	ds_read_b128 v[50:53], v175 offset:49152
	ds_read_b128 v[170:173], v175 offset:50176
	ds_read_b128 v[218:221], v175 offset:51200
	ds_read_b128 v[222:225], v175 offset:52224
	ds_read_b128 v[230:233], v175 offset:53248
	ds_read_b128 v[234:237], v175 offset:54272
	ds_read_b128 v[238:241], v175 offset:55296
	ds_read_b128 v[248:251], v175 offset:56320
	global_load_lds_dwordx4 v[10:11], off
	v_lshl_add_u64 v[10:11], v[210:211], 0, s[24:25]
	s_mov_b32 m0, s38
	s_addc_u32 s7, s31, 0
	global_load_lds_dwordx4 v[10:11], off
	v_lshl_add_u64 v[10:11], s[6:7], 0, v[164:165]
	s_mov_b32 m0, s39
	s_nop 0
	global_load_lds_dwordx4 v[10:11], off
	v_lshl_add_u64 v[10:11], s[6:7], 0, v[162:163]
	s_mov_b32 m0, s51
	s_nop 0
	global_load_lds_dwordx4 v[10:11], off
	v_lshl_add_u64 v[10:11], v[212:213], 0, s[24:25]
	s_mov_b32 m0, s20
	s_nop 0
	global_load_lds_dwordx4 v[10:11], off
	v_lshl_add_u64 v[10:11], v[214:215], 0, s[24:25]
	s_mov_b32 m0, s21
	s_nop 0
	global_load_lds_dwordx4 v[10:11], off
	s_waitcnt vmcnt(8)
	s_waitcnt lgkmcnt(0)
	s_barrier
	s_setprio 1
	s_waitcnt lgkmcnt(0)
	v_mfma_f32_16x16x32_bf16 v[0:3], v[176:179], v[50:53], v[0:3]
	v_mfma_f32_16x16x32_bf16 v[62:65], v[180:183], v[170:173], v[0:3]
	v_mfma_f32_16x16x32_bf16 v[0:3], v[184:187], v[50:53], v[4:7]
	v_mfma_f32_16x16x32_bf16 v[58:61], v[188:191], v[170:173], v[0:3]
	v_mfma_f32_16x16x32_bf16 v[0:3], v[176:179], v[218:221], v[138:141]
	v_mfma_f32_16x16x32_bf16 v[46:49], v[180:183], v[222:225], v[0:3]
	v_mfma_f32_16x16x32_bf16 v[0:3], v[184:187], v[218:221], v[142:145]
	v_mfma_f32_16x16x32_bf16 v[42:45], v[188:191], v[222:225], v[0:3]
	v_mfma_f32_16x16x32_bf16 v[0:3], v[176:179], v[230:233], v[146:149]
	v_mfma_f32_16x16x32_bf16 v[30:33], v[180:183], v[234:237], v[0:3]
	v_mfma_f32_16x16x32_bf16 v[0:3], v[184:187], v[230:233], v[150:153]
	v_mfma_f32_16x16x32_bf16 v[26:29], v[188:191], v[234:237], v[0:3]
	v_mfma_f32_16x16x32_bf16 v[0:3], v[176:179], v[238:241], v[14:17]
	v_mfma_f32_16x16x32_bf16 v[14:17], v[180:183], v[248:251], v[0:3]
	v_mfma_f32_16x16x32_bf16 v[0:3], v[184:187], v[238:241], v[18:21]
	v_mfma_f32_16x16x32_bf16 v[10:13], v[188:191], v[248:251], v[0:3]
	v_mfma_f32_16x16x32_bf16 v[0:3], v[192:195], v[50:53], v[22:25]
	v_mfma_f32_16x16x32_bf16 v[54:57], v[196:199], v[170:173], v[0:3]
	v_mfma_f32_16x16x32_bf16 v[0:3], v[200:203], v[50:53], v[34:37]
	v_mfma_f32_16x16x32_bf16 v[50:53], v[226:229], v[170:173], v[0:3]
	v_mfma_f32_16x16x32_bf16 v[0:3], v[192:195], v[218:221], v[38:41]
	v_mfma_f32_16x16x32_bf16 v[38:41], v[196:199], v[222:225], v[0:3]
	v_mfma_f32_16x16x32_bf16 v[0:3], v[200:203], v[218:221], v[118:121]
	v_mfma_f32_16x16x32_bf16 v[34:37], v[226:229], v[222:225], v[0:3]
	v_mfma_f32_16x16x32_bf16 v[0:3], v[192:195], v[230:233], v[130:133]
	v_mfma_f32_16x16x32_bf16 v[22:25], v[196:199], v[234:237], v[0:3]
	v_mfma_f32_16x16x32_bf16 v[0:3], v[200:203], v[230:233], v[114:117]
	v_mfma_f32_16x16x32_bf16 v[18:21], v[226:229], v[234:237], v[0:3]
	v_mfma_f32_16x16x32_bf16 v[0:3], v[192:195], v[238:241], v[134:137]
	v_mfma_f32_16x16x32_bf16 v[4:7], v[196:199], v[248:251], v[0:3]
	v_mfma_f32_16x16x32_bf16 v[0:3], v[200:203], v[238:241], v[166:169]
	v_mfma_f32_16x16x32_bf16 v[0:3], v[226:229], v[248:251], v[0:3]
	s_setprio 0
	s_barrier
	s_andn2_b64 vcc, exec, s[12:13]
	s_cbranch_vccnz .LBB0_397
	s_barrier

; #define PG8_STAGE(bufoff, gbase, voff) do { _Pragma("unroll") for (int _i = 0; _i < 2; ++_i) \
;         __builtin_amdgcn_global_load_lds((const unsigned*)((const char*)(gbase) + (voff)[_i]), (PG8_LAS unsigned*)(lds + (bufoff) + ldsw + _i * 8192), 16, 0, 0); } while (0)
; #define PG8_LDA(dst, b, h) do { _Pragma("unroll") for (int m = 0; m < 4; ++m) _Pragma("unroll") for (int k = 0; k < 2; ++k) dst[m][k] = *(const PG8_LAS bf16x8*)(lds + PG8_SA(b, h) + aoff + m * 2048 + k * 1024); } while (0)
; #define PG8_LDB(dst, b, h) do { _Pragma("unroll") for (int n = 0; n < 2; ++n) _Pragma("unroll") for (int k = 0; k < 2; ++k) dst[n][k] = *(const PG8_LAS bf16x8*)(lds + PG8_SB(b, h) + boff + n * 2048 + k * 1024); } while (0)
; #define PG8_MMA(ai, bj, At, Bt) do { __builtin_amdgcn_s_setprio(1); _Pragma("unroll") for (int m = 0; m < 4; ++m) _Pragma("unroll") for (int n = 0; n < 2; ++n) _Pragma("unroll") for (int k = 0; k < 2; ++k) \
;         acc[ai][bj][m][n] = __builtin_amdgcn_mfma_f32_16x16x32_bf16(Bt[n][k], At[m][k], acc[ai][bj][m][n], 0, 0, 0); __builtin_amdgcn_s_setprio(0); } while (0)
; template <class Epi, class Sched, bool ALIGN_EPI = false, bool SP2 = false>
; __device__ __forceinline__ void gemm_phase(PG8_LAS unsigned char* lds, int tid_in, const Gemm g, const Sched& S, const Epi& E) {
;     ...
;         const bool has_next = S.next(ui + 1, nxt);
;         const char* nA = has_next ? (const char*)g.A + (size_t)nxt.pm * tstep : cA; const char* nB = has_next ? (const char*)g.Bt + (size_t)nxt.pn * tstep : cB;
;         for (int t = 0; t < nt; t += 2) {
;             const bool last = (t == nt - 2);
;             const char* a1 = cA + (size_t)(t + 1) * kstep;
;             const char* a2 = last ? nA : cA + (size_t)(t + 2) * kstep; const char* b2 = last ? nB : cB + (size_t)(t + 2) * kstep;
;             const char* a3 = a2 + kstep; const char* b3 = b2 + kstep;
;             if (last && has_next) S.a_ready(nxt);
;             if constexpr (SP2) {
;             PG8_LDB(B0, 0, 0); PG8_LDB(B1, 0, 1); PG8_SCHED; PG8_LDA(At, 0, 0); PG8_STAGE(PG8_SA(1, 1), a1 + hstep, voffA);
;             PG8_WAIT_V(8); PG8_WAIT_L(0); PG8_BAR; PG8_MMA(0, 0, At, B0); PG8_MMA(0, 1, At, B1); PG8_BAR; PG8_SCHED;
;             PG8_LDA(At, 0, 1); PG8_STAGE(PG8_SB(0, 0), b2, voffB); PG8_STAGE(PG8_SB(0, 1), b2 + hstep, voffB); PG8_STAGE(PG8_SA(0, 0), a2, voffA);
.LBB0_409:
	s_ashr_i32 s15, s14, 31
	s_lshl_b64 s[16:17], s[14:15], 17
	v_readlane_b32 s30, v253, 16
	v_readlane_b32 s31, v253, 17
	s_add_u32 s16, s30, s16
	s_addc_u32 s17, s31, s17
	s_and_b64 s[30:31], s[4:5], exec
	s_cselect_b32 s49, s17, s51
	s_cselect_b32 s48, s16, s50
	s_ashr_i32 s13, s12, 31
	s_lshl_b64 s[30:31], s[12:13], 17
	s_add_u32 s30, s0, s30
	s_addc_u32 s31, s1, s31
	s_and_b64 s[34:35], s[4:5], exec
	s_cselect_b32 s35, s31, s43
	s_cselect_b32 s34, s30, s42
	s_add_i32 s15, 0, 0x10000
	s_add_i32 s37, 0, 0x14000
	v_add_u32_e32 v206, s15, v136
	v_add_u32_e32 v207, s37, v136
	ds_read_b128 v[0:3], v206
	ds_read_b128 v[4:7], v206 offset:1024
	ds_read_b128 v[10:13], v206 offset:2048
	ds_read_b128 v[14:17], v206 offset:3072
	ds_read_b128 v[18:21], v207
	ds_read_b128 v[22:25], v207 offset:1024
	ds_read_b128 v[26:29], v207 offset:2048
	ds_read_b128 v[30:33], v207 offset:3072
	s_add_u32 s38, s50, 0x10080
	s_addc_u32 s39, s51, 0
	s_add_i32 s53, s21, 0xc000
	v_lshl_add_u64 v[66:67], s[38:39], 0, v[134:135]
	s_mov_b32 m0, s53
	s_add_i32 s13, s21, 0xe000
	ds_read_b128 v[34:37], v137
	ds_read_b128 v[38:41], v137 offset:1024
	ds_read_b128 v[42:45], v137 offset:2048
	ds_read_b128 v[46:49], v137 offset:3072
	ds_read_b128 v[50:53], v137 offset:4096
	ds_read_b128 v[54:57], v137 offset:5120
	ds_read_b128 v[58:61], v137 offset:6144
	ds_read_b128 v[62:65], v137 offset:7168
	global_load_lds_dwordx4 v[66:67], off
	v_lshl_add_u64 v[66:67], s[38:39], 0, v[132:133]
	s_mov_b32 m0, s13
	s_nop 0
	global_load_lds_dwordx4 v[66:67], off
	s_waitcnt vmcnt(8)
	s_waitcnt lgkmcnt(0)
	s_barrier
	s_setprio 1
	s_waitcnt lgkmcnt(0)
	v_mfma_f32_16x16x32_bf16 v[66:69], v[0:3], v[34:37], 0
	v_mfma_f32_16x16x32_bf16 v[70:73], v[10:13], v[34:37], 0
	v_mfma_f32_16x16x32_bf16 v[74:77], v[0:3], v[42:45], 0
	v_mfma_f32_16x16x32_bf16 v[78:81], v[10:13], v[42:45], 0
	v_mfma_f32_16x16x32_bf16 v[82:85], v[0:3], v[50:53], 0
	v_mfma_f32_16x16x32_bf16 v[86:89], v[10:13], v[50:53], 0
	v_mfma_f32_16x16x32_bf16 v[90:93], v[0:3], v[58:61], 0
	v_mfma_f32_16x16x32_bf16 v[94:97], v[10:13], v[58:61], 0
	v_mfma_f32_16x16x32_bf16 v[66:69], v[4:7], v[38:41], v[66:69]
	v_mfma_f32_16x16x32_bf16 v[70:73], v[14:17], v[38:41], v[70:73]
	v_mfma_f32_16x16x32_bf16 v[74:77], v[4:7], v[46:49], v[74:77]
	v_mfma_f32_16x16x32_bf16 v[78:81], v[14:17], v[46:49], v[78:81]
	v_mfma_f32_16x16x32_bf16 v[82:85], v[4:7], v[54:57], v[82:85]
	v_mfma_f32_16x16x32_bf16 v[86:89], v[14:17], v[54:57], v[86:89]
	v_mfma_f32_16x16x32_bf16 v[90:93], v[4:7], v[62:65], v[90:93]
	v_mfma_f32_16x16x32_bf16 v[94:97], v[14:17], v[62:65], v[94:97]
	v_mfma_f32_16x16x32_bf16 v[98:101], v[18:21], v[34:37], 0
	v_mfma_f32_16x16x32_bf16 v[34:37], v[26:29], v[34:37], 0
	v_mfma_f32_16x16x32_bf16 v[98:101], v[22:25], v[38:41], v[98:101]
	v_mfma_f32_16x16x32_bf16 v[34:37], v[30:33], v[38:41], v[34:37]
	v_mfma_f32_16x16x32_bf16 v[38:41], v[18:21], v[42:45], 0
	v_mfma_f32_16x16x32_bf16 v[42:45], v[26:29], v[42:45], 0
	v_mfma_f32_16x16x32_bf16 v[38:41], v[22:25], v[46:49], v[38:41]
	v_mfma_f32_16x16x32_bf16 v[42:45], v[30:33], v[46:49], v[42:45]
	v_mfma_f32_16x16x32_bf16 v[46:49], v[18:21], v[50:53], 0
	v_mfma_f32_16x16x32_bf16 v[50:53], v[26:29], v[50:53], 0
	v_mfma_f32_16x16x32_bf16 v[46:49], v[22:25], v[54:57], v[46:49]
	v_mfma_f32_16x16x32_bf16 v[50:53], v[30:33], v[54:57], v[50:53]
	v_mfma_f32_16x16x32_bf16 v[54:57], v[18:21], v[58:61], 0
	v_mfma_f32_16x16x32_bf16 v[58:61], v[26:29], v[58:61], 0
	v_mfma_f32_16x16x32_bf16 v[54:57], v[22:25], v[62:65], v[54:57]
	v_mfma_f32_16x16x32_bf16 v[58:61], v[30:33], v[62:65], v[58:61]
	s_setprio 0
	s_barrier
	s_add_i32 s39, s15, s20
	v_lshl_add_u64 v[202:203], s[42:43], 0, v[8:9]
	s_mov_b64 s[58:59], 0x100
	s_add_i32 s15, s39, 0x2000
	v_lshl_add_u64 v[138:139], v[202:203], 0, s[58:59]
	s_mov_b32 m0, s39
	v_lshl_add_u64 v[204:205], s[42:43], 0, v[130:131]
	s_add_u32 s56, s42, 0x10100
	ds_read_b128 v[62:65], v137 offset:16384
	ds_read_b128 v[102:105], v137 offset:17408
	ds_read_b128 v[106:109], v137 offset:18432
	ds_read_b128 v[110:113], v137 offset:19456
	ds_read_b128 v[114:117], v137 offset:20480
	ds_read_b128 v[118:121], v137 offset:21504
	ds_read_b128 v[122:125], v137 offset:22528
	ds_read_b128 v[126:129], v137 offset:23552
	global_load_lds_dwordx4 v[138:139], off
	v_lshl_add_u64 v[138:139], v[204:205], 0, s[58:59]
	s_mov_b32 m0, s15
	s_addc_u32 s57, s43, 0
	s_add_i32 s37, s37, s20
	global_load_lds_dwordx4 v[138:139], off
	v_lshl_add_u64 v[138:139], s[56:57], 0, v[8:9]
	s_mov_b32 m0, s37
	s_add_i32 s38, s37, 0x2000
	global_load_lds_dwordx4 v[138:139], off
	v_lshl_add_u64 v[138:139], s[56:57], 0, v[130:131]
	s_mov_b32 m0, s38
	v_lshl_add_u64 v[210:211], s[50:51], 0, v[134:135]
	global_load_lds_dwordx4 v[138:139], off
	v_lshl_add_u64 v[138:139], v[210:211], 0, s[58:59]
	s_mov_b32 m0, s21
	v_lshl_add_u64 v[212:213], s[50:51], 0, v[132:133]
	global_load_lds_dwordx4 v[138:139], off
	v_lshl_add_u64 v[138:139], v[212:213], 0, s[58:59]
	s_mov_b32 m0, s28
	s_nop 0
	global_load_lds_dwordx4 v[138:139], off
	s_waitcnt vmcnt(8)
	s_waitcnt lgkmcnt(0)
	s_barrier
; #define PG8_STAGE(bufoff, gbase, voff) do { _Pragma("unroll") for (int _i = 0; _i < 2; ++_i) \
;         __builtin_amdgcn_global_load_lds((const unsigned*)((const char*)(gbase) + (voff)[_i]), (PG8_LAS unsigned*)(lds + (bufoff) + ldsw + _i * 8192), 16, 0, 0); } while (0)
; #define PG8_LDA(dst, b, h) do { _Pragma("unroll") for (int m = 0; m < 4; ++m) _Pragma("unroll") for (int k = 0; k < 2; ++k) dst[m][k] = *(const PG8_LAS bf16x8*)(lds + PG8_SA(b, h) + aoff + m * 2048 + k * 1024); } while (0)
; #define PG8_LDB(dst, b, h) do { _Pragma("unroll") for (int n = 0; n < 2; ++n) _Pragma("unroll") for (int k = 0; k < 2; ++k) dst[n][k] = *(const PG8_LAS bf16x8*)(lds + PG8_SB(b, h) + boff + n * 2048 + k * 1024); } while (0)
; #define PG8_MMA(ai, bj, At, Bt) do { __builtin_amdgcn_s_setprio(1); _Pragma("unroll") for (int m = 0; m < 4; ++m) _Pragma("unroll") for (int n = 0; n < 2; ++n) _Pragma("unroll") for (int k = 0; k < 2; ++k) \
;         acc[ai][bj][m][n] = __builtin_amdgcn_mfma_f32_16x16x32_bf16(Bt[n][k], At[m][k], acc[ai][bj][m][n], 0, 0, 0); __builtin_amdgcn_s_setprio(0); } while (0)
; #define PG8_WAIT_V(n) asm volatile("s_waitcnt vmcnt(" #n ")" ::: "memory")
; #define PG8_WAIT_L(n) asm volatile("s_waitcnt lgkmcnt(" #n ")" ::: "memory")
; #define PG8_BAR __builtin_amdgcn_s_barrier()
; #define PG8_SCHED __builtin_amdgcn_sched_barrier(0)
; template <class Epi, class Sched, bool ALIGN_EPI = false, bool SP2 = false>
; __device__ __forceinline__ void gemm_phase(PG8_LAS unsigned char* lds, int tid_in, const Gemm g, const Sched& S, const Epi& E) {
;     ...
;             PG8_WAIT_V(8); PG8_WAIT_L(0); PG8_BAR; PG8_MMA(1, 0, At, B0); PG8_MMA(1, 1, At, B1); PG8_BAR; PG8_SCHED;
;             PG8_LDB(B0, 1, 0); PG8_LDB(B1, 1, 1); PG8_SCHED; PG8_LDA(At, 1, 0); PG8_STAGE(PG8_SA(0, 1), a2 + hstep, voffA);
;             PG8_WAIT_V(8); PG8_WAIT_L(0); PG8_BAR; PG8_MMA(0, 0, At, B0); PG8_MMA(0, 1, At, B1); PG8_BAR; PG8_SCHED;
	s_setprio 1
	s_waitcnt lgkmcnt(0)
	v_mfma_f32_16x16x32_bf16 v[138:141], v[0:3], v[62:65], 0
	v_mfma_f32_16x16x32_bf16 v[146:149], v[0:3], v[106:109], 0
	v_mfma_f32_16x16x32_bf16 v[154:157], v[0:3], v[114:117], 0
	v_mfma_f32_16x16x32_bf16 v[0:3], v[0:3], v[122:125], 0
	v_mfma_f32_16x16x32_bf16 v[138:141], v[4:7], v[102:105], v[138:141]
	v_mfma_f32_16x16x32_bf16 v[146:149], v[4:7], v[110:113], v[146:149]
	v_mfma_f32_16x16x32_bf16 v[154:157], v[4:7], v[118:121], v[154:157]
	v_mfma_f32_16x16x32_bf16 v[0:3], v[4:7], v[126:129], v[0:3]
	v_mfma_f32_16x16x32_bf16 v[4:7], v[10:13], v[122:125], 0
	v_mfma_f32_16x16x32_bf16 v[142:145], v[10:13], v[62:65], 0
	v_mfma_f32_16x16x32_bf16 v[150:153], v[10:13], v[106:109], 0
	v_mfma_f32_16x16x32_bf16 v[158:161], v[10:13], v[114:117], 0
	v_mfma_f32_16x16x32_bf16 v[4:7], v[14:17], v[126:129], v[4:7]
	v_mfma_f32_16x16x32_bf16 v[142:145], v[14:17], v[102:105], v[142:145]
	v_mfma_f32_16x16x32_bf16 v[150:153], v[14:17], v[110:113], v[150:153]
	v_mfma_f32_16x16x32_bf16 v[158:161], v[14:17], v[118:121], v[158:161]
	v_mfma_f32_16x16x32_bf16 v[10:13], v[18:21], v[62:65], 0
	v_mfma_f32_16x16x32_bf16 v[14:17], v[26:29], v[62:65], 0
	v_mfma_f32_16x16x32_bf16 v[10:13], v[22:25], v[102:105], v[10:13]
	v_mfma_f32_16x16x32_bf16 v[14:17], v[30:33], v[102:105], v[14:17]
	v_mfma_f32_16x16x32_bf16 v[62:65], v[18:21], v[106:109], 0
	v_mfma_f32_16x16x32_bf16 v[102:105], v[26:29], v[106:109], 0
	v_mfma_f32_16x16x32_bf16 v[106:109], v[18:21], v[114:117], 0
	v_mfma_f32_16x16x32_bf16 v[18:21], v[18:21], v[122:125], 0
	v_mfma_f32_16x16x32_bf16 v[62:65], v[22:25], v[110:113], v[62:65]
	v_mfma_f32_16x16x32_bf16 v[102:105], v[30:33], v[110:113], v[102:105]
	v_mfma_f32_16x16x32_bf16 v[106:109], v[22:25], v[118:121], v[106:109]
	v_mfma_f32_16x16x32_bf16 v[110:113], v[26:29], v[114:117], 0
	v_mfma_f32_16x16x32_bf16 v[18:21], v[22:25], v[126:129], v[18:21]
	v_mfma_f32_16x16x32_bf16 v[22:25], v[26:29], v[122:125], 0
	v_mfma_f32_16x16x32_bf16 v[110:113], v[30:33], v[118:121], v[110:113]
	v_mfma_f32_16x16x32_bf16 v[22:25], v[30:33], v[126:129], v[22:25]
	s_setprio 0
	s_barrier
	s_add_i32 s55, 0, 0x18000
	s_add_i32 s58, 0, 0x1c000
	v_add_u32_e32 v216, s55, v136
	v_add_u32_e32 v217, s58, v136
	ds_read_b128 v[26:29], v216
	ds_read_b128 v[30:33], v216 offset:1024
	ds_read_b128 v[114:117], v216 offset:2048
	ds_read_b128 v[118:121], v216 offset:3072
	ds_read_b128 v[122:125], v217
	ds_read_b128 v[126:129], v217 offset:1024
	ds_read_b128 v[162:165], v217 offset:2048
	ds_read_b128 v[166:169], v217 offset:3072
	s_add_u32 s56, s50, 0x10100
	s_addc_u32 s57, s51, 0
	s_mov_b32 m0, s29
	v_lshl_add_u64 v[214:215], s[56:57], 0, v[134:135]
	ds_read_b128 v[170:173], v137 offset:32768
	ds_read_b128 v[174:177], v137 offset:33792
	ds_read_b128 v[178:181], v137 offset:34816
	ds_read_b128 v[182:185], v137 offset:35840
	ds_read_b128 v[186:189], v137 offset:36864
	ds_read_b128 v[190:193], v137 offset:37888
	ds_read_b128 v[194:197], v137 offset:38912
	ds_read_b128 v[198:201], v137 offset:39936
	global_load_lds_dwordx4 v[214:215], off
	v_lshl_add_u64 v[214:215], s[56:57], 0, v[132:133]
	s_mov_b32 m0, s33
	s_nop 0
	global_load_lds_dwordx4 v[214:215], off
	s_waitcnt vmcnt(8)
	s_waitcnt lgkmcnt(0)
	s_barrier
	s_setprio 1
	s_waitcnt lgkmcnt(0)
	v_mfma_f32_16x16x32_bf16 v[66:69], v[26:29], v[170:173], v[66:69]
	v_mfma_f32_16x16x32_bf16 v[70:73], v[114:117], v[170:173], v[70:73]
	v_mfma_f32_16x16x32_bf16 v[74:77], v[26:29], v[178:181], v[74:77]
	v_mfma_f32_16x16x32_bf16 v[78:81], v[114:117], v[178:181], v[78:81]
	v_mfma_f32_16x16x32_bf16 v[82:85], v[26:29], v[186:189], v[82:85]
	v_mfma_f32_16x16x32_bf16 v[86:89], v[114:117], v[186:189], v[86:89]
	v_mfma_f32_16x16x32_bf16 v[90:93], v[26:29], v[194:197], v[90:93]
	v_mfma_f32_16x16x32_bf16 v[94:97], v[114:117], v[194:197], v[94:97]
	v_mfma_f32_16x16x32_bf16 v[66:69], v[30:33], v[174:177], v[66:69]
	v_mfma_f32_16x16x32_bf16 v[70:73], v[118:121], v[174:177], v[70:73]
	v_mfma_f32_16x16x32_bf16 v[74:77], v[30:33], v[182:185], v[74:77]
	v_mfma_f32_16x16x32_bf16 v[78:81], v[118:121], v[182:185], v[78:81]
	v_mfma_f32_16x16x32_bf16 v[82:85], v[30:33], v[190:193], v[82:85]
	v_mfma_f32_16x16x32_bf16 v[86:89], v[118:121], v[190:193], v[86:89]
	v_mfma_f32_16x16x32_bf16 v[90:93], v[30:33], v[198:201], v[90:93]
	v_mfma_f32_16x16x32_bf16 v[94:97], v[118:121], v[198:201], v[94:97]
	v_mfma_f32_16x16x32_bf16 v[98:101], v[122:125], v[170:173], v[98:101]
	v_mfma_f32_16x16x32_bf16 v[34:37], v[162:165], v[170:173], v[34:37]
	v_mfma_f32_16x16x32_bf16 v[38:41], v[122:125], v[178:181], v[38:41]
	v_mfma_f32_16x16x32_bf16 v[42:45], v[162:165], v[178:181], v[42:45]
	v_mfma_f32_16x16x32_bf16 v[46:49], v[122:125], v[186:189], v[46:49]
	v_mfma_f32_16x16x32_bf16 v[50:53], v[162:165], v[186:189], v[50:53]
	v_mfma_f32_16x16x32_bf16 v[54:57], v[122:125], v[194:197], v[54:57]
	v_mfma_f32_16x16x32_bf16 v[58:61], v[162:165], v[194:197], v[58:61]
	v_mfma_f32_16x16x32_bf16 v[98:101], v[126:129], v[174:177], v[98:101]
	v_mfma_f32_16x16x32_bf16 v[34:37], v[166:169], v[174:177], v[34:37]
	v_mfma_f32_16x16x32_bf16 v[38:41], v[126:129], v[182:185], v[38:41]
	v_mfma_f32_16x16x32_bf16 v[42:45], v[166:169], v[182:185], v[42:45]
	v_mfma_f32_16x16x32_bf16 v[46:49], v[126:129], v[190:193], v[46:49]
	v_mfma_f32_16x16x32_bf16 v[50:53], v[166:169], v[190:193], v[50:53]
	v_mfma_f32_16x16x32_bf16 v[54:57], v[126:129], v[198:201], v[54:57]
	v_mfma_f32_16x16x32_bf16 v[58:61], v[166:169], v[198:201], v[58:61]
	s_setprio 0
	s_barrier
; #define PG8_STAGE(bufoff, gbase, voff) do { _Pragma("unroll") for (int _i = 0; _i < 2; ++_i) \
;         __builtin_amdgcn_global_load_lds((const unsigned*)((const char*)(gbase) + (voff)[_i]), (PG8_LAS unsigned*)(lds + (bufoff) + ldsw + _i * 8192), 16, 0, 0); } while (0)
; #define PG8_LDA(dst, b, h) do { _Pragma("unroll") for (int m = 0; m < 4; ++m) _Pragma("unroll") for (int k = 0; k < 2; ++k) dst[m][k] = *(const PG8_LAS bf16x8*)(lds + PG8_SA(b, h) + aoff + m * 2048 + k * 1024); } while (0)
; #define PG8_LDB(dst, b, h) do { _Pragma("unroll") for (int n = 0; n < 2; ++n) _Pragma("unroll") for (int k = 0; k < 2; ++k) dst[n][k] = *(const PG8_LAS bf16x8*)(lds + PG8_SB(b, h) + boff + n * 2048 + k * 1024); } while (0)
; #define PG8_MMA(ai, bj, At, Bt) do { __builtin_amdgcn_s_setprio(1); _Pragma("unroll") for (int m = 0; m < 4; ++m) _Pragma("unroll") for (int n = 0; n < 2; ++n) _Pragma("unroll") for (int k = 0; k < 2; ++k) \
;         acc[ai][bj][m][n] = __builtin_amdgcn_mfma_f32_16x16x32_bf16(Bt[n][k], At[m][k], acc[ai][bj][m][n], 0, 0, 0); __builtin_amdgcn_s_setprio(0); } while (0)
; #define PG8_BAR __builtin_amdgcn_s_barrier()
; template <class Epi, class Sched, bool ALIGN_EPI = false, bool SP2 = false>
; __device__ __forceinline__ void gemm_phase(PG8_LAS unsigned char* lds, int tid_in, const Gemm g, const Sched& S, const Epi& E) {
;     ...
;             PG8_LDB(B0, 0, 0); PG8_LDB(B1, 0, 1); PG8_SCHED; PG8_LDA(At, 0, 0); PG8_STAGE(PG8_SA(1, 1), a1 + hstep, voffA);
;             PG8_WAIT_V(8); PG8_WAIT_L(0); PG8_BAR; PG8_MMA(0, 0, At, B0); PG8_MMA(0, 1, At, B1); PG8_BAR; PG8_SCHED;
;             PG8_LDA(At, 0, 1); PG8_STAGE(PG8_SB(0, 0), b2, voffB); PG8_STAGE(PG8_SB(0, 1), b2 + hstep, voffB); PG8_STAGE(PG8_SA(0, 0), a2, voffA);
;             PG8_WAIT_V(8); PG8_WAIT_L(0); PG8_BAR; PG8_MMA(1, 0, At, B0); PG8_MMA(1, 1, At, B1); PG8_BAR; PG8_SCHED;
;             PG8_LDB(B0, 1, 0); PG8_LDB(B1, 1, 1); PG8_SCHED; PG8_LDA(At, 1, 0); PG8_STAGE(PG8_SA(0, 1), a2 + hstep, voffA);
;             PG8_WAIT_V(8); PG8_WAIT_L(0); PG8_BAR; PG8_MMA(0, 0, At, B0); PG8_MMA(0, 1, At, B1); PG8_BAR; PG8_SCHED;
;             PG8_LDA(At, 1, 1); PG8_STAGE(PG8_SB(1, 0), b3, voffB); PG8_STAGE(PG8_SB(1, 1), b3 + hstep, voffB); PG8_STAGE(PG8_SA(1, 0), a3, voffA);
;             PG8_WAIT_V(8); PG8_WAIT_L(0); PG8_BAR; PG8_MMA(1, 0, At, B0); PG8_MMA(1, 1, At, B1); PG8_BAR; PG8_SCHED;
	s_add_i32 s55, s55, s20
	s_mov_b64 s[60:61], 0x180
	s_add_i32 s47, s55, 0x2000
	v_lshl_add_u64 v[202:203], v[202:203], 0, s[60:61]
	s_mov_b32 m0, s55
	s_add_u32 s56, s42, 0x10180
	ds_read_b128 v[170:173], v137 offset:49152
	ds_read_b128 v[174:177], v137 offset:50176
	ds_read_b128 v[178:181], v137 offset:51200
	ds_read_b128 v[182:185], v137 offset:52224
	ds_read_b128 v[186:189], v137 offset:53248
	ds_read_b128 v[190:193], v137 offset:54272
	ds_read_b128 v[194:197], v137 offset:55296
	ds_read_b128 v[198:201], v137 offset:56320
	global_load_lds_dwordx4 v[202:203], off
	v_lshl_add_u64 v[202:203], v[204:205], 0, s[60:61]
	s_mov_b32 m0, s47
	s_addc_u32 s57, s43, 0
	s_add_i32 s42, s58, s20
	global_load_lds_dwordx4 v[202:203], off
	v_lshl_add_u64 v[202:203], s[56:57], 0, v[8:9]
	s_mov_b32 m0, s42
	s_add_i32 s43, s42, 0x2000
	global_load_lds_dwordx4 v[202:203], off
	v_lshl_add_u64 v[202:203], s[56:57], 0, v[130:131]
	s_mov_b32 m0, s43
	s_nop 0
	global_load_lds_dwordx4 v[202:203], off
	v_lshl_add_u64 v[202:203], v[210:211], 0, s[60:61]
	s_mov_b32 m0, s45
	s_nop 0
	global_load_lds_dwordx4 v[202:203], off
	v_lshl_add_u64 v[202:203], v[212:213], 0, s[60:61]
	s_mov_b32 m0, s46
	s_nop 0
	global_load_lds_dwordx4 v[202:203], off
	s_waitcnt vmcnt(8)
	s_waitcnt lgkmcnt(0)
	s_barrier
	s_setprio 1
	s_waitcnt lgkmcnt(0)
	v_mfma_f32_16x16x32_bf16 v[0:3], v[26:29], v[194:197], v[0:3]
	v_mfma_f32_16x16x32_bf16 v[4:7], v[114:117], v[194:197], v[4:7]
	v_mfma_f32_16x16x32_bf16 v[138:141], v[26:29], v[170:173], v[138:141]
	v_mfma_f32_16x16x32_bf16 v[142:145], v[114:117], v[170:173], v[142:145]
	v_mfma_f32_16x16x32_bf16 v[146:149], v[26:29], v[178:181], v[146:149]
	v_mfma_f32_16x16x32_bf16 v[150:153], v[114:117], v[178:181], v[150:153]
	v_mfma_f32_16x16x32_bf16 v[154:157], v[26:29], v[186:189], v[154:157]
	v_mfma_f32_16x16x32_bf16 v[158:161], v[114:117], v[186:189], v[158:161]
	v_mfma_f32_16x16x32_bf16 v[0:3], v[30:33], v[198:201], v[0:3]
	v_mfma_f32_16x16x32_bf16 v[4:7], v[118:121], v[198:201], v[4:7]
	v_mfma_f32_16x16x32_bf16 v[138:141], v[30:33], v[174:177], v[138:141]
	v_mfma_f32_16x16x32_bf16 v[142:145], v[118:121], v[174:177], v[142:145]
	v_mfma_f32_16x16x32_bf16 v[146:149], v[30:33], v[182:185], v[146:149]
	v_mfma_f32_16x16x32_bf16 v[150:153], v[118:121], v[182:185], v[150:153]
	v_mfma_f32_16x16x32_bf16 v[154:157], v[30:33], v[190:193], v[154:157]
	v_mfma_f32_16x16x32_bf16 v[158:161], v[118:121], v[190:193], v[158:161]
	v_mfma_f32_16x16x32_bf16 v[10:13], v[122:125], v[170:173], v[10:13]
	v_mfma_f32_16x16x32_bf16 v[14:17], v[162:165], v[170:173], v[14:17]
	v_mfma_f32_16x16x32_bf16 v[26:29], v[122:125], v[178:181], v[62:65]
	v_mfma_f32_16x16x32_bf16 v[30:33], v[162:165], v[178:181], v[102:105]
	v_mfma_f32_16x16x32_bf16 v[62:65], v[122:125], v[186:189], v[106:109]
	v_mfma_f32_16x16x32_bf16 v[102:105], v[162:165], v[186:189], v[110:113]
	v_mfma_f32_16x16x32_bf16 v[18:21], v[122:125], v[194:197], v[18:21]
	v_mfma_f32_16x16x32_bf16 v[22:25], v[162:165], v[194:197], v[22:25]
	v_mfma_f32_16x16x32_bf16 v[10:13], v[126:129], v[174:177], v[10:13]
	v_mfma_f32_16x16x32_bf16 v[14:17], v[166:169], v[174:177], v[14:17]
	v_mfma_f32_16x16x32_bf16 v[26:29], v[126:129], v[182:185], v[26:29]
	v_mfma_f32_16x16x32_bf16 v[30:33], v[166:169], v[182:185], v[30:33]
	v_mfma_f32_16x16x32_bf16 v[62:65], v[126:129], v[190:193], v[62:65]
	v_mfma_f32_16x16x32_bf16 v[102:105], v[166:169], v[190:193], v[102:105]
	v_mfma_f32_16x16x32_bf16 v[18:21], v[126:129], v[198:201], v[18:21]
	v_mfma_f32_16x16x32_bf16 v[22:25], v[166:169], v[198:201], v[22:25]
	s_setprio 0
	s_barrier
	ds_read_b128 v[106:109], v206
	ds_read_b128 v[110:113], v206 offset:1024
	ds_read_b128 v[114:117], v206 offset:2048
	ds_read_b128 v[118:121], v206 offset:3072
	ds_read_b128 v[122:125], v207
	ds_read_b128 v[126:129], v207 offset:1024
	ds_read_b128 v[162:165], v207 offset:2048
	ds_read_b128 v[166:169], v207 offset:3072
	s_add_u32 s50, s50, 0x10180
	s_addc_u32 s51, s51, 0
	s_mov_b32 m0, s53
	v_lshl_add_u64 v[202:203], s[50:51], 0, v[134:135]
	ds_read_b128 v[170:173], v137
	ds_read_b128 v[174:177], v137 offset:1024
	ds_read_b128 v[178:181], v137 offset:2048
	ds_read_b128 v[182:185], v137 offset:3072
	ds_read_b128 v[186:189], v137 offset:4096
	ds_read_b128 v[190:193], v137 offset:5120
	ds_read_b128 v[194:197], v137 offset:6144
	ds_read_b128 v[198:201], v137 offset:7168
	global_load_lds_dwordx4 v[202:203], off
	v_lshl_add_u64 v[202:203], s[50:51], 0, v[132:133]
	s_mov_b32 m0, s13
	s_nop 0
	global_load_lds_dwordx4 v[202:203], off
	s_waitcnt vmcnt(8)
	s_waitcnt lgkmcnt(0)
	s_barrier
; #define PG8_STAGE(bufoff, gbase, voff) do { _Pragma("unroll") for (int _i = 0; _i < 2; ++_i) \
;         __builtin_amdgcn_global_load_lds((const unsigned*)((const char*)(gbase) + (voff)[_i]), (PG8_LAS unsigned*)(lds + (bufoff) + ldsw + _i * 8192), 16, 0, 0); } while (0)
; #define PG8_LDA(dst, b, h) do { _Pragma("unroll") for (int m = 0; m < 4; ++m) _Pragma("unroll") for (int k = 0; k < 2; ++k) dst[m][k] = *(const PG8_LAS bf16x8*)(lds + PG8_SA(b, h) + aoff + m * 2048 + k * 1024); } while (0)
; #define PG8_MMA(ai, bj, At, Bt) do { __builtin_amdgcn_s_setprio(1); _Pragma("unroll") for (int m = 0; m < 4; ++m) _Pragma("unroll") for (int n = 0; n < 2; ++n) _Pragma("unroll") for (int k = 0; k < 2; ++k) \
;         acc[ai][bj][m][n] = __builtin_amdgcn_mfma_f32_16x16x32_bf16(Bt[n][k], At[m][k], acc[ai][bj][m][n], 0, 0, 0); __builtin_amdgcn_s_setprio(0); } while (0)
; #define PG8_WAIT_V(n) asm volatile("s_waitcnt vmcnt(" #n ")" ::: "memory")
; #define PG8_WAIT_L(n) asm volatile("s_waitcnt lgkmcnt(" #n ")" ::: "memory")
; #define PG8_BAR __builtin_amdgcn_s_barrier()
; #define PG8_SCHED __builtin_amdgcn_sched_barrier(0)
; template <class Epi, class Sched, bool ALIGN_EPI = false, bool SP2 = false>
; __device__ __forceinline__ void gemm_phase(PG8_LAS unsigned char* lds, int tid_in, const Gemm g, const Sched& S, const Epi& E) {
;     ...
;             PG8_WAIT_V(8); PG8_WAIT_L(0); PG8_BAR; PG8_MMA(0, 0, At, B0); PG8_MMA(0, 1, At, B1); PG8_BAR; PG8_SCHED;
;             PG8_LDA(At, 0, 1); PG8_STAGE(PG8_SB(0, 0), b2, voffB); PG8_STAGE(PG8_SB(0, 1), b2 + hstep, voffB); PG8_STAGE(PG8_SA(0, 0), a2, voffA);
;             PG8_WAIT_V(8); PG8_WAIT_L(0); PG8_BAR; PG8_MMA(1, 0, At, B0); PG8_MMA(1, 1, At, B1); PG8_BAR; PG8_SCHED;
	s_setprio 1
	s_waitcnt lgkmcnt(0)
	v_mfma_f32_16x16x32_bf16 v[66:69], v[106:109], v[170:173], v[66:69]
	v_mfma_f32_16x16x32_bf16 v[70:73], v[114:117], v[170:173], v[70:73]
	v_mfma_f32_16x16x32_bf16 v[74:77], v[106:109], v[178:181], v[74:77]
	v_mfma_f32_16x16x32_bf16 v[78:81], v[114:117], v[178:181], v[78:81]
	v_mfma_f32_16x16x32_bf16 v[82:85], v[106:109], v[186:189], v[82:85]
	v_mfma_f32_16x16x32_bf16 v[86:89], v[114:117], v[186:189], v[86:89]
	v_mfma_f32_16x16x32_bf16 v[90:93], v[106:109], v[194:197], v[90:93]
	v_mfma_f32_16x16x32_bf16 v[66:69], v[110:113], v[174:177], v[66:69]
	v_mfma_f32_16x16x32_bf16 v[70:73], v[118:121], v[174:177], v[70:73]
	v_mfma_f32_16x16x32_bf16 v[74:77], v[110:113], v[182:185], v[74:77]
	v_mfma_f32_16x16x32_bf16 v[78:81], v[118:121], v[182:185], v[78:81]
	v_mfma_f32_16x16x32_bf16 v[82:85], v[110:113], v[190:193], v[82:85]
	v_mfma_f32_16x16x32_bf16 v[86:89], v[118:121], v[190:193], v[86:89]
	v_mfma_f32_16x16x32_bf16 v[90:93], v[110:113], v[198:201], v[90:93]
	v_mfma_f32_16x16x32_bf16 v[94:97], v[114:117], v[194:197], v[94:97]
	v_mfma_f32_16x16x32_bf16 v[202:205], v[118:121], v[198:201], v[94:97]
	v_mfma_f32_16x16x32_bf16 v[94:97], v[122:125], v[170:173], v[98:101]
	v_mfma_f32_16x16x32_bf16 v[34:37], v[162:165], v[170:173], v[34:37]
	v_mfma_f32_16x16x32_bf16 v[38:41], v[122:125], v[178:181], v[38:41]
	v_mfma_f32_16x16x32_bf16 v[42:45], v[162:165], v[178:181], v[42:45]
	v_mfma_f32_16x16x32_bf16 v[46:49], v[122:125], v[186:189], v[46:49]
	v_mfma_f32_16x16x32_bf16 v[50:53], v[162:165], v[186:189], v[50:53]
	v_mfma_f32_16x16x32_bf16 v[54:57], v[122:125], v[194:197], v[54:57]
	v_mfma_f32_16x16x32_bf16 v[98:101], v[126:129], v[174:177], v[94:97]
	v_mfma_f32_16x16x32_bf16 v[34:37], v[166:169], v[174:177], v[34:37]
	v_mfma_f32_16x16x32_bf16 v[38:41], v[126:129], v[182:185], v[38:41]
	v_mfma_f32_16x16x32_bf16 v[42:45], v[166:169], v[182:185], v[42:45]
	v_mfma_f32_16x16x32_bf16 v[46:49], v[126:129], v[190:193], v[46:49]
	v_mfma_f32_16x16x32_bf16 v[50:53], v[166:169], v[190:193], v[50:53]
	v_mfma_f32_16x16x32_bf16 v[54:57], v[126:129], v[198:201], v[54:57]
	v_mfma_f32_16x16x32_bf16 v[58:61], v[162:165], v[194:197], v[58:61]
	v_mfma_f32_16x16x32_bf16 v[170:173], v[166:169], v[198:201], v[58:61]
	s_setprio 0
	s_barrier
	s_mov_b32 m0, s39
	v_lshl_add_u64 v[242:243], s[34:35], 0, v[8:9]
	s_add_u32 s50, s34, 0x10000
	s_nop 1
	ds_read_b128 v[58:61], v137 offset:16384
	ds_read_b128 v[94:97], v137 offset:17408
	ds_read_b128 v[174:177], v137 offset:18432
	ds_read_b128 v[178:181], v137 offset:19456
	ds_read_b128 v[182:185], v137 offset:20480
	ds_read_b128 v[186:189], v137 offset:21504
	ds_read_b128 v[190:193], v137 offset:22528
	ds_read_b128 v[194:197], v137 offset:23552
	global_load_lds_dwordx4 v[242:243], off
	v_lshl_add_u64 v[208:209], s[34:35], 0, v[130:131]
	s_mov_b32 m0, s15
	s_addc_u32 s51, s35, 0
	global_load_lds_dwordx4 v[208:209], off
	v_lshl_add_u64 v[198:199], s[50:51], 0, v[8:9]
	s_mov_b32 m0, s37
	v_lshl_add_u64 v[244:245], s[48:49], 0, v[134:135]
	global_load_lds_dwordx4 v[198:199], off
	v_lshl_add_u64 v[198:199], s[50:51], 0, v[130:131]
	s_mov_b32 m0, s38
	v_lshl_add_u64 v[206:207], s[48:49], 0, v[132:133]
	global_load_lds_dwordx4 v[198:199], off
	s_mov_b32 m0, s21
	s_nop 0
	global_load_lds_dwordx4 v[244:245], off
	s_mov_b32 m0, s28
	s_nop 0
	global_load_lds_dwordx4 v[206:207], off
	s_waitcnt vmcnt(8)
	s_waitcnt lgkmcnt(0)
	s_barrier
	s_setprio 1
	s_waitcnt lgkmcnt(0)
	v_mfma_f32_16x16x32_bf16 v[0:3], v[106:109], v[190:193], v[0:3]
	v_mfma_f32_16x16x32_bf16 v[4:7], v[114:117], v[190:193], v[4:7]
	v_mfma_f32_16x16x32_bf16 v[138:141], v[106:109], v[58:61], v[138:141]
	v_mfma_f32_16x16x32_bf16 v[142:145], v[114:117], v[58:61], v[142:145]
	v_mfma_f32_16x16x32_bf16 v[146:149], v[106:109], v[174:177], v[146:149]
	v_mfma_f32_16x16x32_bf16 v[150:153], v[114:117], v[174:177], v[150:153]
	v_mfma_f32_16x16x32_bf16 v[154:157], v[106:109], v[182:185], v[154:157]
	v_mfma_f32_16x16x32_bf16 v[158:161], v[114:117], v[182:185], v[158:161]
	v_mfma_f32_16x16x32_bf16 v[0:3], v[110:113], v[194:197], v[0:3]
	v_mfma_f32_16x16x32_bf16 v[4:7], v[118:121], v[194:197], v[4:7]
	v_mfma_f32_16x16x32_bf16 v[138:141], v[110:113], v[94:97], v[138:141]
	v_mfma_f32_16x16x32_bf16 v[142:145], v[118:121], v[94:97], v[142:145]
	v_mfma_f32_16x16x32_bf16 v[146:149], v[110:113], v[178:181], v[146:149]
	v_mfma_f32_16x16x32_bf16 v[150:153], v[118:121], v[178:181], v[150:153]
	v_mfma_f32_16x16x32_bf16 v[154:157], v[110:113], v[186:189], v[154:157]
	v_mfma_f32_16x16x32_bf16 v[158:161], v[118:121], v[186:189], v[158:161]
	v_mfma_f32_16x16x32_bf16 v[10:13], v[122:125], v[58:61], v[10:13]
	v_mfma_f32_16x16x32_bf16 v[198:201], v[126:129], v[94:97], v[10:13]
	v_mfma_f32_16x16x32_bf16 v[10:13], v[162:165], v[58:61], v[14:17]
	v_mfma_f32_16x16x32_bf16 v[218:221], v[166:169], v[94:97], v[10:13]
	v_mfma_f32_16x16x32_bf16 v[10:13], v[122:125], v[174:177], v[26:29]
	v_mfma_f32_16x16x32_bf16 v[222:225], v[126:129], v[178:181], v[10:13]
	v_mfma_f32_16x16x32_bf16 v[10:13], v[162:165], v[174:177], v[30:33]
	v_mfma_f32_16x16x32_bf16 v[174:177], v[166:169], v[178:181], v[10:13]
	v_mfma_f32_16x16x32_bf16 v[10:13], v[122:125], v[182:185], v[62:65]
	v_mfma_f32_16x16x32_bf16 v[178:181], v[126:129], v[186:189], v[10:13]
	v_mfma_f32_16x16x32_bf16 v[10:13], v[162:165], v[182:185], v[102:105]
	v_mfma_f32_16x16x32_bf16 v[182:185], v[166:169], v[186:189], v[10:13]
	v_mfma_f32_16x16x32_bf16 v[10:13], v[122:125], v[190:193], v[18:21]
	v_mfma_f32_16x16x32_bf16 v[186:189], v[126:129], v[194:197], v[10:13]
	v_mfma_f32_16x16x32_bf16 v[10:13], v[162:165], v[190:193], v[22:25]
	v_mfma_f32_16x16x32_bf16 v[162:165], v[166:169], v[194:197], v[10:13]
	s_setprio 0
	s_barrier
; #define PG8_STAGE(bufoff, gbase, voff) do { _Pragma("unroll") for (int _i = 0; _i < 2; ++_i) \
;         __builtin_amdgcn_global_load_lds((const unsigned*)((const char*)(gbase) + (voff)[_i]), (PG8_LAS unsigned*)(lds + (bufoff) + ldsw + _i * 8192), 16, 0, 0); } while (0)
; #define PG8_LDA(dst, b, h) do { _Pragma("unroll") for (int m = 0; m < 4; ++m) _Pragma("unroll") for (int k = 0; k < 2; ++k) dst[m][k] = *(const PG8_LAS bf16x8*)(lds + PG8_SA(b, h) + aoff + m * 2048 + k * 1024); } while (0)
; #define PG8_LDB(dst, b, h) do { _Pragma("unroll") for (int n = 0; n < 2; ++n) _Pragma("unroll") for (int k = 0; k < 2; ++k) dst[n][k] = *(const PG8_LAS bf16x8*)(lds + PG8_SB(b, h) + boff + n * 2048 + k * 1024); } while (0)
; #define PG8_MMA(ai, bj, At, Bt) do { __builtin_amdgcn_s_setprio(1); _Pragma("unroll") for (int m = 0; m < 4; ++m) _Pragma("unroll") for (int n = 0; n < 2; ++n) _Pragma("unroll") for (int k = 0; k < 2; ++k) \
;         acc[ai][bj][m][n] = __builtin_amdgcn_mfma_f32_16x16x32_bf16(Bt[n][k], At[m][k], acc[ai][bj][m][n], 0, 0, 0); __builtin_amdgcn_s_setprio(0); } while (0)
; #define PG8_WAIT_V(n) asm volatile("s_waitcnt vmcnt(" #n ")" ::: "memory")
; #define PG8_WAIT_L(n) asm volatile("s_waitcnt lgkmcnt(" #n ")" ::: "memory")
; #define PG8_BAR __builtin_amdgcn_s_barrier()
; #define PG8_SCHED __builtin_amdgcn_sched_barrier(0)
; template <class Epi, class Sched, bool ALIGN_EPI = false, bool SP2 = false>
; __device__ __forceinline__ void gemm_phase(PG8_LAS unsigned char* lds, int tid_in, const Gemm g, const Sched& S, const Epi& E) {
;     ...
;             PG8_LDB(B0, 1, 0); PG8_LDB(B1, 1, 1); PG8_SCHED; PG8_LDA(At, 1, 0); PG8_STAGE(PG8_SA(0, 1), a2 + hstep, voffA);
;             PG8_WAIT_V(8); PG8_WAIT_L(0); PG8_BAR; PG8_MMA(0, 0, At, B0); PG8_MMA(0, 1, At, B1); PG8_BAR; PG8_SCHED;
;             PG8_LDA(At, 1, 1); PG8_STAGE(PG8_SB(1, 0), b3, voffB); PG8_STAGE(PG8_SB(1, 1), b3 + hstep, voffB); PG8_STAGE(PG8_SA(1, 0), a3, voffA);
;             PG8_WAIT_V(8); PG8_WAIT_L(0); PG8_BAR; PG8_MMA(1, 0, At, B0); PG8_MMA(1, 1, At, B1); PG8_BAR; PG8_SCHED;
;     ...
;         if constexpr (ALIGN_EPI) { if (wr == 0) PG8_BAR; }
	s_nop 4
	ds_read_b128 v[10:13], v216
	ds_read_b128 v[14:17], v216 offset:1024
	ds_read_b128 v[18:21], v216 offset:2048
	ds_read_b128 v[22:25], v216 offset:3072
	ds_read_b128 v[166:169], v217
	ds_read_b128 v[190:193], v217 offset:1024
	ds_read_b128 v[194:197], v217 offset:2048
	ds_read_b128 v[226:229], v217 offset:3072
	s_add_u32 s38, s48, 0x10000
	s_addc_u32 s39, s49, 0
	s_mov_b32 m0, s29
	v_lshl_add_u64 v[58:59], s[38:39], 0, v[134:135]
	ds_read_b128 v[26:29], v137 offset:32768
	ds_read_b128 v[30:33], v137 offset:33792
	ds_read_b128 v[230:233], v137 offset:34816
	ds_read_b128 v[234:237], v137 offset:35840
	ds_read_b128 v[238:241], v137 offset:36864
	ds_read_b128 v[248:251], v137 offset:37888
	ds_read_b128 v[210:213], v137 offset:38912
	ds_read_b128 v[214:217], v137 offset:39936
	global_load_lds_dwordx4 v[58:59], off
	v_lshl_add_u64 v[58:59], s[38:39], 0, v[132:133]
	s_mov_b32 m0, s33
	s_nop 0
	global_load_lds_dwordx4 v[58:59], off
	s_waitcnt vmcnt(8)
	s_waitcnt lgkmcnt(0)
	s_barrier
	s_setprio 1
	s_waitcnt lgkmcnt(0)
	v_mfma_f32_16x16x32_bf16 v[58:61], v[10:13], v[26:29], v[66:69]
	v_mfma_f32_16x16x32_bf16 v[126:129], v[14:17], v[30:33], v[58:61]
	v_mfma_f32_16x16x32_bf16 v[58:61], v[18:21], v[26:29], v[70:73]
	v_mfma_f32_16x16x32_bf16 v[122:125], v[22:25], v[30:33], v[58:61]
	v_mfma_f32_16x16x32_bf16 v[58:61], v[10:13], v[230:233], v[74:77]
	v_mfma_f32_16x16x32_bf16 v[110:113], v[14:17], v[234:237], v[58:61]
	v_mfma_f32_16x16x32_bf16 v[58:61], v[18:21], v[230:233], v[78:81]
	v_mfma_f32_16x16x32_bf16 v[102:105], v[22:25], v[234:237], v[58:61]
	v_mfma_f32_16x16x32_bf16 v[58:61], v[10:13], v[238:241], v[82:85]
	v_mfma_f32_16x16x32_bf16 v[94:97], v[14:17], v[248:251], v[58:61]
	v_mfma_f32_16x16x32_bf16 v[58:61], v[18:21], v[238:241], v[86:89]
	v_mfma_f32_16x16x32_bf16 v[86:89], v[22:25], v[248:251], v[58:61]
	v_mfma_f32_16x16x32_bf16 v[58:61], v[10:13], v[210:213], v[90:93]
	v_mfma_f32_16x16x32_bf16 v[62:65], v[14:17], v[214:217], v[58:61]
	v_mfma_f32_16x16x32_bf16 v[58:61], v[18:21], v[210:213], v[202:205]
	v_mfma_f32_16x16x32_bf16 v[58:61], v[22:25], v[214:217], v[58:61]
	v_mfma_f32_16x16x32_bf16 v[66:69], v[166:169], v[26:29], v[98:101]
	v_mfma_f32_16x16x32_bf16 v[26:29], v[194:197], v[26:29], v[34:37]
	v_mfma_f32_16x16x32_bf16 v[114:117], v[226:229], v[30:33], v[26:29]
	v_mfma_f32_16x16x32_bf16 v[26:29], v[166:169], v[230:233], v[38:41]
	v_mfma_f32_16x16x32_bf16 v[106:109], v[190:193], v[234:237], v[26:29]
	v_mfma_f32_16x16x32_bf16 v[26:29], v[194:197], v[230:233], v[42:45]
	v_mfma_f32_16x16x32_bf16 v[98:101], v[226:229], v[234:237], v[26:29]
	v_mfma_f32_16x16x32_bf16 v[26:29], v[166:169], v[238:241], v[46:49]
	v_mfma_f32_16x16x32_bf16 v[90:93], v[190:193], v[248:251], v[26:29]
	v_mfma_f32_16x16x32_bf16 v[26:29], v[194:197], v[238:241], v[50:53]
	v_mfma_f32_16x16x32_bf16 v[82:85], v[226:229], v[248:251], v[26:29]
	v_mfma_f32_16x16x32_bf16 v[26:29], v[166:169], v[210:213], v[54:57]
	v_mfma_f32_16x16x32_bf16 v[54:57], v[190:193], v[214:217], v[26:29]
	v_mfma_f32_16x16x32_bf16 v[26:29], v[194:197], v[210:213], v[170:173]
	v_mfma_f32_16x16x32_bf16 v[118:121], v[190:193], v[30:33], v[66:69]
	v_mfma_f32_16x16x32_bf16 v[50:53], v[226:229], v[214:217], v[26:29]
	s_setprio 0
	s_barrier
	s_mov_b32 m0, s55
	s_nop 2
	v_lshl_add_u64 v[26:27], v[242:243], 0, s[24:25]
	s_add_u32 s34, s34, 0x10080
	ds_read_b128 v[34:37], v137 offset:49152
	ds_read_b128 v[38:41], v137 offset:50176
	ds_read_b128 v[170:173], v137 offset:51200
	ds_read_b128 v[202:205], v137 offset:52224
	ds_read_b128 v[210:213], v137 offset:53248
	ds_read_b128 v[214:217], v137 offset:54272
	ds_read_b128 v[230:233], v137 offset:55296
	ds_read_b128 v[234:237], v137 offset:56320
	global_load_lds_dwordx4 v[26:27], off
	v_lshl_add_u64 v[26:27], v[208:209], 0, s[24:25]
	s_mov_b32 m0, s47
	s_addc_u32 s35, s35, 0
	global_load_lds_dwordx4 v[26:27], off
	v_lshl_add_u64 v[26:27], s[34:35], 0, v[8:9]
	s_mov_b32 m0, s42
	s_nop 0
	global_load_lds_dwordx4 v[26:27], off
	v_lshl_add_u64 v[26:27], s[34:35], 0, v[130:131]
	s_mov_b32 m0, s43
	s_nop 0
	global_load_lds_dwordx4 v[26:27], off
	v_lshl_add_u64 v[26:27], v[244:245], 0, s[24:25]
	s_mov_b32 m0, s45
	s_nop 0
	global_load_lds_dwordx4 v[26:27], off
	v_lshl_add_u64 v[26:27], v[206:207], 0, s[24:25]
	s_mov_b32 m0, s46
	s_nop 0
	global_load_lds_dwordx4 v[26:27], off
	s_waitcnt vmcnt(8)
	s_waitcnt lgkmcnt(0)
	s_barrier
	s_setprio 1
	s_waitcnt lgkmcnt(0)
	v_mfma_f32_16x16x32_bf16 v[26:29], v[10:13], v[34:37], v[138:141]
	v_mfma_f32_16x16x32_bf16 v[78:81], v[14:17], v[38:41], v[26:29]
	v_mfma_f32_16x16x32_bf16 v[26:29], v[18:21], v[34:37], v[142:145]
	v_mfma_f32_16x16x32_bf16 v[74:77], v[22:25], v[38:41], v[26:29]
	v_mfma_f32_16x16x32_bf16 v[26:29], v[10:13], v[170:173], v[146:149]
	v_mfma_f32_16x16x32_bf16 v[46:49], v[14:17], v[202:205], v[26:29]
	v_mfma_f32_16x16x32_bf16 v[26:29], v[18:21], v[170:173], v[150:153]
	v_mfma_f32_16x16x32_bf16 v[42:45], v[22:25], v[202:205], v[26:29]
	v_mfma_f32_16x16x32_bf16 v[26:29], v[10:13], v[210:213], v[154:157]
	v_mfma_f32_16x16x32_bf16 v[0:3], v[10:13], v[230:233], v[0:3]
	v_mfma_f32_16x16x32_bf16 v[30:33], v[14:17], v[214:217], v[26:29]
	v_mfma_f32_16x16x32_bf16 v[26:29], v[18:21], v[210:213], v[158:161]
	v_mfma_f32_16x16x32_bf16 v[14:17], v[14:17], v[234:237], v[0:3]
	v_mfma_f32_16x16x32_bf16 v[0:3], v[18:21], v[230:233], v[4:7]
	v_mfma_f32_16x16x32_bf16 v[26:29], v[22:25], v[214:217], v[26:29]
	v_mfma_f32_16x16x32_bf16 v[10:13], v[22:25], v[234:237], v[0:3]
	v_mfma_f32_16x16x32_bf16 v[0:3], v[166:169], v[34:37], v[198:201]
	v_mfma_f32_16x16x32_bf16 v[70:73], v[190:193], v[38:41], v[0:3]
	v_mfma_f32_16x16x32_bf16 v[0:3], v[194:197], v[34:37], v[218:221]
	v_mfma_f32_16x16x32_bf16 v[66:69], v[226:229], v[38:41], v[0:3]
	v_mfma_f32_16x16x32_bf16 v[0:3], v[166:169], v[170:173], v[222:225]
	v_mfma_f32_16x16x32_bf16 v[38:41], v[190:193], v[202:205], v[0:3]
	v_mfma_f32_16x16x32_bf16 v[0:3], v[194:197], v[170:173], v[174:177]
	v_mfma_f32_16x16x32_bf16 v[34:37], v[226:229], v[202:205], v[0:3]
	v_mfma_f32_16x16x32_bf16 v[0:3], v[166:169], v[210:213], v[178:181]
	v_mfma_f32_16x16x32_bf16 v[22:25], v[190:193], v[214:217], v[0:3]
	v_mfma_f32_16x16x32_bf16 v[0:3], v[194:197], v[210:213], v[182:185]
	v_mfma_f32_16x16x32_bf16 v[18:21], v[226:229], v[214:217], v[0:3]
	v_mfma_f32_16x16x32_bf16 v[0:3], v[166:169], v[230:233], v[186:189]
	v_mfma_f32_16x16x32_bf16 v[4:7], v[190:193], v[234:237], v[0:3]
	v_mfma_f32_16x16x32_bf16 v[0:3], v[194:197], v[230:233], v[162:165]
	v_mfma_f32_16x16x32_bf16 v[0:3], v[226:229], v[234:237], v[0:3]
	s_setprio 0
	s_barrier
	s_andn2_b64 vcc, exec, s[8:9]
	s_cbranch_vccnz .LBB0_411
	s_barrier

; #define PG8_STAGE(bufoff, gbase, voff) do { _Pragma("unroll") for (int _i = 0; _i < 2; ++_i) \
;         __builtin_amdgcn_global_load_lds((const unsigned*)((const char*)(gbase) + (voff)[_i]), (PG8_LAS unsigned*)(lds + (bufoff) + ldsw + _i * 8192), 16, 0, 0); } while (0)
; #define PG8_LDA(dst, b, h) do { _Pragma("unroll") for (int m = 0; m < 4; ++m) _Pragma("unroll") for (int k = 0; k < 2; ++k) dst[m][k] = *(const PG8_LAS bf16x8*)(lds + PG8_SA(b, h) + aoff + m * 2048 + k * 1024); } while (0)
; #define PG8_LDB(dst, b, h) do { _Pragma("unroll") for (int n = 0; n < 2; ++n) _Pragma("unroll") for (int k = 0; k < 2; ++k) dst[n][k] = *(const PG8_LAS bf16x8*)(lds + PG8_SB(b, h) + boff + n * 2048 + k * 1024); } while (0)
; #define PG8_MMA(ai, bj, At, Bt) do { __builtin_amdgcn_s_setprio(1); _Pragma("unroll") for (int m = 0; m < 4; ++m) _Pragma("unroll") for (int n = 0; n < 2; ++n) _Pragma("unroll") for (int k = 0; k < 2; ++k) \
;         acc[ai][bj][m][n] = __builtin_amdgcn_mfma_f32_16x16x32_bf16(Bt[n][k], At[m][k], acc[ai][bj][m][n], 0, 0, 0); __builtin_amdgcn_s_setprio(0); } while (0)
; template <class Epi, class Sched, bool ALIGN_EPI = false, bool SP2 = false>
; __device__ __forceinline__ void gemm_phase(PG8_LAS unsigned char* lds, int tid_in, const Gemm g, const Sched& S, const Epi& E) {
;     ...
;         const bool has_next = S.next(ui + 1, nxt);
;         const char* nA = has_next ? (const char*)g.A + (size_t)nxt.pm * tstep : cA; const char* nB = has_next ? (const char*)g.Bt + (size_t)nxt.pn * tstep : cB;
;         for (int t = 0; t < nt; t += 2) {
;             const bool last = (t == nt - 2);
;             const char* a1 = cA + (size_t)(t + 1) * kstep;
;             const char* a2 = last ? nA : cA + (size_t)(t + 2) * kstep; const char* b2 = last ? nB : cB + (size_t)(t + 2) * kstep;
;             const char* a3 = a2 + kstep; const char* b3 = b2 + kstep;
;             if (last && has_next) S.a_ready(nxt);
;             if constexpr (SP2) {
;             PG8_LDB(B0, 0, 0); PG8_LDB(B1, 0, 1); PG8_SCHED; PG8_LDA(At, 0, 0); PG8_STAGE(PG8_SA(1, 1), a1 + hstep, voffA);
;             PG8_WAIT_V(8); PG8_WAIT_L(0); PG8_BAR; PG8_MMA(0, 0, At, B0); PG8_MMA(0, 1, At, B1); PG8_BAR; PG8_SCHED;
;             PG8_LDA(At, 0, 1); PG8_STAGE(PG8_SB(0, 0), b2, voffB); PG8_STAGE(PG8_SB(0, 1), b2 + hstep, voffB); PG8_STAGE(PG8_SA(0, 0), a2, voffA);
.LBB0_423:
	s_ashr_i32 s15, s14, 31
	s_lshl_b64 s[16:17], s[14:15], 17
	s_add_u32 s16, s0, s16
	s_addc_u32 s17, s1, s17
	s_and_b64 s[30:31], s[4:5], exec
	s_cselect_b32 s49, s17, s35
	s_cselect_b32 s48, s16, s34
	s_ashr_i32 s13, s12, 31
	s_lshl_b64 s[30:31], s[12:13], 17
	v_readlane_b32 s38, v253, 16
	v_readlane_b32 s39, v253, 17
	s_add_u32 s30, s38, s30
	s_addc_u32 s31, s39, s31
	s_and_b64 s[38:39], s[4:5], exec
	s_cselect_b32 s43, s31, s51
	s_cselect_b32 s42, s30, s50
	s_add_i32 s15, 0, 0x10000
	s_add_i32 s37, 0, 0x14000
	v_add_u32_e32 v212, s15, v136
	v_add_u32_e32 v213, s37, v136
	ds_read_b128 v[0:3], v212
	ds_read_b128 v[4:7], v212 offset:1024
	ds_read_b128 v[10:13], v212 offset:2048
	ds_read_b128 v[14:17], v212 offset:3072
	ds_read_b128 v[18:21], v213
	ds_read_b128 v[22:25], v213 offset:1024
	ds_read_b128 v[26:29], v213 offset:2048
	ds_read_b128 v[30:33], v213 offset:3072
	s_add_u32 s38, s34, 0x10080
	s_addc_u32 s39, s35, 0
	s_add_i32 s53, s21, 0xc000
	v_lshl_add_u64 v[66:67], s[38:39], 0, v[134:135]
	s_mov_b32 m0, s53
	s_add_i32 s13, s21, 0xe000
	ds_read_b128 v[34:37], v137
	ds_read_b128 v[38:41], v137 offset:1024
	ds_read_b128 v[42:45], v137 offset:2048
	ds_read_b128 v[46:49], v137 offset:3072
	ds_read_b128 v[50:53], v137 offset:4096
	ds_read_b128 v[54:57], v137 offset:5120
	ds_read_b128 v[58:61], v137 offset:6144
	ds_read_b128 v[62:65], v137 offset:7168
	global_load_lds_dwordx4 v[66:67], off
	v_lshl_add_u64 v[66:67], s[38:39], 0, v[132:133]
	s_mov_b32 m0, s13
	s_nop 0
	global_load_lds_dwordx4 v[66:67], off
	s_waitcnt vmcnt(8)
	s_waitcnt lgkmcnt(0)
	s_barrier
	s_setprio 1
	s_waitcnt lgkmcnt(0)
	v_mfma_f32_16x16x32_bf16 v[66:69], v[0:3], v[34:37], 0
	v_mfma_f32_16x16x32_bf16 v[70:73], v[10:13], v[34:37], 0
	v_mfma_f32_16x16x32_bf16 v[74:77], v[0:3], v[42:45], 0
	v_mfma_f32_16x16x32_bf16 v[78:81], v[10:13], v[42:45], 0
	v_mfma_f32_16x16x32_bf16 v[82:85], v[0:3], v[50:53], 0
	v_mfma_f32_16x16x32_bf16 v[86:89], v[10:13], v[50:53], 0
	v_mfma_f32_16x16x32_bf16 v[90:93], v[0:3], v[58:61], 0
	v_mfma_f32_16x16x32_bf16 v[94:97], v[10:13], v[58:61], 0
	v_mfma_f32_16x16x32_bf16 v[66:69], v[4:7], v[38:41], v[66:69]
	v_mfma_f32_16x16x32_bf16 v[70:73], v[14:17], v[38:41], v[70:73]
	v_mfma_f32_16x16x32_bf16 v[74:77], v[4:7], v[46:49], v[74:77]
	v_mfma_f32_16x16x32_bf16 v[78:81], v[14:17], v[46:49], v[78:81]
	v_mfma_f32_16x16x32_bf16 v[82:85], v[4:7], v[54:57], v[82:85]
	v_mfma_f32_16x16x32_bf16 v[86:89], v[14:17], v[54:57], v[86:89]
	v_mfma_f32_16x16x32_bf16 v[90:93], v[4:7], v[62:65], v[90:93]
	v_mfma_f32_16x16x32_bf16 v[94:97], v[14:17], v[62:65], v[94:97]
	v_mfma_f32_16x16x32_bf16 v[98:101], v[18:21], v[34:37], 0
	v_mfma_f32_16x16x32_bf16 v[34:37], v[26:29], v[34:37], 0
	v_mfma_f32_16x16x32_bf16 v[98:101], v[22:25], v[38:41], v[98:101]
	v_mfma_f32_16x16x32_bf16 v[34:37], v[30:33], v[38:41], v[34:37]
	v_mfma_f32_16x16x32_bf16 v[38:41], v[18:21], v[42:45], 0
	v_mfma_f32_16x16x32_bf16 v[42:45], v[26:29], v[42:45], 0
	v_mfma_f32_16x16x32_bf16 v[38:41], v[22:25], v[46:49], v[38:41]
	v_mfma_f32_16x16x32_bf16 v[42:45], v[30:33], v[46:49], v[42:45]
	v_mfma_f32_16x16x32_bf16 v[46:49], v[18:21], v[50:53], 0
	v_mfma_f32_16x16x32_bf16 v[50:53], v[26:29], v[50:53], 0
	v_mfma_f32_16x16x32_bf16 v[46:49], v[22:25], v[54:57], v[46:49]
	v_mfma_f32_16x16x32_bf16 v[50:53], v[30:33], v[54:57], v[50:53]
	v_mfma_f32_16x16x32_bf16 v[54:57], v[18:21], v[58:61], 0
	v_mfma_f32_16x16x32_bf16 v[58:61], v[26:29], v[58:61], 0
	v_mfma_f32_16x16x32_bf16 v[54:57], v[22:25], v[62:65], v[54:57]
	v_mfma_f32_16x16x32_bf16 v[58:61], v[30:33], v[62:65], v[58:61]
	s_setprio 0
	s_barrier
	s_add_i32 s39, s15, s20
	v_lshl_add_u64 v[202:203], s[50:51], 0, v[8:9]
	s_mov_b64 s[58:59], 0x100
	s_add_i32 s15, s39, 0x2000
	v_lshl_add_u64 v[138:139], v[202:203], 0, s[58:59]
	s_mov_b32 m0, s39
	v_lshl_add_u64 v[204:205], s[50:51], 0, v[130:131]
	s_add_u32 s56, s50, 0x10100
	ds_read_b128 v[62:65], v137 offset:16384
	ds_read_b128 v[102:105], v137 offset:17408
	ds_read_b128 v[106:109], v137 offset:18432
	ds_read_b128 v[110:113], v137 offset:19456
	ds_read_b128 v[114:117], v137 offset:20480
	ds_read_b128 v[118:121], v137 offset:21504
	ds_read_b128 v[122:125], v137 offset:22528
	ds_read_b128 v[126:129], v137 offset:23552
	global_load_lds_dwordx4 v[138:139], off
	v_lshl_add_u64 v[138:139], v[204:205], 0, s[58:59]
	s_mov_b32 m0, s15
	s_addc_u32 s57, s51, 0
	s_add_i32 s37, s37, s20
	global_load_lds_dwordx4 v[138:139], off
	v_lshl_add_u64 v[138:139], s[56:57], 0, v[8:9]
	s_mov_b32 m0, s37
	s_add_i32 s38, s37, 0x2000
	global_load_lds_dwordx4 v[138:139], off
	v_lshl_add_u64 v[138:139], s[56:57], 0, v[130:131]
	s_mov_b32 m0, s38
	v_lshl_add_u64 v[206:207], s[34:35], 0, v[134:135]
	global_load_lds_dwordx4 v[138:139], off
	v_lshl_add_u64 v[138:139], v[206:207], 0, s[58:59]
	s_mov_b32 m0, s21
	v_lshl_add_u64 v[208:209], s[34:35], 0, v[132:133]
	global_load_lds_dwordx4 v[138:139], off
	v_lshl_add_u64 v[138:139], v[208:209], 0, s[58:59]
	s_mov_b32 m0, s28
	s_nop 0
	global_load_lds_dwordx4 v[138:139], off
	s_waitcnt vmcnt(8)
	s_waitcnt lgkmcnt(0)
	s_barrier
; #define PG8_STAGE(bufoff, gbase, voff) do { _Pragma("unroll") for (int _i = 0; _i < 2; ++_i) \
;         __builtin_amdgcn_global_load_lds((const unsigned*)((const char*)(gbase) + (voff)[_i]), (PG8_LAS unsigned*)(lds + (bufoff) + ldsw + _i * 8192), 16, 0, 0); } while (0)
; #define PG8_LDA(dst, b, h) do { _Pragma("unroll") for (int m = 0; m < 4; ++m) _Pragma("unroll") for (int k = 0; k < 2; ++k) dst[m][k] = *(const PG8_LAS bf16x8*)(lds + PG8_SA(b, h) + aoff + m * 2048 + k * 1024); } while (0)
; #define PG8_LDB(dst, b, h) do { _Pragma("unroll") for (int n = 0; n < 2; ++n) _Pragma("unroll") for (int k = 0; k < 2; ++k) dst[n][k] = *(const PG8_LAS bf16x8*)(lds + PG8_SB(b, h) + boff + n * 2048 + k * 1024); } while (0)
; #define PG8_MMA(ai, bj, At, Bt) do { __builtin_amdgcn_s_setprio(1); _Pragma("unroll") for (int m = 0; m < 4; ++m) _Pragma("unroll") for (int n = 0; n < 2; ++n) _Pragma("unroll") for (int k = 0; k < 2; ++k) \
;         acc[ai][bj][m][n] = __builtin_amdgcn_mfma_f32_16x16x32_bf16(Bt[n][k], At[m][k], acc[ai][bj][m][n], 0, 0, 0); __builtin_amdgcn_s_setprio(0); } while (0)
; #define PG8_WAIT_V(n) asm volatile("s_waitcnt vmcnt(" #n ")" ::: "memory")
; #define PG8_WAIT_L(n) asm volatile("s_waitcnt lgkmcnt(" #n ")" ::: "memory")
; #define PG8_BAR __builtin_amdgcn_s_barrier()
; #define PG8_SCHED __builtin_amdgcn_sched_barrier(0)
; template <class Epi, class Sched, bool ALIGN_EPI = false, bool SP2 = false>
; __device__ __forceinline__ void gemm_phase(PG8_LAS unsigned char* lds, int tid_in, const Gemm g, const Sched& S, const Epi& E) {
;     ...
;             PG8_WAIT_V(8); PG8_WAIT_L(0); PG8_BAR; PG8_MMA(1, 0, At, B0); PG8_MMA(1, 1, At, B1); PG8_BAR; PG8_SCHED;
;             PG8_LDB(B0, 1, 0); PG8_LDB(B1, 1, 1); PG8_SCHED; PG8_LDA(At, 1, 0); PG8_STAGE(PG8_SA(0, 1), a2 + hstep, voffA);
;             PG8_WAIT_V(8); PG8_WAIT_L(0); PG8_BAR; PG8_MMA(0, 0, At, B0); PG8_MMA(0, 1, At, B1); PG8_BAR; PG8_SCHED;
	s_setprio 1
	s_waitcnt lgkmcnt(0)
	v_mfma_f32_16x16x32_bf16 v[138:141], v[0:3], v[62:65], 0
	v_mfma_f32_16x16x32_bf16 v[146:149], v[0:3], v[106:109], 0
	v_mfma_f32_16x16x32_bf16 v[154:157], v[0:3], v[114:117], 0
	v_mfma_f32_16x16x32_bf16 v[0:3], v[0:3], v[122:125], 0
	v_mfma_f32_16x16x32_bf16 v[138:141], v[4:7], v[102:105], v[138:141]
	v_mfma_f32_16x16x32_bf16 v[146:149], v[4:7], v[110:113], v[146:149]
	v_mfma_f32_16x16x32_bf16 v[154:157], v[4:7], v[118:121], v[154:157]
	v_mfma_f32_16x16x32_bf16 v[0:3], v[4:7], v[126:129], v[0:3]
	v_mfma_f32_16x16x32_bf16 v[4:7], v[10:13], v[122:125], 0
	v_mfma_f32_16x16x32_bf16 v[142:145], v[10:13], v[62:65], 0
	v_mfma_f32_16x16x32_bf16 v[150:153], v[10:13], v[106:109], 0
	v_mfma_f32_16x16x32_bf16 v[158:161], v[10:13], v[114:117], 0
	v_mfma_f32_16x16x32_bf16 v[4:7], v[14:17], v[126:129], v[4:7]
	v_mfma_f32_16x16x32_bf16 v[142:145], v[14:17], v[102:105], v[142:145]
	v_mfma_f32_16x16x32_bf16 v[150:153], v[14:17], v[110:113], v[150:153]
	v_mfma_f32_16x16x32_bf16 v[158:161], v[14:17], v[118:121], v[158:161]
	v_mfma_f32_16x16x32_bf16 v[10:13], v[18:21], v[62:65], 0
	v_mfma_f32_16x16x32_bf16 v[14:17], v[26:29], v[62:65], 0
	v_mfma_f32_16x16x32_bf16 v[10:13], v[22:25], v[102:105], v[10:13]
	v_mfma_f32_16x16x32_bf16 v[14:17], v[30:33], v[102:105], v[14:17]
	v_mfma_f32_16x16x32_bf16 v[62:65], v[18:21], v[106:109], 0
	v_mfma_f32_16x16x32_bf16 v[102:105], v[26:29], v[106:109], 0
	v_mfma_f32_16x16x32_bf16 v[106:109], v[18:21], v[114:117], 0
	v_mfma_f32_16x16x32_bf16 v[18:21], v[18:21], v[122:125], 0
	v_mfma_f32_16x16x32_bf16 v[62:65], v[22:25], v[110:113], v[62:65]
	v_mfma_f32_16x16x32_bf16 v[102:105], v[30:33], v[110:113], v[102:105]
	v_mfma_f32_16x16x32_bf16 v[106:109], v[22:25], v[118:121], v[106:109]
	v_mfma_f32_16x16x32_bf16 v[110:113], v[26:29], v[114:117], 0
	v_mfma_f32_16x16x32_bf16 v[18:21], v[22:25], v[126:129], v[18:21]
	v_mfma_f32_16x16x32_bf16 v[22:25], v[26:29], v[122:125], 0
	v_mfma_f32_16x16x32_bf16 v[110:113], v[30:33], v[118:121], v[110:113]
	v_mfma_f32_16x16x32_bf16 v[22:25], v[30:33], v[126:129], v[22:25]
	s_setprio 0
	s_barrier
	s_add_i32 s55, 0, 0x18000
	s_add_i32 s58, 0, 0x1c000
	v_add_u32_e32 v214, s55, v136
	v_add_u32_e32 v222, s58, v136
	ds_read_b128 v[26:29], v214
	ds_read_b128 v[30:33], v214 offset:1024
	ds_read_b128 v[114:117], v214 offset:2048
	ds_read_b128 v[118:121], v214 offset:3072
	ds_read_b128 v[122:125], v222
	ds_read_b128 v[126:129], v222 offset:1024
	ds_read_b128 v[162:165], v222 offset:2048
	ds_read_b128 v[166:169], v222 offset:3072
	s_add_u32 s56, s34, 0x10100
	s_addc_u32 s57, s35, 0
	s_mov_b32 m0, s29
	v_lshl_add_u64 v[210:211], s[56:57], 0, v[134:135]
	ds_read_b128 v[170:173], v137 offset:32768
	ds_read_b128 v[174:177], v137 offset:33792
	ds_read_b128 v[178:181], v137 offset:34816
	ds_read_b128 v[182:185], v137 offset:35840
	ds_read_b128 v[186:189], v137 offset:36864
	ds_read_b128 v[190:193], v137 offset:37888
	ds_read_b128 v[194:197], v137 offset:38912
	ds_read_b128 v[198:201], v137 offset:39936
	global_load_lds_dwordx4 v[210:211], off
	v_lshl_add_u64 v[210:211], s[56:57], 0, v[132:133]
	s_mov_b32 m0, s33
	s_nop 0
	global_load_lds_dwordx4 v[210:211], off
	s_waitcnt vmcnt(8)
	s_waitcnt lgkmcnt(0)
	s_barrier
	s_setprio 1
	s_waitcnt lgkmcnt(0)
	v_mfma_f32_16x16x32_bf16 v[66:69], v[26:29], v[170:173], v[66:69]
	v_mfma_f32_16x16x32_bf16 v[70:73], v[114:117], v[170:173], v[70:73]
	v_mfma_f32_16x16x32_bf16 v[74:77], v[26:29], v[178:181], v[74:77]
	v_mfma_f32_16x16x32_bf16 v[78:81], v[114:117], v[178:181], v[78:81]
	v_mfma_f32_16x16x32_bf16 v[82:85], v[26:29], v[186:189], v[82:85]
	v_mfma_f32_16x16x32_bf16 v[86:89], v[114:117], v[186:189], v[86:89]
	v_mfma_f32_16x16x32_bf16 v[90:93], v[26:29], v[194:197], v[90:93]
	v_mfma_f32_16x16x32_bf16 v[94:97], v[114:117], v[194:197], v[94:97]
	v_mfma_f32_16x16x32_bf16 v[66:69], v[30:33], v[174:177], v[66:69]
	v_mfma_f32_16x16x32_bf16 v[70:73], v[118:121], v[174:177], v[70:73]
	v_mfma_f32_16x16x32_bf16 v[74:77], v[30:33], v[182:185], v[74:77]
	v_mfma_f32_16x16x32_bf16 v[78:81], v[118:121], v[182:185], v[78:81]
	v_mfma_f32_16x16x32_bf16 v[82:85], v[30:33], v[190:193], v[82:85]
	v_mfma_f32_16x16x32_bf16 v[86:89], v[118:121], v[190:193], v[86:89]
	v_mfma_f32_16x16x32_bf16 v[90:93], v[30:33], v[198:201], v[90:93]
	v_mfma_f32_16x16x32_bf16 v[94:97], v[118:121], v[198:201], v[94:97]
	v_mfma_f32_16x16x32_bf16 v[98:101], v[122:125], v[170:173], v[98:101]
	v_mfma_f32_16x16x32_bf16 v[34:37], v[162:165], v[170:173], v[34:37]
	v_mfma_f32_16x16x32_bf16 v[38:41], v[122:125], v[178:181], v[38:41]
	v_mfma_f32_16x16x32_bf16 v[42:45], v[162:165], v[178:181], v[42:45]
	v_mfma_f32_16x16x32_bf16 v[46:49], v[122:125], v[186:189], v[46:49]
	v_mfma_f32_16x16x32_bf16 v[50:53], v[162:165], v[186:189], v[50:53]
	v_mfma_f32_16x16x32_bf16 v[54:57], v[122:125], v[194:197], v[54:57]
	v_mfma_f32_16x16x32_bf16 v[58:61], v[162:165], v[194:197], v[58:61]
	v_mfma_f32_16x16x32_bf16 v[98:101], v[126:129], v[174:177], v[98:101]
	v_mfma_f32_16x16x32_bf16 v[34:37], v[166:169], v[174:177], v[34:37]
	v_mfma_f32_16x16x32_bf16 v[38:41], v[126:129], v[182:185], v[38:41]
	v_mfma_f32_16x16x32_bf16 v[42:45], v[166:169], v[182:185], v[42:45]
	v_mfma_f32_16x16x32_bf16 v[46:49], v[126:129], v[190:193], v[46:49]
	v_mfma_f32_16x16x32_bf16 v[50:53], v[166:169], v[190:193], v[50:53]
	v_mfma_f32_16x16x32_bf16 v[54:57], v[126:129], v[198:201], v[54:57]
	v_mfma_f32_16x16x32_bf16 v[58:61], v[166:169], v[198:201], v[58:61]
	s_setprio 0
	s_barrier
; #define PG8_STAGE(bufoff, gbase, voff) do { _Pragma("unroll") for (int _i = 0; _i < 2; ++_i) \
;         __builtin_amdgcn_global_load_lds((const unsigned*)((const char*)(gbase) + (voff)[_i]), (PG8_LAS unsigned*)(lds + (bufoff) + ldsw + _i * 8192), 16, 0, 0); } while (0)
; #define PG8_LDA(dst, b, h) do { _Pragma("unroll") for (int m = 0; m < 4; ++m) _Pragma("unroll") for (int k = 0; k < 2; ++k) dst[m][k] = *(const PG8_LAS bf16x8*)(lds + PG8_SA(b, h) + aoff + m * 2048 + k * 1024); } while (0)
; #define PG8_LDB(dst, b, h) do { _Pragma("unroll") for (int n = 0; n < 2; ++n) _Pragma("unroll") for (int k = 0; k < 2; ++k) dst[n][k] = *(const PG8_LAS bf16x8*)(lds + PG8_SB(b, h) + boff + n * 2048 + k * 1024); } while (0)
; #define PG8_MMA(ai, bj, At, Bt) do { __builtin_amdgcn_s_setprio(1); _Pragma("unroll") for (int m = 0; m < 4; ++m) _Pragma("unroll") for (int n = 0; n < 2; ++n) _Pragma("unroll") for (int k = 0; k < 2; ++k) \
;         acc[ai][bj][m][n] = __builtin_amdgcn_mfma_f32_16x16x32_bf16(Bt[n][k], At[m][k], acc[ai][bj][m][n], 0, 0, 0); __builtin_amdgcn_s_setprio(0); } while (0)
; #define PG8_BAR __builtin_amdgcn_s_barrier()
; template <class Epi, class Sched, bool ALIGN_EPI = false, bool SP2 = false>
; __device__ __forceinline__ void gemm_phase(PG8_LAS unsigned char* lds, int tid_in, const Gemm g, const Sched& S, const Epi& E) {
;     ...
;             PG8_LDB(B0, 0, 0); PG8_LDB(B1, 0, 1); PG8_SCHED; PG8_LDA(At, 0, 0); PG8_STAGE(PG8_SA(1, 1), a1 + hstep, voffA);
;             PG8_WAIT_V(8); PG8_WAIT_L(0); PG8_BAR; PG8_MMA(0, 0, At, B0); PG8_MMA(0, 1, At, B1); PG8_BAR; PG8_SCHED;
;             PG8_LDA(At, 0, 1); PG8_STAGE(PG8_SB(0, 0), b2, voffB); PG8_STAGE(PG8_SB(0, 1), b2 + hstep, voffB); PG8_STAGE(PG8_SA(0, 0), a2, voffA);
;             PG8_WAIT_V(8); PG8_WAIT_L(0); PG8_BAR; PG8_MMA(1, 0, At, B0); PG8_MMA(1, 1, At, B1); PG8_BAR; PG8_SCHED;
;             PG8_LDB(B0, 1, 0); PG8_LDB(B1, 1, 1); PG8_SCHED; PG8_LDA(At, 1, 0); PG8_STAGE(PG8_SA(0, 1), a2 + hstep, voffA);
;             PG8_WAIT_V(8); PG8_WAIT_L(0); PG8_BAR; PG8_MMA(0, 0, At, B0); PG8_MMA(0, 1, At, B1); PG8_BAR; PG8_SCHED;
;             PG8_LDA(At, 1, 1); PG8_STAGE(PG8_SB(1, 0), b3, voffB); PG8_STAGE(PG8_SB(1, 1), b3 + hstep, voffB); PG8_STAGE(PG8_SA(1, 0), a3, voffA);
;             PG8_WAIT_V(8); PG8_WAIT_L(0); PG8_BAR; PG8_MMA(1, 0, At, B0); PG8_MMA(1, 1, At, B1); PG8_BAR; PG8_SCHED;
	s_add_i32 s55, s55, s20
	s_mov_b64 s[60:61], 0x180
	s_add_i32 s47, s55, 0x2000
	v_lshl_add_u64 v[202:203], v[202:203], 0, s[60:61]
	s_mov_b32 m0, s55
	s_add_u32 s56, s50, 0x10180
	ds_read_b128 v[170:173], v137 offset:49152
	ds_read_b128 v[174:177], v137 offset:50176
	ds_read_b128 v[178:181], v137 offset:51200
	ds_read_b128 v[182:185], v137 offset:52224
	ds_read_b128 v[186:189], v137 offset:53248
	ds_read_b128 v[190:193], v137 offset:54272
	ds_read_b128 v[194:197], v137 offset:55296
	ds_read_b128 v[198:201], v137 offset:56320
	global_load_lds_dwordx4 v[202:203], off
	v_lshl_add_u64 v[202:203], v[204:205], 0, s[60:61]
	s_mov_b32 m0, s47
	s_addc_u32 s57, s51, 0
	s_add_i32 s50, s58, s20
	global_load_lds_dwordx4 v[202:203], off
	v_lshl_add_u64 v[202:203], s[56:57], 0, v[8:9]
	s_mov_b32 m0, s50
	s_add_i32 s51, s50, 0x2000
	global_load_lds_dwordx4 v[202:203], off
	v_lshl_add_u64 v[202:203], s[56:57], 0, v[130:131]
	s_mov_b32 m0, s51
	s_nop 0
	global_load_lds_dwordx4 v[202:203], off
	v_lshl_add_u64 v[202:203], v[206:207], 0, s[60:61]
	s_mov_b32 m0, s45
	s_nop 0
	global_load_lds_dwordx4 v[202:203], off
	v_lshl_add_u64 v[202:203], v[208:209], 0, s[60:61]
	s_mov_b32 m0, s46
	s_nop 0
	global_load_lds_dwordx4 v[202:203], off
	s_waitcnt vmcnt(8)
	s_waitcnt lgkmcnt(0)
	s_barrier
	s_setprio 1
	s_waitcnt lgkmcnt(0)
	v_mfma_f32_16x16x32_bf16 v[0:3], v[26:29], v[194:197], v[0:3]
	v_mfma_f32_16x16x32_bf16 v[4:7], v[114:117], v[194:197], v[4:7]
	v_mfma_f32_16x16x32_bf16 v[138:141], v[26:29], v[170:173], v[138:141]
	v_mfma_f32_16x16x32_bf16 v[142:145], v[114:117], v[170:173], v[142:145]
	v_mfma_f32_16x16x32_bf16 v[146:149], v[26:29], v[178:181], v[146:149]
	v_mfma_f32_16x16x32_bf16 v[150:153], v[114:117], v[178:181], v[150:153]
	v_mfma_f32_16x16x32_bf16 v[154:157], v[26:29], v[186:189], v[154:157]
	v_mfma_f32_16x16x32_bf16 v[158:161], v[114:117], v[186:189], v[158:161]
	v_mfma_f32_16x16x32_bf16 v[0:3], v[30:33], v[198:201], v[0:3]
	v_mfma_f32_16x16x32_bf16 v[4:7], v[118:121], v[198:201], v[4:7]
	v_mfma_f32_16x16x32_bf16 v[138:141], v[30:33], v[174:177], v[138:141]
	v_mfma_f32_16x16x32_bf16 v[142:145], v[118:121], v[174:177], v[142:145]
	v_mfma_f32_16x16x32_bf16 v[146:149], v[30:33], v[182:185], v[146:149]
	v_mfma_f32_16x16x32_bf16 v[150:153], v[118:121], v[182:185], v[150:153]
	v_mfma_f32_16x16x32_bf16 v[154:157], v[30:33], v[190:193], v[154:157]
	v_mfma_f32_16x16x32_bf16 v[158:161], v[118:121], v[190:193], v[158:161]
	v_mfma_f32_16x16x32_bf16 v[10:13], v[122:125], v[170:173], v[10:13]
	v_mfma_f32_16x16x32_bf16 v[14:17], v[162:165], v[170:173], v[14:17]
	v_mfma_f32_16x16x32_bf16 v[26:29], v[122:125], v[178:181], v[62:65]
	v_mfma_f32_16x16x32_bf16 v[30:33], v[162:165], v[178:181], v[102:105]
	v_mfma_f32_16x16x32_bf16 v[62:65], v[122:125], v[186:189], v[106:109]
	v_mfma_f32_16x16x32_bf16 v[102:105], v[162:165], v[186:189], v[110:113]
	v_mfma_f32_16x16x32_bf16 v[18:21], v[122:125], v[194:197], v[18:21]
	v_mfma_f32_16x16x32_bf16 v[22:25], v[162:165], v[194:197], v[22:25]
	v_mfma_f32_16x16x32_bf16 v[10:13], v[126:129], v[174:177], v[10:13]
	v_mfma_f32_16x16x32_bf16 v[14:17], v[166:169], v[174:177], v[14:17]
	v_mfma_f32_16x16x32_bf16 v[26:29], v[126:129], v[182:185], v[26:29]
	v_mfma_f32_16x16x32_bf16 v[30:33], v[166:169], v[182:185], v[30:33]
	v_mfma_f32_16x16x32_bf16 v[62:65], v[126:129], v[190:193], v[62:65]
	v_mfma_f32_16x16x32_bf16 v[102:105], v[166:169], v[190:193], v[102:105]
	v_mfma_f32_16x16x32_bf16 v[18:21], v[126:129], v[198:201], v[18:21]
	v_mfma_f32_16x16x32_bf16 v[22:25], v[166:169], v[198:201], v[22:25]
	s_setprio 0
	s_barrier
	ds_read_b128 v[106:109], v212
	ds_read_b128 v[110:113], v212 offset:1024
	ds_read_b128 v[114:117], v212 offset:2048
	ds_read_b128 v[118:121], v212 offset:3072
	ds_read_b128 v[122:125], v213
	ds_read_b128 v[126:129], v213 offset:1024
	ds_read_b128 v[162:165], v213 offset:2048
	ds_read_b128 v[166:169], v213 offset:3072
	s_add_u32 s34, s34, 0x10180
	s_addc_u32 s35, s35, 0
	s_mov_b32 m0, s53
	v_lshl_add_u64 v[202:203], s[34:35], 0, v[134:135]
	ds_read_b128 v[170:173], v137
	ds_read_b128 v[174:177], v137 offset:1024
	ds_read_b128 v[178:181], v137 offset:2048
	ds_read_b128 v[182:185], v137 offset:3072
	ds_read_b128 v[186:189], v137 offset:4096
	ds_read_b128 v[190:193], v137 offset:5120
	ds_read_b128 v[194:197], v137 offset:6144
	ds_read_b128 v[198:201], v137 offset:7168
	global_load_lds_dwordx4 v[202:203], off
	v_lshl_add_u64 v[202:203], s[34:35], 0, v[132:133]
	s_mov_b32 m0, s13
	s_nop 0
	global_load_lds_dwordx4 v[202:203], off
	s_waitcnt vmcnt(8)
	s_waitcnt lgkmcnt(0)
	s_barrier
; #define PG8_STAGE(bufoff, gbase, voff) do { _Pragma("unroll") for (int _i = 0; _i < 2; ++_i) \
;         __builtin_amdgcn_global_load_lds((const unsigned*)((const char*)(gbase) + (voff)[_i]), (PG8_LAS unsigned*)(lds + (bufoff) + ldsw + _i * 8192), 16, 0, 0); } while (0)
; #define PG8_LDA(dst, b, h) do { _Pragma("unroll") for (int m = 0; m < 4; ++m) _Pragma("unroll") for (int k = 0; k < 2; ++k) dst[m][k] = *(const PG8_LAS bf16x8*)(lds + PG8_SA(b, h) + aoff + m * 2048 + k * 1024); } while (0)
; #define PG8_MMA(ai, bj, At, Bt) do { __builtin_amdgcn_s_setprio(1); _Pragma("unroll") for (int m = 0; m < 4; ++m) _Pragma("unroll") for (int n = 0; n < 2; ++n) _Pragma("unroll") for (int k = 0; k < 2; ++k) \
;         acc[ai][bj][m][n] = __builtin_amdgcn_mfma_f32_16x16x32_bf16(Bt[n][k], At[m][k], acc[ai][bj][m][n], 0, 0, 0); __builtin_amdgcn_s_setprio(0); } while (0)
; #define PG8_WAIT_V(n) asm volatile("s_waitcnt vmcnt(" #n ")" ::: "memory")
; #define PG8_WAIT_L(n) asm volatile("s_waitcnt lgkmcnt(" #n ")" ::: "memory")
; #define PG8_BAR __builtin_amdgcn_s_barrier()
; #define PG8_SCHED __builtin_amdgcn_sched_barrier(0)
; template <class Epi, class Sched, bool ALIGN_EPI = false, bool SP2 = false>
; __device__ __forceinline__ void gemm_phase(PG8_LAS unsigned char* lds, int tid_in, const Gemm g, const Sched& S, const Epi& E) {
;     ...
;             PG8_WAIT_V(8); PG8_WAIT_L(0); PG8_BAR; PG8_MMA(0, 0, At, B0); PG8_MMA(0, 1, At, B1); PG8_BAR; PG8_SCHED;
;             PG8_LDA(At, 0, 1); PG8_STAGE(PG8_SB(0, 0), b2, voffB); PG8_STAGE(PG8_SB(0, 1), b2 + hstep, voffB); PG8_STAGE(PG8_SA(0, 0), a2, voffA);
;             PG8_WAIT_V(8); PG8_WAIT_L(0); PG8_BAR; PG8_MMA(1, 0, At, B0); PG8_MMA(1, 1, At, B1); PG8_BAR; PG8_SCHED;
	s_setprio 1
	s_waitcnt lgkmcnt(0)
	v_mfma_f32_16x16x32_bf16 v[66:69], v[106:109], v[170:173], v[66:69]
	v_mfma_f32_16x16x32_bf16 v[70:73], v[114:117], v[170:173], v[70:73]
	v_mfma_f32_16x16x32_bf16 v[74:77], v[106:109], v[178:181], v[74:77]
	v_mfma_f32_16x16x32_bf16 v[78:81], v[114:117], v[178:181], v[78:81]
	v_mfma_f32_16x16x32_bf16 v[82:85], v[106:109], v[186:189], v[82:85]
	v_mfma_f32_16x16x32_bf16 v[86:89], v[114:117], v[186:189], v[86:89]
	v_mfma_f32_16x16x32_bf16 v[90:93], v[106:109], v[194:197], v[90:93]
	v_mfma_f32_16x16x32_bf16 v[66:69], v[110:113], v[174:177], v[66:69]
	v_mfma_f32_16x16x32_bf16 v[70:73], v[118:121], v[174:177], v[70:73]
	v_mfma_f32_16x16x32_bf16 v[74:77], v[110:113], v[182:185], v[74:77]
	v_mfma_f32_16x16x32_bf16 v[78:81], v[118:121], v[182:185], v[78:81]
	v_mfma_f32_16x16x32_bf16 v[82:85], v[110:113], v[190:193], v[82:85]
	v_mfma_f32_16x16x32_bf16 v[86:89], v[118:121], v[190:193], v[86:89]
	v_mfma_f32_16x16x32_bf16 v[90:93], v[110:113], v[198:201], v[90:93]
	v_mfma_f32_16x16x32_bf16 v[94:97], v[114:117], v[194:197], v[94:97]
	v_mfma_f32_16x16x32_bf16 v[202:205], v[118:121], v[198:201], v[94:97]
	v_mfma_f32_16x16x32_bf16 v[94:97], v[122:125], v[170:173], v[98:101]
	v_mfma_f32_16x16x32_bf16 v[34:37], v[162:165], v[170:173], v[34:37]
	v_mfma_f32_16x16x32_bf16 v[38:41], v[122:125], v[178:181], v[38:41]
	v_mfma_f32_16x16x32_bf16 v[42:45], v[162:165], v[178:181], v[42:45]
	v_mfma_f32_16x16x32_bf16 v[46:49], v[122:125], v[186:189], v[46:49]
	v_mfma_f32_16x16x32_bf16 v[50:53], v[162:165], v[186:189], v[50:53]
	v_mfma_f32_16x16x32_bf16 v[54:57], v[122:125], v[194:197], v[54:57]
	v_mfma_f32_16x16x32_bf16 v[98:101], v[126:129], v[174:177], v[94:97]
	v_mfma_f32_16x16x32_bf16 v[34:37], v[166:169], v[174:177], v[34:37]
	v_mfma_f32_16x16x32_bf16 v[38:41], v[126:129], v[182:185], v[38:41]
	v_mfma_f32_16x16x32_bf16 v[42:45], v[166:169], v[182:185], v[42:45]
	v_mfma_f32_16x16x32_bf16 v[46:49], v[126:129], v[190:193], v[46:49]
	v_mfma_f32_16x16x32_bf16 v[50:53], v[166:169], v[190:193], v[50:53]
	v_mfma_f32_16x16x32_bf16 v[170:173], v[126:129], v[198:201], v[54:57]
	v_mfma_f32_16x16x32_bf16 v[54:57], v[162:165], v[194:197], v[58:61]
	v_mfma_f32_16x16x32_bf16 v[174:177], v[166:169], v[198:201], v[54:57]
	s_setprio 0
	s_barrier
	s_mov_b32 m0, s39
	v_lshl_add_u64 v[206:207], s[42:43], 0, v[8:9]
	s_add_u32 s34, s42, 0x10000
	s_nop 1
	ds_read_b128 v[54:57], v137 offset:16384
	ds_read_b128 v[58:61], v137 offset:17408
	ds_read_b128 v[94:97], v137 offset:18432
	ds_read_b128 v[178:181], v137 offset:19456
	ds_read_b128 v[182:185], v137 offset:20480
	ds_read_b128 v[186:189], v137 offset:21504
	ds_read_b128 v[190:193], v137 offset:22528
	ds_read_b128 v[194:197], v137 offset:23552
	global_load_lds_dwordx4 v[206:207], off
	v_lshl_add_u64 v[208:209], s[42:43], 0, v[130:131]
	s_mov_b32 m0, s15
	s_addc_u32 s35, s43, 0
	global_load_lds_dwordx4 v[208:209], off
	v_lshl_add_u64 v[198:199], s[34:35], 0, v[8:9]
	s_mov_b32 m0, s37
	v_lshl_add_u64 v[242:243], s[48:49], 0, v[134:135]
	global_load_lds_dwordx4 v[198:199], off
	v_lshl_add_u64 v[198:199], s[34:35], 0, v[130:131]
	s_mov_b32 m0, s38
	v_lshl_add_u64 v[244:245], s[48:49], 0, v[132:133]
	global_load_lds_dwordx4 v[198:199], off
	s_mov_b32 m0, s21
	s_nop 0
	global_load_lds_dwordx4 v[242:243], off
	s_mov_b32 m0, s28
	s_nop 0
	global_load_lds_dwordx4 v[244:245], off
	s_waitcnt vmcnt(8)
	s_waitcnt lgkmcnt(0)
	s_barrier
	s_setprio 1
	s_waitcnt lgkmcnt(0)
	v_mfma_f32_16x16x32_bf16 v[0:3], v[106:109], v[190:193], v[0:3]
	v_mfma_f32_16x16x32_bf16 v[4:7], v[114:117], v[190:193], v[4:7]
	v_mfma_f32_16x16x32_bf16 v[138:141], v[106:109], v[54:57], v[138:141]
	v_mfma_f32_16x16x32_bf16 v[142:145], v[114:117], v[54:57], v[142:145]
	v_mfma_f32_16x16x32_bf16 v[146:149], v[106:109], v[94:97], v[146:149]
	v_mfma_f32_16x16x32_bf16 v[150:153], v[114:117], v[94:97], v[150:153]
	v_mfma_f32_16x16x32_bf16 v[154:157], v[106:109], v[182:185], v[154:157]
	v_mfma_f32_16x16x32_bf16 v[158:161], v[114:117], v[182:185], v[158:161]
	v_mfma_f32_16x16x32_bf16 v[0:3], v[110:113], v[194:197], v[0:3]
	v_mfma_f32_16x16x32_bf16 v[4:7], v[118:121], v[194:197], v[4:7]
	v_mfma_f32_16x16x32_bf16 v[138:141], v[110:113], v[58:61], v[138:141]
	v_mfma_f32_16x16x32_bf16 v[142:145], v[118:121], v[58:61], v[142:145]
	v_mfma_f32_16x16x32_bf16 v[146:149], v[110:113], v[178:181], v[146:149]
	v_mfma_f32_16x16x32_bf16 v[150:153], v[118:121], v[178:181], v[150:153]
	v_mfma_f32_16x16x32_bf16 v[154:157], v[110:113], v[186:189], v[154:157]
	v_mfma_f32_16x16x32_bf16 v[158:161], v[118:121], v[186:189], v[158:161]
	v_mfma_f32_16x16x32_bf16 v[14:17], v[162:165], v[54:57], v[14:17]
	v_mfma_f32_16x16x32_bf16 v[198:201], v[166:169], v[58:61], v[14:17]
	v_mfma_f32_16x16x32_bf16 v[14:17], v[122:125], v[94:97], v[26:29]
	v_mfma_f32_16x16x32_bf16 v[26:29], v[126:129], v[178:181], v[14:17]
	v_mfma_f32_16x16x32_bf16 v[14:17], v[162:165], v[94:97], v[30:33]
	v_mfma_f32_16x16x32_bf16 v[178:181], v[166:169], v[178:181], v[14:17]
	v_mfma_f32_16x16x32_bf16 v[14:17], v[122:125], v[182:185], v[62:65]
	v_mfma_f32_16x16x32_bf16 v[210:213], v[126:129], v[186:189], v[14:17]
	v_mfma_f32_16x16x32_bf16 v[14:17], v[162:165], v[182:185], v[102:105]
	v_mfma_f32_16x16x32_bf16 v[10:13], v[122:125], v[54:57], v[10:13]
	v_mfma_f32_16x16x32_bf16 v[182:185], v[166:169], v[186:189], v[14:17]
	v_mfma_f32_16x16x32_bf16 v[14:17], v[122:125], v[190:193], v[18:21]
	v_mfma_f32_16x16x32_bf16 v[10:13], v[126:129], v[58:61], v[10:13]
	v_mfma_f32_16x16x32_bf16 v[186:189], v[126:129], v[194:197], v[14:17]
	v_mfma_f32_16x16x32_bf16 v[14:17], v[162:165], v[190:193], v[22:25]
	v_mfma_f32_16x16x32_bf16 v[162:165], v[166:169], v[194:197], v[14:17]
	s_setprio 0
	s_barrier
; #define PG8_STAGE(bufoff, gbase, voff) do { _Pragma("unroll") for (int _i = 0; _i < 2; ++_i) \
;         __builtin_amdgcn_global_load_lds((const unsigned*)((const char*)(gbase) + (voff)[_i]), (PG8_LAS unsigned*)(lds + (bufoff) + ldsw + _i * 8192), 16, 0, 0); } while (0)
; #define PG8_LDA(dst, b, h) do { _Pragma("unroll") for (int m = 0; m < 4; ++m) _Pragma("unroll") for (int k = 0; k < 2; ++k) dst[m][k] = *(const PG8_LAS bf16x8*)(lds + PG8_SA(b, h) + aoff + m * 2048 + k * 1024); } while (0)
; #define PG8_LDB(dst, b, h) do { _Pragma("unroll") for (int n = 0; n < 2; ++n) _Pragma("unroll") for (int k = 0; k < 2; ++k) dst[n][k] = *(const PG8_LAS bf16x8*)(lds + PG8_SB(b, h) + boff + n * 2048 + k * 1024); } while (0)
; #define PG8_MMA(ai, bj, At, Bt) do { __builtin_amdgcn_s_setprio(1); _Pragma("unroll") for (int m = 0; m < 4; ++m) _Pragma("unroll") for (int n = 0; n < 2; ++n) _Pragma("unroll") for (int k = 0; k < 2; ++k) \
;         acc[ai][bj][m][n] = __builtin_amdgcn_mfma_f32_16x16x32_bf16(Bt[n][k], At[m][k], acc[ai][bj][m][n], 0, 0, 0); __builtin_amdgcn_s_setprio(0); } while (0)
; #define PG8_WAIT_V(n) asm volatile("s_waitcnt vmcnt(" #n ")" ::: "memory")
; #define PG8_WAIT_L(n) asm volatile("s_waitcnt lgkmcnt(" #n ")" ::: "memory")
; #define PG8_BAR __builtin_amdgcn_s_barrier()
; #define PG8_SCHED __builtin_amdgcn_sched_barrier(0)
; template <class Epi, class Sched, bool ALIGN_EPI = false, bool SP2 = false>
; __device__ __forceinline__ void gemm_phase(PG8_LAS unsigned char* lds, int tid_in, const Gemm g, const Sched& S, const Epi& E) {
;     ...
;             PG8_LDB(B0, 1, 0); PG8_LDB(B1, 1, 1); PG8_SCHED; PG8_LDA(At, 1, 0); PG8_STAGE(PG8_SA(0, 1), a2 + hstep, voffA);
;             PG8_WAIT_V(8); PG8_WAIT_L(0); PG8_BAR; PG8_MMA(0, 0, At, B0); PG8_MMA(0, 1, At, B1); PG8_BAR; PG8_SCHED;
;             PG8_LDA(At, 1, 1); PG8_STAGE(PG8_SB(1, 0), b3, voffB); PG8_STAGE(PG8_SB(1, 1), b3 + hstep, voffB); PG8_STAGE(PG8_SA(1, 0), a3, voffA);
;             PG8_WAIT_V(8); PG8_WAIT_L(0); PG8_BAR; PG8_MMA(1, 0, At, B0); PG8_MMA(1, 1, At, B1); PG8_BAR; PG8_SCHED;
;     ...
;         if constexpr (ALIGN_EPI) { if (wr == 0) PG8_BAR; }
	s_nop 4
	ds_read_b128 v[14:17], v214
	ds_read_b128 v[18:21], v214 offset:1024
	ds_read_b128 v[166:169], v214 offset:2048
	ds_read_b128 v[190:193], v214 offset:3072
	ds_read_b128 v[194:197], v222
	ds_read_b128 v[214:217], v222 offset:1024
	ds_read_b128 v[218:221], v222 offset:2048
	ds_read_b128 v[222:225], v222 offset:3072
	s_add_u32 s34, s48, 0x10000
	s_addc_u32 s35, s49, 0
	s_mov_b32 m0, s29
	v_lshl_add_u64 v[54:55], s[34:35], 0, v[134:135]
	ds_read_b128 v[22:25], v137 offset:32768
	ds_read_b128 v[30:33], v137 offset:33792
	ds_read_b128 v[58:61], v137 offset:34816
	ds_read_b128 v[226:229], v137 offset:35840
	ds_read_b128 v[230:233], v137 offset:36864
	ds_read_b128 v[234:237], v137 offset:37888
	ds_read_b128 v[238:241], v137 offset:38912
	ds_read_b128 v[248:251], v137 offset:39936
	global_load_lds_dwordx4 v[54:55], off
	v_lshl_add_u64 v[54:55], s[34:35], 0, v[132:133]
	s_mov_b32 m0, s33
	s_nop 0
	global_load_lds_dwordx4 v[54:55], off
	s_waitcnt vmcnt(8)
	s_waitcnt lgkmcnt(0)
	s_barrier
	s_setprio 1
	s_waitcnt lgkmcnt(0)
	v_mfma_f32_16x16x32_bf16 v[54:57], v[14:17], v[22:25], v[66:69]
	v_mfma_f32_16x16x32_bf16 v[126:129], v[18:21], v[30:33], v[54:57]
	v_mfma_f32_16x16x32_bf16 v[54:57], v[166:169], v[22:25], v[70:73]
	v_mfma_f32_16x16x32_bf16 v[122:125], v[190:193], v[30:33], v[54:57]
	v_mfma_f32_16x16x32_bf16 v[54:57], v[14:17], v[58:61], v[74:77]
	v_mfma_f32_16x16x32_bf16 v[110:113], v[18:21], v[226:229], v[54:57]
	v_mfma_f32_16x16x32_bf16 v[54:57], v[166:169], v[58:61], v[78:81]
	v_mfma_f32_16x16x32_bf16 v[102:105], v[190:193], v[226:229], v[54:57]
	v_mfma_f32_16x16x32_bf16 v[54:57], v[14:17], v[230:233], v[82:85]
	v_mfma_f32_16x16x32_bf16 v[94:97], v[18:21], v[234:237], v[54:57]
	v_mfma_f32_16x16x32_bf16 v[54:57], v[166:169], v[230:233], v[86:89]
	v_mfma_f32_16x16x32_bf16 v[86:89], v[190:193], v[234:237], v[54:57]
	v_mfma_f32_16x16x32_bf16 v[54:57], v[14:17], v[238:241], v[90:93]
	v_mfma_f32_16x16x32_bf16 v[62:65], v[18:21], v[248:251], v[54:57]
	v_mfma_f32_16x16x32_bf16 v[54:57], v[166:169], v[238:241], v[202:205]
	v_mfma_f32_16x16x32_bf16 v[54:57], v[190:193], v[248:251], v[54:57]
	v_mfma_f32_16x16x32_bf16 v[66:69], v[194:197], v[22:25], v[98:101]
	v_mfma_f32_16x16x32_bf16 v[22:25], v[218:221], v[22:25], v[34:37]
	v_mfma_f32_16x16x32_bf16 v[114:117], v[222:225], v[30:33], v[22:25]
	v_mfma_f32_16x16x32_bf16 v[22:25], v[194:197], v[58:61], v[38:41]
	v_mfma_f32_16x16x32_bf16 v[106:109], v[214:217], v[226:229], v[22:25]
	v_mfma_f32_16x16x32_bf16 v[22:25], v[218:221], v[58:61], v[42:45]
	v_mfma_f32_16x16x32_bf16 v[98:101], v[222:225], v[226:229], v[22:25]
	v_mfma_f32_16x16x32_bf16 v[22:25], v[194:197], v[230:233], v[46:49]
	v_mfma_f32_16x16x32_bf16 v[90:93], v[214:217], v[234:237], v[22:25]
	v_mfma_f32_16x16x32_bf16 v[22:25], v[218:221], v[230:233], v[50:53]
	v_mfma_f32_16x16x32_bf16 v[82:85], v[222:225], v[234:237], v[22:25]
	v_mfma_f32_16x16x32_bf16 v[22:25], v[194:197], v[238:241], v[170:173]
	v_mfma_f32_16x16x32_bf16 v[58:61], v[214:217], v[248:251], v[22:25]
	v_mfma_f32_16x16x32_bf16 v[22:25], v[218:221], v[238:241], v[174:177]
	v_mfma_f32_16x16x32_bf16 v[118:121], v[214:217], v[30:33], v[66:69]
	v_mfma_f32_16x16x32_bf16 v[50:53], v[222:225], v[248:251], v[22:25]
	s_setprio 0
	s_barrier
	s_mov_b32 m0, s55
	s_nop 2
	v_lshl_add_u64 v[22:23], v[206:207], 0, s[24:25]
	s_add_u32 s34, s42, 0x10080
	ds_read_b128 v[34:37], v137 offset:49152
	ds_read_b128 v[42:45], v137 offset:50176
	ds_read_b128 v[170:173], v137 offset:51200
	ds_read_b128 v[174:177], v137 offset:52224
	ds_read_b128 v[202:205], v137 offset:53248
	ds_read_b128 v[226:229], v137 offset:54272
	ds_read_b128 v[230:233], v137 offset:55296
	ds_read_b128 v[234:237], v137 offset:56320
	global_load_lds_dwordx4 v[22:23], off
	v_lshl_add_u64 v[22:23], v[208:209], 0, s[24:25]
	s_mov_b32 m0, s47
	s_addc_u32 s35, s43, 0
	global_load_lds_dwordx4 v[22:23], off
	v_lshl_add_u64 v[22:23], s[34:35], 0, v[8:9]
	s_mov_b32 m0, s50
	s_nop 0
	global_load_lds_dwordx4 v[22:23], off
	v_lshl_add_u64 v[22:23], s[34:35], 0, v[130:131]
	s_mov_b32 m0, s51
	s_nop 0
	global_load_lds_dwordx4 v[22:23], off
	v_lshl_add_u64 v[22:23], v[242:243], 0, s[24:25]
	s_mov_b32 m0, s45
	s_nop 0
	global_load_lds_dwordx4 v[22:23], off
	v_lshl_add_u64 v[22:23], v[244:245], 0, s[24:25]
	s_mov_b32 m0, s46
	s_nop 0
	global_load_lds_dwordx4 v[22:23], off
	s_waitcnt vmcnt(8)
	s_waitcnt lgkmcnt(0)
	s_barrier
	s_setprio 1
	s_waitcnt lgkmcnt(0)
	v_mfma_f32_16x16x32_bf16 v[22:25], v[14:17], v[34:37], v[138:141]
	v_mfma_f32_16x16x32_bf16 v[78:81], v[18:21], v[42:45], v[22:25]
	v_mfma_f32_16x16x32_bf16 v[22:25], v[166:169], v[34:37], v[142:145]
	v_mfma_f32_16x16x32_bf16 v[70:73], v[190:193], v[42:45], v[22:25]
	v_mfma_f32_16x16x32_bf16 v[22:25], v[14:17], v[170:173], v[146:149]
	v_mfma_f32_16x16x32_bf16 v[46:49], v[18:21], v[174:177], v[22:25]
	v_mfma_f32_16x16x32_bf16 v[22:25], v[166:169], v[170:173], v[150:153]
	v_mfma_f32_16x16x32_bf16 v[38:41], v[190:193], v[174:177], v[22:25]
	v_mfma_f32_16x16x32_bf16 v[22:25], v[14:17], v[202:205], v[154:157]
	v_mfma_f32_16x16x32_bf16 v[0:3], v[14:17], v[230:233], v[0:3]
	v_mfma_f32_16x16x32_bf16 v[30:33], v[18:21], v[226:229], v[22:25]
	v_mfma_f32_16x16x32_bf16 v[22:25], v[166:169], v[202:205], v[158:161]
	v_mfma_f32_16x16x32_bf16 v[14:17], v[18:21], v[234:237], v[0:3]
	v_mfma_f32_16x16x32_bf16 v[0:3], v[166:169], v[230:233], v[4:7]
	v_mfma_f32_16x16x32_bf16 v[22:25], v[190:193], v[226:229], v[22:25]
	v_mfma_f32_16x16x32_bf16 v[4:7], v[190:193], v[234:237], v[0:3]
	v_mfma_f32_16x16x32_bf16 v[0:3], v[194:197], v[34:37], v[10:13]
	v_mfma_f32_16x16x32_bf16 v[74:77], v[214:217], v[42:45], v[0:3]
	v_mfma_f32_16x16x32_bf16 v[0:3], v[218:221], v[34:37], v[198:201]
	v_mfma_f32_16x16x32_bf16 v[66:69], v[222:225], v[42:45], v[0:3]
	v_mfma_f32_16x16x32_bf16 v[0:3], v[194:197], v[170:173], v[26:29]
	v_mfma_f32_16x16x32_bf16 v[42:45], v[214:217], v[174:177], v[0:3]
	v_mfma_f32_16x16x32_bf16 v[0:3], v[218:221], v[170:173], v[178:181]
	v_mfma_f32_16x16x32_bf16 v[34:37], v[222:225], v[174:177], v[0:3]
	v_mfma_f32_16x16x32_bf16 v[0:3], v[194:197], v[202:205], v[210:213]
	v_mfma_f32_16x16x32_bf16 v[26:29], v[214:217], v[226:229], v[0:3]
	v_mfma_f32_16x16x32_bf16 v[0:3], v[218:221], v[202:205], v[182:185]
	v_mfma_f32_16x16x32_bf16 v[18:21], v[222:225], v[226:229], v[0:3]
	v_mfma_f32_16x16x32_bf16 v[0:3], v[194:197], v[230:233], v[186:189]
	v_mfma_f32_16x16x32_bf16 v[10:13], v[214:217], v[234:237], v[0:3]
	v_mfma_f32_16x16x32_bf16 v[0:3], v[218:221], v[230:233], v[162:165]
	v_mfma_f32_16x16x32_bf16 v[0:3], v[222:225], v[234:237], v[0:3]
	s_setprio 0
	s_barrier
	s_andn2_b64 vcc, exec, s[8:9]
	s_cbranch_vccnz .LBB0_425
	s_barrier

; #define PG8_STAGE(bufoff, gbase, voff) do { _Pragma("unroll") for (int _i = 0; _i < 2; ++_i) \
;         __builtin_amdgcn_global_load_lds((const unsigned*)((const char*)(gbase) + (voff)[_i]), (PG8_LAS unsigned*)(lds + (bufoff) + ldsw + _i * 8192), 16, 0, 0); } while (0)
; #define PG8_LDA(dst, b, h) do { _Pragma("unroll") for (int m = 0; m < 4; ++m) _Pragma("unroll") for (int k = 0; k < 2; ++k) dst[m][k] = *(const PG8_LAS bf16x8*)(lds + PG8_SA(b, h) + aoff + m * 2048 + k * 1024); } while (0)
; #define PG8_LDB(dst, b, h) do { _Pragma("unroll") for (int n = 0; n < 2; ++n) _Pragma("unroll") for (int k = 0; k < 2; ++k) dst[n][k] = *(const PG8_LAS bf16x8*)(lds + PG8_SB(b, h) + boff + n * 2048 + k * 1024); } while (0)
; #define PG8_MMA(ai, bj, At, Bt) do { __builtin_amdgcn_s_setprio(1); _Pragma("unroll") for (int m = 0; m < 4; ++m) _Pragma("unroll") for (int n = 0; n < 2; ++n) _Pragma("unroll") for (int k = 0; k < 2; ++k) \
;         acc[ai][bj][m][n] = __builtin_amdgcn_mfma_f32_16x16x32_bf16(Bt[n][k], At[m][k], acc[ai][bj][m][n], 0, 0, 0); __builtin_amdgcn_s_setprio(0); } while (0)
; #define PG8_WAIT_V(n) asm volatile("s_waitcnt vmcnt(" #n ")" ::: "memory")
; #define PG8_WAIT_L(n) asm volatile("s_waitcnt lgkmcnt(" #n ")" ::: "memory")
; #define PG8_BAR __builtin_amdgcn_s_barrier()
; #define PG8_SCHED __builtin_amdgcn_sched_barrier(0)
; template <class Epi, class Sched, bool ALIGN_EPI = false, bool SP2 = false>
; __device__ __forceinline__ void gemm_phase(PG8_LAS unsigned char* lds, int tid_in, const Gemm g, const Sched& S, const Epi& E) {
;     ...
;         for (int t = 0; t < nt; t += 2) {
;             const bool last = (t == nt - 2);
;             const char* a1 = cA + (size_t)(t + 1) * kstep;
;             const char* a2 = last ? nA : cA + (size_t)(t + 2) * kstep; const char* b2 = last ? nB : cB + (size_t)(t + 2) * kstep;
;             const char* a3 = a2 + kstep; const char* b3 = b2 + kstep;
;             if (last && has_next) S.a_ready(nxt);
;             if constexpr (SP2) {
;             PG8_LDB(B0, 0, 0); PG8_LDB(B1, 0, 1); PG8_SCHED; PG8_LDA(At, 0, 0); PG8_STAGE(PG8_SA(1, 1), a1 + hstep, voffA);
;             PG8_WAIT_V(8); PG8_WAIT_L(0); PG8_BAR; PG8_MMA(0, 0, At, B0); PG8_MMA(0, 1, At, B1); PG8_BAR; PG8_SCHED;
;             PG8_LDA(At, 0, 1); PG8_STAGE(PG8_SB(0, 0), b2, voffB); PG8_STAGE(PG8_SB(0, 1), b2 + hstep, voffB); PG8_STAGE(PG8_SA(0, 0), a2, voffA);
.LBB0_592:
	s_add_u32 s18, s34, 0xfffe0080
	s_addc_u32 s42, s35, -1
	s_add_i32 s55, 0, 0x10000
	s_cmp_eq_u32 s37, 4
	s_cselect_b32 s49, s15, s42
	s_cselect_b32 s48, s53, s18
	s_cselect_b32 s43, s13, s36
	s_cselect_b32 s42, s38, s39
	s_add_i32 s18, 0, 0x14000
	v_add_u32_e32 v134, s55, v228
	v_add_u32_e32 v158, s18, v228
	ds_read_b128 v[118:121], v134
	ds_read_b128 v[126:129], v134 offset:1024
	ds_read_b128 v[130:133], v134 offset:2048
	ds_read_b128 v[134:137], v134 offset:3072
	ds_read_b128 v[138:141], v158
	ds_read_b128 v[150:153], v158 offset:1024
	ds_read_b128 v[154:157], v158 offset:2048
	ds_read_b128 v[158:161], v158 offset:3072
	v_lshl_add_u64 v[204:205], s[34:35], 0, v[196:197]
	s_add_i32 m0, s21, 0xc000
	ds_read_b128 v[162:165], v229
	ds_read_b128 v[166:169], v229 offset:1024
	ds_read_b128 v[170:173], v229 offset:2048
	ds_read_b128 v[174:177], v229 offset:3072
	ds_read_b128 v[178:181], v229 offset:4096
	ds_read_b128 v[182:185], v229 offset:5120
	ds_read_b128 v[186:189], v229 offset:6144
	ds_read_b128 v[200:203], v229 offset:7168
	global_load_lds_dwordx4 v[204:205], off
	v_lshl_add_u64 v[204:205], s[34:35], 0, v[198:199]
	s_add_i32 m0, s21, 0xe000
	s_nop 0
	global_load_lds_dwordx4 v[204:205], off
	s_waitcnt vmcnt(8)
	s_waitcnt lgkmcnt(0)
	s_barrier
	s_setprio 1
	s_waitcnt lgkmcnt(0)
	v_mfma_f32_16x16x32_bf16 v[146:149], v[118:121], v[162:165], v[146:149]
	v_mfma_f32_16x16x32_bf16 v[142:145], v[130:133], v[162:165], v[142:145]
	v_mfma_f32_16x16x32_bf16 v[110:113], v[118:121], v[170:173], v[110:113]
	v_mfma_f32_16x16x32_bf16 v[106:109], v[130:133], v[170:173], v[106:109]
	v_mfma_f32_16x16x32_bf16 v[94:97], v[118:121], v[178:181], v[94:97]
	v_mfma_f32_16x16x32_bf16 v[90:93], v[130:133], v[178:181], v[90:93]
	v_mfma_f32_16x16x32_bf16 v[78:81], v[118:121], v[186:189], v[78:81]
	v_mfma_f32_16x16x32_bf16 v[74:77], v[130:133], v[186:189], v[74:77]
	v_mfma_f32_16x16x32_bf16 v[146:149], v[126:129], v[166:169], v[146:149]
	v_mfma_f32_16x16x32_bf16 v[142:145], v[134:137], v[166:169], v[142:145]
	v_mfma_f32_16x16x32_bf16 v[110:113], v[126:129], v[174:177], v[110:113]
	v_mfma_f32_16x16x32_bf16 v[106:109], v[134:137], v[174:177], v[106:109]
	v_mfma_f32_16x16x32_bf16 v[94:97], v[126:129], v[182:185], v[94:97]
	v_mfma_f32_16x16x32_bf16 v[90:93], v[134:137], v[182:185], v[90:93]
	v_mfma_f32_16x16x32_bf16 v[78:81], v[126:129], v[200:203], v[78:81]
	v_mfma_f32_16x16x32_bf16 v[74:77], v[134:137], v[200:203], v[74:77]
	v_mfma_f32_16x16x32_bf16 v[122:125], v[138:141], v[162:165], v[122:125]
	v_mfma_f32_16x16x32_bf16 v[114:117], v[154:157], v[162:165], v[114:117]
	v_mfma_f32_16x16x32_bf16 v[102:105], v[138:141], v[170:173], v[102:105]
	v_mfma_f32_16x16x32_bf16 v[98:101], v[154:157], v[170:173], v[98:101]
	v_mfma_f32_16x16x32_bf16 v[86:89], v[138:141], v[178:181], v[86:89]
	v_mfma_f32_16x16x32_bf16 v[82:85], v[154:157], v[178:181], v[82:85]
	v_mfma_f32_16x16x32_bf16 v[70:73], v[138:141], v[186:189], v[70:73]
	v_mfma_f32_16x16x32_bf16 v[66:69], v[154:157], v[186:189], v[66:69]
	v_mfma_f32_16x16x32_bf16 v[122:125], v[150:153], v[166:169], v[122:125]
	v_mfma_f32_16x16x32_bf16 v[114:117], v[158:161], v[166:169], v[114:117]
	v_mfma_f32_16x16x32_bf16 v[102:105], v[150:153], v[174:177], v[102:105]
	v_mfma_f32_16x16x32_bf16 v[98:101], v[158:161], v[174:177], v[98:101]
	v_mfma_f32_16x16x32_bf16 v[86:89], v[150:153], v[182:185], v[86:89]
	v_mfma_f32_16x16x32_bf16 v[82:85], v[158:161], v[182:185], v[82:85]
	v_mfma_f32_16x16x32_bf16 v[70:73], v[150:153], v[200:203], v[70:73]
	v_mfma_f32_16x16x32_bf16 v[66:69], v[158:161], v[200:203], v[66:69]
	s_setprio 0
	s_barrier
	s_add_i32 s55, s55, s20
	v_lshl_add_u64 v[204:205], s[42:43], 0, v[8:9]
	s_mov_b32 m0, s55
	ds_read_b128 v[162:165], v229 offset:16384
	ds_read_b128 v[166:169], v229 offset:17408
	ds_read_b128 v[170:173], v229 offset:18432
	ds_read_b128 v[174:177], v229 offset:19456
	ds_read_b128 v[178:181], v229 offset:20480
	ds_read_b128 v[182:185], v229 offset:21504
	ds_read_b128 v[186:189], v229 offset:22528
	ds_read_b128 v[200:203], v229 offset:23552
	global_load_lds_dwordx4 v[204:205], off
	s_add_i32 m0, s55, 0x2000
	s_add_u32 s56, s42, 0x20000
	v_lshl_add_u64 v[206:207], s[42:43], 0, v[190:191]
	s_addc_u32 s57, s43, 0
	s_add_i32 s18, s18, s20
	global_load_lds_dwordx4 v[206:207], off
	v_lshl_add_u64 v[208:209], s[56:57], 0, v[8:9]
	s_mov_b32 m0, s18
	v_lshl_add_u64 v[210:211], s[48:49], 0, v[192:193]
	global_load_lds_dwordx4 v[208:209], off
	v_lshl_add_u64 v[208:209], s[56:57], 0, v[190:191]
	s_add_i32 m0, s18, 0x2000
	s_nop 0
	global_load_lds_dwordx4 v[208:209], off
	v_lshl_add_u64 v[208:209], s[48:49], 0, v[194:195]
	s_mov_b32 m0, s21
	s_nop 0
	global_load_lds_dwordx4 v[208:209], off
	s_mov_b32 m0, s28
	s_nop 0
	global_load_lds_dwordx4 v[210:211], off
	s_waitcnt vmcnt(8)
	s_waitcnt lgkmcnt(0)
	s_barrier
; #define PG8_STAGE(bufoff, gbase, voff) do { _Pragma("unroll") for (int _i = 0; _i < 2; ++_i) \
;         __builtin_amdgcn_global_load_lds((const unsigned*)((const char*)(gbase) + (voff)[_i]), (PG8_LAS unsigned*)(lds + (bufoff) + ldsw + _i * 8192), 16, 0, 0); } while (0)
; #define PG8_LDA(dst, b, h) do { _Pragma("unroll") for (int m = 0; m < 4; ++m) _Pragma("unroll") for (int k = 0; k < 2; ++k) dst[m][k] = *(const PG8_LAS bf16x8*)(lds + PG8_SA(b, h) + aoff + m * 2048 + k * 1024); } while (0)
; #define PG8_LDB(dst, b, h) do { _Pragma("unroll") for (int n = 0; n < 2; ++n) _Pragma("unroll") for (int k = 0; k < 2; ++k) dst[n][k] = *(const PG8_LAS bf16x8*)(lds + PG8_SB(b, h) + boff + n * 2048 + k * 1024); } while (0)
; #define PG8_MMA(ai, bj, At, Bt) do { __builtin_amdgcn_s_setprio(1); _Pragma("unroll") for (int m = 0; m < 4; ++m) _Pragma("unroll") for (int n = 0; n < 2; ++n) _Pragma("unroll") for (int k = 0; k < 2; ++k) \
;         acc[ai][bj][m][n] = __builtin_amdgcn_mfma_f32_16x16x32_bf16(Bt[n][k], At[m][k], acc[ai][bj][m][n], 0, 0, 0); __builtin_amdgcn_s_setprio(0); } while (0)
; #define PG8_WAIT_V(n) asm volatile("s_waitcnt vmcnt(" #n ")" ::: "memory")
; #define PG8_WAIT_L(n) asm volatile("s_waitcnt lgkmcnt(" #n ")" ::: "memory")
; #define PG8_BAR __builtin_amdgcn_s_barrier()
; #define PG8_SCHED __builtin_amdgcn_sched_barrier(0)
; template <class Epi, class Sched, bool ALIGN_EPI = false, bool SP2 = false>
; __device__ __forceinline__ void gemm_phase(PG8_LAS unsigned char* lds, int tid_in, const Gemm g, const Sched& S, const Epi& E) {
;     ...
;             PG8_WAIT_V(8); PG8_WAIT_L(0); PG8_BAR; PG8_MMA(1, 0, At, B0); PG8_MMA(1, 1, At, B1); PG8_BAR; PG8_SCHED;
;             PG8_LDB(B0, 1, 0); PG8_LDB(B1, 1, 1); PG8_SCHED; PG8_LDA(At, 1, 0); PG8_STAGE(PG8_SA(0, 1), a2 + hstep, voffA);
;             PG8_WAIT_V(8); PG8_WAIT_L(0); PG8_BAR; PG8_MMA(0, 0, At, B0); PG8_MMA(0, 1, At, B1); PG8_BAR; PG8_SCHED;
	s_setprio 1
	s_waitcnt lgkmcnt(0)
	v_mfma_f32_16x16x32_bf16 v[62:65], v[118:121], v[162:165], v[62:65]
	v_mfma_f32_16x16x32_bf16 v[58:61], v[130:133], v[162:165], v[58:61]
	v_mfma_f32_16x16x32_bf16 v[46:49], v[118:121], v[170:173], v[46:49]
	v_mfma_f32_16x16x32_bf16 v[42:45], v[130:133], v[170:173], v[42:45]
	v_mfma_f32_16x16x32_bf16 v[30:33], v[118:121], v[178:181], v[30:33]
	v_mfma_f32_16x16x32_bf16 v[26:29], v[130:133], v[178:181], v[26:29]
	v_mfma_f32_16x16x32_bf16 v[14:17], v[118:121], v[186:189], v[14:17]
	v_mfma_f32_16x16x32_bf16 v[10:13], v[130:133], v[186:189], v[10:13]
	v_mfma_f32_16x16x32_bf16 v[62:65], v[126:129], v[166:169], v[62:65]
	v_mfma_f32_16x16x32_bf16 v[58:61], v[134:137], v[166:169], v[58:61]
	v_mfma_f32_16x16x32_bf16 v[46:49], v[126:129], v[174:177], v[46:49]
	v_mfma_f32_16x16x32_bf16 v[42:45], v[134:137], v[174:177], v[42:45]
	v_mfma_f32_16x16x32_bf16 v[30:33], v[126:129], v[182:185], v[30:33]
	v_mfma_f32_16x16x32_bf16 v[26:29], v[134:137], v[182:185], v[26:29]
	v_mfma_f32_16x16x32_bf16 v[14:17], v[126:129], v[200:203], v[14:17]
	v_mfma_f32_16x16x32_bf16 v[10:13], v[134:137], v[200:203], v[10:13]
	v_mfma_f32_16x16x32_bf16 v[54:57], v[138:141], v[162:165], v[54:57]
	v_mfma_f32_16x16x32_bf16 v[50:53], v[154:157], v[162:165], v[50:53]
	v_mfma_f32_16x16x32_bf16 v[38:41], v[138:141], v[170:173], v[38:41]
	v_mfma_f32_16x16x32_bf16 v[34:37], v[154:157], v[170:173], v[34:37]
	v_mfma_f32_16x16x32_bf16 v[22:25], v[138:141], v[178:181], v[22:25]
	v_mfma_f32_16x16x32_bf16 v[18:21], v[154:157], v[178:181], v[18:21]
	v_mfma_f32_16x16x32_bf16 v[4:7], v[138:141], v[186:189], v[4:7]
	v_mfma_f32_16x16x32_bf16 v[0:3], v[154:157], v[186:189], v[0:3]
	v_mfma_f32_16x16x32_bf16 v[54:57], v[150:153], v[166:169], v[54:57]
	v_mfma_f32_16x16x32_bf16 v[50:53], v[158:161], v[166:169], v[50:53]
	v_mfma_f32_16x16x32_bf16 v[38:41], v[150:153], v[174:177], v[38:41]
	v_mfma_f32_16x16x32_bf16 v[34:37], v[158:161], v[174:177], v[34:37]
	v_mfma_f32_16x16x32_bf16 v[22:25], v[150:153], v[182:185], v[22:25]
	v_mfma_f32_16x16x32_bf16 v[18:21], v[158:161], v[182:185], v[18:21]
	v_mfma_f32_16x16x32_bf16 v[4:7], v[150:153], v[200:203], v[4:7]
	v_mfma_f32_16x16x32_bf16 v[0:3], v[158:161], v[200:203], v[0:3]
	s_setprio 0
	s_barrier
	s_add_i32 s18, 0, 0x18000
	s_add_i32 s55, 0, 0x1c000
	v_add_u32_e32 v134, s18, v228
	v_add_u32_e32 v158, s55, v228
	ds_read_b128 v[118:121], v134
	ds_read_b128 v[126:129], v134 offset:1024
	ds_read_b128 v[130:133], v134 offset:2048
	ds_read_b128 v[134:137], v134 offset:3072
	ds_read_b128 v[138:141], v158
	ds_read_b128 v[150:153], v158 offset:1024
	ds_read_b128 v[154:157], v158 offset:2048
	ds_read_b128 v[158:161], v158 offset:3072
	s_add_u32 s48, s48, 0x20000
	s_addc_u32 s49, s49, 0
	s_mov_b32 m0, s29
	v_lshl_add_u64 v[212:213], s[48:49], 0, v[194:195]
	ds_read_b128 v[162:165], v229 offset:32768
	ds_read_b128 v[166:169], v229 offset:33792
	ds_read_b128 v[170:173], v229 offset:34816
	ds_read_b128 v[174:177], v229 offset:35840
	ds_read_b128 v[178:181], v229 offset:36864
	ds_read_b128 v[182:185], v229 offset:37888
	ds_read_b128 v[186:189], v229 offset:38912
	ds_read_b128 v[200:203], v229 offset:39936
	global_load_lds_dwordx4 v[212:213], off
	v_lshl_add_u64 v[212:213], s[48:49], 0, v[192:193]
	s_mov_b32 m0, s33
	s_nop 0
	global_load_lds_dwordx4 v[212:213], off
	s_waitcnt vmcnt(8)
	s_waitcnt lgkmcnt(0)
	s_barrier
	s_setprio 1
	s_waitcnt lgkmcnt(0)
	v_mfma_f32_16x16x32_bf16 v[146:149], v[118:121], v[162:165], v[146:149]
	v_mfma_f32_16x16x32_bf16 v[142:145], v[130:133], v[162:165], v[142:145]
	v_mfma_f32_16x16x32_bf16 v[110:113], v[118:121], v[170:173], v[110:113]
	v_mfma_f32_16x16x32_bf16 v[106:109], v[130:133], v[170:173], v[106:109]
	v_mfma_f32_16x16x32_bf16 v[94:97], v[118:121], v[178:181], v[94:97]
	v_mfma_f32_16x16x32_bf16 v[90:93], v[130:133], v[178:181], v[90:93]
	v_mfma_f32_16x16x32_bf16 v[78:81], v[118:121], v[186:189], v[78:81]
	v_mfma_f32_16x16x32_bf16 v[74:77], v[130:133], v[186:189], v[74:77]
	v_mfma_f32_16x16x32_bf16 v[146:149], v[126:129], v[166:169], v[146:149]
	v_mfma_f32_16x16x32_bf16 v[142:145], v[134:137], v[166:169], v[142:145]
	v_mfma_f32_16x16x32_bf16 v[110:113], v[126:129], v[174:177], v[110:113]
	v_mfma_f32_16x16x32_bf16 v[106:109], v[134:137], v[174:177], v[106:109]
	v_mfma_f32_16x16x32_bf16 v[94:97], v[126:129], v[182:185], v[94:97]
	v_mfma_f32_16x16x32_bf16 v[90:93], v[134:137], v[182:185], v[90:93]
	v_mfma_f32_16x16x32_bf16 v[78:81], v[126:129], v[200:203], v[78:81]
	v_mfma_f32_16x16x32_bf16 v[74:77], v[134:137], v[200:203], v[74:77]
	v_mfma_f32_16x16x32_bf16 v[122:125], v[138:141], v[162:165], v[122:125]
	v_mfma_f32_16x16x32_bf16 v[114:117], v[154:157], v[162:165], v[114:117]
	v_mfma_f32_16x16x32_bf16 v[102:105], v[138:141], v[170:173], v[102:105]
	v_mfma_f32_16x16x32_bf16 v[98:101], v[154:157], v[170:173], v[98:101]
	v_mfma_f32_16x16x32_bf16 v[86:89], v[138:141], v[178:181], v[86:89]
	v_mfma_f32_16x16x32_bf16 v[82:85], v[154:157], v[178:181], v[82:85]
	v_mfma_f32_16x16x32_bf16 v[70:73], v[138:141], v[186:189], v[70:73]
	v_mfma_f32_16x16x32_bf16 v[66:69], v[154:157], v[186:189], v[66:69]
	v_mfma_f32_16x16x32_bf16 v[122:125], v[150:153], v[166:169], v[122:125]
	v_mfma_f32_16x16x32_bf16 v[114:117], v[158:161], v[166:169], v[114:117]
	v_mfma_f32_16x16x32_bf16 v[102:105], v[150:153], v[174:177], v[102:105]
	v_mfma_f32_16x16x32_bf16 v[98:101], v[158:161], v[174:177], v[98:101]
	v_mfma_f32_16x16x32_bf16 v[86:89], v[150:153], v[182:185], v[86:89]
	v_mfma_f32_16x16x32_bf16 v[82:85], v[158:161], v[182:185], v[82:85]
	v_mfma_f32_16x16x32_bf16 v[70:73], v[150:153], v[200:203], v[70:73]
	v_mfma_f32_16x16x32_bf16 v[66:69], v[158:161], v[200:203], v[66:69]
	s_setprio 0
	s_barrier
; #define PG8_STAGE(bufoff, gbase, voff) do { _Pragma("unroll") for (int _i = 0; _i < 2; ++_i) \
;         __builtin_amdgcn_global_load_lds((const unsigned*)((const char*)(gbase) + (voff)[_i]), (PG8_LAS unsigned*)(lds + (bufoff) + ldsw + _i * 8192), 16, 0, 0); } while (0)
; #define PG8_LDA(dst, b, h) do { _Pragma("unroll") for (int m = 0; m < 4; ++m) _Pragma("unroll") for (int k = 0; k < 2; ++k) dst[m][k] = *(const PG8_LAS bf16x8*)(lds + PG8_SA(b, h) + aoff + m * 2048 + k * 1024); } while (0)
; #define PG8_WAIT_V(n) asm volatile("s_waitcnt vmcnt(" #n ")" ::: "memory")
; #define PG8_WAIT_L(n) asm volatile("s_waitcnt lgkmcnt(" #n ")" ::: "memory")
; template <class Epi, class Sched, bool ALIGN_EPI = false, bool SP2 = false>
; __device__ __forceinline__ void gemm_phase(PG8_LAS unsigned char* lds, int tid_in, const Gemm g, const Sched& S, const Epi& E) {
;     ...
;         for (int t = 0; t < nt; t += 2) {
;             const bool last = (t == nt - 2);
;             const char* a1 = cA + (size_t)(t + 1) * kstep;
;             const char* a2 = last ? nA : cA + (size_t)(t + 2) * kstep; const char* b2 = last ? nB : cB + (size_t)(t + 2) * kstep;
;             const char* a3 = a2 + kstep; const char* b3 = b2 + kstep;
;             if (last && has_next) S.a_ready(nxt);
;             if constexpr (SP2) {
;             PG8_LDB(B0, 0, 0); PG8_LDB(B1, 0, 1); PG8_SCHED; PG8_LDA(At, 0, 0); PG8_STAGE(PG8_SA(1, 1), a1 + hstep, voffA);
;             PG8_WAIT_V(8); PG8_WAIT_L(0); PG8_BAR; PG8_MMA(0, 0, At, B0); PG8_MMA(0, 1, At, B1); PG8_BAR; PG8_SCHED;
;             PG8_LDA(At, 0, 1); PG8_STAGE(PG8_SB(0, 0), b2, voffB); PG8_STAGE(PG8_SB(0, 1), b2 + hstep, voffB); PG8_STAGE(PG8_SA(0, 0), a2, voffA);
;             PG8_WAIT_V(8); PG8_WAIT_L(0); PG8_BAR; PG8_MMA(1, 0, At, B0); PG8_MMA(1, 1, At, B1); PG8_BAR; PG8_SCHED;
;             PG8_LDB(B0, 1, 0); PG8_LDB(B1, 1, 1); PG8_SCHED; PG8_LDA(At, 1, 0); PG8_STAGE(PG8_SA(0, 1), a2 + hstep, voffA);
;             PG8_WAIT_V(8); PG8_WAIT_L(0); PG8_BAR; PG8_MMA(0, 0, At, B0); PG8_MMA(0, 1, At, B1); PG8_BAR; PG8_SCHED;
;             PG8_LDA(At, 1, 1); PG8_STAGE(PG8_SB(1, 0), b3, voffB); PG8_STAGE(PG8_SB(1, 1), b3 + hstep, voffB); PG8_STAGE(PG8_SA(1, 0), a3, voffA);
;             PG8_WAIT_V(8); PG8_WAIT_L(0); PG8_BAR; PG8_MMA(1, 0, At, B0); PG8_MMA(1, 1, At, B1); PG8_BAR; PG8_SCHED;
;     ...
;         if constexpr (ALIGN_EPI) { if (wr == 0) PG8_BAR; }
	s_add_i32 s18, s18, s20
	v_lshl_add_u64 v[204:205], v[204:205], 0, s[24:25]
	s_mov_b32 m0, s18
	ds_read_b128 v[162:165], v229 offset:49152
	ds_read_b128 v[166:169], v229 offset:50176
	ds_read_b128 v[170:173], v229 offset:51200
	ds_read_b128 v[174:177], v229 offset:52224
	ds_read_b128 v[178:181], v229 offset:53248
	ds_read_b128 v[182:185], v229 offset:54272
	ds_read_b128 v[186:189], v229 offset:55296
	ds_read_b128 v[200:203], v229 offset:56320
	global_load_lds_dwordx4 v[204:205], off
	s_add_i32 m0, s18, 0x2000
	s_add_u32 s42, s42, 0x20080
	v_lshl_add_u64 v[204:205], v[206:207], 0, s[24:25]
	s_addc_u32 s43, s43, 0
	s_add_i32 s18, s55, s20
	global_load_lds_dwordx4 v[204:205], off
	v_lshl_add_u64 v[204:205], s[42:43], 0, v[8:9]
	s_mov_b32 m0, s18
	s_nop 0
	global_load_lds_dwordx4 v[204:205], off
	v_lshl_add_u64 v[204:205], s[42:43], 0, v[190:191]
	s_add_i32 m0, s18, 0x2000
	s_nop 0
	global_load_lds_dwordx4 v[204:205], off
	v_lshl_add_u64 v[204:205], v[208:209], 0, s[24:25]
	s_mov_b32 m0, s45
	s_nop 0
	global_load_lds_dwordx4 v[204:205], off
	v_lshl_add_u64 v[204:205], v[210:211], 0, s[24:25]
	s_mov_b32 m0, s46
	s_nop 0
	global_load_lds_dwordx4 v[204:205], off
	s_waitcnt vmcnt(8)
	s_waitcnt lgkmcnt(0)
	s_barrier
	s_setprio 1
	s_waitcnt lgkmcnt(0)
	v_mfma_f32_16x16x32_bf16 v[62:65], v[118:121], v[162:165], v[62:65]
	v_mfma_f32_16x16x32_bf16 v[58:61], v[130:133], v[162:165], v[58:61]
	v_mfma_f32_16x16x32_bf16 v[46:49], v[118:121], v[170:173], v[46:49]
	v_mfma_f32_16x16x32_bf16 v[42:45], v[130:133], v[170:173], v[42:45]
	v_mfma_f32_16x16x32_bf16 v[30:33], v[118:121], v[178:181], v[30:33]
	v_mfma_f32_16x16x32_bf16 v[26:29], v[130:133], v[178:181], v[26:29]
	v_mfma_f32_16x16x32_bf16 v[14:17], v[118:121], v[186:189], v[14:17]
	v_mfma_f32_16x16x32_bf16 v[10:13], v[130:133], v[186:189], v[10:13]
	v_mfma_f32_16x16x32_bf16 v[62:65], v[126:129], v[166:169], v[62:65]
	v_mfma_f32_16x16x32_bf16 v[58:61], v[134:137], v[166:169], v[58:61]
	v_mfma_f32_16x16x32_bf16 v[46:49], v[126:129], v[174:177], v[46:49]
	v_mfma_f32_16x16x32_bf16 v[42:45], v[134:137], v[174:177], v[42:45]
	v_mfma_f32_16x16x32_bf16 v[30:33], v[126:129], v[182:185], v[30:33]
	v_mfma_f32_16x16x32_bf16 v[26:29], v[134:137], v[182:185], v[26:29]
	v_mfma_f32_16x16x32_bf16 v[14:17], v[126:129], v[200:203], v[14:17]
	v_mfma_f32_16x16x32_bf16 v[10:13], v[134:137], v[200:203], v[10:13]
	v_mfma_f32_16x16x32_bf16 v[54:57], v[138:141], v[162:165], v[54:57]
	v_mfma_f32_16x16x32_bf16 v[50:53], v[154:157], v[162:165], v[50:53]
	v_mfma_f32_16x16x32_bf16 v[38:41], v[138:141], v[170:173], v[38:41]
	v_mfma_f32_16x16x32_bf16 v[34:37], v[154:157], v[170:173], v[34:37]
	v_mfma_f32_16x16x32_bf16 v[22:25], v[138:141], v[178:181], v[22:25]
	v_mfma_f32_16x16x32_bf16 v[18:21], v[154:157], v[178:181], v[18:21]
	v_mfma_f32_16x16x32_bf16 v[4:7], v[138:141], v[186:189], v[4:7]
	v_mfma_f32_16x16x32_bf16 v[0:3], v[154:157], v[186:189], v[0:3]
	v_mfma_f32_16x16x32_bf16 v[54:57], v[150:153], v[166:169], v[54:57]
	v_mfma_f32_16x16x32_bf16 v[50:53], v[158:161], v[166:169], v[50:53]
	v_mfma_f32_16x16x32_bf16 v[38:41], v[150:153], v[174:177], v[38:41]
	v_mfma_f32_16x16x32_bf16 v[34:37], v[158:161], v[174:177], v[34:37]
	v_mfma_f32_16x16x32_bf16 v[22:25], v[150:153], v[182:185], v[22:25]
	v_mfma_f32_16x16x32_bf16 v[18:21], v[158:161], v[182:185], v[18:21]
	v_mfma_f32_16x16x32_bf16 v[4:7], v[150:153], v[200:203], v[4:7]
	v_mfma_f32_16x16x32_bf16 v[0:3], v[158:161], v[200:203], v[0:3]
	s_setprio 0
	s_barrier
	s_add_i32 s37, s37, 2
	s_add_u32 s34, s34, 0x100
	s_addc_u32 s35, s35, 0
	s_add_u32 s39, s39, 0x100
	s_addc_u32 s36, s36, 0
	s_cmp_gt_u32 s37, 5
	s_cbranch_scc0 .LBB0_592
	s_and_b64 vcc, exec, s[10:11]
	s_cbranch_vccz .LBB0_595
	s_barrier

; #define PG8_STAGE(bufoff, gbase, voff) do { _Pragma("unroll") for (int _i = 0; _i < 2; ++_i) \
;         __builtin_amdgcn_global_load_lds((const unsigned*)((const char*)(gbase) + (voff)[_i]), (PG8_LAS unsigned*)(lds + (bufoff) + ldsw + _i * 8192), 16, 0, 0); } while (0)
; #define PG8_LDA(dst, b, h) do { _Pragma("unroll") for (int m = 0; m < 4; ++m) _Pragma("unroll") for (int k = 0; k < 2; ++k) dst[m][k] = *(const PG8_LAS bf16x8*)(lds + PG8_SA(b, h) + aoff + m * 2048 + k * 1024); } while (0)
; #define PG8_LDB(dst, b, h) do { _Pragma("unroll") for (int n = 0; n < 2; ++n) _Pragma("unroll") for (int k = 0; k < 2; ++k) dst[n][k] = *(const PG8_LAS bf16x8*)(lds + PG8_SB(b, h) + boff + n * 2048 + k * 1024); } while (0)
; #define PG8_MMA(ai, bj, At, Bt) do { __builtin_amdgcn_s_setprio(1); _Pragma("unroll") for (int m = 0; m < 4; ++m) _Pragma("unroll") for (int n = 0; n < 2; ++n) _Pragma("unroll") for (int k = 0; k < 2; ++k) \
;         acc[ai][bj][m][n] = __builtin_amdgcn_mfma_f32_16x16x32_bf16(Bt[n][k], At[m][k], acc[ai][bj][m][n], 0, 0, 0); __builtin_amdgcn_s_setprio(0); } while (0)
; template <class Epi, class Sched, bool ALIGN_EPI = false, bool SP2 = false>
; __device__ __forceinline__ void gemm_phase(PG8_LAS unsigned char* lds, int tid_in, const Gemm g, const Sched& S, const Epi& E) {
;     ...
;         const bool has_next = S.next(ui + 1, nxt);
;         const char* nA = has_next ? (const char*)g.A + (size_t)nxt.pm * tstep : cA; const char* nB = has_next ? (const char*)g.Bt + (size_t)nxt.pn * tstep : cB;
;         for (int t = 0; t < nt; t += 2) {
;             const bool last = (t == nt - 2);
;             const char* a1 = cA + (size_t)(t + 1) * kstep;
;             const char* a2 = last ? nA : cA + (size_t)(t + 2) * kstep; const char* b2 = last ? nB : cB + (size_t)(t + 2) * kstep;
;             const char* a3 = a2 + kstep; const char* b3 = b2 + kstep;
;             if (last && has_next) S.a_ready(nxt);
;             if constexpr (SP2) {
;             PG8_LDB(B0, 0, 0); PG8_LDB(B1, 0, 1); PG8_SCHED; PG8_LDA(At, 0, 0); PG8_STAGE(PG8_SA(1, 1), a1 + hstep, voffA);
;             PG8_WAIT_V(8); PG8_WAIT_L(0); PG8_BAR; PG8_MMA(0, 0, At, B0); PG8_MMA(0, 1, At, B1); PG8_BAR; PG8_SCHED;
;             PG8_LDA(At, 0, 1); PG8_STAGE(PG8_SB(0, 0), b2, voffB); PG8_STAGE(PG8_SB(0, 1), b2 + hstep, voffB); PG8_STAGE(PG8_SA(0, 0), a2, voffA);
.LBB0_611:
	s_ashr_i32 s17, s16, 31
	s_lshl_b64 s[30:31], s[16:17], 17
	v_readlane_b32 s34, v253, 36
	v_readlane_b32 s35, v253, 37
	s_add_u32 s30, s34, s30
	s_addc_u32 s31, s35, s31
	s_and_b64 s[34:35], s[6:7], exec
	s_cselect_b32 s51, s31, s59
	s_cselect_b32 s50, s30, s58
	s_ashr_i32 s15, s14, 31
	s_lshl_b64 s[34:35], s[14:15], 17
	s_add_u32 s34, s0, s34
	s_addc_u32 s35, s1, s35
	s_and_b64 s[38:39], s[6:7], exec
	s_cselect_b32 s49, s35, s43
	s_cselect_b32 s48, s34, s42
	s_add_i32 s17, 0, 0x10000
	s_add_i32 s37, 0, 0x14000
	v_add_u32_e32 v210, s17, v218
	v_add_u32_e32 v211, s37, v218
	ds_read_b128 v[0:3], v210
	ds_read_b128 v[4:7], v210 offset:1024
	ds_read_b128 v[10:13], v210 offset:2048
	ds_read_b128 v[14:17], v210 offset:3072
	ds_read_b128 v[18:21], v211
	ds_read_b128 v[22:25], v211 offset:1024
	ds_read_b128 v[26:29], v211 offset:2048
	s_waitcnt vmcnt(0)
	ds_read_b128 v[30:33], v211 offset:3072
	s_add_u32 s38, s58, 0x10080
	s_addc_u32 s39, s59, 0
	s_add_i32 s53, s21, 0xc000
	v_lshl_add_u64 v[66:67], s[38:39], 0, v[190:191]
	s_mov_b32 m0, s53
	s_add_i32 s15, s21, 0xe000
	ds_read_b128 v[34:37], v219
	ds_read_b128 v[38:41], v219 offset:1024
	ds_read_b128 v[42:45], v219 offset:2048
	ds_read_b128 v[46:49], v219 offset:3072
	ds_read_b128 v[50:53], v219 offset:4096
	ds_read_b128 v[54:57], v219 offset:5120
	ds_read_b128 v[58:61], v219 offset:6144
	ds_read_b128 v[62:65], v219 offset:7168
	global_load_lds_dwordx4 v[66:67], off
	v_lshl_add_u64 v[66:67], s[38:39], 0, v[188:189]
	s_mov_b32 m0, s15
	s_nop 0
	global_load_lds_dwordx4 v[66:67], off
	s_waitcnt vmcnt(8)
	s_waitcnt lgkmcnt(0)
	s_barrier
	s_setprio 1
	s_waitcnt lgkmcnt(0)
	v_mfma_f32_16x16x32_bf16 v[66:69], v[0:3], v[34:37], 0
	v_mfma_f32_16x16x32_bf16 v[70:73], v[10:13], v[34:37], 0
	v_mfma_f32_16x16x32_bf16 v[74:77], v[0:3], v[42:45], 0
	v_mfma_f32_16x16x32_bf16 v[78:81], v[10:13], v[42:45], 0
	v_mfma_f32_16x16x32_bf16 v[82:85], v[0:3], v[50:53], 0
	v_mfma_f32_16x16x32_bf16 v[86:89], v[10:13], v[50:53], 0
	v_mfma_f32_16x16x32_bf16 v[66:69], v[4:7], v[38:41], v[66:69]
	v_mfma_f32_16x16x32_bf16 v[70:73], v[14:17], v[38:41], v[70:73]
	v_mfma_f32_16x16x32_bf16 v[74:77], v[4:7], v[46:49], v[74:77]
	v_mfma_f32_16x16x32_bf16 v[78:81], v[14:17], v[46:49], v[78:81]
	v_mfma_f32_16x16x32_bf16 v[82:85], v[4:7], v[54:57], v[82:85]
	v_mfma_f32_16x16x32_bf16 v[86:89], v[14:17], v[54:57], v[86:89]
	v_mfma_f32_16x16x32_bf16 v[90:93], v[0:3], v[58:61], 0
	v_mfma_f32_16x16x32_bf16 v[94:97], v[10:13], v[58:61], 0
	v_mfma_f32_16x16x32_bf16 v[90:93], v[4:7], v[62:65], v[90:93]
	v_mfma_f32_16x16x32_bf16 v[94:97], v[14:17], v[62:65], v[94:97]
	v_mfma_f32_16x16x32_bf16 v[98:101], v[18:21], v[34:37], 0
	v_mfma_f32_16x16x32_bf16 v[34:37], v[26:29], v[34:37], 0
	v_mfma_f32_16x16x32_bf16 v[98:101], v[22:25], v[38:41], v[98:101]
	v_mfma_f32_16x16x32_bf16 v[34:37], v[30:33], v[38:41], v[34:37]
	v_mfma_f32_16x16x32_bf16 v[38:41], v[18:21], v[42:45], 0
	v_mfma_f32_16x16x32_bf16 v[42:45], v[26:29], v[42:45], 0
	v_mfma_f32_16x16x32_bf16 v[38:41], v[22:25], v[46:49], v[38:41]
	v_mfma_f32_16x16x32_bf16 v[42:45], v[30:33], v[46:49], v[42:45]
	v_mfma_f32_16x16x32_bf16 v[46:49], v[18:21], v[50:53], 0
	v_mfma_f32_16x16x32_bf16 v[50:53], v[26:29], v[50:53], 0
	v_mfma_f32_16x16x32_bf16 v[46:49], v[22:25], v[54:57], v[46:49]
	v_mfma_f32_16x16x32_bf16 v[50:53], v[30:33], v[54:57], v[50:53]
	v_mfma_f32_16x16x32_bf16 v[54:57], v[18:21], v[58:61], 0
	v_mfma_f32_16x16x32_bf16 v[58:61], v[26:29], v[58:61], 0
	v_mfma_f32_16x16x32_bf16 v[54:57], v[22:25], v[62:65], v[54:57]
	v_mfma_f32_16x16x32_bf16 v[58:61], v[30:33], v[62:65], v[58:61]
	s_setprio 0
	s_barrier
	s_add_i32 s39, s17, s20
	v_lshl_add_u64 v[200:201], s[42:43], 0, v[8:9]
	s_mov_b64 s[60:61], 0x100
	s_add_i32 s17, s39, 0x2000
	v_lshl_add_u64 v[130:131], v[200:201], 0, s[60:61]
	s_mov_b32 m0, s39
	v_lshl_add_u64 v[202:203], s[42:43], 0, v[186:187]
	s_add_u32 s56, s42, 0x10100
	ds_read_b128 v[62:65], v219 offset:16384
	ds_read_b128 v[102:105], v219 offset:17408
	ds_read_b128 v[106:109], v219 offset:18432
	ds_read_b128 v[110:113], v219 offset:19456
	ds_read_b128 v[114:117], v219 offset:20480
	ds_read_b128 v[118:121], v219 offset:21504
	ds_read_b128 v[122:125], v219 offset:22528
	ds_read_b128 v[126:129], v219 offset:23552
	global_load_lds_dwordx4 v[130:131], off
	v_lshl_add_u64 v[130:131], v[202:203], 0, s[60:61]
	s_mov_b32 m0, s17
	s_addc_u32 s57, s43, 0
	s_add_i32 s37, s37, s20
	global_load_lds_dwordx4 v[130:131], off
	v_lshl_add_u64 v[130:131], s[56:57], 0, v[8:9]
	s_mov_b32 m0, s37
	s_add_i32 s38, s37, 0x2000
	global_load_lds_dwordx4 v[130:131], off
	v_lshl_add_u64 v[130:131], s[56:57], 0, v[186:187]
	s_mov_b32 m0, s38
	v_lshl_add_u64 v[204:205], s[58:59], 0, v[190:191]
	global_load_lds_dwordx4 v[130:131], off
	v_lshl_add_u64 v[130:131], v[204:205], 0, s[60:61]
	s_mov_b32 m0, s21
	v_lshl_add_u64 v[206:207], s[58:59], 0, v[188:189]
	global_load_lds_dwordx4 v[130:131], off
	v_lshl_add_u64 v[130:131], v[206:207], 0, s[60:61]
	s_mov_b32 m0, s28
	s_nop 0
	global_load_lds_dwordx4 v[130:131], off
	s_waitcnt vmcnt(8)
	s_waitcnt lgkmcnt(0)
	s_barrier
; #define PG8_STAGE(bufoff, gbase, voff) do { _Pragma("unroll") for (int _i = 0; _i < 2; ++_i) \
;         __builtin_amdgcn_global_load_lds((const unsigned*)((const char*)(gbase) + (voff)[_i]), (PG8_LAS unsigned*)(lds + (bufoff) + ldsw + _i * 8192), 16, 0, 0); } while (0)
; #define PG8_LDA(dst, b, h) do { _Pragma("unroll") for (int m = 0; m < 4; ++m) _Pragma("unroll") for (int k = 0; k < 2; ++k) dst[m][k] = *(const PG8_LAS bf16x8*)(lds + PG8_SA(b, h) + aoff + m * 2048 + k * 1024); } while (0)
; #define PG8_LDB(dst, b, h) do { _Pragma("unroll") for (int n = 0; n < 2; ++n) _Pragma("unroll") for (int k = 0; k < 2; ++k) dst[n][k] = *(const PG8_LAS bf16x8*)(lds + PG8_SB(b, h) + boff + n * 2048 + k * 1024); } while (0)
; #define PG8_MMA(ai, bj, At, Bt) do { __builtin_amdgcn_s_setprio(1); _Pragma("unroll") for (int m = 0; m < 4; ++m) _Pragma("unroll") for (int n = 0; n < 2; ++n) _Pragma("unroll") for (int k = 0; k < 2; ++k) \
;         acc[ai][bj][m][n] = __builtin_amdgcn_mfma_f32_16x16x32_bf16(Bt[n][k], At[m][k], acc[ai][bj][m][n], 0, 0, 0); __builtin_amdgcn_s_setprio(0); } while (0)
; #define PG8_WAIT_V(n) asm volatile("s_waitcnt vmcnt(" #n ")" ::: "memory")
; #define PG8_WAIT_L(n) asm volatile("s_waitcnt lgkmcnt(" #n ")" ::: "memory")
; #define PG8_BAR __builtin_amdgcn_s_barrier()
; #define PG8_SCHED __builtin_amdgcn_sched_barrier(0)
; template <class Epi, class Sched, bool ALIGN_EPI = false, bool SP2 = false>
; __device__ __forceinline__ void gemm_phase(PG8_LAS unsigned char* lds, int tid_in, const Gemm g, const Sched& S, const Epi& E) {
;     ...
;             PG8_WAIT_V(8); PG8_WAIT_L(0); PG8_BAR; PG8_MMA(1, 0, At, B0); PG8_MMA(1, 1, At, B1); PG8_BAR; PG8_SCHED;
;             PG8_LDB(B0, 1, 0); PG8_LDB(B1, 1, 1); PG8_SCHED; PG8_LDA(At, 1, 0); PG8_STAGE(PG8_SA(0, 1), a2 + hstep, voffA);
;             PG8_WAIT_V(8); PG8_WAIT_L(0); PG8_BAR; PG8_MMA(0, 0, At, B0); PG8_MMA(0, 1, At, B1); PG8_BAR; PG8_SCHED;
	s_setprio 1
	s_waitcnt lgkmcnt(0)
	v_mfma_f32_16x16x32_bf16 v[130:133], v[0:3], v[62:65], 0
	v_mfma_f32_16x16x32_bf16 v[138:141], v[0:3], v[106:109], 0
	v_mfma_f32_16x16x32_bf16 v[146:149], v[0:3], v[114:117], 0
	v_mfma_f32_16x16x32_bf16 v[0:3], v[0:3], v[122:125], 0
	v_mfma_f32_16x16x32_bf16 v[130:133], v[4:7], v[102:105], v[130:133]
	v_mfma_f32_16x16x32_bf16 v[134:137], v[10:13], v[62:65], 0
	v_mfma_f32_16x16x32_bf16 v[138:141], v[4:7], v[110:113], v[138:141]
	v_mfma_f32_16x16x32_bf16 v[146:149], v[4:7], v[118:121], v[146:149]
	v_mfma_f32_16x16x32_bf16 v[0:3], v[4:7], v[126:129], v[0:3]
	v_mfma_f32_16x16x32_bf16 v[4:7], v[10:13], v[122:125], 0
	v_mfma_f32_16x16x32_bf16 v[134:137], v[14:17], v[102:105], v[134:137]
	v_mfma_f32_16x16x32_bf16 v[142:145], v[10:13], v[106:109], 0
	v_mfma_f32_16x16x32_bf16 v[150:153], v[10:13], v[114:117], 0
	v_mfma_f32_16x16x32_bf16 v[4:7], v[14:17], v[126:129], v[4:7]
	v_mfma_f32_16x16x32_bf16 v[142:145], v[14:17], v[110:113], v[142:145]
	v_mfma_f32_16x16x32_bf16 v[150:153], v[14:17], v[118:121], v[150:153]
	v_mfma_f32_16x16x32_bf16 v[10:13], v[18:21], v[62:65], 0
	v_mfma_f32_16x16x32_bf16 v[14:17], v[26:29], v[62:65], 0
	v_mfma_f32_16x16x32_bf16 v[10:13], v[22:25], v[102:105], v[10:13]
	v_mfma_f32_16x16x32_bf16 v[14:17], v[30:33], v[102:105], v[14:17]
	v_mfma_f32_16x16x32_bf16 v[62:65], v[18:21], v[106:109], 0
	v_mfma_f32_16x16x32_bf16 v[102:105], v[26:29], v[106:109], 0
	v_mfma_f32_16x16x32_bf16 v[106:109], v[18:21], v[114:117], 0
	v_mfma_f32_16x16x32_bf16 v[18:21], v[18:21], v[122:125], 0
	v_mfma_f32_16x16x32_bf16 v[62:65], v[22:25], v[110:113], v[62:65]
	v_mfma_f32_16x16x32_bf16 v[106:109], v[22:25], v[118:121], v[106:109]
	v_mfma_f32_16x16x32_bf16 v[18:21], v[22:25], v[126:129], v[18:21]
	v_mfma_f32_16x16x32_bf16 v[22:25], v[26:29], v[122:125], 0
	v_mfma_f32_16x16x32_bf16 v[102:105], v[30:33], v[110:113], v[102:105]
	v_mfma_f32_16x16x32_bf16 v[110:113], v[26:29], v[114:117], 0
	v_mfma_f32_16x16x32_bf16 v[22:25], v[30:33], v[126:129], v[22:25]
	v_mfma_f32_16x16x32_bf16 v[110:113], v[30:33], v[118:121], v[110:113]
	s_setprio 0
	s_barrier
	s_add_i32 s55, 0, 0x18000
	s_add_i32 s60, 0, 0x1c000
	v_add_u32_e32 v224, s55, v218
	v_add_u32_e32 v225, s60, v218
	ds_read_b128 v[26:29], v224
	ds_read_b128 v[30:33], v224 offset:1024
	ds_read_b128 v[114:117], v224 offset:2048
	ds_read_b128 v[118:121], v224 offset:3072
	ds_read_b128 v[122:125], v225
	ds_read_b128 v[126:129], v225 offset:1024
	ds_read_b128 v[154:157], v225 offset:2048
	ds_read_b128 v[158:161], v225 offset:3072
	s_add_u32 s56, s58, 0x10100
	s_addc_u32 s57, s59, 0
	s_mov_b32 m0, s29
	v_lshl_add_u64 v[208:209], s[56:57], 0, v[190:191]
	ds_read_b128 v[162:165], v219 offset:32768
	ds_read_b128 v[166:169], v219 offset:33792
	ds_read_b128 v[170:173], v219 offset:34816
	ds_read_b128 v[174:177], v219 offset:35840
	ds_read_b128 v[178:181], v219 offset:36864
	ds_read_b128 v[182:185], v219 offset:37888
	ds_read_b128 v[192:195], v219 offset:38912
	ds_read_b128 v[196:199], v219 offset:39936
	global_load_lds_dwordx4 v[208:209], off
	v_lshl_add_u64 v[208:209], s[56:57], 0, v[188:189]
	s_mov_b32 m0, s33
	s_nop 0
	global_load_lds_dwordx4 v[208:209], off
	s_waitcnt vmcnt(8)
	s_waitcnt lgkmcnt(0)
	s_barrier
	s_setprio 1
	s_waitcnt lgkmcnt(0)
	v_mfma_f32_16x16x32_bf16 v[66:69], v[26:29], v[162:165], v[66:69]
	v_mfma_f32_16x16x32_bf16 v[70:73], v[114:117], v[162:165], v[70:73]
	v_mfma_f32_16x16x32_bf16 v[74:77], v[26:29], v[170:173], v[74:77]
	v_mfma_f32_16x16x32_bf16 v[78:81], v[114:117], v[170:173], v[78:81]
	v_mfma_f32_16x16x32_bf16 v[82:85], v[26:29], v[178:181], v[82:85]
	v_mfma_f32_16x16x32_bf16 v[86:89], v[114:117], v[178:181], v[86:89]
	v_mfma_f32_16x16x32_bf16 v[66:69], v[30:33], v[166:169], v[66:69]
	v_mfma_f32_16x16x32_bf16 v[70:73], v[118:121], v[166:169], v[70:73]
	v_mfma_f32_16x16x32_bf16 v[74:77], v[30:33], v[174:177], v[74:77]
	v_mfma_f32_16x16x32_bf16 v[78:81], v[118:121], v[174:177], v[78:81]
	v_mfma_f32_16x16x32_bf16 v[82:85], v[30:33], v[182:185], v[82:85]
	v_mfma_f32_16x16x32_bf16 v[86:89], v[118:121], v[182:185], v[86:89]
	v_mfma_f32_16x16x32_bf16 v[90:93], v[26:29], v[192:195], v[90:93]
	v_mfma_f32_16x16x32_bf16 v[94:97], v[114:117], v[192:195], v[94:97]
	v_mfma_f32_16x16x32_bf16 v[90:93], v[30:33], v[196:199], v[90:93]
	v_mfma_f32_16x16x32_bf16 v[94:97], v[118:121], v[196:199], v[94:97]
	v_mfma_f32_16x16x32_bf16 v[98:101], v[122:125], v[162:165], v[98:101]
	v_mfma_f32_16x16x32_bf16 v[34:37], v[154:157], v[162:165], v[34:37]
	v_mfma_f32_16x16x32_bf16 v[38:41], v[122:125], v[170:173], v[38:41]
	v_mfma_f32_16x16x32_bf16 v[42:45], v[154:157], v[170:173], v[42:45]
	v_mfma_f32_16x16x32_bf16 v[46:49], v[122:125], v[178:181], v[46:49]
	v_mfma_f32_16x16x32_bf16 v[50:53], v[154:157], v[178:181], v[50:53]
	v_mfma_f32_16x16x32_bf16 v[54:57], v[122:125], v[192:195], v[54:57]
	v_mfma_f32_16x16x32_bf16 v[58:61], v[154:157], v[192:195], v[58:61]
	v_mfma_f32_16x16x32_bf16 v[98:101], v[126:129], v[166:169], v[98:101]
	v_mfma_f32_16x16x32_bf16 v[34:37], v[158:161], v[166:169], v[34:37]
	v_mfma_f32_16x16x32_bf16 v[38:41], v[126:129], v[174:177], v[38:41]
	v_mfma_f32_16x16x32_bf16 v[42:45], v[158:161], v[174:177], v[42:45]
	v_mfma_f32_16x16x32_bf16 v[46:49], v[126:129], v[182:185], v[46:49]
	v_mfma_f32_16x16x32_bf16 v[50:53], v[158:161], v[182:185], v[50:53]
	v_mfma_f32_16x16x32_bf16 v[54:57], v[126:129], v[196:199], v[54:57]
	v_mfma_f32_16x16x32_bf16 v[58:61], v[158:161], v[196:199], v[58:61]
	s_setprio 0
	s_barrier
; #define PG8_STAGE(bufoff, gbase, voff) do { _Pragma("unroll") for (int _i = 0; _i < 2; ++_i) \
;         __builtin_amdgcn_global_load_lds((const unsigned*)((const char*)(gbase) + (voff)[_i]), (PG8_LAS unsigned*)(lds + (bufoff) + ldsw + _i * 8192), 16, 0, 0); } while (0)
; #define PG8_LDA(dst, b, h) do { _Pragma("unroll") for (int m = 0; m < 4; ++m) _Pragma("unroll") for (int k = 0; k < 2; ++k) dst[m][k] = *(const PG8_LAS bf16x8*)(lds + PG8_SA(b, h) + aoff + m * 2048 + k * 1024); } while (0)
; #define PG8_LDB(dst, b, h) do { _Pragma("unroll") for (int n = 0; n < 2; ++n) _Pragma("unroll") for (int k = 0; k < 2; ++k) dst[n][k] = *(const PG8_LAS bf16x8*)(lds + PG8_SB(b, h) + boff + n * 2048 + k * 1024); } while (0)
; #define PG8_MMA(ai, bj, At, Bt) do { __builtin_amdgcn_s_setprio(1); _Pragma("unroll") for (int m = 0; m < 4; ++m) _Pragma("unroll") for (int n = 0; n < 2; ++n) _Pragma("unroll") for (int k = 0; k < 2; ++k) \
;         acc[ai][bj][m][n] = __builtin_amdgcn_mfma_f32_16x16x32_bf16(Bt[n][k], At[m][k], acc[ai][bj][m][n], 0, 0, 0); __builtin_amdgcn_s_setprio(0); } while (0)
; #define PG8_BAR __builtin_amdgcn_s_barrier()
; template <class Epi, class Sched, bool ALIGN_EPI = false, bool SP2 = false>
; __device__ __forceinline__ void gemm_phase(PG8_LAS unsigned char* lds, int tid_in, const Gemm g, const Sched& S, const Epi& E) {
;     ...
;             PG8_LDB(B0, 0, 0); PG8_LDB(B1, 0, 1); PG8_SCHED; PG8_LDA(At, 0, 0); PG8_STAGE(PG8_SA(1, 1), a1 + hstep, voffA);
;             PG8_WAIT_V(8); PG8_WAIT_L(0); PG8_BAR; PG8_MMA(0, 0, At, B0); PG8_MMA(0, 1, At, B1); PG8_BAR; PG8_SCHED;
;             PG8_LDA(At, 0, 1); PG8_STAGE(PG8_SB(0, 0), b2, voffB); PG8_STAGE(PG8_SB(0, 1), b2 + hstep, voffB); PG8_STAGE(PG8_SA(0, 0), a2, voffA);
;             PG8_WAIT_V(8); PG8_WAIT_L(0); PG8_BAR; PG8_MMA(1, 0, At, B0); PG8_MMA(1, 1, At, B1); PG8_BAR; PG8_SCHED;
;             PG8_LDB(B0, 1, 0); PG8_LDB(B1, 1, 1); PG8_SCHED; PG8_LDA(At, 1, 0); PG8_STAGE(PG8_SA(0, 1), a2 + hstep, voffA);
;             PG8_WAIT_V(8); PG8_WAIT_L(0); PG8_BAR; PG8_MMA(0, 0, At, B0); PG8_MMA(0, 1, At, B1); PG8_BAR; PG8_SCHED;
;             PG8_LDA(At, 1, 1); PG8_STAGE(PG8_SB(1, 0), b3, voffB); PG8_STAGE(PG8_SB(1, 1), b3 + hstep, voffB); PG8_STAGE(PG8_SA(1, 0), a3, voffA);
;             PG8_WAIT_V(8); PG8_WAIT_L(0); PG8_BAR; PG8_MMA(1, 0, At, B0); PG8_MMA(1, 1, At, B1); PG8_BAR; PG8_SCHED;
	s_add_i32 s55, s55, s20
	s_mov_b64 vcc, 0x180
	s_add_i32 s47, s55, 0x2000
	v_lshl_add_u64 v[200:201], v[200:201], 0, vcc
	s_mov_b32 m0, s55
	s_add_u32 s56, s42, 0x10180
	ds_read_b128 v[162:165], v219 offset:49152
	ds_read_b128 v[166:169], v219 offset:50176
	ds_read_b128 v[170:173], v219 offset:51200
	ds_read_b128 v[174:177], v219 offset:52224
	ds_read_b128 v[178:181], v219 offset:53248
	ds_read_b128 v[182:185], v219 offset:54272
	ds_read_b128 v[192:195], v219 offset:55296
	ds_read_b128 v[196:199], v219 offset:56320
	global_load_lds_dwordx4 v[200:201], off
	v_lshl_add_u64 v[200:201], v[202:203], 0, vcc
	s_mov_b32 m0, s47
	s_addc_u32 s57, s43, 0
	s_add_i32 s42, s60, s20
	global_load_lds_dwordx4 v[200:201], off
	v_lshl_add_u64 v[200:201], s[56:57], 0, v[8:9]
	s_mov_b32 m0, s42
	s_add_i32 s43, s42, 0x2000
	global_load_lds_dwordx4 v[200:201], off
	v_lshl_add_u64 v[200:201], s[56:57], 0, v[186:187]
	s_mov_b32 m0, s43
	s_nop 0
	global_load_lds_dwordx4 v[200:201], off
	v_lshl_add_u64 v[200:201], v[204:205], 0, vcc
	s_mov_b32 m0, s45
	s_nop 0
	global_load_lds_dwordx4 v[200:201], off
	v_lshl_add_u64 v[200:201], v[206:207], 0, vcc
	s_mov_b32 m0, s46
	s_nop 0
	global_load_lds_dwordx4 v[200:201], off
	s_waitcnt vmcnt(8)
	s_waitcnt lgkmcnt(0)
	s_barrier
	s_setprio 1
	s_waitcnt lgkmcnt(0)
	v_mfma_f32_16x16x32_bf16 v[130:133], v[26:29], v[162:165], v[130:133]
	v_mfma_f32_16x16x32_bf16 v[134:137], v[114:117], v[162:165], v[134:137]
	v_mfma_f32_16x16x32_bf16 v[0:3], v[26:29], v[192:195], v[0:3]
	v_mfma_f32_16x16x32_bf16 v[4:7], v[114:117], v[192:195], v[4:7]
	v_mfma_f32_16x16x32_bf16 v[130:133], v[30:33], v[166:169], v[130:133]
	v_mfma_f32_16x16x32_bf16 v[134:137], v[118:121], v[166:169], v[134:137]
	v_mfma_f32_16x16x32_bf16 v[138:141], v[26:29], v[170:173], v[138:141]
	v_mfma_f32_16x16x32_bf16 v[142:145], v[114:117], v[170:173], v[142:145]
	v_mfma_f32_16x16x32_bf16 v[146:149], v[26:29], v[178:181], v[146:149]
	v_mfma_f32_16x16x32_bf16 v[150:153], v[114:117], v[178:181], v[150:153]
	v_mfma_f32_16x16x32_bf16 v[0:3], v[30:33], v[196:199], v[0:3]
	v_mfma_f32_16x16x32_bf16 v[4:7], v[118:121], v[196:199], v[4:7]
	v_mfma_f32_16x16x32_bf16 v[138:141], v[30:33], v[174:177], v[138:141]
	v_mfma_f32_16x16x32_bf16 v[142:145], v[118:121], v[174:177], v[142:145]
	v_mfma_f32_16x16x32_bf16 v[146:149], v[30:33], v[182:185], v[146:149]
	v_mfma_f32_16x16x32_bf16 v[150:153], v[118:121], v[182:185], v[150:153]
	v_mfma_f32_16x16x32_bf16 v[10:13], v[122:125], v[162:165], v[10:13]
	v_mfma_f32_16x16x32_bf16 v[14:17], v[154:157], v[162:165], v[14:17]
	v_mfma_f32_16x16x32_bf16 v[26:29], v[122:125], v[170:173], v[62:65]
	v_mfma_f32_16x16x32_bf16 v[30:33], v[154:157], v[170:173], v[102:105]
	v_mfma_f32_16x16x32_bf16 v[62:65], v[122:125], v[178:181], v[106:109]
	v_mfma_f32_16x16x32_bf16 v[102:105], v[154:157], v[178:181], v[110:113]
	v_mfma_f32_16x16x32_bf16 v[18:21], v[122:125], v[192:195], v[18:21]
	v_mfma_f32_16x16x32_bf16 v[22:25], v[154:157], v[192:195], v[22:25]
	v_mfma_f32_16x16x32_bf16 v[10:13], v[126:129], v[166:169], v[10:13]
	v_mfma_f32_16x16x32_bf16 v[14:17], v[158:161], v[166:169], v[14:17]
	v_mfma_f32_16x16x32_bf16 v[26:29], v[126:129], v[174:177], v[26:29]
	v_mfma_f32_16x16x32_bf16 v[30:33], v[158:161], v[174:177], v[30:33]
	v_mfma_f32_16x16x32_bf16 v[62:65], v[126:129], v[182:185], v[62:65]
	v_mfma_f32_16x16x32_bf16 v[102:105], v[158:161], v[182:185], v[102:105]
	v_mfma_f32_16x16x32_bf16 v[18:21], v[126:129], v[196:199], v[18:21]
	v_mfma_f32_16x16x32_bf16 v[22:25], v[158:161], v[196:199], v[22:25]
	s_setprio 0
	s_barrier
	ds_read_b128 v[106:109], v210
	ds_read_b128 v[110:113], v210 offset:1024
	ds_read_b128 v[114:117], v210 offset:2048
	ds_read_b128 v[118:121], v210 offset:3072
	ds_read_b128 v[122:125], v211
	ds_read_b128 v[126:129], v211 offset:1024
	ds_read_b128 v[154:157], v211 offset:2048
	ds_read_b128 v[158:161], v211 offset:3072
	s_add_u32 s56, s58, 0x10180
	s_addc_u32 s57, s59, 0
	s_mov_b32 m0, s53
	v_lshl_add_u64 v[200:201], s[56:57], 0, v[190:191]
	ds_read_b128 v[162:165], v219
	ds_read_b128 v[166:169], v219 offset:1024
	ds_read_b128 v[170:173], v219 offset:2048
	ds_read_b128 v[174:177], v219 offset:3072
	ds_read_b128 v[178:181], v219 offset:4096
	ds_read_b128 v[182:185], v219 offset:5120
	ds_read_b128 v[192:195], v219 offset:6144
	ds_read_b128 v[196:199], v219 offset:7168
	global_load_lds_dwordx4 v[200:201], off
	v_lshl_add_u64 v[200:201], s[56:57], 0, v[188:189]
	s_mov_b32 m0, s15
	s_nop 0
	global_load_lds_dwordx4 v[200:201], off
	s_waitcnt vmcnt(8)
	s_waitcnt lgkmcnt(0)
	s_barrier
; #define PG8_STAGE(bufoff, gbase, voff) do { _Pragma("unroll") for (int _i = 0; _i < 2; ++_i) \
;         __builtin_amdgcn_global_load_lds((const unsigned*)((const char*)(gbase) + (voff)[_i]), (PG8_LAS unsigned*)(lds + (bufoff) + ldsw + _i * 8192), 16, 0, 0); } while (0)
; #define PG8_LDA(dst, b, h) do { _Pragma("unroll") for (int m = 0; m < 4; ++m) _Pragma("unroll") for (int k = 0; k < 2; ++k) dst[m][k] = *(const PG8_LAS bf16x8*)(lds + PG8_SA(b, h) + aoff + m * 2048 + k * 1024); } while (0)
; #define PG8_MMA(ai, bj, At, Bt) do { __builtin_amdgcn_s_setprio(1); _Pragma("unroll") for (int m = 0; m < 4; ++m) _Pragma("unroll") for (int n = 0; n < 2; ++n) _Pragma("unroll") for (int k = 0; k < 2; ++k) \
;         acc[ai][bj][m][n] = __builtin_amdgcn_mfma_f32_16x16x32_bf16(Bt[n][k], At[m][k], acc[ai][bj][m][n], 0, 0, 0); __builtin_amdgcn_s_setprio(0); } while (0)
; #define PG8_WAIT_V(n) asm volatile("s_waitcnt vmcnt(" #n ")" ::: "memory")
; #define PG8_WAIT_L(n) asm volatile("s_waitcnt lgkmcnt(" #n ")" ::: "memory")
; #define PG8_BAR __builtin_amdgcn_s_barrier()
; #define PG8_SCHED __builtin_amdgcn_sched_barrier(0)
; template <class Epi, class Sched, bool ALIGN_EPI = false, bool SP2 = false>
; __device__ __forceinline__ void gemm_phase(PG8_LAS unsigned char* lds, int tid_in, const Gemm g, const Sched& S, const Epi& E) {
;     ...
;             PG8_WAIT_V(8); PG8_WAIT_L(0); PG8_BAR; PG8_MMA(0, 0, At, B0); PG8_MMA(0, 1, At, B1); PG8_BAR; PG8_SCHED;
;             PG8_LDA(At, 0, 1); PG8_STAGE(PG8_SB(0, 0), b2, voffB); PG8_STAGE(PG8_SB(0, 1), b2 + hstep, voffB); PG8_STAGE(PG8_SA(0, 0), a2, voffA);
;             PG8_WAIT_V(8); PG8_WAIT_L(0); PG8_BAR; PG8_MMA(1, 0, At, B0); PG8_MMA(1, 1, At, B1); PG8_BAR; PG8_SCHED;
	s_setprio 1
	s_waitcnt lgkmcnt(0)
	v_mfma_f32_16x16x32_bf16 v[66:69], v[106:109], v[162:165], v[66:69]
	v_mfma_f32_16x16x32_bf16 v[70:73], v[114:117], v[162:165], v[70:73]
	v_mfma_f32_16x16x32_bf16 v[74:77], v[106:109], v[170:173], v[74:77]
	v_mfma_f32_16x16x32_bf16 v[78:81], v[114:117], v[170:173], v[78:81]
	v_mfma_f32_16x16x32_bf16 v[82:85], v[106:109], v[178:181], v[82:85]
	v_mfma_f32_16x16x32_bf16 v[86:89], v[114:117], v[178:181], v[86:89]
	v_mfma_f32_16x16x32_bf16 v[66:69], v[110:113], v[166:169], v[66:69]
	v_mfma_f32_16x16x32_bf16 v[70:73], v[118:121], v[166:169], v[70:73]
	v_mfma_f32_16x16x32_bf16 v[74:77], v[110:113], v[174:177], v[74:77]
	v_mfma_f32_16x16x32_bf16 v[78:81], v[118:121], v[174:177], v[78:81]
	v_mfma_f32_16x16x32_bf16 v[82:85], v[110:113], v[182:185], v[82:85]
	v_mfma_f32_16x16x32_bf16 v[86:89], v[118:121], v[182:185], v[86:89]
	v_mfma_f32_16x16x32_bf16 v[90:93], v[106:109], v[192:195], v[90:93]
	v_mfma_f32_16x16x32_bf16 v[94:97], v[114:117], v[192:195], v[94:97]
	v_mfma_f32_16x16x32_bf16 v[90:93], v[110:113], v[196:199], v[90:93]
	v_mfma_f32_16x16x32_bf16 v[94:97], v[118:121], v[196:199], v[94:97]
	v_mfma_f32_16x16x32_bf16 v[34:37], v[154:157], v[162:165], v[34:37]
	v_mfma_f32_16x16x32_bf16 v[38:41], v[122:125], v[170:173], v[38:41]
	v_mfma_f32_16x16x32_bf16 v[42:45], v[154:157], v[170:173], v[42:45]
	v_mfma_f32_16x16x32_bf16 v[46:49], v[122:125], v[178:181], v[46:49]
	v_mfma_f32_16x16x32_bf16 v[50:53], v[154:157], v[178:181], v[50:53]
	v_mfma_f32_16x16x32_bf16 v[54:57], v[122:125], v[192:195], v[54:57]
	v_mfma_f32_16x16x32_bf16 v[58:61], v[154:157], v[192:195], v[58:61]
	v_mfma_f32_16x16x32_bf16 v[98:101], v[122:125], v[162:165], v[98:101]
	v_mfma_f32_16x16x32_bf16 v[34:37], v[158:161], v[166:169], v[34:37]
	v_mfma_f32_16x16x32_bf16 v[38:41], v[126:129], v[174:177], v[38:41]
	v_mfma_f32_16x16x32_bf16 v[42:45], v[158:161], v[174:177], v[42:45]
	v_mfma_f32_16x16x32_bf16 v[46:49], v[126:129], v[182:185], v[46:49]
	v_mfma_f32_16x16x32_bf16 v[50:53], v[158:161], v[182:185], v[50:53]
	v_mfma_f32_16x16x32_bf16 v[54:57], v[126:129], v[196:199], v[54:57]
	v_mfma_f32_16x16x32_bf16 v[58:61], v[158:161], v[196:199], v[58:61]
	v_mfma_f32_16x16x32_bf16 v[200:203], v[126:129], v[166:169], v[98:101]
	s_setprio 0
	s_barrier
	s_mov_b32 m0, s39
	v_lshl_add_u64 v[204:205], s[48:49], 0, v[8:9]
	s_add_u32 s56, s48, 0x10000
	ds_read_b128 v[98:101], v219 offset:16384
	ds_read_b128 v[162:165], v219 offset:17408
	ds_read_b128 v[166:169], v219 offset:18432
	ds_read_b128 v[170:173], v219 offset:19456
	ds_read_b128 v[174:177], v219 offset:20480
	ds_read_b128 v[178:181], v219 offset:21504
	ds_read_b128 v[182:185], v219 offset:22528
	ds_read_b128 v[192:195], v219 offset:23552
	global_load_lds_dwordx4 v[204:205], off
	v_lshl_add_u64 v[206:207], s[48:49], 0, v[186:187]
	s_mov_b32 m0, s17
	s_addc_u32 s57, s49, 0
	global_load_lds_dwordx4 v[206:207], off
	v_lshl_add_u64 v[196:197], s[56:57], 0, v[8:9]
	s_mov_b32 m0, s37
	v_lshl_add_u64 v[208:209], s[50:51], 0, v[190:191]
	global_load_lds_dwordx4 v[196:197], off
	v_lshl_add_u64 v[196:197], s[56:57], 0, v[186:187]
	s_mov_b32 m0, s38
	v_lshl_add_u64 v[244:245], s[50:51], 0, v[188:189]
	global_load_lds_dwordx4 v[196:197], off
	s_mov_b32 m0, s21
	s_nop 0
	global_load_lds_dwordx4 v[208:209], off
	s_mov_b32 m0, s28
	s_nop 0
	global_load_lds_dwordx4 v[244:245], off
	s_waitcnt vmcnt(8)
	s_waitcnt lgkmcnt(0)
	s_barrier
	s_setprio 1
	s_waitcnt lgkmcnt(0)
	v_mfma_f32_16x16x32_bf16 v[130:133], v[106:109], v[98:101], v[130:133]
	v_mfma_f32_16x16x32_bf16 v[196:199], v[110:113], v[162:165], v[130:133]
	v_mfma_f32_16x16x32_bf16 v[130:133], v[114:117], v[98:101], v[134:137]
	v_mfma_f32_16x16x32_bf16 v[210:213], v[118:121], v[162:165], v[130:133]
	v_mfma_f32_16x16x32_bf16 v[130:133], v[106:109], v[166:169], v[138:141]
	v_mfma_f32_16x16x32_bf16 v[138:141], v[110:113], v[170:173], v[130:133]
	v_mfma_f32_16x16x32_bf16 v[130:133], v[114:117], v[166:169], v[142:145]
	v_mfma_f32_16x16x32_bf16 v[142:145], v[118:121], v[170:173], v[130:133]
	v_mfma_f32_16x16x32_bf16 v[130:133], v[106:109], v[174:177], v[146:149]
	v_mfma_f32_16x16x32_bf16 v[0:3], v[106:109], v[182:185], v[0:3]
	v_mfma_f32_16x16x32_bf16 v[4:7], v[114:117], v[182:185], v[4:7]
	v_mfma_f32_16x16x32_bf16 v[146:149], v[110:113], v[178:181], v[130:133]
	v_mfma_f32_16x16x32_bf16 v[130:133], v[114:117], v[174:177], v[150:153]
	v_mfma_f32_16x16x32_bf16 v[0:3], v[110:113], v[192:195], v[0:3]
	v_mfma_f32_16x16x32_bf16 v[4:7], v[118:121], v[192:195], v[4:7]
	v_mfma_f32_16x16x32_bf16 v[150:153], v[118:121], v[178:181], v[130:133]
	v_mfma_f32_16x16x32_bf16 v[10:13], v[122:125], v[98:101], v[10:13]
	v_mfma_f32_16x16x32_bf16 v[106:109], v[126:129], v[162:165], v[10:13]
	v_mfma_f32_16x16x32_bf16 v[10:13], v[154:157], v[98:101], v[14:17]
	v_mfma_f32_16x16x32_bf16 v[110:113], v[158:161], v[162:165], v[10:13]
	v_mfma_f32_16x16x32_bf16 v[10:13], v[122:125], v[166:169], v[26:29]
	v_mfma_f32_16x16x32_bf16 v[162:165], v[126:129], v[170:173], v[10:13]
	v_mfma_f32_16x16x32_bf16 v[10:13], v[154:157], v[166:169], v[30:33]
	v_mfma_f32_16x16x32_bf16 v[166:169], v[158:161], v[170:173], v[10:13]
	v_mfma_f32_16x16x32_bf16 v[10:13], v[122:125], v[174:177], v[62:65]
	v_mfma_f32_16x16x32_bf16 v[214:217], v[126:129], v[178:181], v[10:13]
	v_mfma_f32_16x16x32_bf16 v[10:13], v[154:157], v[174:177], v[102:105]
	v_mfma_f32_16x16x32_bf16 v[220:223], v[158:161], v[178:181], v[10:13]
	v_mfma_f32_16x16x32_bf16 v[10:13], v[122:125], v[182:185], v[18:21]
	v_mfma_f32_16x16x32_bf16 v[122:125], v[126:129], v[192:195], v[10:13]
	v_mfma_f32_16x16x32_bf16 v[10:13], v[154:157], v[182:185], v[22:25]
	v_mfma_f32_16x16x32_bf16 v[126:129], v[158:161], v[192:195], v[10:13]
	s_setprio 0
	s_barrier
; #define PG8_STAGE(bufoff, gbase, voff) do { _Pragma("unroll") for (int _i = 0; _i < 2; ++_i) \
;         __builtin_amdgcn_global_load_lds((const unsigned*)((const char*)(gbase) + (voff)[_i]), (PG8_LAS unsigned*)(lds + (bufoff) + ldsw + _i * 8192), 16, 0, 0); } while (0)
; #define PG8_LDA(dst, b, h) do { _Pragma("unroll") for (int m = 0; m < 4; ++m) _Pragma("unroll") for (int k = 0; k < 2; ++k) dst[m][k] = *(const PG8_LAS bf16x8*)(lds + PG8_SA(b, h) + aoff + m * 2048 + k * 1024); } while (0)
; #define PG8_LDB(dst, b, h) do { _Pragma("unroll") for (int n = 0; n < 2; ++n) _Pragma("unroll") for (int k = 0; k < 2; ++k) dst[n][k] = *(const PG8_LAS bf16x8*)(lds + PG8_SB(b, h) + boff + n * 2048 + k * 1024); } while (0)
; #define PG8_MMA(ai, bj, At, Bt) do { __builtin_amdgcn_s_setprio(1); _Pragma("unroll") for (int m = 0; m < 4; ++m) _Pragma("unroll") for (int n = 0; n < 2; ++n) _Pragma("unroll") for (int k = 0; k < 2; ++k) \
;         acc[ai][bj][m][n] = __builtin_amdgcn_mfma_f32_16x16x32_bf16(Bt[n][k], At[m][k], acc[ai][bj][m][n], 0, 0, 0); __builtin_amdgcn_s_setprio(0); } while (0)
; #define PG8_WAIT_V(n) asm volatile("s_waitcnt vmcnt(" #n ")" ::: "memory")
; #define PG8_WAIT_L(n) asm volatile("s_waitcnt lgkmcnt(" #n ")" ::: "memory")
; #define PG8_BAR __builtin_amdgcn_s_barrier()
; #define PG8_SCHED __builtin_amdgcn_sched_barrier(0)
; template <class Epi, class Sched, bool ALIGN_EPI = false, bool SP2 = false>
; __device__ __forceinline__ void gemm_phase(PG8_LAS unsigned char* lds, int tid_in, const Gemm g, const Sched& S, const Epi& E) {
;     ...
;             PG8_LDB(B0, 1, 0); PG8_LDB(B1, 1, 1); PG8_SCHED; PG8_LDA(At, 1, 0); PG8_STAGE(PG8_SA(0, 1), a2 + hstep, voffA);
;             PG8_WAIT_V(8); PG8_WAIT_L(0); PG8_BAR; PG8_MMA(0, 0, At, B0); PG8_MMA(0, 1, At, B1); PG8_BAR; PG8_SCHED;
;             PG8_LDA(At, 1, 1); PG8_STAGE(PG8_SB(1, 0), b3, voffB); PG8_STAGE(PG8_SB(1, 1), b3 + hstep, voffB); PG8_STAGE(PG8_SA(1, 0), a3, voffA);
;             PG8_WAIT_V(8); PG8_WAIT_L(0); PG8_BAR; PG8_MMA(1, 0, At, B0); PG8_MMA(1, 1, At, B1); PG8_BAR; PG8_SCHED;
;     ...
;         if constexpr (ALIGN_EPI) { if (wr == 0) PG8_BAR; }
	s_nop 4
	ds_read_b128 v[10:13], v224
	ds_read_b128 v[14:17], v224 offset:1024
	ds_read_b128 v[18:21], v224 offset:2048
	ds_read_b128 v[22:25], v224 offset:3072
	ds_read_b128 v[154:157], v225
	ds_read_b128 v[158:161], v225 offset:1024
	ds_read_b128 v[192:195], v225 offset:2048
	ds_read_b128 v[224:227], v225 offset:3072
	s_add_u32 s38, s50, 0x10000
	s_addc_u32 s39, s51, 0
	s_mov_b32 m0, s29
	v_lshl_add_u64 v[98:99], s[38:39], 0, v[190:191]
	ds_read_b128 v[26:29], v219 offset:32768
	ds_read_b128 v[30:33], v219 offset:33792
	ds_read_b128 v[62:65], v219 offset:34816
	ds_read_b128 v[114:117], v219 offset:35840
	ds_read_b128 v[228:231], v219 offset:36864
	ds_read_b128 v[232:235], v219 offset:37888
	ds_read_b128 v[236:239], v219 offset:38912
	ds_read_b128 v[240:243], v219 offset:39936
	global_load_lds_dwordx4 v[98:99], off
	v_lshl_add_u64 v[98:99], s[38:39], 0, v[188:189]
	s_mov_b32 m0, s33
	s_nop 0
	global_load_lds_dwordx4 v[98:99], off
	s_waitcnt vmcnt(8)
	s_waitcnt lgkmcnt(0)
	s_barrier
	s_setprio 1
	s_waitcnt lgkmcnt(0)
	v_mfma_f32_16x16x32_bf16 v[66:69], v[10:13], v[26:29], v[66:69]
	v_mfma_f32_16x16x32_bf16 v[182:185], v[14:17], v[30:33], v[66:69]
	v_mfma_f32_16x16x32_bf16 v[66:69], v[18:21], v[26:29], v[70:73]
	v_mfma_f32_16x16x32_bf16 v[178:181], v[22:25], v[30:33], v[66:69]
	v_mfma_f32_16x16x32_bf16 v[66:69], v[10:13], v[62:65], v[74:77]
	v_mfma_f32_16x16x32_bf16 v[134:137], v[14:17], v[114:117], v[66:69]
	v_mfma_f32_16x16x32_bf16 v[66:69], v[18:21], v[62:65], v[78:81]
	v_mfma_f32_16x16x32_bf16 v[130:133], v[22:25], v[114:117], v[66:69]
	v_mfma_f32_16x16x32_bf16 v[66:69], v[10:13], v[228:231], v[82:85]
	v_mfma_f32_16x16x32_bf16 v[102:105], v[14:17], v[232:235], v[66:69]
	v_mfma_f32_16x16x32_bf16 v[66:69], v[18:21], v[228:231], v[86:89]
	v_mfma_f32_16x16x32_bf16 v[98:101], v[22:25], v[232:235], v[66:69]
	v_mfma_f32_16x16x32_bf16 v[66:69], v[10:13], v[236:239], v[90:93]
	v_mfma_f32_16x16x32_bf16 v[78:81], v[14:17], v[240:243], v[66:69]
	v_mfma_f32_16x16x32_bf16 v[66:69], v[18:21], v[236:239], v[94:97]
	v_mfma_f32_16x16x32_bf16 v[74:77], v[22:25], v[240:243], v[66:69]
	v_mfma_f32_16x16x32_bf16 v[66:69], v[154:157], v[26:29], v[200:203]
	v_mfma_f32_16x16x32_bf16 v[26:29], v[192:195], v[26:29], v[34:37]
	v_mfma_f32_16x16x32_bf16 v[170:173], v[224:227], v[30:33], v[26:29]
	v_mfma_f32_16x16x32_bf16 v[26:29], v[154:157], v[62:65], v[38:41]
	v_mfma_f32_16x16x32_bf16 v[118:121], v[158:161], v[114:117], v[26:29]
	v_mfma_f32_16x16x32_bf16 v[26:29], v[192:195], v[62:65], v[42:45]
	v_mfma_f32_16x16x32_bf16 v[114:117], v[224:227], v[114:117], v[26:29]
	v_mfma_f32_16x16x32_bf16 v[26:29], v[154:157], v[228:231], v[46:49]
	v_mfma_f32_16x16x32_bf16 v[86:89], v[158:161], v[232:235], v[26:29]
	v_mfma_f32_16x16x32_bf16 v[26:29], v[192:195], v[228:231], v[50:53]
	v_mfma_f32_16x16x32_bf16 v[82:85], v[224:227], v[232:235], v[26:29]
	v_mfma_f32_16x16x32_bf16 v[26:29], v[154:157], v[236:239], v[54:57]
	v_mfma_f32_16x16x32_bf16 v[70:73], v[158:161], v[240:243], v[26:29]
	v_mfma_f32_16x16x32_bf16 v[26:29], v[192:195], v[236:239], v[58:61]
	v_mfma_f32_16x16x32_bf16 v[174:177], v[158:161], v[30:33], v[66:69]
	v_mfma_f32_16x16x32_bf16 v[66:69], v[224:227], v[240:243], v[26:29]
	s_setprio 0
	s_barrier
	s_mov_b32 m0, s55
	s_nop 2
	v_lshl_add_u64 v[26:27], v[204:205], 0, s[24:25]
	s_add_u32 s38, s48, 0x10080
	ds_read_b128 v[34:37], v219 offset:49152
	ds_read_b128 v[38:41], v219 offset:50176
	ds_read_b128 v[90:93], v219 offset:51200
	ds_read_b128 v[94:97], v219 offset:52224
	ds_read_b128 v[200:203], v219 offset:53248
	ds_read_b128 v[228:231], v219 offset:54272
	ds_read_b128 v[232:235], v219 offset:55296
	ds_read_b128 v[236:239], v219 offset:56320
	global_load_lds_dwordx4 v[26:27], off
	v_lshl_add_u64 v[26:27], v[206:207], 0, s[24:25]
	s_mov_b32 m0, s47
	s_addc_u32 s39, s49, 0
	global_load_lds_dwordx4 v[26:27], off
	v_lshl_add_u64 v[26:27], s[38:39], 0, v[8:9]
	s_mov_b32 m0, s42
	s_nop 0
	global_load_lds_dwordx4 v[26:27], off
	v_lshl_add_u64 v[26:27], s[38:39], 0, v[186:187]
	s_mov_b32 m0, s43
	s_nop 0
	global_load_lds_dwordx4 v[26:27], off
	v_lshl_add_u64 v[26:27], v[208:209], 0, s[24:25]
	s_mov_b32 m0, s45
	s_nop 0
	global_load_lds_dwordx4 v[26:27], off
	v_lshl_add_u64 v[26:27], v[244:245], 0, s[24:25]
	s_mov_b32 m0, s46
	s_nop 0
	global_load_lds_dwordx4 v[26:27], off
	s_waitcnt vmcnt(8)
	s_waitcnt lgkmcnt(0)
	s_barrier
	s_setprio 1
	s_waitcnt lgkmcnt(0)
	v_mfma_f32_16x16x32_bf16 v[26:29], v[10:13], v[34:37], v[196:199]
	v_mfma_f32_16x16x32_bf16 v[62:65], v[14:17], v[38:41], v[26:29]
	v_mfma_f32_16x16x32_bf16 v[26:29], v[18:21], v[34:37], v[210:213]
	v_mfma_f32_16x16x32_bf16 v[58:61], v[22:25], v[38:41], v[26:29]
	v_mfma_f32_16x16x32_bf16 v[26:29], v[10:13], v[90:93], v[138:141]
	v_mfma_f32_16x16x32_bf16 v[46:49], v[14:17], v[94:97], v[26:29]
	v_mfma_f32_16x16x32_bf16 v[26:29], v[18:21], v[90:93], v[142:145]
	v_mfma_f32_16x16x32_bf16 v[42:45], v[22:25], v[94:97], v[26:29]
	v_mfma_f32_16x16x32_bf16 v[26:29], v[10:13], v[200:203], v[146:149]
	v_mfma_f32_16x16x32_bf16 v[0:3], v[10:13], v[232:235], v[0:3]
	v_mfma_f32_16x16x32_bf16 v[30:33], v[14:17], v[228:231], v[26:29]
	v_mfma_f32_16x16x32_bf16 v[26:29], v[18:21], v[200:203], v[150:153]
	v_mfma_f32_16x16x32_bf16 v[14:17], v[14:17], v[236:239], v[0:3]
	v_mfma_f32_16x16x32_bf16 v[0:3], v[18:21], v[232:235], v[4:7]
	v_mfma_f32_16x16x32_bf16 v[26:29], v[22:25], v[228:231], v[26:29]
	v_mfma_f32_16x16x32_bf16 v[10:13], v[22:25], v[236:239], v[0:3]
	v_mfma_f32_16x16x32_bf16 v[0:3], v[154:157], v[34:37], v[106:109]
	v_mfma_f32_16x16x32_bf16 v[54:57], v[158:161], v[38:41], v[0:3]
	v_mfma_f32_16x16x32_bf16 v[0:3], v[192:195], v[34:37], v[110:113]
	v_mfma_f32_16x16x32_bf16 v[50:53], v[224:227], v[38:41], v[0:3]
	v_mfma_f32_16x16x32_bf16 v[0:3], v[154:157], v[90:93], v[162:165]
	v_mfma_f32_16x16x32_bf16 v[38:41], v[158:161], v[94:97], v[0:3]
	v_mfma_f32_16x16x32_bf16 v[0:3], v[192:195], v[90:93], v[166:169]
	v_mfma_f32_16x16x32_bf16 v[34:37], v[224:227], v[94:97], v[0:3]
	v_mfma_f32_16x16x32_bf16 v[0:3], v[154:157], v[200:203], v[214:217]
	v_mfma_f32_16x16x32_bf16 v[22:25], v[158:161], v[228:231], v[0:3]
	v_mfma_f32_16x16x32_bf16 v[0:3], v[192:195], v[200:203], v[220:223]
	v_mfma_f32_16x16x32_bf16 v[18:21], v[224:227], v[228:231], v[0:3]
	v_mfma_f32_16x16x32_bf16 v[0:3], v[154:157], v[232:235], v[122:125]
	v_mfma_f32_16x16x32_bf16 v[4:7], v[158:161], v[236:239], v[0:3]
	v_mfma_f32_16x16x32_bf16 v[0:3], v[192:195], v[232:235], v[126:129]
	v_mfma_f32_16x16x32_bf16 v[0:3], v[224:227], v[236:239], v[0:3]
	s_setprio 0
	s_barrier
	s_andn2_b64 vcc, exec, s[10:11]
	s_cbranch_vccnz .LBB0_613
	s_barrier

; #define PG8_STAGE(bufoff, gbase, voff) do { _Pragma("unroll") for (int _i = 0; _i < 2; ++_i) \
;         __builtin_amdgcn_global_load_lds((const unsigned*)((const char*)(gbase) + (voff)[_i]), (PG8_LAS unsigned*)(lds + (bufoff) + ldsw + _i * 8192), 16, 0, 0); } while (0)
; #define PG8_LDA(dst, b, h) do { _Pragma("unroll") for (int m = 0; m < 4; ++m) _Pragma("unroll") for (int k = 0; k < 2; ++k) dst[m][k] = *(const PG8_LAS bf16x8*)(lds + PG8_SA(b, h) + aoff + m * 2048 + k * 1024); } while (0)
; #define PG8_LDB(dst, b, h) do { _Pragma("unroll") for (int n = 0; n < 2; ++n) _Pragma("unroll") for (int k = 0; k < 2; ++k) dst[n][k] = *(const PG8_LAS bf16x8*)(lds + PG8_SB(b, h) + boff + n * 2048 + k * 1024); } while (0)
; #define PG8_MMA(ai, bj, At, Bt) do { __builtin_amdgcn_s_setprio(1); _Pragma("unroll") for (int m = 0; m < 4; ++m) _Pragma("unroll") for (int n = 0; n < 2; ++n) _Pragma("unroll") for (int k = 0; k < 2; ++k) \
;         acc[ai][bj][m][n] = __builtin_amdgcn_mfma_f32_16x16x32_bf16(Bt[n][k], At[m][k], acc[ai][bj][m][n], 0, 0, 0); __builtin_amdgcn_s_setprio(0); } while (0)
; template <class Epi, class Sched, bool ALIGN_EPI = false, bool SP2 = false>
; __device__ __forceinline__ void gemm_phase(PG8_LAS unsigned char* lds, int tid_in, const Gemm g, const Sched& S, const Epi& E) {
;     ...
;         const bool has_next = S.next(ui + 1, nxt);
;         const char* nA = has_next ? (const char*)g.A + (size_t)nxt.pm * tstep : cA; const char* nB = has_next ? (const char*)g.Bt + (size_t)nxt.pn * tstep : cB;
;         for (int t = 0; t < nt; t += 2) {
;             const bool last = (t == nt - 2);
;             const char* a1 = cA + (size_t)(t + 1) * kstep;
;             const char* a2 = last ? nA : cA + (size_t)(t + 2) * kstep; const char* b2 = last ? nB : cB + (size_t)(t + 2) * kstep;
;             const char* a3 = a2 + kstep; const char* b3 = b2 + kstep;
;             if (last && has_next) S.a_ready(nxt);
;             if constexpr (SP2) {
;             PG8_LDB(B0, 0, 0); PG8_LDB(B1, 0, 1); PG8_SCHED; PG8_LDA(At, 0, 0); PG8_STAGE(PG8_SA(1, 1), a1 + hstep, voffA);
;             PG8_WAIT_V(8); PG8_WAIT_L(0); PG8_BAR; PG8_MMA(0, 0, At, B0); PG8_MMA(0, 1, At, B1); PG8_BAR; PG8_SCHED;
;             PG8_LDA(At, 0, 1); PG8_STAGE(PG8_SB(0, 0), b2, voffB); PG8_STAGE(PG8_SB(0, 1), b2 + hstep, voffB); PG8_STAGE(PG8_SA(0, 0), a2, voffA);
.LBB0_629:
	s_ashr_i32 s15, s14, 31
	s_lshl_b64 s[16:17], s[14:15], 17
	v_readlane_b32 s30, v253, 42
	v_readlane_b32 s31, v253, 43
	s_add_u32 s16, s30, s16
	s_addc_u32 s17, s31, s17
	s_and_b64 s[30:31], s[4:5], exec
	s_cselect_b32 s49, s17, s51
	s_cselect_b32 s48, s16, s50
	s_ashr_i32 s13, s12, 31
	s_lshl_b64 s[30:31], s[12:13], 17
	s_add_u32 s30, s0, s30
	s_addc_u32 s31, s1, s31
	s_and_b64 s[38:39], s[4:5], exec
	s_cselect_b32 s43, s31, s35
	s_cselect_b32 s42, s30, s34
	s_add_i32 s15, 0, 0x10000
	s_add_i32 s37, 0, 0x14000
	v_add_u32_e32 v210, s15, v218
	v_add_u32_e32 v211, s37, v218
	ds_read_b128 v[0:3], v210
	ds_read_b128 v[4:7], v210 offset:1024
	ds_read_b128 v[10:13], v210 offset:2048
	ds_read_b128 v[14:17], v210 offset:3072
	ds_read_b128 v[18:21], v211
	ds_read_b128 v[22:25], v211 offset:1024
	ds_read_b128 v[26:29], v211 offset:2048
	s_waitcnt vmcnt(0)
	ds_read_b128 v[30:33], v211 offset:3072
	s_add_u32 s38, s50, 0x10080
	s_addc_u32 s39, s51, 0
	s_add_i32 s53, s21, 0xc000
	v_lshl_add_u64 v[66:67], s[38:39], 0, v[190:191]
	s_mov_b32 m0, s53
	s_add_i32 s13, s21, 0xe000
	ds_read_b128 v[34:37], v219
	ds_read_b128 v[38:41], v219 offset:1024
	ds_read_b128 v[42:45], v219 offset:2048
	ds_read_b128 v[46:49], v219 offset:3072
	ds_read_b128 v[50:53], v219 offset:4096
	ds_read_b128 v[54:57], v219 offset:5120
	ds_read_b128 v[58:61], v219 offset:6144
	ds_read_b128 v[62:65], v219 offset:7168
	global_load_lds_dwordx4 v[66:67], off
	v_lshl_add_u64 v[66:67], s[38:39], 0, v[188:189]
	s_mov_b32 m0, s13
	s_nop 0
	global_load_lds_dwordx4 v[66:67], off
	s_waitcnt vmcnt(8)
	s_waitcnt lgkmcnt(0)
	s_barrier
	s_setprio 1
	s_waitcnt lgkmcnt(0)
	v_mfma_f32_16x16x32_bf16 v[66:69], v[0:3], v[34:37], 0
	v_mfma_f32_16x16x32_bf16 v[70:73], v[10:13], v[34:37], 0
	v_mfma_f32_16x16x32_bf16 v[74:77], v[0:3], v[42:45], 0
	v_mfma_f32_16x16x32_bf16 v[78:81], v[10:13], v[42:45], 0
	v_mfma_f32_16x16x32_bf16 v[82:85], v[0:3], v[50:53], 0
	v_mfma_f32_16x16x32_bf16 v[86:89], v[10:13], v[50:53], 0
	v_mfma_f32_16x16x32_bf16 v[66:69], v[4:7], v[38:41], v[66:69]
	v_mfma_f32_16x16x32_bf16 v[70:73], v[14:17], v[38:41], v[70:73]
	v_mfma_f32_16x16x32_bf16 v[74:77], v[4:7], v[46:49], v[74:77]
	v_mfma_f32_16x16x32_bf16 v[78:81], v[14:17], v[46:49], v[78:81]
	v_mfma_f32_16x16x32_bf16 v[82:85], v[4:7], v[54:57], v[82:85]
	v_mfma_f32_16x16x32_bf16 v[86:89], v[14:17], v[54:57], v[86:89]
	v_mfma_f32_16x16x32_bf16 v[90:93], v[0:3], v[58:61], 0
	v_mfma_f32_16x16x32_bf16 v[94:97], v[10:13], v[58:61], 0
	v_mfma_f32_16x16x32_bf16 v[90:93], v[4:7], v[62:65], v[90:93]
	v_mfma_f32_16x16x32_bf16 v[94:97], v[14:17], v[62:65], v[94:97]
	v_mfma_f32_16x16x32_bf16 v[98:101], v[18:21], v[34:37], 0
	v_mfma_f32_16x16x32_bf16 v[34:37], v[26:29], v[34:37], 0
	v_mfma_f32_16x16x32_bf16 v[98:101], v[22:25], v[38:41], v[98:101]
	v_mfma_f32_16x16x32_bf16 v[34:37], v[30:33], v[38:41], v[34:37]
	v_mfma_f32_16x16x32_bf16 v[38:41], v[18:21], v[42:45], 0
	v_mfma_f32_16x16x32_bf16 v[42:45], v[26:29], v[42:45], 0
	v_mfma_f32_16x16x32_bf16 v[38:41], v[22:25], v[46:49], v[38:41]
	v_mfma_f32_16x16x32_bf16 v[42:45], v[30:33], v[46:49], v[42:45]
	v_mfma_f32_16x16x32_bf16 v[46:49], v[18:21], v[50:53], 0
	v_mfma_f32_16x16x32_bf16 v[50:53], v[26:29], v[50:53], 0
	v_mfma_f32_16x16x32_bf16 v[46:49], v[22:25], v[54:57], v[46:49]
	v_mfma_f32_16x16x32_bf16 v[50:53], v[30:33], v[54:57], v[50:53]
	v_mfma_f32_16x16x32_bf16 v[54:57], v[18:21], v[58:61], 0
	v_mfma_f32_16x16x32_bf16 v[58:61], v[26:29], v[58:61], 0
	v_mfma_f32_16x16x32_bf16 v[54:57], v[22:25], v[62:65], v[54:57]
	v_mfma_f32_16x16x32_bf16 v[58:61], v[30:33], v[62:65], v[58:61]
	s_setprio 0
	s_barrier
	s_add_i32 s39, s15, s20
	v_lshl_add_u64 v[200:201], s[34:35], 0, v[8:9]
	s_mov_b64 s[58:59], 0x100
	s_add_i32 s15, s39, 0x2000
	v_lshl_add_u64 v[130:131], v[200:201], 0, s[58:59]
	s_mov_b32 m0, s39
	v_lshl_add_u64 v[202:203], s[34:35], 0, v[186:187]
	s_add_u32 s56, s34, 0x10100
	ds_read_b128 v[62:65], v219 offset:16384
	ds_read_b128 v[102:105], v219 offset:17408
	ds_read_b128 v[106:109], v219 offset:18432
	ds_read_b128 v[110:113], v219 offset:19456
	ds_read_b128 v[114:117], v219 offset:20480
	ds_read_b128 v[118:121], v219 offset:21504
	ds_read_b128 v[122:125], v219 offset:22528
	ds_read_b128 v[126:129], v219 offset:23552
	global_load_lds_dwordx4 v[130:131], off
	v_lshl_add_u64 v[130:131], v[202:203], 0, s[58:59]
	s_mov_b32 m0, s15
	s_addc_u32 s57, s35, 0
	s_add_i32 s37, s37, s20
	global_load_lds_dwordx4 v[130:131], off
	v_lshl_add_u64 v[130:131], s[56:57], 0, v[8:9]
	s_mov_b32 m0, s37
	s_add_i32 s38, s37, 0x2000
	global_load_lds_dwordx4 v[130:131], off
	v_lshl_add_u64 v[130:131], s[56:57], 0, v[186:187]
	s_mov_b32 m0, s38
	v_lshl_add_u64 v[204:205], s[50:51], 0, v[190:191]
	global_load_lds_dwordx4 v[130:131], off
	v_lshl_add_u64 v[130:131], v[204:205], 0, s[58:59]
	s_mov_b32 m0, s21
	v_lshl_add_u64 v[206:207], s[50:51], 0, v[188:189]
	global_load_lds_dwordx4 v[130:131], off
	v_lshl_add_u64 v[130:131], v[206:207], 0, s[58:59]
	s_mov_b32 m0, s28
	s_nop 0
	global_load_lds_dwordx4 v[130:131], off
	s_waitcnt vmcnt(8)
	s_waitcnt lgkmcnt(0)
	s_barrier
; #define PG8_STAGE(bufoff, gbase, voff) do { _Pragma("unroll") for (int _i = 0; _i < 2; ++_i) \
;         __builtin_amdgcn_global_load_lds((const unsigned*)((const char*)(gbase) + (voff)[_i]), (PG8_LAS unsigned*)(lds + (bufoff) + ldsw + _i * 8192), 16, 0, 0); } while (0)
; #define PG8_LDA(dst, b, h) do { _Pragma("unroll") for (int m = 0; m < 4; ++m) _Pragma("unroll") for (int k = 0; k < 2; ++k) dst[m][k] = *(const PG8_LAS bf16x8*)(lds + PG8_SA(b, h) + aoff + m * 2048 + k * 1024); } while (0)
; #define PG8_LDB(dst, b, h) do { _Pragma("unroll") for (int n = 0; n < 2; ++n) _Pragma("unroll") for (int k = 0; k < 2; ++k) dst[n][k] = *(const PG8_LAS bf16x8*)(lds + PG8_SB(b, h) + boff + n * 2048 + k * 1024); } while (0)
; #define PG8_MMA(ai, bj, At, Bt) do { __builtin_amdgcn_s_setprio(1); _Pragma("unroll") for (int m = 0; m < 4; ++m) _Pragma("unroll") for (int n = 0; n < 2; ++n) _Pragma("unroll") for (int k = 0; k < 2; ++k) \
;         acc[ai][bj][m][n] = __builtin_amdgcn_mfma_f32_16x16x32_bf16(Bt[n][k], At[m][k], acc[ai][bj][m][n], 0, 0, 0); __builtin_amdgcn_s_setprio(0); } while (0)
; #define PG8_WAIT_V(n) asm volatile("s_waitcnt vmcnt(" #n ")" ::: "memory")
; #define PG8_WAIT_L(n) asm volatile("s_waitcnt lgkmcnt(" #n ")" ::: "memory")
; #define PG8_BAR __builtin_amdgcn_s_barrier()
; #define PG8_SCHED __builtin_amdgcn_sched_barrier(0)
; template <class Epi, class Sched, bool ALIGN_EPI = false, bool SP2 = false>
; __device__ __forceinline__ void gemm_phase(PG8_LAS unsigned char* lds, int tid_in, const Gemm g, const Sched& S, const Epi& E) {
;     ...
;             PG8_WAIT_V(8); PG8_WAIT_L(0); PG8_BAR; PG8_MMA(1, 0, At, B0); PG8_MMA(1, 1, At, B1); PG8_BAR; PG8_SCHED;
;             PG8_LDB(B0, 1, 0); PG8_LDB(B1, 1, 1); PG8_SCHED; PG8_LDA(At, 1, 0); PG8_STAGE(PG8_SA(0, 1), a2 + hstep, voffA);
;             PG8_WAIT_V(8); PG8_WAIT_L(0); PG8_BAR; PG8_MMA(0, 0, At, B0); PG8_MMA(0, 1, At, B1); PG8_BAR; PG8_SCHED;
	s_setprio 1
	s_waitcnt lgkmcnt(0)
	v_mfma_f32_16x16x32_bf16 v[130:133], v[0:3], v[62:65], 0
	v_mfma_f32_16x16x32_bf16 v[138:141], v[0:3], v[106:109], 0
	v_mfma_f32_16x16x32_bf16 v[146:149], v[0:3], v[114:117], 0
	v_mfma_f32_16x16x32_bf16 v[0:3], v[0:3], v[122:125], 0
	v_mfma_f32_16x16x32_bf16 v[130:133], v[4:7], v[102:105], v[130:133]
	v_mfma_f32_16x16x32_bf16 v[134:137], v[10:13], v[62:65], 0
	v_mfma_f32_16x16x32_bf16 v[138:141], v[4:7], v[110:113], v[138:141]
	v_mfma_f32_16x16x32_bf16 v[146:149], v[4:7], v[118:121], v[146:149]
	v_mfma_f32_16x16x32_bf16 v[0:3], v[4:7], v[126:129], v[0:3]
	v_mfma_f32_16x16x32_bf16 v[4:7], v[10:13], v[122:125], 0
	v_mfma_f32_16x16x32_bf16 v[134:137], v[14:17], v[102:105], v[134:137]
	v_mfma_f32_16x16x32_bf16 v[142:145], v[10:13], v[106:109], 0
	v_mfma_f32_16x16x32_bf16 v[150:153], v[10:13], v[114:117], 0
	v_mfma_f32_16x16x32_bf16 v[4:7], v[14:17], v[126:129], v[4:7]
	v_mfma_f32_16x16x32_bf16 v[142:145], v[14:17], v[110:113], v[142:145]
	v_mfma_f32_16x16x32_bf16 v[150:153], v[14:17], v[118:121], v[150:153]
	v_mfma_f32_16x16x32_bf16 v[10:13], v[18:21], v[62:65], 0
	v_mfma_f32_16x16x32_bf16 v[14:17], v[26:29], v[62:65], 0
	v_mfma_f32_16x16x32_bf16 v[10:13], v[22:25], v[102:105], v[10:13]
	v_mfma_f32_16x16x32_bf16 v[14:17], v[30:33], v[102:105], v[14:17]
	v_mfma_f32_16x16x32_bf16 v[62:65], v[18:21], v[106:109], 0
	v_mfma_f32_16x16x32_bf16 v[102:105], v[26:29], v[106:109], 0
	v_mfma_f32_16x16x32_bf16 v[106:109], v[18:21], v[114:117], 0
	v_mfma_f32_16x16x32_bf16 v[18:21], v[18:21], v[122:125], 0
	v_mfma_f32_16x16x32_bf16 v[62:65], v[22:25], v[110:113], v[62:65]
	v_mfma_f32_16x16x32_bf16 v[106:109], v[22:25], v[118:121], v[106:109]
	v_mfma_f32_16x16x32_bf16 v[18:21], v[22:25], v[126:129], v[18:21]
	v_mfma_f32_16x16x32_bf16 v[22:25], v[26:29], v[122:125], 0
	v_mfma_f32_16x16x32_bf16 v[102:105], v[30:33], v[110:113], v[102:105]
	v_mfma_f32_16x16x32_bf16 v[110:113], v[26:29], v[114:117], 0
	v_mfma_f32_16x16x32_bf16 v[22:25], v[30:33], v[126:129], v[22:25]
	v_mfma_f32_16x16x32_bf16 v[110:113], v[30:33], v[118:121], v[110:113]
	s_setprio 0
	s_barrier
	s_add_i32 s55, 0, 0x18000
	s_add_i32 s58, 0, 0x1c000
	v_add_u32_e32 v224, s55, v218
	v_add_u32_e32 v225, s58, v218
	ds_read_b128 v[26:29], v224
	ds_read_b128 v[30:33], v224 offset:1024
	ds_read_b128 v[114:117], v224 offset:2048
	ds_read_b128 v[118:121], v224 offset:3072
	ds_read_b128 v[122:125], v225
	ds_read_b128 v[126:129], v225 offset:1024
	ds_read_b128 v[154:157], v225 offset:2048
	ds_read_b128 v[158:161], v225 offset:3072
	s_add_u32 s56, s50, 0x10100
	s_addc_u32 s57, s51, 0
	s_mov_b32 m0, s29
	v_lshl_add_u64 v[208:209], s[56:57], 0, v[190:191]
	ds_read_b128 v[162:165], v219 offset:32768
	ds_read_b128 v[166:169], v219 offset:33792
	ds_read_b128 v[170:173], v219 offset:34816
	ds_read_b128 v[174:177], v219 offset:35840
	ds_read_b128 v[178:181], v219 offset:36864
	ds_read_b128 v[182:185], v219 offset:37888
	ds_read_b128 v[192:195], v219 offset:38912
	ds_read_b128 v[196:199], v219 offset:39936
	global_load_lds_dwordx4 v[208:209], off
	v_lshl_add_u64 v[208:209], s[56:57], 0, v[188:189]
	s_mov_b32 m0, s33
	s_nop 0
	global_load_lds_dwordx4 v[208:209], off
	s_waitcnt vmcnt(8)
	s_waitcnt lgkmcnt(0)
	s_barrier
	s_setprio 1
	s_waitcnt lgkmcnt(0)
	v_mfma_f32_16x16x32_bf16 v[66:69], v[26:29], v[162:165], v[66:69]
	v_mfma_f32_16x16x32_bf16 v[70:73], v[114:117], v[162:165], v[70:73]
	v_mfma_f32_16x16x32_bf16 v[74:77], v[26:29], v[170:173], v[74:77]
	v_mfma_f32_16x16x32_bf16 v[78:81], v[114:117], v[170:173], v[78:81]
	v_mfma_f32_16x16x32_bf16 v[82:85], v[26:29], v[178:181], v[82:85]
	v_mfma_f32_16x16x32_bf16 v[86:89], v[114:117], v[178:181], v[86:89]
	v_mfma_f32_16x16x32_bf16 v[66:69], v[30:33], v[166:169], v[66:69]
	v_mfma_f32_16x16x32_bf16 v[70:73], v[118:121], v[166:169], v[70:73]
	v_mfma_f32_16x16x32_bf16 v[74:77], v[30:33], v[174:177], v[74:77]
	v_mfma_f32_16x16x32_bf16 v[78:81], v[118:121], v[174:177], v[78:81]
	v_mfma_f32_16x16x32_bf16 v[82:85], v[30:33], v[182:185], v[82:85]
	v_mfma_f32_16x16x32_bf16 v[86:89], v[118:121], v[182:185], v[86:89]
	v_mfma_f32_16x16x32_bf16 v[90:93], v[26:29], v[192:195], v[90:93]
	v_mfma_f32_16x16x32_bf16 v[94:97], v[114:117], v[192:195], v[94:97]
	v_mfma_f32_16x16x32_bf16 v[90:93], v[30:33], v[196:199], v[90:93]
	v_mfma_f32_16x16x32_bf16 v[94:97], v[118:121], v[196:199], v[94:97]
	v_mfma_f32_16x16x32_bf16 v[98:101], v[122:125], v[162:165], v[98:101]
	v_mfma_f32_16x16x32_bf16 v[34:37], v[154:157], v[162:165], v[34:37]
	v_mfma_f32_16x16x32_bf16 v[38:41], v[122:125], v[170:173], v[38:41]
	v_mfma_f32_16x16x32_bf16 v[42:45], v[154:157], v[170:173], v[42:45]
	v_mfma_f32_16x16x32_bf16 v[46:49], v[122:125], v[178:181], v[46:49]
	v_mfma_f32_16x16x32_bf16 v[50:53], v[154:157], v[178:181], v[50:53]
	v_mfma_f32_16x16x32_bf16 v[54:57], v[122:125], v[192:195], v[54:57]
	v_mfma_f32_16x16x32_bf16 v[58:61], v[154:157], v[192:195], v[58:61]
	v_mfma_f32_16x16x32_bf16 v[98:101], v[126:129], v[166:169], v[98:101]
	v_mfma_f32_16x16x32_bf16 v[34:37], v[158:161], v[166:169], v[34:37]
	v_mfma_f32_16x16x32_bf16 v[38:41], v[126:129], v[174:177], v[38:41]
	v_mfma_f32_16x16x32_bf16 v[42:45], v[158:161], v[174:177], v[42:45]
	v_mfma_f32_16x16x32_bf16 v[46:49], v[126:129], v[182:185], v[46:49]
	v_mfma_f32_16x16x32_bf16 v[50:53], v[158:161], v[182:185], v[50:53]
	v_mfma_f32_16x16x32_bf16 v[54:57], v[126:129], v[196:199], v[54:57]
	v_mfma_f32_16x16x32_bf16 v[58:61], v[158:161], v[196:199], v[58:61]
	s_setprio 0
	s_barrier
; #define PG8_STAGE(bufoff, gbase, voff) do { _Pragma("unroll") for (int _i = 0; _i < 2; ++_i) \
;         __builtin_amdgcn_global_load_lds((const unsigned*)((const char*)(gbase) + (voff)[_i]), (PG8_LAS unsigned*)(lds + (bufoff) + ldsw + _i * 8192), 16, 0, 0); } while (0)
; #define PG8_LDA(dst, b, h) do { _Pragma("unroll") for (int m = 0; m < 4; ++m) _Pragma("unroll") for (int k = 0; k < 2; ++k) dst[m][k] = *(const PG8_LAS bf16x8*)(lds + PG8_SA(b, h) + aoff + m * 2048 + k * 1024); } while (0)
; #define PG8_LDB(dst, b, h) do { _Pragma("unroll") for (int n = 0; n < 2; ++n) _Pragma("unroll") for (int k = 0; k < 2; ++k) dst[n][k] = *(const PG8_LAS bf16x8*)(lds + PG8_SB(b, h) + boff + n * 2048 + k * 1024); } while (0)
; #define PG8_MMA(ai, bj, At, Bt) do { __builtin_amdgcn_s_setprio(1); _Pragma("unroll") for (int m = 0; m < 4; ++m) _Pragma("unroll") for (int n = 0; n < 2; ++n) _Pragma("unroll") for (int k = 0; k < 2; ++k) \
;         acc[ai][bj][m][n] = __builtin_amdgcn_mfma_f32_16x16x32_bf16(Bt[n][k], At[m][k], acc[ai][bj][m][n], 0, 0, 0); __builtin_amdgcn_s_setprio(0); } while (0)
; #define PG8_BAR __builtin_amdgcn_s_barrier()
; template <class Epi, class Sched, bool ALIGN_EPI = false, bool SP2 = false>
; __device__ __forceinline__ void gemm_phase(PG8_LAS unsigned char* lds, int tid_in, const Gemm g, const Sched& S, const Epi& E) {
;     ...
;             PG8_LDB(B0, 0, 0); PG8_LDB(B1, 0, 1); PG8_SCHED; PG8_LDA(At, 0, 0); PG8_STAGE(PG8_SA(1, 1), a1 + hstep, voffA);
;             PG8_WAIT_V(8); PG8_WAIT_L(0); PG8_BAR; PG8_MMA(0, 0, At, B0); PG8_MMA(0, 1, At, B1); PG8_BAR; PG8_SCHED;
;             PG8_LDA(At, 0, 1); PG8_STAGE(PG8_SB(0, 0), b2, voffB); PG8_STAGE(PG8_SB(0, 1), b2 + hstep, voffB); PG8_STAGE(PG8_SA(0, 0), a2, voffA);
;             PG8_WAIT_V(8); PG8_WAIT_L(0); PG8_BAR; PG8_MMA(1, 0, At, B0); PG8_MMA(1, 1, At, B1); PG8_BAR; PG8_SCHED;
;             PG8_LDB(B0, 1, 0); PG8_LDB(B1, 1, 1); PG8_SCHED; PG8_LDA(At, 1, 0); PG8_STAGE(PG8_SA(0, 1), a2 + hstep, voffA);
;             PG8_WAIT_V(8); PG8_WAIT_L(0); PG8_BAR; PG8_MMA(0, 0, At, B0); PG8_MMA(0, 1, At, B1); PG8_BAR; PG8_SCHED;
;             PG8_LDA(At, 1, 1); PG8_STAGE(PG8_SB(1, 0), b3, voffB); PG8_STAGE(PG8_SB(1, 1), b3 + hstep, voffB); PG8_STAGE(PG8_SA(1, 0), a3, voffA);
;             PG8_WAIT_V(8); PG8_WAIT_L(0); PG8_BAR; PG8_MMA(1, 0, At, B0); PG8_MMA(1, 1, At, B1); PG8_BAR; PG8_SCHED;
	s_add_i32 s55, s55, s20
	s_mov_b64 s[60:61], 0x180
	s_add_i32 s47, s55, 0x2000
	v_lshl_add_u64 v[200:201], v[200:201], 0, s[60:61]
	s_mov_b32 m0, s55
	s_add_u32 s56, s34, 0x10180
	ds_read_b128 v[162:165], v219 offset:49152
	ds_read_b128 v[166:169], v219 offset:50176
	ds_read_b128 v[170:173], v219 offset:51200
	ds_read_b128 v[174:177], v219 offset:52224
	ds_read_b128 v[178:181], v219 offset:53248
	ds_read_b128 v[182:185], v219 offset:54272
	ds_read_b128 v[192:195], v219 offset:55296
	ds_read_b128 v[196:199], v219 offset:56320
	global_load_lds_dwordx4 v[200:201], off
	v_lshl_add_u64 v[200:201], v[202:203], 0, s[60:61]
	s_mov_b32 m0, s47
	s_addc_u32 s57, s35, 0
	s_add_i32 s34, s58, s20
	global_load_lds_dwordx4 v[200:201], off
	v_lshl_add_u64 v[200:201], s[56:57], 0, v[8:9]
	s_mov_b32 m0, s34
	s_add_i32 s35, s34, 0x2000
	global_load_lds_dwordx4 v[200:201], off
	v_lshl_add_u64 v[200:201], s[56:57], 0, v[186:187]
	s_mov_b32 m0, s35
	s_nop 0
	global_load_lds_dwordx4 v[200:201], off
	v_lshl_add_u64 v[200:201], v[204:205], 0, s[60:61]
	s_mov_b32 m0, s45
	s_nop 0
	global_load_lds_dwordx4 v[200:201], off
	v_lshl_add_u64 v[200:201], v[206:207], 0, s[60:61]
	s_mov_b32 m0, s46
	s_nop 0
	global_load_lds_dwordx4 v[200:201], off
	s_waitcnt vmcnt(8)
	s_waitcnt lgkmcnt(0)
	s_barrier
	s_setprio 1
	s_waitcnt lgkmcnt(0)
	v_mfma_f32_16x16x32_bf16 v[130:133], v[26:29], v[162:165], v[130:133]
	v_mfma_f32_16x16x32_bf16 v[134:137], v[114:117], v[162:165], v[134:137]
	v_mfma_f32_16x16x32_bf16 v[0:3], v[26:29], v[192:195], v[0:3]
	v_mfma_f32_16x16x32_bf16 v[4:7], v[114:117], v[192:195], v[4:7]
	v_mfma_f32_16x16x32_bf16 v[130:133], v[30:33], v[166:169], v[130:133]
	v_mfma_f32_16x16x32_bf16 v[134:137], v[118:121], v[166:169], v[134:137]
	v_mfma_f32_16x16x32_bf16 v[138:141], v[26:29], v[170:173], v[138:141]
	v_mfma_f32_16x16x32_bf16 v[142:145], v[114:117], v[170:173], v[142:145]
	v_mfma_f32_16x16x32_bf16 v[146:149], v[26:29], v[178:181], v[146:149]
	v_mfma_f32_16x16x32_bf16 v[150:153], v[114:117], v[178:181], v[150:153]
	v_mfma_f32_16x16x32_bf16 v[0:3], v[30:33], v[196:199], v[0:3]
	v_mfma_f32_16x16x32_bf16 v[4:7], v[118:121], v[196:199], v[4:7]
	v_mfma_f32_16x16x32_bf16 v[138:141], v[30:33], v[174:177], v[138:141]
	v_mfma_f32_16x16x32_bf16 v[142:145], v[118:121], v[174:177], v[142:145]
	v_mfma_f32_16x16x32_bf16 v[146:149], v[30:33], v[182:185], v[146:149]
	v_mfma_f32_16x16x32_bf16 v[150:153], v[118:121], v[182:185], v[150:153]
	v_mfma_f32_16x16x32_bf16 v[10:13], v[122:125], v[162:165], v[10:13]
	v_mfma_f32_16x16x32_bf16 v[14:17], v[154:157], v[162:165], v[14:17]
	v_mfma_f32_16x16x32_bf16 v[26:29], v[122:125], v[170:173], v[62:65]
	v_mfma_f32_16x16x32_bf16 v[30:33], v[154:157], v[170:173], v[102:105]
	v_mfma_f32_16x16x32_bf16 v[62:65], v[122:125], v[178:181], v[106:109]
	v_mfma_f32_16x16x32_bf16 v[102:105], v[154:157], v[178:181], v[110:113]
	v_mfma_f32_16x16x32_bf16 v[18:21], v[122:125], v[192:195], v[18:21]
	v_mfma_f32_16x16x32_bf16 v[22:25], v[154:157], v[192:195], v[22:25]
	v_mfma_f32_16x16x32_bf16 v[10:13], v[126:129], v[166:169], v[10:13]
	v_mfma_f32_16x16x32_bf16 v[14:17], v[158:161], v[166:169], v[14:17]
	v_mfma_f32_16x16x32_bf16 v[26:29], v[126:129], v[174:177], v[26:29]
	v_mfma_f32_16x16x32_bf16 v[30:33], v[158:161], v[174:177], v[30:33]
	v_mfma_f32_16x16x32_bf16 v[62:65], v[126:129], v[182:185], v[62:65]
	v_mfma_f32_16x16x32_bf16 v[102:105], v[158:161], v[182:185], v[102:105]
	v_mfma_f32_16x16x32_bf16 v[18:21], v[126:129], v[196:199], v[18:21]
	v_mfma_f32_16x16x32_bf16 v[22:25], v[158:161], v[196:199], v[22:25]
	s_setprio 0
	s_barrier
	ds_read_b128 v[106:109], v210
	ds_read_b128 v[110:113], v210 offset:1024
	ds_read_b128 v[114:117], v210 offset:2048
	ds_read_b128 v[118:121], v210 offset:3072
	ds_read_b128 v[122:125], v211
	ds_read_b128 v[126:129], v211 offset:1024
	ds_read_b128 v[154:157], v211 offset:2048
	ds_read_b128 v[158:161], v211 offset:3072
	s_add_u32 s50, s50, 0x10180
	s_addc_u32 s51, s51, 0
	s_mov_b32 m0, s53
	v_lshl_add_u64 v[200:201], s[50:51], 0, v[190:191]
	ds_read_b128 v[162:165], v219
	ds_read_b128 v[166:169], v219 offset:1024
	ds_read_b128 v[170:173], v219 offset:2048
	ds_read_b128 v[174:177], v219 offset:3072
	ds_read_b128 v[178:181], v219 offset:4096
	ds_read_b128 v[182:185], v219 offset:5120
	ds_read_b128 v[192:195], v219 offset:6144
	ds_read_b128 v[196:199], v219 offset:7168
	global_load_lds_dwordx4 v[200:201], off
	v_lshl_add_u64 v[200:201], s[50:51], 0, v[188:189]
	s_mov_b32 m0, s13
	s_nop 0
	global_load_lds_dwordx4 v[200:201], off
	s_waitcnt vmcnt(8)
	s_waitcnt lgkmcnt(0)
	s_barrier
; #define PG8_STAGE(bufoff, gbase, voff) do { _Pragma("unroll") for (int _i = 0; _i < 2; ++_i) \
;         __builtin_amdgcn_global_load_lds((const unsigned*)((const char*)(gbase) + (voff)[_i]), (PG8_LAS unsigned*)(lds + (bufoff) + ldsw + _i * 8192), 16, 0, 0); } while (0)
; #define PG8_LDA(dst, b, h) do { _Pragma("unroll") for (int m = 0; m < 4; ++m) _Pragma("unroll") for (int k = 0; k < 2; ++k) dst[m][k] = *(const PG8_LAS bf16x8*)(lds + PG8_SA(b, h) + aoff + m * 2048 + k * 1024); } while (0)
; #define PG8_LDB(dst, b, h) do { _Pragma("unroll") for (int n = 0; n < 2; ++n) _Pragma("unroll") for (int k = 0; k < 2; ++k) dst[n][k] = *(const PG8_LAS bf16x8*)(lds + PG8_SB(b, h) + boff + n * 2048 + k * 1024); } while (0)
; #define PG8_MMA(ai, bj, At, Bt) do { __builtin_amdgcn_s_setprio(1); _Pragma("unroll") for (int m = 0; m < 4; ++m) _Pragma("unroll") for (int n = 0; n < 2; ++n) _Pragma("unroll") for (int k = 0; k < 2; ++k) \
;         acc[ai][bj][m][n] = __builtin_amdgcn_mfma_f32_16x16x32_bf16(Bt[n][k], At[m][k], acc[ai][bj][m][n], 0, 0, 0); __builtin_amdgcn_s_setprio(0); } while (0)
; #define PG8_BAR __builtin_amdgcn_s_barrier()
; template <class Epi, class Sched, bool ALIGN_EPI = false, bool SP2 = false>
; __device__ __forceinline__ void gemm_phase(PG8_LAS unsigned char* lds, int tid_in, const Gemm g, const Sched& S, const Epi& E) {
;     ...
;             PG8_LDB(B0, 0, 0); PG8_LDB(B1, 0, 1); PG8_SCHED; PG8_LDA(At, 0, 0); PG8_STAGE(PG8_SA(1, 1), a1 + hstep, voffA);
;             PG8_WAIT_V(8); PG8_WAIT_L(0); PG8_BAR; PG8_MMA(0, 0, At, B0); PG8_MMA(0, 1, At, B1); PG8_BAR; PG8_SCHED;
;             PG8_LDA(At, 0, 1); PG8_STAGE(PG8_SB(0, 0), b2, voffB); PG8_STAGE(PG8_SB(0, 1), b2 + hstep, voffB); PG8_STAGE(PG8_SA(0, 0), a2, voffA);
;             PG8_WAIT_V(8); PG8_WAIT_L(0); PG8_BAR; PG8_MMA(1, 0, At, B0); PG8_MMA(1, 1, At, B1); PG8_BAR; PG8_SCHED;
;             PG8_LDB(B0, 1, 0); PG8_LDB(B1, 1, 1); PG8_SCHED; PG8_LDA(At, 1, 0); PG8_STAGE(PG8_SA(0, 1), a2 + hstep, voffA);
;             PG8_WAIT_V(8); PG8_WAIT_L(0); PG8_BAR; PG8_MMA(0, 0, At, B0); PG8_MMA(0, 1, At, B1); PG8_BAR; PG8_SCHED;
;             PG8_LDA(At, 1, 1); PG8_STAGE(PG8_SB(1, 0), b3, voffB); PG8_STAGE(PG8_SB(1, 1), b3 + hstep, voffB); PG8_STAGE(PG8_SA(1, 0), a3, voffA);
;             PG8_WAIT_V(8); PG8_WAIT_L(0); PG8_BAR; PG8_MMA(1, 0, At, B0); PG8_MMA(1, 1, At, B1); PG8_BAR; PG8_SCHED;
	s_setprio 1
	s_waitcnt lgkmcnt(0)
	v_mfma_f32_16x16x32_bf16 v[66:69], v[106:109], v[162:165], v[66:69]
	v_mfma_f32_16x16x32_bf16 v[70:73], v[114:117], v[162:165], v[70:73]
	v_mfma_f32_16x16x32_bf16 v[74:77], v[106:109], v[170:173], v[74:77]
	v_mfma_f32_16x16x32_bf16 v[78:81], v[114:117], v[170:173], v[78:81]
	v_mfma_f32_16x16x32_bf16 v[82:85], v[106:109], v[178:181], v[82:85]
	v_mfma_f32_16x16x32_bf16 v[86:89], v[114:117], v[178:181], v[86:89]
	v_mfma_f32_16x16x32_bf16 v[66:69], v[110:113], v[166:169], v[66:69]
	v_mfma_f32_16x16x32_bf16 v[70:73], v[118:121], v[166:169], v[70:73]
	v_mfma_f32_16x16x32_bf16 v[74:77], v[110:113], v[174:177], v[74:77]
	v_mfma_f32_16x16x32_bf16 v[78:81], v[118:121], v[174:177], v[78:81]
	v_mfma_f32_16x16x32_bf16 v[82:85], v[110:113], v[182:185], v[82:85]
	v_mfma_f32_16x16x32_bf16 v[86:89], v[118:121], v[182:185], v[86:89]
	v_mfma_f32_16x16x32_bf16 v[90:93], v[106:109], v[192:195], v[90:93]
	v_mfma_f32_16x16x32_bf16 v[94:97], v[114:117], v[192:195], v[94:97]
	v_mfma_f32_16x16x32_bf16 v[90:93], v[110:113], v[196:199], v[90:93]
	v_mfma_f32_16x16x32_bf16 v[94:97], v[118:121], v[196:199], v[94:97]
	v_mfma_f32_16x16x32_bf16 v[34:37], v[154:157], v[162:165], v[34:37]
	v_mfma_f32_16x16x32_bf16 v[38:41], v[122:125], v[170:173], v[38:41]
	v_mfma_f32_16x16x32_bf16 v[42:45], v[154:157], v[170:173], v[42:45]
	v_mfma_f32_16x16x32_bf16 v[46:49], v[122:125], v[178:181], v[46:49]
	v_mfma_f32_16x16x32_bf16 v[50:53], v[154:157], v[178:181], v[50:53]
	v_mfma_f32_16x16x32_bf16 v[54:57], v[122:125], v[192:195], v[54:57]
	v_mfma_f32_16x16x32_bf16 v[58:61], v[154:157], v[192:195], v[58:61]
	v_mfma_f32_16x16x32_bf16 v[98:101], v[122:125], v[162:165], v[98:101]
	v_mfma_f32_16x16x32_bf16 v[34:37], v[158:161], v[166:169], v[34:37]
	v_mfma_f32_16x16x32_bf16 v[38:41], v[126:129], v[174:177], v[38:41]
	v_mfma_f32_16x16x32_bf16 v[42:45], v[158:161], v[174:177], v[42:45]
	v_mfma_f32_16x16x32_bf16 v[46:49], v[126:129], v[182:185], v[46:49]
	v_mfma_f32_16x16x32_bf16 v[50:53], v[158:161], v[182:185], v[50:53]
	v_mfma_f32_16x16x32_bf16 v[54:57], v[126:129], v[196:199], v[54:57]
	v_mfma_f32_16x16x32_bf16 v[58:61], v[158:161], v[196:199], v[58:61]
	v_mfma_f32_16x16x32_bf16 v[200:203], v[126:129], v[166:169], v[98:101]
	s_setprio 0
	s_barrier
	s_mov_b32 m0, s39
	v_lshl_add_u64 v[204:205], s[42:43], 0, v[8:9]
	s_add_u32 s50, s42, 0x10000
	ds_read_b128 v[98:101], v219 offset:16384
	ds_read_b128 v[162:165], v219 offset:17408
	ds_read_b128 v[166:169], v219 offset:18432
	ds_read_b128 v[170:173], v219 offset:19456
	ds_read_b128 v[174:177], v219 offset:20480
	ds_read_b128 v[178:181], v219 offset:21504
	ds_read_b128 v[182:185], v219 offset:22528
	ds_read_b128 v[192:195], v219 offset:23552
	global_load_lds_dwordx4 v[204:205], off
	v_lshl_add_u64 v[206:207], s[42:43], 0, v[186:187]
	s_mov_b32 m0, s15
	s_addc_u32 s51, s43, 0
	global_load_lds_dwordx4 v[206:207], off
	v_lshl_add_u64 v[196:197], s[50:51], 0, v[8:9]
	s_mov_b32 m0, s37
	v_lshl_add_u64 v[208:209], s[48:49], 0, v[190:191]
	global_load_lds_dwordx4 v[196:197], off
	v_lshl_add_u64 v[196:197], s[50:51], 0, v[186:187]
	s_mov_b32 m0, s38
	v_lshl_add_u64 v[244:245], s[48:49], 0, v[188:189]
	global_load_lds_dwordx4 v[196:197], off
	s_mov_b32 m0, s21
	s_nop 0
	global_load_lds_dwordx4 v[208:209], off
	s_mov_b32 m0, s28
	s_nop 0
	global_load_lds_dwordx4 v[244:245], off
	s_waitcnt vmcnt(8)
	s_waitcnt lgkmcnt(0)
	s_barrier
	s_setprio 1
	s_waitcnt lgkmcnt(0)
	v_mfma_f32_16x16x32_bf16 v[130:133], v[106:109], v[98:101], v[130:133]
	v_mfma_f32_16x16x32_bf16 v[196:199], v[110:113], v[162:165], v[130:133]
	v_mfma_f32_16x16x32_bf16 v[130:133], v[114:117], v[98:101], v[134:137]
	v_mfma_f32_16x16x32_bf16 v[210:213], v[118:121], v[162:165], v[130:133]
	v_mfma_f32_16x16x32_bf16 v[130:133], v[106:109], v[166:169], v[138:141]
	v_mfma_f32_16x16x32_bf16 v[138:141], v[110:113], v[170:173], v[130:133]
	v_mfma_f32_16x16x32_bf16 v[130:133], v[114:117], v[166:169], v[142:145]
	v_mfma_f32_16x16x32_bf16 v[142:145], v[118:121], v[170:173], v[130:133]
	v_mfma_f32_16x16x32_bf16 v[130:133], v[106:109], v[174:177], v[146:149]
	v_mfma_f32_16x16x32_bf16 v[0:3], v[106:109], v[182:185], v[0:3]
	v_mfma_f32_16x16x32_bf16 v[4:7], v[114:117], v[182:185], v[4:7]
	v_mfma_f32_16x16x32_bf16 v[146:149], v[110:113], v[178:181], v[130:133]
	v_mfma_f32_16x16x32_bf16 v[130:133], v[114:117], v[174:177], v[150:153]
	v_mfma_f32_16x16x32_bf16 v[0:3], v[110:113], v[192:195], v[0:3]
	v_mfma_f32_16x16x32_bf16 v[4:7], v[118:121], v[192:195], v[4:7]
	v_mfma_f32_16x16x32_bf16 v[150:153], v[118:121], v[178:181], v[130:133]
	v_mfma_f32_16x16x32_bf16 v[10:13], v[122:125], v[98:101], v[10:13]
	v_mfma_f32_16x16x32_bf16 v[106:109], v[126:129], v[162:165], v[10:13]
	v_mfma_f32_16x16x32_bf16 v[10:13], v[154:157], v[98:101], v[14:17]
	v_mfma_f32_16x16x32_bf16 v[110:113], v[158:161], v[162:165], v[10:13]
	v_mfma_f32_16x16x32_bf16 v[10:13], v[122:125], v[166:169], v[26:29]
	v_mfma_f32_16x16x32_bf16 v[162:165], v[126:129], v[170:173], v[10:13]
	v_mfma_f32_16x16x32_bf16 v[10:13], v[154:157], v[166:169], v[30:33]
	v_mfma_f32_16x16x32_bf16 v[166:169], v[158:161], v[170:173], v[10:13]
	v_mfma_f32_16x16x32_bf16 v[10:13], v[122:125], v[174:177], v[62:65]
	v_mfma_f32_16x16x32_bf16 v[214:217], v[126:129], v[178:181], v[10:13]
	v_mfma_f32_16x16x32_bf16 v[10:13], v[154:157], v[174:177], v[102:105]
	v_mfma_f32_16x16x32_bf16 v[220:223], v[158:161], v[178:181], v[10:13]
	v_mfma_f32_16x16x32_bf16 v[10:13], v[122:125], v[182:185], v[18:21]
	v_mfma_f32_16x16x32_bf16 v[122:125], v[126:129], v[192:195], v[10:13]
	v_mfma_f32_16x16x32_bf16 v[10:13], v[154:157], v[182:185], v[22:25]
	v_mfma_f32_16x16x32_bf16 v[126:129], v[158:161], v[192:195], v[10:13]
	s_setprio 0
	s_barrier
; #define PG8_STAGE(bufoff, gbase, voff) do { _Pragma("unroll") for (int _i = 0; _i < 2; ++_i) \
;         __builtin_amdgcn_global_load_lds((const unsigned*)((const char*)(gbase) + (voff)[_i]), (PG8_LAS unsigned*)(lds + (bufoff) + ldsw + _i * 8192), 16, 0, 0); } while (0)
; #define PG8_LDA(dst, b, h) do { _Pragma("unroll") for (int m = 0; m < 4; ++m) _Pragma("unroll") for (int k = 0; k < 2; ++k) dst[m][k] = *(const PG8_LAS bf16x8*)(lds + PG8_SA(b, h) + aoff + m * 2048 + k * 1024); } while (0)
; #define PG8_LDB(dst, b, h) do { _Pragma("unroll") for (int n = 0; n < 2; ++n) _Pragma("unroll") for (int k = 0; k < 2; ++k) dst[n][k] = *(const PG8_LAS bf16x8*)(lds + PG8_SB(b, h) + boff + n * 2048 + k * 1024); } while (0)
; #define PG8_MMA(ai, bj, At, Bt) do { __builtin_amdgcn_s_setprio(1); _Pragma("unroll") for (int m = 0; m < 4; ++m) _Pragma("unroll") for (int n = 0; n < 2; ++n) _Pragma("unroll") for (int k = 0; k < 2; ++k) \
;         acc[ai][bj][m][n] = __builtin_amdgcn_mfma_f32_16x16x32_bf16(Bt[n][k], At[m][k], acc[ai][bj][m][n], 0, 0, 0); __builtin_amdgcn_s_setprio(0); } while (0)
; template <class Epi, class Sched, bool ALIGN_EPI = false, bool SP2 = false>
; __device__ __forceinline__ void gemm_phase(PG8_LAS unsigned char* lds, int tid_in, const Gemm g, const Sched& S, const Epi& E) {
;     ...
;             PG8_LDB(B0, 0, 0); PG8_LDB(B1, 0, 1); PG8_SCHED; PG8_LDA(At, 0, 0); PG8_STAGE(PG8_SA(1, 1), a1 + hstep, voffA);
;             PG8_WAIT_V(8); PG8_WAIT_L(0); PG8_BAR; PG8_MMA(0, 0, At, B0); PG8_MMA(0, 1, At, B1); PG8_BAR; PG8_SCHED;
;             PG8_LDA(At, 0, 1); PG8_STAGE(PG8_SB(0, 0), b2, voffB); PG8_STAGE(PG8_SB(0, 1), b2 + hstep, voffB); PG8_STAGE(PG8_SA(0, 0), a2, voffA);
;             PG8_WAIT_V(8); PG8_WAIT_L(0); PG8_BAR; PG8_MMA(1, 0, At, B0); PG8_MMA(1, 1, At, B1); PG8_BAR; PG8_SCHED;
;             PG8_LDB(B0, 1, 0); PG8_LDB(B1, 1, 1); PG8_SCHED; PG8_LDA(At, 1, 0); PG8_STAGE(PG8_SA(0, 1), a2 + hstep, voffA);
;             PG8_WAIT_V(8); PG8_WAIT_L(0); PG8_BAR; PG8_MMA(0, 0, At, B0); PG8_MMA(0, 1, At, B1); PG8_BAR; PG8_SCHED;
;             PG8_LDA(At, 1, 1); PG8_STAGE(PG8_SB(1, 0), b3, voffB); PG8_STAGE(PG8_SB(1, 1), b3 + hstep, voffB); PG8_STAGE(PG8_SA(1, 0), a3, voffA);
;             PG8_WAIT_V(8); PG8_WAIT_L(0); PG8_BAR; PG8_MMA(1, 0, At, B0); PG8_MMA(1, 1, At, B1); PG8_BAR; PG8_SCHED;
;     ...
;         if constexpr (ALIGN_EPI) { if (wr == 0) PG8_BAR; }
	s_nop 4
	ds_read_b128 v[10:13], v224
	ds_read_b128 v[14:17], v224 offset:1024
	ds_read_b128 v[18:21], v224 offset:2048
	ds_read_b128 v[22:25], v224 offset:3072
	ds_read_b128 v[154:157], v225
	ds_read_b128 v[158:161], v225 offset:1024
	ds_read_b128 v[192:195], v225 offset:2048
	ds_read_b128 v[224:227], v225 offset:3072
	s_add_u32 s38, s48, 0x10000
	s_addc_u32 s39, s49, 0
	s_mov_b32 m0, s29
	v_lshl_add_u64 v[98:99], s[38:39], 0, v[190:191]
	ds_read_b128 v[26:29], v219 offset:32768
	ds_read_b128 v[30:33], v219 offset:33792
	ds_read_b128 v[62:65], v219 offset:34816
	ds_read_b128 v[114:117], v219 offset:35840
	ds_read_b128 v[228:231], v219 offset:36864
	ds_read_b128 v[232:235], v219 offset:37888
	ds_read_b128 v[236:239], v219 offset:38912
	ds_read_b128 v[240:243], v219 offset:39936
	global_load_lds_dwordx4 v[98:99], off
	v_lshl_add_u64 v[98:99], s[38:39], 0, v[188:189]
	s_mov_b32 m0, s33
	s_nop 0
	global_load_lds_dwordx4 v[98:99], off
	s_waitcnt vmcnt(8)
	s_waitcnt lgkmcnt(0)
	s_barrier
	s_setprio 1
	s_waitcnt lgkmcnt(0)
	v_mfma_f32_16x16x32_bf16 v[66:69], v[10:13], v[26:29], v[66:69]
	v_mfma_f32_16x16x32_bf16 v[182:185], v[14:17], v[30:33], v[66:69]
	v_mfma_f32_16x16x32_bf16 v[66:69], v[18:21], v[26:29], v[70:73]
	v_mfma_f32_16x16x32_bf16 v[178:181], v[22:25], v[30:33], v[66:69]
	v_mfma_f32_16x16x32_bf16 v[66:69], v[10:13], v[62:65], v[74:77]
	v_mfma_f32_16x16x32_bf16 v[134:137], v[14:17], v[114:117], v[66:69]
	v_mfma_f32_16x16x32_bf16 v[66:69], v[18:21], v[62:65], v[78:81]
	v_mfma_f32_16x16x32_bf16 v[130:133], v[22:25], v[114:117], v[66:69]
	v_mfma_f32_16x16x32_bf16 v[66:69], v[10:13], v[228:231], v[82:85]
	v_mfma_f32_16x16x32_bf16 v[102:105], v[14:17], v[232:235], v[66:69]
	v_mfma_f32_16x16x32_bf16 v[66:69], v[18:21], v[228:231], v[86:89]
	v_mfma_f32_16x16x32_bf16 v[98:101], v[22:25], v[232:235], v[66:69]
	v_mfma_f32_16x16x32_bf16 v[66:69], v[10:13], v[236:239], v[90:93]
	v_mfma_f32_16x16x32_bf16 v[78:81], v[14:17], v[240:243], v[66:69]
	v_mfma_f32_16x16x32_bf16 v[66:69], v[18:21], v[236:239], v[94:97]
	v_mfma_f32_16x16x32_bf16 v[74:77], v[22:25], v[240:243], v[66:69]
	v_mfma_f32_16x16x32_bf16 v[66:69], v[154:157], v[26:29], v[200:203]
	v_mfma_f32_16x16x32_bf16 v[26:29], v[192:195], v[26:29], v[34:37]
	v_mfma_f32_16x16x32_bf16 v[170:173], v[224:227], v[30:33], v[26:29]
	v_mfma_f32_16x16x32_bf16 v[26:29], v[154:157], v[62:65], v[38:41]
	v_mfma_f32_16x16x32_bf16 v[118:121], v[158:161], v[114:117], v[26:29]
	v_mfma_f32_16x16x32_bf16 v[26:29], v[192:195], v[62:65], v[42:45]
	v_mfma_f32_16x16x32_bf16 v[114:117], v[224:227], v[114:117], v[26:29]
	v_mfma_f32_16x16x32_bf16 v[26:29], v[154:157], v[228:231], v[46:49]
	v_mfma_f32_16x16x32_bf16 v[86:89], v[158:161], v[232:235], v[26:29]
	v_mfma_f32_16x16x32_bf16 v[26:29], v[192:195], v[228:231], v[50:53]
	v_mfma_f32_16x16x32_bf16 v[82:85], v[224:227], v[232:235], v[26:29]
	v_mfma_f32_16x16x32_bf16 v[26:29], v[154:157], v[236:239], v[54:57]
	v_mfma_f32_16x16x32_bf16 v[70:73], v[158:161], v[240:243], v[26:29]
	v_mfma_f32_16x16x32_bf16 v[26:29], v[192:195], v[236:239], v[58:61]
	v_mfma_f32_16x16x32_bf16 v[174:177], v[158:161], v[30:33], v[66:69]
	v_mfma_f32_16x16x32_bf16 v[66:69], v[224:227], v[240:243], v[26:29]
	s_setprio 0
	s_barrier
	s_mov_b32 m0, s55
	s_nop 2
	v_lshl_add_u64 v[26:27], v[204:205], 0, s[24:25]
	s_add_u32 s38, s42, 0x10080
	ds_read_b128 v[34:37], v219 offset:49152
	ds_read_b128 v[38:41], v219 offset:50176
	ds_read_b128 v[90:93], v219 offset:51200
	ds_read_b128 v[94:97], v219 offset:52224
	ds_read_b128 v[200:203], v219 offset:53248
	ds_read_b128 v[228:231], v219 offset:54272
	ds_read_b128 v[232:235], v219 offset:55296
	ds_read_b128 v[236:239], v219 offset:56320
	global_load_lds_dwordx4 v[26:27], off
	v_lshl_add_u64 v[26:27], v[206:207], 0, s[24:25]
	s_mov_b32 m0, s47
	s_addc_u32 s39, s43, 0
	global_load_lds_dwordx4 v[26:27], off
	v_lshl_add_u64 v[26:27], s[38:39], 0, v[8:9]
	s_mov_b32 m0, s34
	s_nop 0
	global_load_lds_dwordx4 v[26:27], off
	v_lshl_add_u64 v[26:27], s[38:39], 0, v[186:187]
	s_mov_b32 m0, s35
	s_nop 0
	global_load_lds_dwordx4 v[26:27], off
	v_lshl_add_u64 v[26:27], v[208:209], 0, s[24:25]
	s_mov_b32 m0, s45
	s_nop 0
	global_load_lds_dwordx4 v[26:27], off
	v_lshl_add_u64 v[26:27], v[244:245], 0, s[24:25]
	s_mov_b32 m0, s46
	s_nop 0
	global_load_lds_dwordx4 v[26:27], off
	s_waitcnt vmcnt(8)
	s_waitcnt lgkmcnt(0)
	s_barrier
	s_setprio 1
	s_waitcnt lgkmcnt(0)
	v_mfma_f32_16x16x32_bf16 v[26:29], v[10:13], v[34:37], v[196:199]
	v_mfma_f32_16x16x32_bf16 v[62:65], v[14:17], v[38:41], v[26:29]
	v_mfma_f32_16x16x32_bf16 v[26:29], v[18:21], v[34:37], v[210:213]
	v_mfma_f32_16x16x32_bf16 v[58:61], v[22:25], v[38:41], v[26:29]
	v_mfma_f32_16x16x32_bf16 v[26:29], v[10:13], v[90:93], v[138:141]
	v_mfma_f32_16x16x32_bf16 v[46:49], v[14:17], v[94:97], v[26:29]
	v_mfma_f32_16x16x32_bf16 v[26:29], v[18:21], v[90:93], v[142:145]
	v_mfma_f32_16x16x32_bf16 v[42:45], v[22:25], v[94:97], v[26:29]
	v_mfma_f32_16x16x32_bf16 v[26:29], v[10:13], v[200:203], v[146:149]
	v_mfma_f32_16x16x32_bf16 v[0:3], v[10:13], v[232:235], v[0:3]
	v_mfma_f32_16x16x32_bf16 v[30:33], v[14:17], v[228:231], v[26:29]
	v_mfma_f32_16x16x32_bf16 v[26:29], v[18:21], v[200:203], v[150:153]
	v_mfma_f32_16x16x32_bf16 v[14:17], v[14:17], v[236:239], v[0:3]
	v_mfma_f32_16x16x32_bf16 v[0:3], v[18:21], v[232:235], v[4:7]
	v_mfma_f32_16x16x32_bf16 v[26:29], v[22:25], v[228:231], v[26:29]
	v_mfma_f32_16x16x32_bf16 v[10:13], v[22:25], v[236:239], v[0:3]
	v_mfma_f32_16x16x32_bf16 v[0:3], v[154:157], v[34:37], v[106:109]
	v_mfma_f32_16x16x32_bf16 v[54:57], v[158:161], v[38:41], v[0:3]
	v_mfma_f32_16x16x32_bf16 v[0:3], v[192:195], v[34:37], v[110:113]
	v_mfma_f32_16x16x32_bf16 v[50:53], v[224:227], v[38:41], v[0:3]
	v_mfma_f32_16x16x32_bf16 v[0:3], v[154:157], v[90:93], v[162:165]
	v_mfma_f32_16x16x32_bf16 v[38:41], v[158:161], v[94:97], v[0:3]
	v_mfma_f32_16x16x32_bf16 v[0:3], v[192:195], v[90:93], v[166:169]
	v_mfma_f32_16x16x32_bf16 v[34:37], v[224:227], v[94:97], v[0:3]
	v_mfma_f32_16x16x32_bf16 v[0:3], v[154:157], v[200:203], v[214:217]
	v_mfma_f32_16x16x32_bf16 v[22:25], v[158:161], v[228:231], v[0:3]
	v_mfma_f32_16x16x32_bf16 v[0:3], v[192:195], v[200:203], v[220:223]
	v_mfma_f32_16x16x32_bf16 v[18:21], v[224:227], v[228:231], v[0:3]
	v_mfma_f32_16x16x32_bf16 v[0:3], v[154:157], v[232:235], v[122:125]
	v_mfma_f32_16x16x32_bf16 v[4:7], v[158:161], v[236:239], v[0:3]
	v_mfma_f32_16x16x32_bf16 v[0:3], v[192:195], v[232:235], v[126:129]
	v_mfma_f32_16x16x32_bf16 v[0:3], v[224:227], v[236:239], v[0:3]
	s_setprio 0
	s_barrier
	s_andn2_b64 vcc, exec, s[8:9]
	s_cbranch_vccnz .LBB0_631
	s_barrier

; #define PG8_STAGE(bufoff, gbase, voff) do { _Pragma("unroll") for (int _i = 0; _i < 2; ++_i) \
;         __builtin_amdgcn_global_load_lds((const unsigned*)((const char*)(gbase) + (voff)[_i]), (PG8_LAS unsigned*)(lds + (bufoff) + ldsw + _i * 8192), 16, 0, 0); } while (0)
; #define PG8_LDA(dst, b, h) do { _Pragma("unroll") for (int m = 0; m < 4; ++m) _Pragma("unroll") for (int k = 0; k < 2; ++k) dst[m][k] = *(const PG8_LAS bf16x8*)(lds + PG8_SA(b, h) + aoff + m * 2048 + k * 1024); } while (0)
; #define PG8_LDB(dst, b, h) do { _Pragma("unroll") for (int n = 0; n < 2; ++n) _Pragma("unroll") for (int k = 0; k < 2; ++k) dst[n][k] = *(const PG8_LAS bf16x8*)(lds + PG8_SB(b, h) + boff + n * 2048 + k * 1024); } while (0)
; #define PG8_MMA(ai, bj, At, Bt) do { __builtin_amdgcn_s_setprio(1); _Pragma("unroll") for (int m = 0; m < 4; ++m) _Pragma("unroll") for (int n = 0; n < 2; ++n) _Pragma("unroll") for (int k = 0; k < 2; ++k) \
;         acc[ai][bj][m][n] = __builtin_amdgcn_mfma_f32_16x16x32_bf16(Bt[n][k], At[m][k], acc[ai][bj][m][n], 0, 0, 0); __builtin_amdgcn_s_setprio(0); } while (0)
; #define PG8_WAIT_V(n) asm volatile("s_waitcnt vmcnt(" #n ")" ::: "memory")
; #define PG8_WAIT_L(n) asm volatile("s_waitcnt lgkmcnt(" #n ")" ::: "memory")
; #define PG8_BAR __builtin_amdgcn_s_barrier()
; #define PG8_SCHED __builtin_amdgcn_sched_barrier(0)
; template <class Epi, class Sched, bool ALIGN_EPI = false, bool SP2 = false>
; __device__ __forceinline__ void gemm_phase(PG8_LAS unsigned char* lds, int tid_in, const Gemm g, const Sched& S, const Epi& E) {
;     ...
;             const char* a2 = last ? nA : cA + (size_t)(t + 2) * kstep; const char* b2 = last ? nB : cB + (size_t)(t + 2) * kstep;
;     ...
;             PG8_LDB(B0, 0, 0); PG8_LDB(B1, 0, 1); PG8_SCHED; PG8_LDA(At, 0, 0); PG8_STAGE(PG8_SA(1, 1), a1 + hstep, voffA);
;             PG8_WAIT_V(8); PG8_WAIT_L(0); PG8_BAR; PG8_MMA(0, 0, At, B0); PG8_MMA(0, 1, At, B1); PG8_BAR; PG8_SCHED;
;             PG8_LDA(At, 0, 1); PG8_STAGE(PG8_SB(0, 0), b2, voffB); PG8_STAGE(PG8_SB(0, 1), b2 + hstep, voffB); PG8_STAGE(PG8_SA(0, 0), a2, voffA);
;             PG8_WAIT_V(8); PG8_WAIT_L(0); PG8_BAR; PG8_MMA(1, 0, At, B0); PG8_MMA(1, 1, At, B1); PG8_BAR; PG8_SCHED;
.LBB0_708:
	s_add_u32 s18, s48, 0xfffc0080
	s_addc_u32 s50, s49, -1
	s_add_i32 s64, 0, 0x10000
	s_cmp_eq_u32 s37, 12
	s_cselect_b32 s59, s17, s50
	s_cselect_b32 s58, s96, s18
	s_cselect_b32 s51, s15, s36
	s_cselect_b32 s50, s38, s39
	s_add_i32 s18, 0, 0x14000
	v_add_u32_e32 v134, s64, v228
	v_add_u32_e32 v158, s18, v228
	ds_read_b128 v[122:125], v134
	ds_read_b128 v[126:129], v134 offset:1024
	ds_read_b128 v[130:133], v134 offset:2048
	ds_read_b128 v[134:137], v134 offset:3072
	ds_read_b128 v[146:149], v158
	ds_read_b128 v[150:153], v158 offset:1024
	ds_read_b128 v[154:157], v158 offset:2048
	ds_read_b128 v[158:161], v158 offset:3072
	v_lshl_add_u64 v[204:205], s[48:49], 0, v[196:197]
	s_add_i32 m0, s21, 0xc000
	ds_read_b128 v[162:165], v229
	ds_read_b128 v[166:169], v229 offset:1024
	ds_read_b128 v[170:173], v229 offset:2048
	ds_read_b128 v[174:177], v229 offset:3072
	ds_read_b128 v[178:181], v229 offset:4096
	ds_read_b128 v[182:185], v229 offset:5120
	ds_read_b128 v[186:189], v229 offset:6144
	ds_read_b128 v[200:203], v229 offset:7168
	global_load_lds_dwordx4 v[204:205], off
	v_lshl_add_u64 v[204:205], s[48:49], 0, v[198:199]
	s_add_i32 m0, s21, 0xe000
	s_nop 0
	global_load_lds_dwordx4 v[204:205], off
	s_waitcnt vmcnt(8)
	s_waitcnt lgkmcnt(0)
	s_barrier
	s_setprio 1
	s_waitcnt lgkmcnt(0)
	v_mfma_f32_16x16x32_bf16 v[142:145], v[122:125], v[162:165], v[142:145]
	v_mfma_f32_16x16x32_bf16 v[138:141], v[130:133], v[162:165], v[138:141]
	v_mfma_f32_16x16x32_bf16 v[110:113], v[122:125], v[170:173], v[110:113]
	v_mfma_f32_16x16x32_bf16 v[106:109], v[130:133], v[170:173], v[106:109]
	v_mfma_f32_16x16x32_bf16 v[94:97], v[122:125], v[178:181], v[94:97]
	v_mfma_f32_16x16x32_bf16 v[90:93], v[130:133], v[178:181], v[90:93]
	v_mfma_f32_16x16x32_bf16 v[78:81], v[122:125], v[186:189], v[78:81]
	v_mfma_f32_16x16x32_bf16 v[74:77], v[130:133], v[186:189], v[74:77]
	v_mfma_f32_16x16x32_bf16 v[142:145], v[126:129], v[166:169], v[142:145]
	v_mfma_f32_16x16x32_bf16 v[138:141], v[134:137], v[166:169], v[138:141]
	v_mfma_f32_16x16x32_bf16 v[110:113], v[126:129], v[174:177], v[110:113]
	v_mfma_f32_16x16x32_bf16 v[106:109], v[134:137], v[174:177], v[106:109]
	v_mfma_f32_16x16x32_bf16 v[94:97], v[126:129], v[182:185], v[94:97]
	v_mfma_f32_16x16x32_bf16 v[90:93], v[134:137], v[182:185], v[90:93]
	v_mfma_f32_16x16x32_bf16 v[78:81], v[126:129], v[200:203], v[78:81]
	v_mfma_f32_16x16x32_bf16 v[74:77], v[134:137], v[200:203], v[74:77]
	v_mfma_f32_16x16x32_bf16 v[118:121], v[146:149], v[162:165], v[118:121]
	v_mfma_f32_16x16x32_bf16 v[114:117], v[154:157], v[162:165], v[114:117]
	v_mfma_f32_16x16x32_bf16 v[102:105], v[146:149], v[170:173], v[102:105]
	v_mfma_f32_16x16x32_bf16 v[98:101], v[154:157], v[170:173], v[98:101]
	v_mfma_f32_16x16x32_bf16 v[86:89], v[146:149], v[178:181], v[86:89]
	v_mfma_f32_16x16x32_bf16 v[82:85], v[154:157], v[178:181], v[82:85]
	v_mfma_f32_16x16x32_bf16 v[70:73], v[146:149], v[186:189], v[70:73]
	v_mfma_f32_16x16x32_bf16 v[66:69], v[154:157], v[186:189], v[66:69]
	v_mfma_f32_16x16x32_bf16 v[118:121], v[150:153], v[166:169], v[118:121]
	v_mfma_f32_16x16x32_bf16 v[114:117], v[158:161], v[166:169], v[114:117]
	v_mfma_f32_16x16x32_bf16 v[102:105], v[150:153], v[174:177], v[102:105]
	v_mfma_f32_16x16x32_bf16 v[98:101], v[158:161], v[174:177], v[98:101]
	v_mfma_f32_16x16x32_bf16 v[86:89], v[150:153], v[182:185], v[86:89]
	v_mfma_f32_16x16x32_bf16 v[82:85], v[158:161], v[182:185], v[82:85]
	v_mfma_f32_16x16x32_bf16 v[70:73], v[150:153], v[200:203], v[70:73]
	v_mfma_f32_16x16x32_bf16 v[66:69], v[158:161], v[200:203], v[66:69]
	s_setprio 0
	s_barrier
	s_add_i32 s64, s64, s20
	v_lshl_add_u64 v[204:205], s[50:51], 0, v[8:9]
	s_mov_b32 m0, s64
	ds_read_b128 v[162:165], v229 offset:16384
	ds_read_b128 v[166:169], v229 offset:17408
	ds_read_b128 v[170:173], v229 offset:18432
	ds_read_b128 v[174:177], v229 offset:19456
	ds_read_b128 v[178:181], v229 offset:20480
	ds_read_b128 v[182:185], v229 offset:21504
	ds_read_b128 v[186:189], v229 offset:22528
	ds_read_b128 v[200:203], v229 offset:23552
	global_load_lds_dwordx4 v[204:205], off
	s_add_i32 m0, s64, 0x2000
	s_add_u32 vcc_lo, s50, 0x40000
	v_lshl_add_u64 v[206:207], s[50:51], 0, v[194:195]
	s_addc_u32 vcc_hi, s51, 0
	s_add_i32 s18, s18, s20
	global_load_lds_dwordx4 v[206:207], off
	v_lshl_add_u64 v[208:209], vcc, 0, v[8:9]
	s_mov_b32 m0, s18
	v_lshl_add_u64 v[210:211], s[58:59], 0, v[192:193]
	global_load_lds_dwordx4 v[208:209], off
	v_lshl_add_u64 v[208:209], vcc, 0, v[194:195]
	s_add_i32 m0, s18, 0x2000
	s_nop 0
	global_load_lds_dwordx4 v[208:209], off
	v_lshl_add_u64 v[208:209], s[58:59], 0, v[190:191]
	s_mov_b32 m0, s21
	s_nop 0
	global_load_lds_dwordx4 v[208:209], off
	s_mov_b32 m0, s28
	s_nop 0
	global_load_lds_dwordx4 v[210:211], off
	s_waitcnt vmcnt(8)
	s_waitcnt lgkmcnt(0)
	s_barrier
; #define PG8_STAGE(bufoff, gbase, voff) do { _Pragma("unroll") for (int _i = 0; _i < 2; ++_i) \
;         __builtin_amdgcn_global_load_lds((const unsigned*)((const char*)(gbase) + (voff)[_i]), (PG8_LAS unsigned*)(lds + (bufoff) + ldsw + _i * 8192), 16, 0, 0); } while (0)
; #define PG8_LDA(dst, b, h) do { _Pragma("unroll") for (int m = 0; m < 4; ++m) _Pragma("unroll") for (int k = 0; k < 2; ++k) dst[m][k] = *(const PG8_LAS bf16x8*)(lds + PG8_SA(b, h) + aoff + m * 2048 + k * 1024); } while (0)
; #define PG8_LDB(dst, b, h) do { _Pragma("unroll") for (int n = 0; n < 2; ++n) _Pragma("unroll") for (int k = 0; k < 2; ++k) dst[n][k] = *(const PG8_LAS bf16x8*)(lds + PG8_SB(b, h) + boff + n * 2048 + k * 1024); } while (0)
; #define PG8_MMA(ai, bj, At, Bt) do { __builtin_amdgcn_s_setprio(1); _Pragma("unroll") for (int m = 0; m < 4; ++m) _Pragma("unroll") for (int n = 0; n < 2; ++n) _Pragma("unroll") for (int k = 0; k < 2; ++k) \
;         acc[ai][bj][m][n] = __builtin_amdgcn_mfma_f32_16x16x32_bf16(Bt[n][k], At[m][k], acc[ai][bj][m][n], 0, 0, 0); __builtin_amdgcn_s_setprio(0); } while (0)
; #define PG8_WAIT_V(n) asm volatile("s_waitcnt vmcnt(" #n ")" ::: "memory")
; #define PG8_WAIT_L(n) asm volatile("s_waitcnt lgkmcnt(" #n ")" ::: "memory")
; #define PG8_BAR __builtin_amdgcn_s_barrier()
; #define PG8_SCHED __builtin_amdgcn_sched_barrier(0)
; template <class Epi, class Sched, bool ALIGN_EPI = false, bool SP2 = false>
; __device__ __forceinline__ void gemm_phase(PG8_LAS unsigned char* lds, int tid_in, const Gemm g, const Sched& S, const Epi& E) {
;     ...
;             PG8_WAIT_V(8); PG8_WAIT_L(0); PG8_BAR; PG8_MMA(1, 0, At, B0); PG8_MMA(1, 1, At, B1); PG8_BAR; PG8_SCHED;
;             PG8_LDB(B0, 1, 0); PG8_LDB(B1, 1, 1); PG8_SCHED; PG8_LDA(At, 1, 0); PG8_STAGE(PG8_SA(0, 1), a2 + hstep, voffA);
;             PG8_WAIT_V(8); PG8_WAIT_L(0); PG8_BAR; PG8_MMA(0, 0, At, B0); PG8_MMA(0, 1, At, B1); PG8_BAR; PG8_SCHED;
	s_setprio 1
	s_waitcnt lgkmcnt(0)
	v_mfma_f32_16x16x32_bf16 v[62:65], v[122:125], v[162:165], v[62:65]
	v_mfma_f32_16x16x32_bf16 v[58:61], v[130:133], v[162:165], v[58:61]
	v_mfma_f32_16x16x32_bf16 v[46:49], v[122:125], v[170:173], v[46:49]
	v_mfma_f32_16x16x32_bf16 v[42:45], v[130:133], v[170:173], v[42:45]
	v_mfma_f32_16x16x32_bf16 v[30:33], v[122:125], v[178:181], v[30:33]
	v_mfma_f32_16x16x32_bf16 v[26:29], v[130:133], v[178:181], v[26:29]
	v_mfma_f32_16x16x32_bf16 v[14:17], v[122:125], v[186:189], v[14:17]
	v_mfma_f32_16x16x32_bf16 v[10:13], v[130:133], v[186:189], v[10:13]
	v_mfma_f32_16x16x32_bf16 v[62:65], v[126:129], v[166:169], v[62:65]
	v_mfma_f32_16x16x32_bf16 v[58:61], v[134:137], v[166:169], v[58:61]
	v_mfma_f32_16x16x32_bf16 v[46:49], v[126:129], v[174:177], v[46:49]
	v_mfma_f32_16x16x32_bf16 v[42:45], v[134:137], v[174:177], v[42:45]
	v_mfma_f32_16x16x32_bf16 v[30:33], v[126:129], v[182:185], v[30:33]
	v_mfma_f32_16x16x32_bf16 v[26:29], v[134:137], v[182:185], v[26:29]
	v_mfma_f32_16x16x32_bf16 v[14:17], v[126:129], v[200:203], v[14:17]
	v_mfma_f32_16x16x32_bf16 v[10:13], v[134:137], v[200:203], v[10:13]
	v_mfma_f32_16x16x32_bf16 v[54:57], v[146:149], v[162:165], v[54:57]
	v_mfma_f32_16x16x32_bf16 v[50:53], v[154:157], v[162:165], v[50:53]
	v_mfma_f32_16x16x32_bf16 v[38:41], v[146:149], v[170:173], v[38:41]
	v_mfma_f32_16x16x32_bf16 v[34:37], v[154:157], v[170:173], v[34:37]
	v_mfma_f32_16x16x32_bf16 v[22:25], v[146:149], v[178:181], v[22:25]
	v_mfma_f32_16x16x32_bf16 v[18:21], v[154:157], v[178:181], v[18:21]
	v_mfma_f32_16x16x32_bf16 v[4:7], v[146:149], v[186:189], v[4:7]
	v_mfma_f32_16x16x32_bf16 v[0:3], v[154:157], v[186:189], v[0:3]
	v_mfma_f32_16x16x32_bf16 v[54:57], v[150:153], v[166:169], v[54:57]
	v_mfma_f32_16x16x32_bf16 v[50:53], v[158:161], v[166:169], v[50:53]
	v_mfma_f32_16x16x32_bf16 v[38:41], v[150:153], v[174:177], v[38:41]
	v_mfma_f32_16x16x32_bf16 v[34:37], v[158:161], v[174:177], v[34:37]
	v_mfma_f32_16x16x32_bf16 v[22:25], v[150:153], v[182:185], v[22:25]
	v_mfma_f32_16x16x32_bf16 v[18:21], v[158:161], v[182:185], v[18:21]
	v_mfma_f32_16x16x32_bf16 v[4:7], v[150:153], v[200:203], v[4:7]
	v_mfma_f32_16x16x32_bf16 v[0:3], v[158:161], v[200:203], v[0:3]
	s_setprio 0
	s_barrier
	s_add_i32 s18, 0, 0x18000
	s_add_i32 s64, 0, 0x1c000
	v_add_u32_e32 v134, s18, v228
	v_add_u32_e32 v158, s64, v228
	ds_read_b128 v[122:125], v134
	ds_read_b128 v[126:129], v134 offset:1024
	ds_read_b128 v[130:133], v134 offset:2048
	ds_read_b128 v[134:137], v134 offset:3072
	ds_read_b128 v[146:149], v158
	ds_read_b128 v[150:153], v158 offset:1024
	ds_read_b128 v[154:157], v158 offset:2048
	ds_read_b128 v[158:161], v158 offset:3072
	s_add_u32 s58, s58, 0x40000
	s_addc_u32 s59, s59, 0
	s_mov_b32 m0, s29
	v_lshl_add_u64 v[212:213], s[58:59], 0, v[190:191]
	ds_read_b128 v[162:165], v229 offset:32768
	ds_read_b128 v[166:169], v229 offset:33792
	ds_read_b128 v[170:173], v229 offset:34816
	ds_read_b128 v[174:177], v229 offset:35840
	ds_read_b128 v[178:181], v229 offset:36864
	ds_read_b128 v[182:185], v229 offset:37888
	ds_read_b128 v[186:189], v229 offset:38912
	ds_read_b128 v[200:203], v229 offset:39936
	global_load_lds_dwordx4 v[212:213], off
	v_lshl_add_u64 v[212:213], s[58:59], 0, v[192:193]
	s_mov_b32 m0, s55
	s_nop 0
	global_load_lds_dwordx4 v[212:213], off
	s_waitcnt vmcnt(8)
	s_waitcnt lgkmcnt(0)
	s_barrier
	s_setprio 1
	s_waitcnt lgkmcnt(0)
	v_mfma_f32_16x16x32_bf16 v[142:145], v[122:125], v[162:165], v[142:145]
	v_mfma_f32_16x16x32_bf16 v[138:141], v[130:133], v[162:165], v[138:141]
	v_mfma_f32_16x16x32_bf16 v[110:113], v[122:125], v[170:173], v[110:113]
	v_mfma_f32_16x16x32_bf16 v[106:109], v[130:133], v[170:173], v[106:109]
	v_mfma_f32_16x16x32_bf16 v[94:97], v[122:125], v[178:181], v[94:97]
	v_mfma_f32_16x16x32_bf16 v[90:93], v[130:133], v[178:181], v[90:93]
	v_mfma_f32_16x16x32_bf16 v[78:81], v[122:125], v[186:189], v[78:81]
	v_mfma_f32_16x16x32_bf16 v[74:77], v[130:133], v[186:189], v[74:77]
	v_mfma_f32_16x16x32_bf16 v[142:145], v[126:129], v[166:169], v[142:145]
	v_mfma_f32_16x16x32_bf16 v[138:141], v[134:137], v[166:169], v[138:141]
	v_mfma_f32_16x16x32_bf16 v[110:113], v[126:129], v[174:177], v[110:113]
	v_mfma_f32_16x16x32_bf16 v[106:109], v[134:137], v[174:177], v[106:109]
	v_mfma_f32_16x16x32_bf16 v[94:97], v[126:129], v[182:185], v[94:97]
	v_mfma_f32_16x16x32_bf16 v[90:93], v[134:137], v[182:185], v[90:93]
	v_mfma_f32_16x16x32_bf16 v[78:81], v[126:129], v[200:203], v[78:81]
	v_mfma_f32_16x16x32_bf16 v[74:77], v[134:137], v[200:203], v[74:77]
	v_mfma_f32_16x16x32_bf16 v[118:121], v[146:149], v[162:165], v[118:121]
	v_mfma_f32_16x16x32_bf16 v[114:117], v[154:157], v[162:165], v[114:117]
	v_mfma_f32_16x16x32_bf16 v[102:105], v[146:149], v[170:173], v[102:105]
	v_mfma_f32_16x16x32_bf16 v[98:101], v[154:157], v[170:173], v[98:101]
	v_mfma_f32_16x16x32_bf16 v[86:89], v[146:149], v[178:181], v[86:89]
	v_mfma_f32_16x16x32_bf16 v[82:85], v[154:157], v[178:181], v[82:85]
	v_mfma_f32_16x16x32_bf16 v[70:73], v[146:149], v[186:189], v[70:73]
	v_mfma_f32_16x16x32_bf16 v[66:69], v[154:157], v[186:189], v[66:69]
	v_mfma_f32_16x16x32_bf16 v[118:121], v[150:153], v[166:169], v[118:121]
	v_mfma_f32_16x16x32_bf16 v[114:117], v[158:161], v[166:169], v[114:117]
	v_mfma_f32_16x16x32_bf16 v[102:105], v[150:153], v[174:177], v[102:105]
	v_mfma_f32_16x16x32_bf16 v[98:101], v[158:161], v[174:177], v[98:101]
	v_mfma_f32_16x16x32_bf16 v[86:89], v[150:153], v[182:185], v[86:89]
	v_mfma_f32_16x16x32_bf16 v[82:85], v[158:161], v[182:185], v[82:85]
	v_mfma_f32_16x16x32_bf16 v[70:73], v[150:153], v[200:203], v[70:73]
	v_mfma_f32_16x16x32_bf16 v[66:69], v[158:161], v[200:203], v[66:69]
	s_setprio 0
	s_barrier
; #define PG8_STAGE(bufoff, gbase, voff) do { _Pragma("unroll") for (int _i = 0; _i < 2; ++_i) \
;         __builtin_amdgcn_global_load_lds((const unsigned*)((const char*)(gbase) + (voff)[_i]), (PG8_LAS unsigned*)(lds + (bufoff) + ldsw + _i * 8192), 16, 0, 0); } while (0)
; #define PG8_LDA(dst, b, h) do { _Pragma("unroll") for (int m = 0; m < 4; ++m) _Pragma("unroll") for (int k = 0; k < 2; ++k) dst[m][k] = *(const PG8_LAS bf16x8*)(lds + PG8_SA(b, h) + aoff + m * 2048 + k * 1024); } while (0)
; #define PG8_MMA(ai, bj, At, Bt) do { __builtin_amdgcn_s_setprio(1); _Pragma("unroll") for (int m = 0; m < 4; ++m) _Pragma("unroll") for (int n = 0; n < 2; ++n) _Pragma("unroll") for (int k = 0; k < 2; ++k) \
;         acc[ai][bj][m][n] = __builtin_amdgcn_mfma_f32_16x16x32_bf16(Bt[n][k], At[m][k], acc[ai][bj][m][n], 0, 0, 0); __builtin_amdgcn_s_setprio(0); } while (0)
; #define PG8_WAIT_V(n) asm volatile("s_waitcnt vmcnt(" #n ")" ::: "memory")
; #define PG8_WAIT_L(n) asm volatile("s_waitcnt lgkmcnt(" #n ")" ::: "memory")
; #define PG8_BAR __builtin_amdgcn_s_barrier()
; #define PG8_SCHED __builtin_amdgcn_sched_barrier(0)
; template <class Epi, class Sched, bool ALIGN_EPI = false, bool SP2 = false>
; __device__ __forceinline__ void gemm_phase(PG8_LAS unsigned char* lds, int tid_in, const Gemm g, const Sched& S, const Epi& E) {
;     ...
;         for (int t = 0; t < nt; t += 2) {
;     ...
;             PG8_LDA(At, 1, 1); PG8_STAGE(PG8_SB(1, 0), b3, voffB); PG8_STAGE(PG8_SB(1, 1), b3 + hstep, voffB); PG8_STAGE(PG8_SA(1, 0), a3, voffA);
;             PG8_WAIT_V(8); PG8_WAIT_L(0); PG8_BAR; PG8_MMA(1, 0, At, B0); PG8_MMA(1, 1, At, B1); PG8_BAR; PG8_SCHED;
;     ...
;         if constexpr (ALIGN_EPI) { if (wr == 0) PG8_BAR; }
	s_add_i32 s18, s18, s20
	v_lshl_add_u64 v[204:205], v[204:205], 0, s[24:25]
	s_mov_b32 m0, s18
	ds_read_b128 v[162:165], v229 offset:49152
	ds_read_b128 v[166:169], v229 offset:50176
	ds_read_b128 v[170:173], v229 offset:51200
	ds_read_b128 v[174:177], v229 offset:52224
	ds_read_b128 v[178:181], v229 offset:53248
	ds_read_b128 v[182:185], v229 offset:54272
	ds_read_b128 v[186:189], v229 offset:55296
	ds_read_b128 v[200:203], v229 offset:56320
	global_load_lds_dwordx4 v[204:205], off
	s_add_i32 m0, s18, 0x2000
	s_add_u32 s50, s50, 0x40080
	v_lshl_add_u64 v[204:205], v[206:207], 0, s[24:25]
	s_addc_u32 s51, s51, 0
	s_add_i32 s18, s64, s20
	global_load_lds_dwordx4 v[204:205], off
	v_lshl_add_u64 v[204:205], s[50:51], 0, v[8:9]
	s_mov_b32 m0, s18
	s_nop 0
	global_load_lds_dwordx4 v[204:205], off
	v_lshl_add_u64 v[204:205], s[50:51], 0, v[194:195]
	s_add_i32 m0, s18, 0x2000
	s_nop 0
	global_load_lds_dwordx4 v[204:205], off
	v_lshl_add_u64 v[204:205], v[208:209], 0, s[24:25]
	s_mov_b32 m0, s61
	s_nop 0
	global_load_lds_dwordx4 v[204:205], off
	v_lshl_add_u64 v[204:205], v[210:211], 0, s[24:25]
	s_mov_b32 m0, s62
	s_nop 0
	global_load_lds_dwordx4 v[204:205], off
	s_waitcnt vmcnt(8)
	s_waitcnt lgkmcnt(0)
	s_barrier
	s_setprio 1
	s_waitcnt lgkmcnt(0)
	v_mfma_f32_16x16x32_bf16 v[62:65], v[122:125], v[162:165], v[62:65]
	v_mfma_f32_16x16x32_bf16 v[58:61], v[130:133], v[162:165], v[58:61]
	v_mfma_f32_16x16x32_bf16 v[46:49], v[122:125], v[170:173], v[46:49]
	v_mfma_f32_16x16x32_bf16 v[42:45], v[130:133], v[170:173], v[42:45]
	v_mfma_f32_16x16x32_bf16 v[30:33], v[122:125], v[178:181], v[30:33]
	v_mfma_f32_16x16x32_bf16 v[26:29], v[130:133], v[178:181], v[26:29]
	v_mfma_f32_16x16x32_bf16 v[14:17], v[122:125], v[186:189], v[14:17]
	v_mfma_f32_16x16x32_bf16 v[10:13], v[130:133], v[186:189], v[10:13]
	v_mfma_f32_16x16x32_bf16 v[62:65], v[126:129], v[166:169], v[62:65]
	v_mfma_f32_16x16x32_bf16 v[58:61], v[134:137], v[166:169], v[58:61]
	v_mfma_f32_16x16x32_bf16 v[46:49], v[126:129], v[174:177], v[46:49]
	v_mfma_f32_16x16x32_bf16 v[42:45], v[134:137], v[174:177], v[42:45]
	v_mfma_f32_16x16x32_bf16 v[30:33], v[126:129], v[182:185], v[30:33]
	v_mfma_f32_16x16x32_bf16 v[26:29], v[134:137], v[182:185], v[26:29]
	v_mfma_f32_16x16x32_bf16 v[14:17], v[126:129], v[200:203], v[14:17]
	v_mfma_f32_16x16x32_bf16 v[10:13], v[134:137], v[200:203], v[10:13]
	v_mfma_f32_16x16x32_bf16 v[54:57], v[146:149], v[162:165], v[54:57]
	v_mfma_f32_16x16x32_bf16 v[50:53], v[154:157], v[162:165], v[50:53]
	v_mfma_f32_16x16x32_bf16 v[38:41], v[146:149], v[170:173], v[38:41]
	v_mfma_f32_16x16x32_bf16 v[34:37], v[154:157], v[170:173], v[34:37]
	v_mfma_f32_16x16x32_bf16 v[22:25], v[146:149], v[178:181], v[22:25]
	v_mfma_f32_16x16x32_bf16 v[18:21], v[154:157], v[178:181], v[18:21]
	v_mfma_f32_16x16x32_bf16 v[4:7], v[146:149], v[186:189], v[4:7]
	v_mfma_f32_16x16x32_bf16 v[0:3], v[154:157], v[186:189], v[0:3]
	v_mfma_f32_16x16x32_bf16 v[54:57], v[150:153], v[166:169], v[54:57]
	v_mfma_f32_16x16x32_bf16 v[50:53], v[158:161], v[166:169], v[50:53]
	v_mfma_f32_16x16x32_bf16 v[38:41], v[150:153], v[174:177], v[38:41]
	v_mfma_f32_16x16x32_bf16 v[34:37], v[158:161], v[174:177], v[34:37]
	v_mfma_f32_16x16x32_bf16 v[22:25], v[150:153], v[182:185], v[22:25]
	v_mfma_f32_16x16x32_bf16 v[18:21], v[158:161], v[182:185], v[18:21]
	v_mfma_f32_16x16x32_bf16 v[4:7], v[150:153], v[200:203], v[4:7]
	v_mfma_f32_16x16x32_bf16 v[0:3], v[158:161], v[200:203], v[0:3]
	s_setprio 0
	s_barrier
	s_add_i32 s37, s37, 2
	s_add_u32 s48, s48, 0x100
	s_addc_u32 s49, s49, 0
	s_add_u32 s39, s39, 0x100
	s_addc_u32 s36, s36, 0
	s_cmp_gt_u32 s37, 13
	s_cbranch_scc0 .LBB0_708
	s_and_b64 vcc, exec, s[12:13]
	s_movk_i32 s64, 0x1ff
	s_mov_b32 s96, 0x800000
	s_mov_b64 s[38:39], 0x800
	s_cbranch_vccz .LBB0_711
	s_barrier

; #define PG8_STAGE(bufoff, gbase, voff) do { _Pragma("unroll") for (int _i = 0; _i < 2; ++_i) \
;         __builtin_amdgcn_global_load_lds((const unsigned*)((const char*)(gbase) + (voff)[_i]), (PG8_LAS unsigned*)(lds + (bufoff) + ldsw + _i * 8192), 16, 0, 0); } while (0)
; #define PG8_LDA(dst, b, h) do { _Pragma("unroll") for (int m = 0; m < 4; ++m) _Pragma("unroll") for (int k = 0; k < 2; ++k) dst[m][k] = *(const PG8_LAS bf16x8*)(lds + PG8_SA(b, h) + aoff + m * 2048 + k * 1024); } while (0)
; #define PG8_LDB(dst, b, h) do { _Pragma("unroll") for (int n = 0; n < 2; ++n) _Pragma("unroll") for (int k = 0; k < 2; ++k) dst[n][k] = *(const PG8_LAS bf16x8*)(lds + PG8_SB(b, h) + boff + n * 2048 + k * 1024); } while (0)
; #define PG8_MMA(ai, bj, At, Bt) do { __builtin_amdgcn_s_setprio(1); _Pragma("unroll") for (int m = 0; m < 4; ++m) _Pragma("unroll") for (int n = 0; n < 2; ++n) _Pragma("unroll") for (int k = 0; k < 2; ++k) \
;         acc[ai][bj][m][n] = __builtin_amdgcn_mfma_f32_16x16x32_bf16(Bt[n][k], At[m][k], acc[ai][bj][m][n], 0, 0, 0); __builtin_amdgcn_s_setprio(0); } while (0)
; #define PG8_WAIT_V(n) asm volatile("s_waitcnt vmcnt(" #n ")" ::: "memory")
; #define PG8_WAIT_L(n) asm volatile("s_waitcnt lgkmcnt(" #n ")" ::: "memory")
; #define PG8_BAR __builtin_amdgcn_s_barrier()
; #define PG8_SCHED __builtin_amdgcn_sched_barrier(0)
; template <class Epi, class Sched, bool ALIGN_EPI = false, bool SP2 = false>
; __device__ __forceinline__ void gemm_phase(PG8_LAS unsigned char* lds, int tid_in, const Gemm g, const Sched& S, const Epi& E) {
;     ...
;             const char* a2 = last ? nA : cA + (size_t)(t + 2) * kstep; const char* b2 = last ? nB : cB + (size_t)(t + 2) * kstep;
;     ...
;             PG8_LDB(B0, 0, 0); PG8_LDB(B1, 0, 1); PG8_SCHED; PG8_LDA(At, 0, 0); PG8_STAGE(PG8_SA(1, 1), a1 + hstep, voffA);
;             PG8_WAIT_V(8); PG8_WAIT_L(0); PG8_BAR; PG8_MMA(0, 0, At, B0); PG8_MMA(0, 1, At, B1); PG8_BAR; PG8_SCHED;
;             PG8_LDA(At, 0, 1); PG8_STAGE(PG8_SB(0, 0), b2, voffB); PG8_STAGE(PG8_SB(0, 1), b2 + hstep, voffB); PG8_STAGE(PG8_SA(0, 0), a2, voffA);
;             PG8_WAIT_V(8); PG8_WAIT_L(0); PG8_BAR; PG8_MMA(1, 0, At, B0); PG8_MMA(1, 1, At, B1); PG8_BAR; PG8_SCHED;
.LBB0_835:
	s_add_u32 s18, s34, 0xfffc0080
	s_addc_u32 s42, s35, -1
	s_add_i32 s55, 0, 0x10000
	s_cmp_eq_u32 s37, 12
	s_cselect_b32 s49, s17, s42
	s_cselect_b32 s48, s53, s18
	s_cselect_b32 s43, s15, s36
	s_cselect_b32 s42, s38, s39
	s_add_i32 s18, 0, 0x14000
	v_add_u32_e32 v118, s55, v158
	v_add_u32_e32 v156, s18, v158
	ds_read_b128 v[106:109], v118
	ds_read_b128 v[110:113], v118 offset:1024
	ds_read_b128 v[114:117], v118 offset:2048
	ds_read_b128 v[118:121], v118 offset:3072
	ds_read_b128 v[160:163], v156
	ds_read_b128 v[164:167], v156 offset:1024
	ds_read_b128 v[168:171], v156 offset:2048
	ds_read_b128 v[172:175], v156 offset:3072
	v_lshl_add_u64 v[156:157], s[34:35], 0, v[152:153]
	s_add_i32 m0, s0, 0xc000
	ds_read_b128 v[176:179], v159
	ds_read_b128 v[180:183], v159 offset:1024
	ds_read_b128 v[184:187], v159 offset:2048
	ds_read_b128 v[188:191], v159 offset:3072
	ds_read_b128 v[192:195], v159 offset:4096
	ds_read_b128 v[196:199], v159 offset:5120
	ds_read_b128 v[200:203], v159 offset:6144
	ds_read_b128 v[210:213], v159 offset:7168
	global_load_lds_dwordx4 v[156:157], off
	v_lshl_add_u64 v[156:157], s[34:35], 0, v[154:155]
	s_add_i32 m0, s0, 0xe000
	s_nop 0
	global_load_lds_dwordx4 v[156:157], off
	s_waitcnt vmcnt(8)
	s_waitcnt lgkmcnt(0)
	s_barrier
	s_setprio 1
	s_waitcnt lgkmcnt(0)
	v_mfma_f32_16x16x32_bf16 v[142:145], v[106:109], v[176:179], v[142:145]
	v_mfma_f32_16x16x32_bf16 v[138:141], v[114:117], v[176:179], v[138:141]
	v_mfma_f32_16x16x32_bf16 v[126:129], v[106:109], v[184:187], v[126:129]
	v_mfma_f32_16x16x32_bf16 v[122:125], v[114:117], v[184:187], v[122:125]
	v_mfma_f32_16x16x32_bf16 v[94:97], v[106:109], v[192:195], v[94:97]
	v_mfma_f32_16x16x32_bf16 v[90:93], v[114:117], v[192:195], v[90:93]
	v_mfma_f32_16x16x32_bf16 v[78:81], v[106:109], v[200:203], v[78:81]
	v_mfma_f32_16x16x32_bf16 v[74:77], v[114:117], v[200:203], v[74:77]
	v_mfma_f32_16x16x32_bf16 v[142:145], v[110:113], v[180:183], v[142:145]
	v_mfma_f32_16x16x32_bf16 v[138:141], v[118:121], v[180:183], v[138:141]
	v_mfma_f32_16x16x32_bf16 v[126:129], v[110:113], v[188:191], v[126:129]
	v_mfma_f32_16x16x32_bf16 v[122:125], v[118:121], v[188:191], v[122:125]
	v_mfma_f32_16x16x32_bf16 v[94:97], v[110:113], v[196:199], v[94:97]
	v_mfma_f32_16x16x32_bf16 v[90:93], v[118:121], v[196:199], v[90:93]
	v_mfma_f32_16x16x32_bf16 v[78:81], v[110:113], v[210:213], v[78:81]
	v_mfma_f32_16x16x32_bf16 v[74:77], v[118:121], v[210:213], v[74:77]
	v_mfma_f32_16x16x32_bf16 v[134:137], v[160:163], v[176:179], v[134:137]
	v_mfma_f32_16x16x32_bf16 v[130:133], v[168:171], v[176:179], v[130:133]
	v_mfma_f32_16x16x32_bf16 v[102:105], v[160:163], v[184:187], v[102:105]
	v_mfma_f32_16x16x32_bf16 v[98:101], v[168:171], v[184:187], v[98:101]
	v_mfma_f32_16x16x32_bf16 v[86:89], v[160:163], v[192:195], v[86:89]
	v_mfma_f32_16x16x32_bf16 v[82:85], v[168:171], v[192:195], v[82:85]
	v_mfma_f32_16x16x32_bf16 v[70:73], v[160:163], v[200:203], v[70:73]
	v_mfma_f32_16x16x32_bf16 v[66:69], v[168:171], v[200:203], v[66:69]
	v_mfma_f32_16x16x32_bf16 v[134:137], v[164:167], v[180:183], v[134:137]
	v_mfma_f32_16x16x32_bf16 v[130:133], v[172:175], v[180:183], v[130:133]
	v_mfma_f32_16x16x32_bf16 v[102:105], v[164:167], v[188:191], v[102:105]
	v_mfma_f32_16x16x32_bf16 v[98:101], v[172:175], v[188:191], v[98:101]
	v_mfma_f32_16x16x32_bf16 v[86:89], v[164:167], v[196:199], v[86:89]
	v_mfma_f32_16x16x32_bf16 v[82:85], v[172:175], v[196:199], v[82:85]
	v_mfma_f32_16x16x32_bf16 v[70:73], v[164:167], v[210:213], v[70:73]
	v_mfma_f32_16x16x32_bf16 v[66:69], v[172:175], v[210:213], v[66:69]
	s_setprio 0
	s_barrier
	s_add_i32 s55, s55, s44
	v_lshl_add_u64 v[156:157], s[42:43], 0, v[8:9]
	s_mov_b32 m0, s55
	ds_read_b128 v[176:179], v159 offset:16384
	ds_read_b128 v[180:183], v159 offset:17408
	ds_read_b128 v[184:187], v159 offset:18432
	ds_read_b128 v[188:191], v159 offset:19456
	ds_read_b128 v[192:195], v159 offset:20480
	ds_read_b128 v[196:199], v159 offset:21504
	ds_read_b128 v[200:203], v159 offset:22528
	ds_read_b128 v[210:213], v159 offset:23552
	global_load_lds_dwordx4 v[156:157], off
	s_add_i32 m0, s55, 0x2000
	s_add_u32 s56, s42, 0x40000
	v_lshl_add_u64 v[204:205], s[42:43], 0, v[146:147]
	s_addc_u32 s57, s43, 0
	s_add_i32 s18, s18, s44
	global_load_lds_dwordx4 v[204:205], off
	v_lshl_add_u64 v[206:207], s[56:57], 0, v[8:9]
	s_mov_b32 m0, s18
	v_lshl_add_u64 v[208:209], s[48:49], 0, v[148:149]
	global_load_lds_dwordx4 v[206:207], off
	v_lshl_add_u64 v[206:207], s[56:57], 0, v[146:147]
	s_add_i32 m0, s18, 0x2000
	s_nop 0
	global_load_lds_dwordx4 v[206:207], off
	v_lshl_add_u64 v[206:207], s[48:49], 0, v[150:151]
	s_mov_b32 m0, s0
	s_nop 0
	global_load_lds_dwordx4 v[206:207], off
	s_mov_b32 m0, s1
	s_nop 0
	global_load_lds_dwordx4 v[208:209], off
	s_waitcnt vmcnt(8)
	s_waitcnt lgkmcnt(0)
	s_barrier
; #define PG8_STAGE(bufoff, gbase, voff) do { _Pragma("unroll") for (int _i = 0; _i < 2; ++_i) \
;         __builtin_amdgcn_global_load_lds((const unsigned*)((const char*)(gbase) + (voff)[_i]), (PG8_LAS unsigned*)(lds + (bufoff) + ldsw + _i * 8192), 16, 0, 0); } while (0)
; #define PG8_LDA(dst, b, h) do { _Pragma("unroll") for (int m = 0; m < 4; ++m) _Pragma("unroll") for (int k = 0; k < 2; ++k) dst[m][k] = *(const PG8_LAS bf16x8*)(lds + PG8_SA(b, h) + aoff + m * 2048 + k * 1024); } while (0)
; #define PG8_LDB(dst, b, h) do { _Pragma("unroll") for (int n = 0; n < 2; ++n) _Pragma("unroll") for (int k = 0; k < 2; ++k) dst[n][k] = *(const PG8_LAS bf16x8*)(lds + PG8_SB(b, h) + boff + n * 2048 + k * 1024); } while (0)
; #define PG8_MMA(ai, bj, At, Bt) do { __builtin_amdgcn_s_setprio(1); _Pragma("unroll") for (int m = 0; m < 4; ++m) _Pragma("unroll") for (int n = 0; n < 2; ++n) _Pragma("unroll") for (int k = 0; k < 2; ++k) \
;         acc[ai][bj][m][n] = __builtin_amdgcn_mfma_f32_16x16x32_bf16(Bt[n][k], At[m][k], acc[ai][bj][m][n], 0, 0, 0); __builtin_amdgcn_s_setprio(0); } while (0)
; #define PG8_WAIT_V(n) asm volatile("s_waitcnt vmcnt(" #n ")" ::: "memory")
; #define PG8_WAIT_L(n) asm volatile("s_waitcnt lgkmcnt(" #n ")" ::: "memory")
; #define PG8_BAR __builtin_amdgcn_s_barrier()
; #define PG8_SCHED __builtin_amdgcn_sched_barrier(0)
; template <class Epi, class Sched, bool ALIGN_EPI = false, bool SP2 = false>
; __device__ __forceinline__ void gemm_phase(PG8_LAS unsigned char* lds, int tid_in, const Gemm g, const Sched& S, const Epi& E) {
;     ...
;             PG8_WAIT_V(8); PG8_WAIT_L(0); PG8_BAR; PG8_MMA(1, 0, At, B0); PG8_MMA(1, 1, At, B1); PG8_BAR; PG8_SCHED;
;             PG8_LDB(B0, 1, 0); PG8_LDB(B1, 1, 1); PG8_SCHED; PG8_LDA(At, 1, 0); PG8_STAGE(PG8_SA(0, 1), a2 + hstep, voffA);
;             PG8_WAIT_V(8); PG8_WAIT_L(0); PG8_BAR; PG8_MMA(0, 0, At, B0); PG8_MMA(0, 1, At, B1); PG8_BAR; PG8_SCHED;
	s_setprio 1
	s_waitcnt lgkmcnt(0)
	v_mfma_f32_16x16x32_bf16 v[62:65], v[106:109], v[176:179], v[62:65]
	v_mfma_f32_16x16x32_bf16 v[58:61], v[114:117], v[176:179], v[58:61]
	v_mfma_f32_16x16x32_bf16 v[46:49], v[106:109], v[184:187], v[46:49]
	v_mfma_f32_16x16x32_bf16 v[42:45], v[114:117], v[184:187], v[42:45]
	v_mfma_f32_16x16x32_bf16 v[30:33], v[106:109], v[192:195], v[30:33]
	v_mfma_f32_16x16x32_bf16 v[26:29], v[114:117], v[192:195], v[26:29]
	v_mfma_f32_16x16x32_bf16 v[14:17], v[106:109], v[200:203], v[14:17]
	v_mfma_f32_16x16x32_bf16 v[10:13], v[114:117], v[200:203], v[10:13]
	v_mfma_f32_16x16x32_bf16 v[62:65], v[110:113], v[180:183], v[62:65]
	v_mfma_f32_16x16x32_bf16 v[58:61], v[118:121], v[180:183], v[58:61]
	v_mfma_f32_16x16x32_bf16 v[46:49], v[110:113], v[188:191], v[46:49]
	v_mfma_f32_16x16x32_bf16 v[42:45], v[118:121], v[188:191], v[42:45]
	v_mfma_f32_16x16x32_bf16 v[30:33], v[110:113], v[196:199], v[30:33]
	v_mfma_f32_16x16x32_bf16 v[26:29], v[118:121], v[196:199], v[26:29]
	v_mfma_f32_16x16x32_bf16 v[14:17], v[110:113], v[210:213], v[14:17]
	v_mfma_f32_16x16x32_bf16 v[10:13], v[118:121], v[210:213], v[10:13]
	v_mfma_f32_16x16x32_bf16 v[54:57], v[160:163], v[176:179], v[54:57]
	v_mfma_f32_16x16x32_bf16 v[50:53], v[168:171], v[176:179], v[50:53]
	v_mfma_f32_16x16x32_bf16 v[38:41], v[160:163], v[184:187], v[38:41]
	v_mfma_f32_16x16x32_bf16 v[34:37], v[168:171], v[184:187], v[34:37]
	v_mfma_f32_16x16x32_bf16 v[22:25], v[160:163], v[192:195], v[22:25]
	v_mfma_f32_16x16x32_bf16 v[18:21], v[168:171], v[192:195], v[18:21]
	v_mfma_f32_16x16x32_bf16 v[4:7], v[160:163], v[200:203], v[4:7]
	v_mfma_f32_16x16x32_bf16 v[0:3], v[168:171], v[200:203], v[0:3]
	v_mfma_f32_16x16x32_bf16 v[54:57], v[164:167], v[180:183], v[54:57]
	v_mfma_f32_16x16x32_bf16 v[50:53], v[172:175], v[180:183], v[50:53]
	v_mfma_f32_16x16x32_bf16 v[38:41], v[164:167], v[188:191], v[38:41]
	v_mfma_f32_16x16x32_bf16 v[34:37], v[172:175], v[188:191], v[34:37]
	v_mfma_f32_16x16x32_bf16 v[22:25], v[164:167], v[196:199], v[22:25]
	v_mfma_f32_16x16x32_bf16 v[18:21], v[172:175], v[196:199], v[18:21]
	v_mfma_f32_16x16x32_bf16 v[4:7], v[164:167], v[210:213], v[4:7]
	v_mfma_f32_16x16x32_bf16 v[0:3], v[172:175], v[210:213], v[0:3]
	s_setprio 0
	s_barrier
	s_add_i32 s18, 0, 0x18000
	s_add_i32 s55, 0, 0x1c000
	v_add_u32_e32 v118, s18, v158
	v_add_u32_e32 v172, s55, v158
	ds_read_b128 v[106:109], v118
	ds_read_b128 v[110:113], v118 offset:1024
	ds_read_b128 v[114:117], v118 offset:2048
	ds_read_b128 v[118:121], v118 offset:3072
	ds_read_b128 v[160:163], v172
	ds_read_b128 v[164:167], v172 offset:1024
	ds_read_b128 v[168:171], v172 offset:2048
	ds_read_b128 v[172:175], v172 offset:3072
	s_add_u32 s48, s48, 0x40000
	s_addc_u32 s49, s49, 0
	s_mov_b32 m0, s20
	v_lshl_add_u64 v[214:215], s[48:49], 0, v[150:151]
	ds_read_b128 v[176:179], v159 offset:32768
	ds_read_b128 v[180:183], v159 offset:33792
	ds_read_b128 v[184:187], v159 offset:34816
	ds_read_b128 v[188:191], v159 offset:35840
	ds_read_b128 v[192:195], v159 offset:36864
	ds_read_b128 v[196:199], v159 offset:37888
	ds_read_b128 v[200:203], v159 offset:38912
	ds_read_b128 v[210:213], v159 offset:39936
	global_load_lds_dwordx4 v[214:215], off
	v_lshl_add_u64 v[214:215], s[48:49], 0, v[148:149]
	s_mov_b32 m0, s21
	s_nop 0
	global_load_lds_dwordx4 v[214:215], off
	s_waitcnt vmcnt(8)
	s_waitcnt lgkmcnt(0)
	s_barrier
	s_setprio 1
	s_waitcnt lgkmcnt(0)
	v_mfma_f32_16x16x32_bf16 v[142:145], v[106:109], v[176:179], v[142:145]
	v_mfma_f32_16x16x32_bf16 v[138:141], v[114:117], v[176:179], v[138:141]
	v_mfma_f32_16x16x32_bf16 v[126:129], v[106:109], v[184:187], v[126:129]
	v_mfma_f32_16x16x32_bf16 v[122:125], v[114:117], v[184:187], v[122:125]
	v_mfma_f32_16x16x32_bf16 v[94:97], v[106:109], v[192:195], v[94:97]
	v_mfma_f32_16x16x32_bf16 v[90:93], v[114:117], v[192:195], v[90:93]
	v_mfma_f32_16x16x32_bf16 v[78:81], v[106:109], v[200:203], v[78:81]
	v_mfma_f32_16x16x32_bf16 v[74:77], v[114:117], v[200:203], v[74:77]
	v_mfma_f32_16x16x32_bf16 v[142:145], v[110:113], v[180:183], v[142:145]
	v_mfma_f32_16x16x32_bf16 v[138:141], v[118:121], v[180:183], v[138:141]
	v_mfma_f32_16x16x32_bf16 v[126:129], v[110:113], v[188:191], v[126:129]
	v_mfma_f32_16x16x32_bf16 v[122:125], v[118:121], v[188:191], v[122:125]
	v_mfma_f32_16x16x32_bf16 v[94:97], v[110:113], v[196:199], v[94:97]
	v_mfma_f32_16x16x32_bf16 v[90:93], v[118:121], v[196:199], v[90:93]
	v_mfma_f32_16x16x32_bf16 v[78:81], v[110:113], v[210:213], v[78:81]
	v_mfma_f32_16x16x32_bf16 v[74:77], v[118:121], v[210:213], v[74:77]
	v_mfma_f32_16x16x32_bf16 v[134:137], v[160:163], v[176:179], v[134:137]
	v_mfma_f32_16x16x32_bf16 v[130:133], v[168:171], v[176:179], v[130:133]
	v_mfma_f32_16x16x32_bf16 v[102:105], v[160:163], v[184:187], v[102:105]
	v_mfma_f32_16x16x32_bf16 v[98:101], v[168:171], v[184:187], v[98:101]
	v_mfma_f32_16x16x32_bf16 v[86:89], v[160:163], v[192:195], v[86:89]
	v_mfma_f32_16x16x32_bf16 v[82:85], v[168:171], v[192:195], v[82:85]
	v_mfma_f32_16x16x32_bf16 v[70:73], v[160:163], v[200:203], v[70:73]
	v_mfma_f32_16x16x32_bf16 v[66:69], v[168:171], v[200:203], v[66:69]
	v_mfma_f32_16x16x32_bf16 v[134:137], v[164:167], v[180:183], v[134:137]
	v_mfma_f32_16x16x32_bf16 v[130:133], v[172:175], v[180:183], v[130:133]
	v_mfma_f32_16x16x32_bf16 v[102:105], v[164:167], v[188:191], v[102:105]
	v_mfma_f32_16x16x32_bf16 v[98:101], v[172:175], v[188:191], v[98:101]
	v_mfma_f32_16x16x32_bf16 v[86:89], v[164:167], v[196:199], v[86:89]
	v_mfma_f32_16x16x32_bf16 v[82:85], v[172:175], v[196:199], v[82:85]
	v_mfma_f32_16x16x32_bf16 v[70:73], v[164:167], v[210:213], v[70:73]
	v_mfma_f32_16x16x32_bf16 v[66:69], v[172:175], v[210:213], v[66:69]
	s_setprio 0
	s_barrier
; #define PG8_STAGE(bufoff, gbase, voff) do { _Pragma("unroll") for (int _i = 0; _i < 2; ++_i) \
;         __builtin_amdgcn_global_load_lds((const unsigned*)((const char*)(gbase) + (voff)[_i]), (PG8_LAS unsigned*)(lds + (bufoff) + ldsw + _i * 8192), 16, 0, 0); } while (0)
; #define PG8_LDA(dst, b, h) do { _Pragma("unroll") for (int m = 0; m < 4; ++m) _Pragma("unroll") for (int k = 0; k < 2; ++k) dst[m][k] = *(const PG8_LAS bf16x8*)(lds + PG8_SA(b, h) + aoff + m * 2048 + k * 1024); } while (0)
; #define PG8_MMA(ai, bj, At, Bt) do { __builtin_amdgcn_s_setprio(1); _Pragma("unroll") for (int m = 0; m < 4; ++m) _Pragma("unroll") for (int n = 0; n < 2; ++n) _Pragma("unroll") for (int k = 0; k < 2; ++k) \
;         acc[ai][bj][m][n] = __builtin_amdgcn_mfma_f32_16x16x32_bf16(Bt[n][k], At[m][k], acc[ai][bj][m][n], 0, 0, 0); __builtin_amdgcn_s_setprio(0); } while (0)
; #define PG8_WAIT_V(n) asm volatile("s_waitcnt vmcnt(" #n ")" ::: "memory")
; #define PG8_WAIT_L(n) asm volatile("s_waitcnt lgkmcnt(" #n ")" ::: "memory")
; #define PG8_BAR __builtin_amdgcn_s_barrier()
; #define PG8_SCHED __builtin_amdgcn_sched_barrier(0)
; template <class Epi, class Sched, bool ALIGN_EPI = false, bool SP2 = false>
; __device__ __forceinline__ void gemm_phase(PG8_LAS unsigned char* lds, int tid_in, const Gemm g, const Sched& S, const Epi& E) {
;     ...
;         for (int t = 0; t < nt; t += 2) {
;     ...
;             PG8_LDA(At, 1, 1); PG8_STAGE(PG8_SB(1, 0), b3, voffB); PG8_STAGE(PG8_SB(1, 1), b3 + hstep, voffB); PG8_STAGE(PG8_SA(1, 0), a3, voffA);
;             PG8_WAIT_V(8); PG8_WAIT_L(0); PG8_BAR; PG8_MMA(1, 0, At, B0); PG8_MMA(1, 1, At, B1); PG8_BAR; PG8_SCHED;
;     ...
;         if constexpr (ALIGN_EPI) { if (wr == 0) PG8_BAR; }
	s_add_i32 s18, s18, s44
	v_lshl_add_u64 v[156:157], v[156:157], 0, s[24:25]
	s_mov_b32 m0, s18
	ds_read_b128 v[176:179], v159 offset:49152
	ds_read_b128 v[180:183], v159 offset:50176
	ds_read_b128 v[184:187], v159 offset:51200
	ds_read_b128 v[188:191], v159 offset:52224
	ds_read_b128 v[192:195], v159 offset:53248
	ds_read_b128 v[196:199], v159 offset:54272
	ds_read_b128 v[200:203], v159 offset:55296
	ds_read_b128 v[210:213], v159 offset:56320
	global_load_lds_dwordx4 v[156:157], off
	s_add_i32 m0, s18, 0x2000
	s_add_u32 s42, s42, 0x40080
	v_lshl_add_u64 v[156:157], v[204:205], 0, s[24:25]
	s_addc_u32 s43, s43, 0
	s_add_i32 s18, s55, s44
	global_load_lds_dwordx4 v[156:157], off
	v_lshl_add_u64 v[156:157], s[42:43], 0, v[8:9]
	s_mov_b32 m0, s18
	s_nop 0
	global_load_lds_dwordx4 v[156:157], off
	v_lshl_add_u64 v[156:157], s[42:43], 0, v[146:147]
	s_add_i32 m0, s18, 0x2000
	s_nop 0
	global_load_lds_dwordx4 v[156:157], off
	v_lshl_add_u64 v[156:157], v[206:207], 0, s[24:25]
	s_mov_b32 m0, s29
	s_nop 0
	global_load_lds_dwordx4 v[156:157], off
	v_lshl_add_u64 v[156:157], v[208:209], 0, s[24:25]
	s_mov_b32 m0, s46
	s_nop 0
	global_load_lds_dwordx4 v[156:157], off
	s_waitcnt vmcnt(8)
	s_waitcnt lgkmcnt(0)
	s_barrier
	s_setprio 1
	s_waitcnt lgkmcnt(0)
	v_mfma_f32_16x16x32_bf16 v[62:65], v[106:109], v[176:179], v[62:65]
	v_mfma_f32_16x16x32_bf16 v[58:61], v[114:117], v[176:179], v[58:61]
	v_mfma_f32_16x16x32_bf16 v[46:49], v[106:109], v[184:187], v[46:49]
	v_mfma_f32_16x16x32_bf16 v[42:45], v[114:117], v[184:187], v[42:45]
	v_mfma_f32_16x16x32_bf16 v[30:33], v[106:109], v[192:195], v[30:33]
	v_mfma_f32_16x16x32_bf16 v[26:29], v[114:117], v[192:195], v[26:29]
	v_mfma_f32_16x16x32_bf16 v[14:17], v[106:109], v[200:203], v[14:17]
	v_mfma_f32_16x16x32_bf16 v[10:13], v[114:117], v[200:203], v[10:13]
	v_mfma_f32_16x16x32_bf16 v[62:65], v[110:113], v[180:183], v[62:65]
	v_mfma_f32_16x16x32_bf16 v[58:61], v[118:121], v[180:183], v[58:61]
	v_mfma_f32_16x16x32_bf16 v[46:49], v[110:113], v[188:191], v[46:49]
	v_mfma_f32_16x16x32_bf16 v[42:45], v[118:121], v[188:191], v[42:45]
	v_mfma_f32_16x16x32_bf16 v[30:33], v[110:113], v[196:199], v[30:33]
	v_mfma_f32_16x16x32_bf16 v[26:29], v[118:121], v[196:199], v[26:29]
	v_mfma_f32_16x16x32_bf16 v[14:17], v[110:113], v[210:213], v[14:17]
	v_mfma_f32_16x16x32_bf16 v[10:13], v[118:121], v[210:213], v[10:13]
	v_mfma_f32_16x16x32_bf16 v[54:57], v[160:163], v[176:179], v[54:57]
	v_mfma_f32_16x16x32_bf16 v[50:53], v[168:171], v[176:179], v[50:53]
	v_mfma_f32_16x16x32_bf16 v[38:41], v[160:163], v[184:187], v[38:41]
	v_mfma_f32_16x16x32_bf16 v[34:37], v[168:171], v[184:187], v[34:37]
	v_mfma_f32_16x16x32_bf16 v[22:25], v[160:163], v[192:195], v[22:25]
	v_mfma_f32_16x16x32_bf16 v[18:21], v[168:171], v[192:195], v[18:21]
	v_mfma_f32_16x16x32_bf16 v[4:7], v[160:163], v[200:203], v[4:7]
	v_mfma_f32_16x16x32_bf16 v[0:3], v[168:171], v[200:203], v[0:3]
	v_mfma_f32_16x16x32_bf16 v[54:57], v[164:167], v[180:183], v[54:57]
	v_mfma_f32_16x16x32_bf16 v[50:53], v[172:175], v[180:183], v[50:53]
	v_mfma_f32_16x16x32_bf16 v[38:41], v[164:167], v[188:191], v[38:41]
	v_mfma_f32_16x16x32_bf16 v[34:37], v[172:175], v[188:191], v[34:37]
	v_mfma_f32_16x16x32_bf16 v[22:25], v[164:167], v[196:199], v[22:25]
	v_mfma_f32_16x16x32_bf16 v[18:21], v[172:175], v[196:199], v[18:21]
	v_mfma_f32_16x16x32_bf16 v[4:7], v[164:167], v[210:213], v[4:7]
	v_mfma_f32_16x16x32_bf16 v[0:3], v[172:175], v[210:213], v[0:3]
	s_setprio 0
	s_barrier
	s_add_i32 s37, s37, 2
	s_add_u32 s34, s34, 0x100
	s_addc_u32 s35, s35, 0
	s_add_u32 s39, s39, 0x100
	s_addc_u32 s36, s36, 0
	s_cmp_gt_u32 s37, 13
	s_cbranch_scc0 .LBB0_835
	s_and_b64 vcc, exec, s[12:13]
	s_cbranch_vccz .LBB0_838
	s_barrier

; #define PG8_STAGE(bufoff, gbase, voff) do { _Pragma("unroll") for (int _i = 0; _i < 2; ++_i) \
;         __builtin_amdgcn_global_load_lds((const unsigned*)((const char*)(gbase) + (voff)[_i]), (PG8_LAS unsigned*)(lds + (bufoff) + ldsw + _i * 8192), 16, 0, 0); } while (0)
; #define PG8_LDA(dst, b, h) do { _Pragma("unroll") for (int m = 0; m < 4; ++m) _Pragma("unroll") for (int k = 0; k < 2; ++k) dst[m][k] = *(const PG8_LAS bf16x8*)(lds + PG8_SA(b, h) + aoff + m * 2048 + k * 1024); } while (0)
; #define PG8_LDB(dst, b, h) do { _Pragma("unroll") for (int n = 0; n < 2; ++n) _Pragma("unroll") for (int k = 0; k < 2; ++k) dst[n][k] = *(const PG8_LAS bf16x8*)(lds + PG8_SB(b, h) + boff + n * 2048 + k * 1024); } while (0)
; #define PG8_MMA(ai, bj, At, Bt) do { __builtin_amdgcn_s_setprio(1); _Pragma("unroll") for (int m = 0; m < 4; ++m) _Pragma("unroll") for (int n = 0; n < 2; ++n) _Pragma("unroll") for (int k = 0; k < 2; ++k) \
;         acc[ai][bj][m][n] = __builtin_amdgcn_mfma_f32_16x16x32_bf16(Bt[n][k], At[m][k], acc[ai][bj][m][n], 0, 0, 0); __builtin_amdgcn_s_setprio(0); } while (0)
; #define PG8_WAIT_V(n) asm volatile("s_waitcnt vmcnt(" #n ")" ::: "memory")
; #define PG8_WAIT_L(n) asm volatile("s_waitcnt lgkmcnt(" #n ")" ::: "memory")
; #define PG8_BAR __builtin_amdgcn_s_barrier()
; #define PG8_SCHED __builtin_amdgcn_sched_barrier(0)
; template <class Epi, class Sched, bool ALIGN_EPI = false, bool SP2 = false>
; __device__ __forceinline__ void gemm_phase(PG8_LAS unsigned char* lds, int tid_in, const Gemm g, const Sched& S, const Epi& E) {
;     ...
;             const char* a2 = last ? nA : cA + (size_t)(t + 2) * kstep; const char* b2 = last ? nB : cB + (size_t)(t + 2) * kstep;
;     ...
;             PG8_LDB(B0, 0, 0); PG8_LDB(B1, 0, 1); PG8_SCHED; PG8_LDA(At, 0, 0); PG8_STAGE(PG8_SA(1, 1), a1 + hstep, voffA);
;             PG8_WAIT_V(8); PG8_WAIT_L(0); PG8_BAR; PG8_MMA(0, 0, At, B0); PG8_MMA(0, 1, At, B1); PG8_BAR; PG8_SCHED;
;             PG8_LDA(At, 0, 1); PG8_STAGE(PG8_SB(0, 0), b2, voffB); PG8_STAGE(PG8_SB(0, 1), b2 + hstep, voffB); PG8_STAGE(PG8_SA(0, 0), a2, voffA);
;             PG8_WAIT_V(8); PG8_WAIT_L(0); PG8_BAR; PG8_MMA(1, 0, At, B0); PG8_MMA(1, 1, At, B1); PG8_BAR; PG8_SCHED;
.LBB0_915:
	s_add_u32 s8, s6, 0xfff00080
	s_addc_u32 s9, s7, -1
	s_add_i32 s64, 0, 0x10000
	s_cmp_eq_u32 s18, 60
	s_cselect_b32 vcc_hi, s59, s9
	s_cselect_b32 vcc_lo, s38, s8
	s_cselect_b32 s9, s39, s37
	s_cselect_b32 s8, s43, s36
	s_add_i32 s66, 0, 0x14000
	v_add_u32_e32 v126, s64, v245
	v_add_u32_e32 v150, s66, v245
	ds_read_b128 v[110:113], v126
	ds_read_b128 v[118:121], v126 offset:1024
	ds_read_b128 v[122:125], v126 offset:2048
	ds_read_b128 v[126:129], v126 offset:3072
	ds_read_b128 v[134:137], v150
	ds_read_b128 v[142:145], v150 offset:1024
	ds_read_b128 v[146:149], v150 offset:2048
	ds_read_b128 v[150:153], v150 offset:3072
	v_lshl_add_u64 v[194:195], s[6:7], 0, v[224:225]
	s_add_i32 m0, s49, 0xc000
	ds_read_b128 v[154:157], v247
	ds_read_b128 v[166:169], v247 offset:1024
	ds_read_b128 v[170:173], v247 offset:2048
	ds_read_b128 v[174:177], v247 offset:3072
	ds_read_b128 v[178:181], v247 offset:4096
	ds_read_b128 v[182:185], v247 offset:5120
	ds_read_b128 v[186:189], v247 offset:6144
	ds_read_b128 v[190:193], v247 offset:7168
	global_load_lds_dwordx4 v[194:195], off
	v_lshl_add_u64 v[194:195], s[6:7], 0, v[226:227]
	s_add_i32 m0, s49, 0xe000
	s_nop 0
	global_load_lds_dwordx4 v[194:195], off
	s_waitcnt vmcnt(8)
	s_waitcnt lgkmcnt(0)
	s_barrier
	s_setprio 1
	s_waitcnt lgkmcnt(0)
	v_mfma_f32_16x16x32_bf16 v[162:165], v[110:113], v[154:157], v[162:165]
	v_mfma_f32_16x16x32_bf16 v[158:161], v[122:125], v[154:157], v[158:161]
	v_mfma_f32_16x16x32_bf16 v[114:117], v[110:113], v[170:173], v[114:117]
	v_mfma_f32_16x16x32_bf16 v[106:109], v[122:125], v[170:173], v[106:109]
	v_mfma_f32_16x16x32_bf16 v[94:97], v[110:113], v[178:181], v[94:97]
	v_mfma_f32_16x16x32_bf16 v[90:93], v[122:125], v[178:181], v[90:93]
	v_mfma_f32_16x16x32_bf16 v[78:81], v[110:113], v[186:189], v[78:81]
	v_mfma_f32_16x16x32_bf16 v[74:77], v[122:125], v[186:189], v[74:77]
	v_mfma_f32_16x16x32_bf16 v[162:165], v[118:121], v[166:169], v[162:165]
	v_mfma_f32_16x16x32_bf16 v[158:161], v[126:129], v[166:169], v[158:161]
	v_mfma_f32_16x16x32_bf16 v[114:117], v[118:121], v[174:177], v[114:117]
	v_mfma_f32_16x16x32_bf16 v[106:109], v[126:129], v[174:177], v[106:109]
	v_mfma_f32_16x16x32_bf16 v[94:97], v[118:121], v[182:185], v[94:97]
	v_mfma_f32_16x16x32_bf16 v[90:93], v[126:129], v[182:185], v[90:93]
	v_mfma_f32_16x16x32_bf16 v[78:81], v[118:121], v[190:193], v[78:81]
	v_mfma_f32_16x16x32_bf16 v[74:77], v[126:129], v[190:193], v[74:77]
	v_mfma_f32_16x16x32_bf16 v[138:141], v[134:137], v[154:157], v[138:141]
	v_mfma_f32_16x16x32_bf16 v[130:133], v[146:149], v[154:157], v[130:133]
	v_mfma_f32_16x16x32_bf16 v[102:105], v[134:137], v[170:173], v[102:105]
	v_mfma_f32_16x16x32_bf16 v[98:101], v[146:149], v[170:173], v[98:101]
	v_mfma_f32_16x16x32_bf16 v[86:89], v[134:137], v[178:181], v[86:89]
	v_mfma_f32_16x16x32_bf16 v[82:85], v[146:149], v[178:181], v[82:85]
	v_mfma_f32_16x16x32_bf16 v[70:73], v[134:137], v[186:189], v[70:73]
	v_mfma_f32_16x16x32_bf16 v[66:69], v[146:149], v[186:189], v[66:69]
	v_mfma_f32_16x16x32_bf16 v[138:141], v[142:145], v[166:169], v[138:141]
	v_mfma_f32_16x16x32_bf16 v[130:133], v[150:153], v[166:169], v[130:133]
	v_mfma_f32_16x16x32_bf16 v[102:105], v[142:145], v[174:177], v[102:105]
	v_mfma_f32_16x16x32_bf16 v[98:101], v[150:153], v[174:177], v[98:101]
	v_mfma_f32_16x16x32_bf16 v[86:89], v[142:145], v[182:185], v[86:89]
	v_mfma_f32_16x16x32_bf16 v[82:85], v[150:153], v[182:185], v[82:85]
	v_mfma_f32_16x16x32_bf16 v[70:73], v[142:145], v[190:193], v[70:73]
	v_mfma_f32_16x16x32_bf16 v[66:69], v[150:153], v[190:193], v[66:69]
	s_setprio 0
	s_barrier
	s_add_i32 s64, s64, s55
	v_lshl_add_u64 v[194:195], s[8:9], 0, v[8:9]
	s_mov_b32 m0, s64
	ds_read_b128 v[154:157], v247 offset:16384
	ds_read_b128 v[166:169], v247 offset:17408
	ds_read_b128 v[170:173], v247 offset:18432
	ds_read_b128 v[174:177], v247 offset:19456
	ds_read_b128 v[178:181], v247 offset:20480
	ds_read_b128 v[182:185], v247 offset:21504
	ds_read_b128 v[186:189], v247 offset:22528
	ds_read_b128 v[190:193], v247 offset:23552
	global_load_lds_dwordx4 v[194:195], off
	s_add_i32 m0, s64, 0x2000
	s_add_u32 s64, s8, 0x100000
	v_lshl_add_u64 v[196:197], s[8:9], 0, v[222:223]
	s_addc_u32 s65, s9, 0
	s_add_i32 s66, s66, s55
	global_load_lds_dwordx4 v[196:197], off
	v_lshl_add_u64 v[198:199], s[64:65], 0, v[8:9]
	s_mov_b32 m0, s66
	v_lshl_add_u64 v[200:201], vcc, 0, v[220:221]
	global_load_lds_dwordx4 v[198:199], off
	v_lshl_add_u64 v[198:199], s[64:65], 0, v[222:223]
	s_add_i32 m0, s66, 0x2000
	s_nop 0
	global_load_lds_dwordx4 v[198:199], off
	v_lshl_add_u64 v[198:199], vcc, 0, v[218:219]
	s_mov_b32 m0, s49
	s_nop 0
	global_load_lds_dwordx4 v[198:199], off
	s_mov_b32 m0, s62
	s_nop 0
	global_load_lds_dwordx4 v[200:201], off
	s_waitcnt vmcnt(8)
	s_waitcnt lgkmcnt(0)
	s_barrier
; #define PG8_STAGE(bufoff, gbase, voff) do { _Pragma("unroll") for (int _i = 0; _i < 2; ++_i) \
;         __builtin_amdgcn_global_load_lds((const unsigned*)((const char*)(gbase) + (voff)[_i]), (PG8_LAS unsigned*)(lds + (bufoff) + ldsw + _i * 8192), 16, 0, 0); } while (0)
; #define PG8_LDA(dst, b, h) do { _Pragma("unroll") for (int m = 0; m < 4; ++m) _Pragma("unroll") for (int k = 0; k < 2; ++k) dst[m][k] = *(const PG8_LAS bf16x8*)(lds + PG8_SA(b, h) + aoff + m * 2048 + k * 1024); } while (0)
; #define PG8_LDB(dst, b, h) do { _Pragma("unroll") for (int n = 0; n < 2; ++n) _Pragma("unroll") for (int k = 0; k < 2; ++k) dst[n][k] = *(const PG8_LAS bf16x8*)(lds + PG8_SB(b, h) + boff + n * 2048 + k * 1024); } while (0)
; #define PG8_MMA(ai, bj, At, Bt) do { __builtin_amdgcn_s_setprio(1); _Pragma("unroll") for (int m = 0; m < 4; ++m) _Pragma("unroll") for (int n = 0; n < 2; ++n) _Pragma("unroll") for (int k = 0; k < 2; ++k) \
;         acc[ai][bj][m][n] = __builtin_amdgcn_mfma_f32_16x16x32_bf16(Bt[n][k], At[m][k], acc[ai][bj][m][n], 0, 0, 0); __builtin_amdgcn_s_setprio(0); } while (0)
; #define PG8_WAIT_V(n) asm volatile("s_waitcnt vmcnt(" #n ")" ::: "memory")
; #define PG8_WAIT_L(n) asm volatile("s_waitcnt lgkmcnt(" #n ")" ::: "memory")
; #define PG8_BAR __builtin_amdgcn_s_barrier()
; #define PG8_SCHED __builtin_amdgcn_sched_barrier(0)
; template <class Epi, class Sched, bool ALIGN_EPI = false, bool SP2 = false>
; __device__ __forceinline__ void gemm_phase(PG8_LAS unsigned char* lds, int tid_in, const Gemm g, const Sched& S, const Epi& E) {
;     ...
;             PG8_WAIT_V(8); PG8_WAIT_L(0); PG8_BAR; PG8_MMA(1, 0, At, B0); PG8_MMA(1, 1, At, B1); PG8_BAR; PG8_SCHED;
;             PG8_LDB(B0, 1, 0); PG8_LDB(B1, 1, 1); PG8_SCHED; PG8_LDA(At, 1, 0); PG8_STAGE(PG8_SA(0, 1), a2 + hstep, voffA);
;             PG8_WAIT_V(8); PG8_WAIT_L(0); PG8_BAR; PG8_MMA(0, 0, At, B0); PG8_MMA(0, 1, At, B1); PG8_BAR; PG8_SCHED;
	s_setprio 1
	s_waitcnt lgkmcnt(0)
	v_mfma_f32_16x16x32_bf16 v[62:65], v[110:113], v[154:157], v[62:65]
	v_mfma_f32_16x16x32_bf16 v[58:61], v[122:125], v[154:157], v[58:61]
	v_mfma_f32_16x16x32_bf16 v[46:49], v[110:113], v[170:173], v[46:49]
	v_mfma_f32_16x16x32_bf16 v[42:45], v[122:125], v[170:173], v[42:45]
	v_mfma_f32_16x16x32_bf16 v[30:33], v[110:113], v[178:181], v[30:33]
	v_mfma_f32_16x16x32_bf16 v[26:29], v[122:125], v[178:181], v[26:29]
	v_mfma_f32_16x16x32_bf16 v[14:17], v[110:113], v[186:189], v[14:17]
	v_mfma_f32_16x16x32_bf16 v[10:13], v[122:125], v[186:189], v[10:13]
	v_mfma_f32_16x16x32_bf16 v[62:65], v[118:121], v[166:169], v[62:65]
	v_mfma_f32_16x16x32_bf16 v[58:61], v[126:129], v[166:169], v[58:61]
	v_mfma_f32_16x16x32_bf16 v[46:49], v[118:121], v[174:177], v[46:49]
	v_mfma_f32_16x16x32_bf16 v[42:45], v[126:129], v[174:177], v[42:45]
	v_mfma_f32_16x16x32_bf16 v[30:33], v[118:121], v[182:185], v[30:33]
	v_mfma_f32_16x16x32_bf16 v[26:29], v[126:129], v[182:185], v[26:29]
	v_mfma_f32_16x16x32_bf16 v[14:17], v[118:121], v[190:193], v[14:17]
	v_mfma_f32_16x16x32_bf16 v[10:13], v[126:129], v[190:193], v[10:13]
	v_mfma_f32_16x16x32_bf16 v[54:57], v[134:137], v[154:157], v[54:57]
	v_mfma_f32_16x16x32_bf16 v[50:53], v[146:149], v[154:157], v[50:53]
	v_mfma_f32_16x16x32_bf16 v[38:41], v[134:137], v[170:173], v[38:41]
	v_mfma_f32_16x16x32_bf16 v[34:37], v[146:149], v[170:173], v[34:37]
	v_mfma_f32_16x16x32_bf16 v[22:25], v[134:137], v[178:181], v[22:25]
	v_mfma_f32_16x16x32_bf16 v[18:21], v[146:149], v[178:181], v[18:21]
	v_mfma_f32_16x16x32_bf16 v[4:7], v[134:137], v[186:189], v[4:7]
	v_mfma_f32_16x16x32_bf16 v[0:3], v[146:149], v[186:189], v[0:3]
	v_mfma_f32_16x16x32_bf16 v[54:57], v[142:145], v[166:169], v[54:57]
	v_mfma_f32_16x16x32_bf16 v[50:53], v[150:153], v[166:169], v[50:53]
	v_mfma_f32_16x16x32_bf16 v[38:41], v[142:145], v[174:177], v[38:41]
	v_mfma_f32_16x16x32_bf16 v[34:37], v[150:153], v[174:177], v[34:37]
	v_mfma_f32_16x16x32_bf16 v[22:25], v[142:145], v[182:185], v[22:25]
	v_mfma_f32_16x16x32_bf16 v[18:21], v[150:153], v[182:185], v[18:21]
	v_mfma_f32_16x16x32_bf16 v[4:7], v[142:145], v[190:193], v[4:7]
	v_mfma_f32_16x16x32_bf16 v[0:3], v[150:153], v[190:193], v[0:3]
	s_setprio 0
	s_barrier
	s_add_i32 s66, 0, 0x18000
	s_add_i32 s67, 0, 0x1c000
	v_add_u32_e32 v126, s66, v245
	v_add_u32_e32 v150, s67, v245
	ds_read_b128 v[110:113], v126
	ds_read_b128 v[118:121], v126 offset:1024
	ds_read_b128 v[122:125], v126 offset:2048
	ds_read_b128 v[126:129], v126 offset:3072
	ds_read_b128 v[134:137], v150
	ds_read_b128 v[142:145], v150 offset:1024
	ds_read_b128 v[146:149], v150 offset:2048
	ds_read_b128 v[150:153], v150 offset:3072
	s_add_u32 s64, vcc_lo, 0x100000
	s_addc_u32 s65, vcc_hi, 0
	s_mov_b32 m0, s63
	v_lshl_add_u64 v[202:203], s[64:65], 0, v[218:219]
	ds_read_b128 v[154:157], v247 offset:32768
	ds_read_b128 v[166:169], v247 offset:33792
	ds_read_b128 v[170:173], v247 offset:34816
	ds_read_b128 v[174:177], v247 offset:35840
	ds_read_b128 v[178:181], v247 offset:36864
	ds_read_b128 v[182:185], v247 offset:37888
	ds_read_b128 v[186:189], v247 offset:38912
	ds_read_b128 v[190:193], v247 offset:39936
	global_load_lds_dwordx4 v[202:203], off
	v_lshl_add_u64 v[202:203], s[64:65], 0, v[220:221]
	s_mov_b32 m0, s0
	s_nop 0
	global_load_lds_dwordx4 v[202:203], off
	s_waitcnt vmcnt(8)
	s_waitcnt lgkmcnt(0)
	s_barrier
	s_setprio 1
	s_waitcnt lgkmcnt(0)
	v_mfma_f32_16x16x32_bf16 v[162:165], v[110:113], v[154:157], v[162:165]
	v_mfma_f32_16x16x32_bf16 v[158:161], v[122:125], v[154:157], v[158:161]
	v_mfma_f32_16x16x32_bf16 v[114:117], v[110:113], v[170:173], v[114:117]
	v_mfma_f32_16x16x32_bf16 v[106:109], v[122:125], v[170:173], v[106:109]
	v_mfma_f32_16x16x32_bf16 v[94:97], v[110:113], v[178:181], v[94:97]
	v_mfma_f32_16x16x32_bf16 v[90:93], v[122:125], v[178:181], v[90:93]
	v_mfma_f32_16x16x32_bf16 v[78:81], v[110:113], v[186:189], v[78:81]
	v_mfma_f32_16x16x32_bf16 v[74:77], v[122:125], v[186:189], v[74:77]
	v_mfma_f32_16x16x32_bf16 v[162:165], v[118:121], v[166:169], v[162:165]
	v_mfma_f32_16x16x32_bf16 v[158:161], v[126:129], v[166:169], v[158:161]
	v_mfma_f32_16x16x32_bf16 v[114:117], v[118:121], v[174:177], v[114:117]
	v_mfma_f32_16x16x32_bf16 v[106:109], v[126:129], v[174:177], v[106:109]
	v_mfma_f32_16x16x32_bf16 v[94:97], v[118:121], v[182:185], v[94:97]
	v_mfma_f32_16x16x32_bf16 v[90:93], v[126:129], v[182:185], v[90:93]
	v_mfma_f32_16x16x32_bf16 v[78:81], v[118:121], v[190:193], v[78:81]
	v_mfma_f32_16x16x32_bf16 v[74:77], v[126:129], v[190:193], v[74:77]
	v_mfma_f32_16x16x32_bf16 v[138:141], v[134:137], v[154:157], v[138:141]
	v_mfma_f32_16x16x32_bf16 v[130:133], v[146:149], v[154:157], v[130:133]
	v_mfma_f32_16x16x32_bf16 v[102:105], v[134:137], v[170:173], v[102:105]
	v_mfma_f32_16x16x32_bf16 v[98:101], v[146:149], v[170:173], v[98:101]
	v_mfma_f32_16x16x32_bf16 v[86:89], v[134:137], v[178:181], v[86:89]
	v_mfma_f32_16x16x32_bf16 v[82:85], v[146:149], v[178:181], v[82:85]
	v_mfma_f32_16x16x32_bf16 v[70:73], v[134:137], v[186:189], v[70:73]
	v_mfma_f32_16x16x32_bf16 v[66:69], v[146:149], v[186:189], v[66:69]
	v_mfma_f32_16x16x32_bf16 v[138:141], v[142:145], v[166:169], v[138:141]
	v_mfma_f32_16x16x32_bf16 v[130:133], v[150:153], v[166:169], v[130:133]
	v_mfma_f32_16x16x32_bf16 v[102:105], v[142:145], v[174:177], v[102:105]
	v_mfma_f32_16x16x32_bf16 v[98:101], v[150:153], v[174:177], v[98:101]
	v_mfma_f32_16x16x32_bf16 v[86:89], v[142:145], v[182:185], v[86:89]
	v_mfma_f32_16x16x32_bf16 v[82:85], v[150:153], v[182:185], v[82:85]
	v_mfma_f32_16x16x32_bf16 v[70:73], v[142:145], v[190:193], v[70:73]
	v_mfma_f32_16x16x32_bf16 v[66:69], v[150:153], v[190:193], v[66:69]
	s_setprio 0
	s_barrier
; #define PG8_STAGE(bufoff, gbase, voff) do { _Pragma("unroll") for (int _i = 0; _i < 2; ++_i) \
;         __builtin_amdgcn_global_load_lds((const unsigned*)((const char*)(gbase) + (voff)[_i]), (PG8_LAS unsigned*)(lds + (bufoff) + ldsw + _i * 8192), 16, 0, 0); } while (0)
; #define PG8_LDA(dst, b, h) do { _Pragma("unroll") for (int m = 0; m < 4; ++m) _Pragma("unroll") for (int k = 0; k < 2; ++k) dst[m][k] = *(const PG8_LAS bf16x8*)(lds + PG8_SA(b, h) + aoff + m * 2048 + k * 1024); } while (0)
; #define PG8_MMA(ai, bj, At, Bt) do { __builtin_amdgcn_s_setprio(1); _Pragma("unroll") for (int m = 0; m < 4; ++m) _Pragma("unroll") for (int n = 0; n < 2; ++n) _Pragma("unroll") for (int k = 0; k < 2; ++k) \
;         acc[ai][bj][m][n] = __builtin_amdgcn_mfma_f32_16x16x32_bf16(Bt[n][k], At[m][k], acc[ai][bj][m][n], 0, 0, 0); __builtin_amdgcn_s_setprio(0); } while (0)
; #define PG8_WAIT_V(n) asm volatile("s_waitcnt vmcnt(" #n ")" ::: "memory")
; #define PG8_WAIT_L(n) asm volatile("s_waitcnt lgkmcnt(" #n ")" ::: "memory")
; #define PG8_BAR __builtin_amdgcn_s_barrier()
; #define PG8_SCHED __builtin_amdgcn_sched_barrier(0)
; template <class Epi, class Sched, bool ALIGN_EPI = false, bool SP2 = false>
; __device__ __forceinline__ void gemm_phase(PG8_LAS unsigned char* lds, int tid_in, const Gemm g, const Sched& S, const Epi& E) {
;     ...
;         for (int t = 0; t < nt; t += 2) {
;     ...
;             PG8_LDA(At, 1, 1); PG8_STAGE(PG8_SB(1, 0), b3, voffB); PG8_STAGE(PG8_SB(1, 1), b3 + hstep, voffB); PG8_STAGE(PG8_SA(1, 0), a3, voffA);
;             PG8_WAIT_V(8); PG8_WAIT_L(0); PG8_BAR; PG8_MMA(1, 0, At, B0); PG8_MMA(1, 1, At, B1); PG8_BAR; PG8_SCHED;
;     ...
;         if constexpr (ALIGN_EPI) { if (wr == 0) PG8_BAR; }
	s_add_i32 s64, s66, s55
	v_lshl_add_u64 v[194:195], v[194:195], 0, s[24:25]
	s_mov_b32 m0, s64
	ds_read_b128 v[154:157], v247 offset:49152
	ds_read_b128 v[166:169], v247 offset:50176
	ds_read_b128 v[170:173], v247 offset:51200
	ds_read_b128 v[174:177], v247 offset:52224
	ds_read_b128 v[178:181], v247 offset:53248
	ds_read_b128 v[182:185], v247 offset:54272
	ds_read_b128 v[186:189], v247 offset:55296
	ds_read_b128 v[190:193], v247 offset:56320
	global_load_lds_dwordx4 v[194:195], off
	s_add_i32 m0, s64, 0x2000
	s_add_u32 s8, s8, 0x100080
	v_lshl_add_u64 v[194:195], v[196:197], 0, s[24:25]
	s_addc_u32 s9, s9, 0
	s_add_i32 s64, s67, s55
	global_load_lds_dwordx4 v[194:195], off
	v_lshl_add_u64 v[194:195], s[8:9], 0, v[8:9]
	s_mov_b32 m0, s64
	s_nop 0
	global_load_lds_dwordx4 v[194:195], off
	v_lshl_add_u64 v[194:195], s[8:9], 0, v[222:223]
	s_add_i32 m0, s64, 0x2000
	s_nop 0
	global_load_lds_dwordx4 v[194:195], off
	v_lshl_add_u64 v[194:195], v[198:199], 0, s[24:25]
	s_mov_b32 m0, s21
	s_nop 0
	global_load_lds_dwordx4 v[194:195], off
	v_lshl_add_u64 v[194:195], v[200:201], 0, s[24:25]
	s_mov_b32 m0, s96
	s_nop 0
	global_load_lds_dwordx4 v[194:195], off
	s_waitcnt vmcnt(8)
	s_waitcnt lgkmcnt(0)
	s_barrier
	s_setprio 1
	s_waitcnt lgkmcnt(0)
	v_mfma_f32_16x16x32_bf16 v[62:65], v[110:113], v[154:157], v[62:65]
	v_mfma_f32_16x16x32_bf16 v[58:61], v[122:125], v[154:157], v[58:61]
	v_mfma_f32_16x16x32_bf16 v[46:49], v[110:113], v[170:173], v[46:49]
	v_mfma_f32_16x16x32_bf16 v[42:45], v[122:125], v[170:173], v[42:45]
	v_mfma_f32_16x16x32_bf16 v[30:33], v[110:113], v[178:181], v[30:33]
	v_mfma_f32_16x16x32_bf16 v[26:29], v[122:125], v[178:181], v[26:29]
	v_mfma_f32_16x16x32_bf16 v[14:17], v[110:113], v[186:189], v[14:17]
	v_mfma_f32_16x16x32_bf16 v[10:13], v[122:125], v[186:189], v[10:13]
	v_mfma_f32_16x16x32_bf16 v[62:65], v[118:121], v[166:169], v[62:65]
	v_mfma_f32_16x16x32_bf16 v[58:61], v[126:129], v[166:169], v[58:61]
	v_mfma_f32_16x16x32_bf16 v[46:49], v[118:121], v[174:177], v[46:49]
	v_mfma_f32_16x16x32_bf16 v[42:45], v[126:129], v[174:177], v[42:45]
	v_mfma_f32_16x16x32_bf16 v[30:33], v[118:121], v[182:185], v[30:33]
	v_mfma_f32_16x16x32_bf16 v[26:29], v[126:129], v[182:185], v[26:29]
	v_mfma_f32_16x16x32_bf16 v[14:17], v[118:121], v[190:193], v[14:17]
	v_mfma_f32_16x16x32_bf16 v[10:13], v[126:129], v[190:193], v[10:13]
	v_mfma_f32_16x16x32_bf16 v[54:57], v[134:137], v[154:157], v[54:57]
	v_mfma_f32_16x16x32_bf16 v[50:53], v[146:149], v[154:157], v[50:53]
	v_mfma_f32_16x16x32_bf16 v[38:41], v[134:137], v[170:173], v[38:41]
	v_mfma_f32_16x16x32_bf16 v[34:37], v[146:149], v[170:173], v[34:37]
	v_mfma_f32_16x16x32_bf16 v[22:25], v[134:137], v[178:181], v[22:25]
	v_mfma_f32_16x16x32_bf16 v[18:21], v[146:149], v[178:181], v[18:21]
	v_mfma_f32_16x16x32_bf16 v[4:7], v[134:137], v[186:189], v[4:7]
	v_mfma_f32_16x16x32_bf16 v[0:3], v[146:149], v[186:189], v[0:3]
	v_mfma_f32_16x16x32_bf16 v[54:57], v[142:145], v[166:169], v[54:57]
	v_mfma_f32_16x16x32_bf16 v[50:53], v[150:153], v[166:169], v[50:53]
	v_mfma_f32_16x16x32_bf16 v[38:41], v[142:145], v[174:177], v[38:41]
	v_mfma_f32_16x16x32_bf16 v[34:37], v[150:153], v[174:177], v[34:37]
	v_mfma_f32_16x16x32_bf16 v[22:25], v[142:145], v[182:185], v[22:25]
	v_mfma_f32_16x16x32_bf16 v[18:21], v[150:153], v[182:185], v[18:21]
	v_mfma_f32_16x16x32_bf16 v[4:7], v[142:145], v[190:193], v[4:7]
	v_mfma_f32_16x16x32_bf16 v[0:3], v[150:153], v[190:193], v[0:3]
	s_setprio 0
	s_barrier
	s_add_i32 s18, s18, 2
	s_add_u32 s6, s6, 0x100
	s_addc_u32 s7, s7, 0
	s_add_u32 s36, s36, 0x100
	s_addc_u32 s37, s37, 0
	s_cmp_gt_u32 s18, 61
	s_cbranch_scc0 .LBB0_915
	s_and_b64 vcc, exec, s[34:35]
	s_cbranch_vccz .LBB0_918
	s_barrier
